# batched-load fast paths for prologue x->bf16 rows and final-norm rows (one round trip per row), saddr-form LDS-DMA in GEMM K-loops, MIX restructure
# speedup vs baseline: 1.0064x; 1.0064x over previous
.LBB0_12:
	s_or_b64 exec, exec, s[4:5]
	s_ashr_i32 s1, s1, 6
	s_add_u32 s2, s82, 0xba67300
	s_addc_u32 s3, s83, 0
	v_writelane_b32 v255, s2, 11
	s_add_u32 s10, s82, 0x3a00
	s_addc_u32 s11, s83, 0
	v_writelane_b32 v255, s3, 12
	s_lshl_b32 s2, s70, 3
	s_add_i32 s4, s1, s2
	v_writelane_b32 v255, s2, 13
	s_cmpk_gt_i32 s4, 0x407f
	s_cbranch_scc1 .LBB0_21
	v_and_b32_e32 v0, 63, v30
	s_lshl_b32 s12, s0, 3
	v_readlane_b32 s2, v255, 11
	v_lshlrev_b32_e32 v10, 2, v0
	v_cmp_eq_u32_e64 s[6:7], 0, v0
	v_mov_b32_e32 v1, 0
	v_lshlrev_b32_e32 v0, 3, v0
	v_readlane_b32 s3, v255, 12
	s_ashr_i32 s5, s4, 31
	s_ashr_i32 s13, s12, 31
	s_mov_b32 s9, 0
	v_xor_b32_e32 v4, 0x80, v10
	v_xor_b32_e32 v5, 64, v10
	v_xor_b32_e32 v6, 32, v10
	v_xor_b32_e32 v7, 16, v10
	v_xor_b32_e32 v8, 8, v10
	v_xor_b32_e32 v9, 4, v10
	v_lshl_add_u64 v[2:3], s[2:3], 0, v[0:1]
	s_lshl_b64 s[14:15], s[4:5], 12
	s_lshl_b64 s[16:17], s[12:13], 12
	v_lshlrev_b32_e32 v0, 2, v10
	v_readlane_b32 s18, v255, 2
	v_readlane_b32 s19, v255, 3
	s_lshl_b64 s[28:29], s[12:13], 11
	s_lshl_b64 s[30:31], s[12:13], 2
	s_nop 3
	s_load_dwordx2 s[24:25], s[18:19], 0x0
	s_waitcnt lgkmcnt(0)
.Lmy_pro_loop:
	s_cmpk_lt_i32 s4, 0x4000
	s_cbranch_scc0 .Lmy_pro_done
	s_add_u32 s20, s24, s14
	s_addc_u32 s21, s25, s15
	global_load_dwordx4 v[100:103], v0, s[20:21]
	global_load_dwordx4 v[104:107], v0, s[20:21] offset:1024
	global_load_dwordx4 v[108:111], v0, s[20:21] offset:2048
	global_load_dwordx4 v[112:115], v0, s[20:21] offset:3072
	s_add_u32 s14, s14, s16
	s_addc_u32 s15, s15, s17
	s_add_u32 s20, s24, s14
	s_addc_u32 s21, s25, s15
	global_load_dwordx4 v[116:119], v0, s[20:21]
	global_load_dwordx4 v[120:123], v0, s[20:21] offset:1024
	global_load_dwordx4 v[124:127], v0, s[20:21] offset:2048
	global_load_dwordx4 v[128:131], v0, s[20:21] offset:3072
	s_add_u32 s14, s14, s16
	s_addc_u32 s15, s15, s17
	s_lshl_b64 s[26:27], s[4:5], 11
	v_lshl_add_u64 v[26:27], v[2:3], 0, s[26:27]
	v_lshl_add_u64 v[28:29], v[26:27], 0, s[28:29]
	s_lshl_b64 s[2:3], s[4:5], 2
	s_add_u32 s2, s10, s2
	s_addc_u32 s3, s11, s3
	s_add_u32 s22, s2, s30
	s_addc_u32 s23, s3, s31
	s_waitcnt vmcnt(4)
	v_cvt_pk_bf16_f32 v132, v100, v101
	v_cvt_pk_bf16_f32 v133, v102, v103
	global_store_dwordx2 v[26:27], v[132:133], off
	v_cvt_pk_bf16_f32 v134, v104, v105
	v_cvt_pk_bf16_f32 v135, v106, v107
	global_store_dwordx2 v[26:27], v[134:135], off offset:512
	v_cvt_pk_bf16_f32 v136, v108, v109
	v_cvt_pk_bf16_f32 v137, v110, v111
	global_store_dwordx2 v[26:27], v[136:137], off offset:1024
	v_cvt_pk_bf16_f32 v138, v112, v113
	v_cvt_pk_bf16_f32 v139, v114, v115
	global_store_dwordx2 v[26:27], v[138:139], off offset:1536
	v_mul_f32_e32 v140, v101, v101
	v_mul_f32_e32 v141, v103, v103
	v_fmac_f32_e32 v140, v100, v100
	v_fmac_f32_e32 v141, v102, v102
	v_add_f32_e32 v142, v140, v141
	v_mul_f32_e32 v140, v105, v105
	v_mul_f32_e32 v141, v107, v107
	v_fmac_f32_e32 v140, v104, v104
	v_fmac_f32_e32 v141, v106, v106
	v_add_f32_e32 v140, v140, v141
	v_add_f32_e32 v142, v142, v140
	v_mul_f32_e32 v140, v109, v109
	v_mul_f32_e32 v141, v111, v111
	v_fmac_f32_e32 v140, v108, v108
	v_fmac_f32_e32 v141, v110, v110
	v_add_f32_e32 v140, v140, v141
	v_add_f32_e32 v142, v142, v140
	v_mul_f32_e32 v140, v113, v113
	v_mul_f32_e32 v141, v115, v115
	v_fmac_f32_e32 v140, v112, v112
	v_fmac_f32_e32 v141, v114, v114
	v_add_f32_e32 v140, v140, v141
	v_add_f32_e32 v142, v142, v140
	s_waitcnt vmcnt(4)
	v_cvt_pk_bf16_f32 v132, v116, v117
	v_cvt_pk_bf16_f32 v133, v118, v119
	global_store_dwordx2 v[28:29], v[132:133], off
	v_cvt_pk_bf16_f32 v134, v120, v121
	v_cvt_pk_bf16_f32 v135, v122, v123
	global_store_dwordx2 v[28:29], v[134:135], off offset:512
	v_cvt_pk_bf16_f32 v136, v124, v125
	v_cvt_pk_bf16_f32 v137, v126, v127
	global_store_dwordx2 v[28:29], v[136:137], off offset:1024
	v_cvt_pk_bf16_f32 v138, v128, v129
	v_cvt_pk_bf16_f32 v139, v130, v131
	global_store_dwordx2 v[28:29], v[138:139], off offset:1536
	v_mul_f32_e32 v140, v117, v117
	v_mul_f32_e32 v141, v119, v119
	v_fmac_f32_e32 v140, v116, v116
	v_fmac_f32_e32 v141, v118, v118
	v_add_f32_e32 v143, v140, v141
	v_mul_f32_e32 v140, v121, v121
	v_mul_f32_e32 v141, v123, v123
	v_fmac_f32_e32 v140, v120, v120
	v_fmac_f32_e32 v141, v122, v122
	v_add_f32_e32 v140, v140, v141
	v_add_f32_e32 v143, v143, v140
	v_mul_f32_e32 v140, v125, v125
	v_mul_f32_e32 v141, v127, v127
	v_fmac_f32_e32 v140, v124, v124
	v_fmac_f32_e32 v141, v126, v126
	v_add_f32_e32 v140, v140, v141
	v_add_f32_e32 v143, v143, v140
	v_mul_f32_e32 v140, v129, v129
	v_mul_f32_e32 v141, v131, v131
	v_fmac_f32_e32 v140, v128, v128
	v_fmac_f32_e32 v141, v130, v130
	v_add_f32_e32 v140, v140, v141
	v_add_f32_e32 v143, v143, v140
	ds_bpermute_b32 v144, v4, v142
	ds_bpermute_b32 v145, v4, v143
	s_waitcnt lgkmcnt(0)
	v_add_f32_e32 v142, v142, v144
	v_add_f32_e32 v143, v143, v145
	ds_bpermute_b32 v144, v5, v142
	ds_bpermute_b32 v145, v5, v143
	s_waitcnt lgkmcnt(0)
	v_add_f32_e32 v142, v142, v144
	v_add_f32_e32 v143, v143, v145
	ds_bpermute_b32 v144, v6, v142
	ds_bpermute_b32 v145, v6, v143
	s_waitcnt lgkmcnt(0)
	v_add_f32_e32 v142, v142, v144
	v_add_f32_e32 v143, v143, v145
	ds_bpermute_b32 v144, v7, v142
	ds_bpermute_b32 v145, v7, v143
	s_waitcnt lgkmcnt(0)
	v_add_f32_e32 v142, v142, v144
	v_add_f32_e32 v143, v143, v145
	ds_bpermute_b32 v144, v8, v142
	ds_bpermute_b32 v145, v8, v143
	s_waitcnt lgkmcnt(0)
	v_add_f32_e32 v142, v142, v144
	v_add_f32_e32 v143, v143, v145
	ds_bpermute_b32 v144, v9, v142
	ds_bpermute_b32 v145, v9, v143
	s_waitcnt lgkmcnt(0)
	v_add_f32_e32 v142, v142, v144
	v_add_f32_e32 v143, v143, v145
	s_and_saveexec_b64 s[20:21], s[6:7]
	global_store_dword v1, v142, s[2:3]
	global_store_dword v1, v143, s[22:23]
	s_or_b64 exec, exec, s[20:21]
	s_add_u32 s4, s4, s12
	s_addc_u32 s5, s5, s13
	s_add_u32 s4, s4, s12
	s_addc_u32 s5, s5, s13
	s_branch .Lmy_pro_loop
.Lmy_pro_done:
	s_cmpk_gt_i32 s4, 0x407f
	s_cbranch_scc1 .LBB0_21
	s_branch .LBB0_15

.LBB0_127:
	ds_read_b128 v[148:151], v234
	ds_read_b128 v[152:155], v234 offset:1024
	ds_read_b128 v[156:159], v234 offset:2048
	ds_read_b128 v[160:163], v234 offset:3072
	s_add_u32 s8, s40, 0xfffc0080
	s_addc_u32 s9, s41, -1
	s_cmp_eq_u32 s29, s64
	s_cselect_b32 s45, s2, s9
	s_cselect_b32 s44, s17, s8
	s_cselect_b32 s43, s25, s63
	s_cselect_b32 s42, s27, s39
	s_add_i32 m0, s46, 0xc000
	s_waitcnt lgkmcnt(0)
	ds_read_b128 v[164:167], v235
	ds_read_b128 v[168:171], v235 offset:1024
	ds_read_b128 v[172:175], v235 offset:2048
	ds_read_b128 v[176:179], v235 offset:3072
	ds_read_b128 v[180:183], v235 offset:4096
	ds_read_b128 v[184:187], v235 offset:5120
	ds_read_b128 v[188:191], v235 offset:6144
	ds_read_b128 v[192:195], v235 offset:7168
	global_load_lds_dwordx4 v214, s[40:41]
	s_add_i32 m0, s46, 0xe000
	s_nop 0
	global_load_lds_dwordx4 v216, s[40:41]
	s_waitcnt lgkmcnt(8)
	s_barrier
	s_waitcnt lgkmcnt(0)
	s_setprio 1
	s_waitcnt lgkmcnt(0)
	v_mfma_f32_16x16x32_bf16 v[72:75], v[148:151], v[164:167], v[72:75]
	v_mfma_f32_16x16x32_bf16 v[68:71], v[156:159], v[164:167], v[68:71]
	v_mfma_f32_16x16x32_bf16 v[56:59], v[148:151], v[172:175], v[56:59]
	v_mfma_f32_16x16x32_bf16 v[52:55], v[156:159], v[172:175], v[52:55]
	v_mfma_f32_16x16x32_bf16 v[40:43], v[148:151], v[180:183], v[40:43]
	v_mfma_f32_16x16x32_bf16 v[36:39], v[156:159], v[180:183], v[36:39]
	v_mfma_f32_16x16x32_bf16 v[24:27], v[148:151], v[188:191], v[24:27]
	v_mfma_f32_16x16x32_bf16 v[20:23], v[156:159], v[188:191], v[20:23]
	v_mfma_f32_16x16x32_bf16 v[72:75], v[152:155], v[168:171], v[72:75]
	v_mfma_f32_16x16x32_bf16 v[68:71], v[160:163], v[168:171], v[68:71]
	v_mfma_f32_16x16x32_bf16 v[56:59], v[152:155], v[176:179], v[56:59]
	v_mfma_f32_16x16x32_bf16 v[52:55], v[160:163], v[176:179], v[52:55]
	v_mfma_f32_16x16x32_bf16 v[40:43], v[152:155], v[184:187], v[40:43]
	v_mfma_f32_16x16x32_bf16 v[36:39], v[160:163], v[184:187], v[36:39]
	v_mfma_f32_16x16x32_bf16 v[24:27], v[152:155], v[192:195], v[24:27]
	v_mfma_f32_16x16x32_bf16 v[20:23], v[160:163], v[192:195], v[20:23]
	s_setprio 0
	s_barrier
	s_add_i32 s8, s59, s19
	v_lshl_add_u64 v[222:223], s[42:43], 0, v[198:199]
	s_mov_b32 m0, s8
	ds_read_b128 v[132:135], v237
	ds_read_b128 v[136:139], v237 offset:1024
	ds_read_b128 v[140:143], v237 offset:2048
	ds_read_b128 v[144:147], v237 offset:3072
	global_load_lds_dwordx4 v198, s[42:43]
	v_lshl_add_u64 v[224:225], s[42:43], 0, v[202:203]
	s_add_i32 m0, s8, 0x2000
	s_nop 0
	global_load_lds_dwordx4 v202, s[42:43]
	s_barrier
	s_waitcnt lgkmcnt(0)
	s_setprio 1
	s_waitcnt lgkmcnt(0)
	v_mfma_f32_16x16x32_bf16 v[64:67], v[132:135], v[164:167], v[64:67]
	v_mfma_f32_16x16x32_bf16 v[60:63], v[140:143], v[164:167], v[60:63]
	v_mfma_f32_16x16x32_bf16 v[48:51], v[132:135], v[172:175], v[48:51]
	v_mfma_f32_16x16x32_bf16 v[44:47], v[140:143], v[172:175], v[44:47]
	v_mfma_f32_16x16x32_bf16 v[32:35], v[132:135], v[180:183], v[32:35]
	v_mfma_f32_16x16x32_bf16 v[28:31], v[140:143], v[180:183], v[28:31]
	v_mfma_f32_16x16x32_bf16 v[16:19], v[132:135], v[188:191], v[16:19]
	v_mfma_f32_16x16x32_bf16 v[2:5], v[140:143], v[188:191], v[4:7]
	v_mfma_f32_16x16x32_bf16 v[64:67], v[136:139], v[168:171], v[64:67]
	v_mfma_f32_16x16x32_bf16 v[60:63], v[144:147], v[168:171], v[60:63]
	v_mfma_f32_16x16x32_bf16 v[48:51], v[136:139], v[176:179], v[48:51]
	v_mfma_f32_16x16x32_bf16 v[44:47], v[144:147], v[176:179], v[44:47]
	v_mfma_f32_16x16x32_bf16 v[32:35], v[136:139], v[184:187], v[32:35]
	v_mfma_f32_16x16x32_bf16 v[28:31], v[144:147], v[184:187], v[28:31]
	v_mfma_f32_16x16x32_bf16 v[16:19], v[136:139], v[192:195], v[16:19]
	v_mfma_f32_16x16x32_bf16 v[2:5], v[144:147], v[192:195], v[2:5]
	s_setprio 0
	s_mov_b32 m0, s46
	v_lshl_add_u64 v[226:227], s[44:45], 0, v[196:197]
	s_barrier
	ds_read_b128 v[188:191], v235 offset:16384
	ds_read_b128 v[192:195], v235 offset:17408
	ds_read_b128 v[180:183], v235 offset:18432
	ds_read_b128 v[184:187], v235 offset:19456
	ds_read_b128 v[172:175], v235 offset:20480
	ds_read_b128 v[176:179], v235 offset:21504
	ds_read_b128 v[164:167], v235 offset:22528
	ds_read_b128 v[168:171], v235 offset:23552
	global_load_lds_dwordx4 v196, s[44:45]
	v_lshl_add_u64 v[228:229], s[44:45], 0, v[200:201]
	s_mov_b32 m0, s47
	v_cmp_ne_u32_e64 s[8:9], 1, v245
	global_load_lds_dwordx4 v200, s[44:45]
	s_barrier
	s_waitcnt lgkmcnt(0)
	s_andn2_b64 vcc, exec, s[4:5]
	s_cbranch_vccnz .LBB0_129
	s_setprio 1
	s_waitcnt lgkmcnt(0)
	v_mfma_f32_16x16x32_bf16 v[128:131], v[148:151], v[188:191], v[128:131]
	v_mfma_f32_16x16x32_bf16 v[124:127], v[156:159], v[188:191], v[124:127]
	v_mfma_f32_16x16x32_bf16 v[112:115], v[148:151], v[180:183], v[112:115]
	v_mfma_f32_16x16x32_bf16 v[108:111], v[156:159], v[180:183], v[108:111]
	v_mfma_f32_16x16x32_bf16 v[96:99], v[148:151], v[172:175], v[96:99]
	v_mfma_f32_16x16x32_bf16 v[92:95], v[156:159], v[172:175], v[92:95]
	v_mfma_f32_16x16x32_bf16 v[80:83], v[148:151], v[164:167], v[80:83]
	v_mfma_f32_16x16x32_bf16 v[76:79], v[156:159], v[164:167], v[76:79]
	v_mfma_f32_16x16x32_bf16 v[128:131], v[152:155], v[192:195], v[128:131]
	v_mfma_f32_16x16x32_bf16 v[124:127], v[160:163], v[192:195], v[124:127]
	v_mfma_f32_16x16x32_bf16 v[112:115], v[152:155], v[184:187], v[112:115]
	v_mfma_f32_16x16x32_bf16 v[108:111], v[160:163], v[184:187], v[108:111]
	v_mfma_f32_16x16x32_bf16 v[96:99], v[152:155], v[176:179], v[96:99]
	v_mfma_f32_16x16x32_bf16 v[92:95], v[160:163], v[176:179], v[92:95]
	v_mfma_f32_16x16x32_bf16 v[80:83], v[152:155], v[168:171], v[80:83]
	v_mfma_f32_16x16x32_bf16 v[76:79], v[160:163], v[168:171], v[76:79]
	s_setprio 0
.LBB0_129:
	s_barrier
	s_add_u32 s66, s42, 0x40000
	s_addc_u32 s67, s43, 0
	s_mov_b32 m0, s48
	s_nop 0
	global_load_lds_dwordx4 v198, s[66:67]
	s_mov_b32 m0, s49
	s_and_b64 vcc, exec, s[8:9]
	global_load_lds_dwordx4 v202, s[66:67]
	s_waitcnt vmcnt(6)
	s_barrier
	s_cbranch_vccnz .LBB0_131
	s_setprio 1
	s_waitcnt lgkmcnt(0)
	v_mfma_f32_16x16x32_bf16 v[120:123], v[132:135], v[188:191], v[120:123]
	v_mfma_f32_16x16x32_bf16 v[116:119], v[140:143], v[188:191], v[116:119]
	v_mfma_f32_16x16x32_bf16 v[104:107], v[132:135], v[180:183], v[104:107]
	v_mfma_f32_16x16x32_bf16 v[100:103], v[140:143], v[180:183], v[100:103]
	v_mfma_f32_16x16x32_bf16 v[88:91], v[132:135], v[172:175], v[88:91]
	v_mfma_f32_16x16x32_bf16 v[84:87], v[140:143], v[172:175], v[84:87]
	v_mfma_f32_16x16x32_bf16 v[12:15], v[132:135], v[164:167], v[12:15]
	v_mfma_f32_16x16x32_bf16 v[6:9], v[140:143], v[164:167], v[8:11]
	v_mfma_f32_16x16x32_bf16 v[120:123], v[136:139], v[192:195], v[120:123]
	v_mfma_f32_16x16x32_bf16 v[116:119], v[144:147], v[192:195], v[116:119]
	v_mfma_f32_16x16x32_bf16 v[104:107], v[136:139], v[184:187], v[104:107]
	v_mfma_f32_16x16x32_bf16 v[100:103], v[144:147], v[184:187], v[100:103]
	v_mfma_f32_16x16x32_bf16 v[88:91], v[136:139], v[176:179], v[88:91]
	v_mfma_f32_16x16x32_bf16 v[84:87], v[144:147], v[176:179], v[84:87]
	v_mfma_f32_16x16x32_bf16 v[12:15], v[136:139], v[168:171], v[12:15]
	v_mfma_f32_16x16x32_bf16 v[8:11], v[144:147], v[168:171], v[6:9]
	s_setprio 0
.LBB0_131:
	s_add_i32 s65, 0, 0x18000
	v_add_u32_e32 v1, s65, v230
	s_barrier
	ds_read_b128 v[148:151], v1
	ds_read_b128 v[152:155], v1 offset:1024
	ds_read_b128 v[156:159], v1 offset:2048
	ds_read_b128 v[160:163], v1 offset:3072
	s_add_u32 s44, s44, 0x40000
	s_addc_u32 s45, s45, 0
	s_mov_b32 m0, s50
	s_waitcnt lgkmcnt(0)
	ds_read_b128 v[164:167], v235 offset:32768
	ds_read_b128 v[168:171], v235 offset:33792
	ds_read_b128 v[172:175], v235 offset:34816
	ds_read_b128 v[176:179], v235 offset:35840
	ds_read_b128 v[180:183], v235 offset:36864
	ds_read_b128 v[184:187], v235 offset:37888
	ds_read_b128 v[188:191], v235 offset:38912
	ds_read_b128 v[192:195], v235 offset:39936
	global_load_lds_dwordx4 v196, s[44:45]
	s_mov_b32 m0, s51
	s_nop 0
	global_load_lds_dwordx4 v200, s[44:45]
	s_waitcnt lgkmcnt(8)
	s_barrier
	s_waitcnt lgkmcnt(0)
	s_setprio 1
	s_waitcnt lgkmcnt(0)
	v_mfma_f32_16x16x32_bf16 v[72:75], v[148:151], v[164:167], v[72:75]
	v_mfma_f32_16x16x32_bf16 v[68:71], v[156:159], v[164:167], v[68:71]
	v_mfma_f32_16x16x32_bf16 v[56:59], v[148:151], v[172:175], v[56:59]
	v_mfma_f32_16x16x32_bf16 v[52:55], v[156:159], v[172:175], v[52:55]
	v_mfma_f32_16x16x32_bf16 v[40:43], v[148:151], v[180:183], v[40:43]
	v_mfma_f32_16x16x32_bf16 v[36:39], v[156:159], v[180:183], v[36:39]
	v_mfma_f32_16x16x32_bf16 v[24:27], v[148:151], v[188:191], v[24:27]
	v_mfma_f32_16x16x32_bf16 v[20:23], v[156:159], v[188:191], v[20:23]
	v_mfma_f32_16x16x32_bf16 v[72:75], v[152:155], v[168:171], v[72:75]
	v_mfma_f32_16x16x32_bf16 v[68:71], v[160:163], v[168:171], v[68:71]
	v_mfma_f32_16x16x32_bf16 v[56:59], v[152:155], v[176:179], v[56:59]
	v_mfma_f32_16x16x32_bf16 v[52:55], v[160:163], v[176:179], v[52:55]
	v_mfma_f32_16x16x32_bf16 v[40:43], v[152:155], v[184:187], v[40:43]
	v_mfma_f32_16x16x32_bf16 v[36:39], v[160:163], v[184:187], v[36:39]
	v_mfma_f32_16x16x32_bf16 v[24:27], v[152:155], v[192:195], v[24:27]
	v_mfma_f32_16x16x32_bf16 v[20:23], v[160:163], v[192:195], v[20:23]
	s_setprio 0
	s_barrier
	s_add_i32 s44, s65, s19
	v_add_u32_e32 v1, 0x1c000, v236
	v_lshl_add_u64 v[6:7], v[222:223], 0, s[22:23]
	s_mov_b32 m0, s44
	ds_read_b128 v[132:135], v1
	ds_read_b128 v[136:139], v1 offset:1024
	ds_read_b128 v[140:143], v1 offset:2048
	ds_read_b128 v[144:147], v1 offset:3072
	global_load_lds_dwordx4 v[6:7], off
	v_lshl_add_u64 v[6:7], v[224:225], 0, s[22:23]
	s_add_i32 m0, s44, 0x2000
	s_nop 0
	global_load_lds_dwordx4 v[6:7], off
	s_barrier
	s_waitcnt lgkmcnt(0)
	s_setprio 1
	s_waitcnt lgkmcnt(0)
	v_mfma_f32_16x16x32_bf16 v[64:67], v[132:135], v[164:167], v[64:67]
	v_mfma_f32_16x16x32_bf16 v[60:63], v[140:143], v[164:167], v[60:63]
	v_mfma_f32_16x16x32_bf16 v[48:51], v[132:135], v[172:175], v[48:51]
	v_mfma_f32_16x16x32_bf16 v[44:47], v[140:143], v[172:175], v[44:47]
	v_mfma_f32_16x16x32_bf16 v[32:35], v[132:135], v[180:183], v[32:35]
	v_mfma_f32_16x16x32_bf16 v[28:31], v[140:143], v[180:183], v[28:31]
	v_mfma_f32_16x16x32_bf16 v[16:19], v[132:135], v[188:191], v[16:19]
	v_mfma_f32_16x16x32_bf16 v[2:5], v[140:143], v[188:191], v[2:5]
	v_mfma_f32_16x16x32_bf16 v[64:67], v[136:139], v[168:171], v[64:67]
	v_mfma_f32_16x16x32_bf16 v[60:63], v[144:147], v[168:171], v[60:63]
	v_mfma_f32_16x16x32_bf16 v[48:51], v[136:139], v[176:179], v[48:51]
	v_mfma_f32_16x16x32_bf16 v[44:47], v[144:147], v[176:179], v[44:47]
	v_mfma_f32_16x16x32_bf16 v[32:35], v[136:139], v[184:187], v[32:35]
	v_mfma_f32_16x16x32_bf16 v[28:31], v[144:147], v[184:187], v[28:31]
	v_mfma_f32_16x16x32_bf16 v[16:19], v[136:139], v[192:195], v[16:19]
	v_mfma_f32_16x16x32_bf16 v[4:7], v[144:147], v[192:195], v[2:5]
	s_setprio 0
	s_mov_b32 m0, s53
	s_nop 0
	v_lshl_add_u64 v[2:3], v[226:227], 0, s[22:23]
	s_barrier
	ds_read_b128 v[188:191], v235 offset:49152
	ds_read_b128 v[192:195], v235 offset:50176
	ds_read_b128 v[180:183], v235 offset:51200
	ds_read_b128 v[184:187], v235 offset:52224
	ds_read_b128 v[172:175], v235 offset:53248
	ds_read_b128 v[176:179], v235 offset:54272
	ds_read_b128 v[164:167], v235 offset:55296
	ds_read_b128 v[168:171], v235 offset:56320
	global_load_lds_dwordx4 v[2:3], off
	v_lshl_add_u64 v[2:3], v[228:229], 0, s[22:23]
	s_mov_b32 m0, s54
	s_and_b64 vcc, exec, s[8:9]
	global_load_lds_dwordx4 v[2:3], off
	s_barrier
	s_waitcnt lgkmcnt(0)
	s_cbranch_vccnz .LBB0_133
	s_setprio 1
	s_waitcnt lgkmcnt(0)
	v_mfma_f32_16x16x32_bf16 v[128:131], v[148:151], v[188:191], v[128:131]
	v_mfma_f32_16x16x32_bf16 v[124:127], v[156:159], v[188:191], v[124:127]
	v_mfma_f32_16x16x32_bf16 v[112:115], v[148:151], v[180:183], v[112:115]
	v_mfma_f32_16x16x32_bf16 v[108:111], v[156:159], v[180:183], v[108:111]
	v_mfma_f32_16x16x32_bf16 v[96:99], v[148:151], v[172:175], v[96:99]
	v_mfma_f32_16x16x32_bf16 v[92:95], v[156:159], v[172:175], v[92:95]
	v_mfma_f32_16x16x32_bf16 v[80:83], v[148:151], v[164:167], v[80:83]
	v_mfma_f32_16x16x32_bf16 v[76:79], v[156:159], v[164:167], v[76:79]
	v_mfma_f32_16x16x32_bf16 v[128:131], v[152:155], v[192:195], v[128:131]
	v_mfma_f32_16x16x32_bf16 v[124:127], v[160:163], v[192:195], v[124:127]
	v_mfma_f32_16x16x32_bf16 v[112:115], v[152:155], v[184:187], v[112:115]
	v_mfma_f32_16x16x32_bf16 v[108:111], v[160:163], v[184:187], v[108:111]
	v_mfma_f32_16x16x32_bf16 v[96:99], v[152:155], v[176:179], v[96:99]
	v_mfma_f32_16x16x32_bf16 v[92:95], v[160:163], v[176:179], v[92:95]
	v_mfma_f32_16x16x32_bf16 v[80:83], v[152:155], v[168:171], v[80:83]
	v_mfma_f32_16x16x32_bf16 v[76:79], v[160:163], v[168:171], v[76:79]
	s_setprio 0
.LBB0_133:
	s_barrier
	s_add_u32 s42, s42, 0x40080
	s_addc_u32 s43, s43, 0
	s_mov_b32 m0, s55
	s_nop 0
	global_load_lds_dwordx4 v198, s[42:43]
	s_mov_b32 m0, s56
	s_and_b64 vcc, exec, s[8:9]
	global_load_lds_dwordx4 v202, s[42:43]
	s_waitcnt vmcnt(6)
	s_barrier
	s_cbranch_vccnz .LBB0_126
	s_setprio 1
	s_waitcnt lgkmcnt(0)
	v_mfma_f32_16x16x32_bf16 v[120:123], v[132:135], v[188:191], v[120:123]
	v_mfma_f32_16x16x32_bf16 v[116:119], v[140:143], v[188:191], v[116:119]
	v_mfma_f32_16x16x32_bf16 v[104:107], v[132:135], v[180:183], v[104:107]
	v_mfma_f32_16x16x32_bf16 v[100:103], v[140:143], v[180:183], v[100:103]
	v_mfma_f32_16x16x32_bf16 v[88:91], v[132:135], v[172:175], v[88:91]
	v_mfma_f32_16x16x32_bf16 v[84:87], v[140:143], v[172:175], v[84:87]
	v_mfma_f32_16x16x32_bf16 v[12:15], v[132:135], v[164:167], v[12:15]
	v_mfma_f32_16x16x32_bf16 v[8:11], v[140:143], v[164:167], v[8:11]
	v_mfma_f32_16x16x32_bf16 v[120:123], v[136:139], v[192:195], v[120:123]
	v_mfma_f32_16x16x32_bf16 v[116:119], v[144:147], v[192:195], v[116:119]
	v_mfma_f32_16x16x32_bf16 v[104:107], v[136:139], v[184:187], v[104:107]
	v_mfma_f32_16x16x32_bf16 v[100:103], v[144:147], v[184:187], v[100:103]
	v_mfma_f32_16x16x32_bf16 v[88:91], v[136:139], v[176:179], v[88:91]
	v_mfma_f32_16x16x32_bf16 v[84:87], v[144:147], v[176:179], v[84:87]
	v_mfma_f32_16x16x32_bf16 v[12:15], v[136:139], v[168:171], v[12:15]
	v_mfma_f32_16x16x32_bf16 v[8:11], v[144:147], v[168:171], v[8:11]
	s_setprio 0
	s_branch .LBB0_126

.LBB0_391:
	ds_read_b128 v[148:151], v205
	ds_read_b128 v[152:155], v205 offset:1024
	ds_read_b128 v[156:159], v205 offset:2048
	ds_read_b128 v[160:163], v205 offset:3072
	s_add_u32 s12, s30, 0xfff80080
	s_addc_u32 s13, s31, -1
	s_cmp_eq_u32 s21, s55
	s_cselect_b32 s37, s2, s13
	s_cselect_b32 s36, s5, s12
	s_cselect_b32 s35, s17, s54
	s_cselect_b32 s34, s19, s53
	s_add_i32 m0, s9, 0xc000
	s_waitcnt lgkmcnt(0)
	ds_read_b128 v[164:167], v230
	ds_read_b128 v[168:171], v230 offset:1024
	ds_read_b128 v[172:175], v230 offset:2048
	ds_read_b128 v[176:179], v230 offset:3072
	ds_read_b128 v[180:183], v230 offset:4096
	ds_read_b128 v[184:187], v230 offset:5120
	ds_read_b128 v[188:191], v230 offset:6144
	ds_read_b128 v[192:195], v230 offset:7168
	global_load_lds_dwordx4 v214, s[30:31]
	s_add_i32 m0, s9, 0xe000
	s_nop 0
	global_load_lds_dwordx4 v216, s[30:31]
	s_waitcnt lgkmcnt(8)
	s_barrier
	s_waitcnt lgkmcnt(0)
	s_setprio 1
	s_waitcnt lgkmcnt(0)
	v_mfma_f32_16x16x32_bf16 v[84:87], v[148:151], v[164:167], v[84:87]
	v_mfma_f32_16x16x32_bf16 v[76:79], v[156:159], v[164:167], v[76:79]
	v_mfma_f32_16x16x32_bf16 v[64:67], v[148:151], v[172:175], v[64:67]
	v_mfma_f32_16x16x32_bf16 v[60:63], v[156:159], v[172:175], v[60:63]
	v_mfma_f32_16x16x32_bf16 v[48:51], v[148:151], v[180:183], v[48:51]
	v_mfma_f32_16x16x32_bf16 v[44:47], v[156:159], v[180:183], v[44:47]
	v_mfma_f32_16x16x32_bf16 v[32:35], v[148:151], v[188:191], v[32:35]
	v_mfma_f32_16x16x32_bf16 v[24:27], v[156:159], v[188:191], v[24:27]
	v_mfma_f32_16x16x32_bf16 v[84:87], v[152:155], v[168:171], v[84:87]
	v_mfma_f32_16x16x32_bf16 v[76:79], v[160:163], v[168:171], v[76:79]
	v_mfma_f32_16x16x32_bf16 v[64:67], v[152:155], v[176:179], v[64:67]
	v_mfma_f32_16x16x32_bf16 v[60:63], v[160:163], v[176:179], v[60:63]
	v_mfma_f32_16x16x32_bf16 v[48:51], v[152:155], v[184:187], v[48:51]
	v_mfma_f32_16x16x32_bf16 v[44:47], v[160:163], v[184:187], v[44:47]
	v_mfma_f32_16x16x32_bf16 v[32:35], v[152:155], v[192:195], v[32:35]
	v_mfma_f32_16x16x32_bf16 v[24:27], v[160:163], v[192:195], v[24:27]
	s_setprio 0
	s_barrier
	s_add_i32 s12, s51, s38
	v_lshl_add_u64 v[2:3], s[34:35], 0, v[198:199]
	s_mov_b32 m0, s12
	ds_read_b128 v[132:135], v232
	ds_read_b128 v[136:139], v232 offset:1024
	ds_read_b128 v[140:143], v232 offset:2048
	ds_read_b128 v[144:147], v232 offset:3072
	global_load_lds_dwordx4 v198, s[34:35]
	v_lshl_add_u64 v[220:221], s[34:35], 0, v[202:203]
	s_add_i32 m0, s12, 0x2000
	s_nop 0
	global_load_lds_dwordx4 v202, s[34:35]
	s_barrier
	s_waitcnt lgkmcnt(0)
	s_setprio 1
	s_waitcnt lgkmcnt(0)
	v_mfma_f32_16x16x32_bf16 v[72:75], v[132:135], v[164:167], v[72:75]
	v_mfma_f32_16x16x32_bf16 v[68:71], v[140:143], v[164:167], v[68:71]
	v_mfma_f32_16x16x32_bf16 v[56:59], v[132:135], v[172:175], v[56:59]
	v_mfma_f32_16x16x32_bf16 v[52:55], v[140:143], v[172:175], v[52:55]
	v_mfma_f32_16x16x32_bf16 v[40:43], v[132:135], v[180:183], v[40:43]
	v_mfma_f32_16x16x32_bf16 v[36:39], v[140:143], v[180:183], v[36:39]
	v_mfma_f32_16x16x32_bf16 v[20:23], v[132:135], v[188:191], v[20:23]
	v_mfma_f32_16x16x32_bf16 v[12:15], v[140:143], v[188:191], v[12:15]
	v_mfma_f32_16x16x32_bf16 v[72:75], v[136:139], v[168:171], v[72:75]
	v_mfma_f32_16x16x32_bf16 v[68:71], v[144:147], v[168:171], v[68:71]
	v_mfma_f32_16x16x32_bf16 v[56:59], v[136:139], v[176:179], v[56:59]
	v_mfma_f32_16x16x32_bf16 v[52:55], v[144:147], v[176:179], v[52:55]
	v_mfma_f32_16x16x32_bf16 v[40:43], v[136:139], v[184:187], v[40:43]
	v_mfma_f32_16x16x32_bf16 v[36:39], v[144:147], v[184:187], v[36:39]
	v_mfma_f32_16x16x32_bf16 v[20:23], v[136:139], v[192:195], v[20:23]
	v_mfma_f32_16x16x32_bf16 v[12:15], v[144:147], v[192:195], v[12:15]
	s_setprio 0
	s_mov_b32 m0, s9
	v_lshl_add_u64 v[222:223], s[36:37], 0, v[196:197]
	s_barrier
	ds_read_b128 v[188:191], v230 offset:16384
	ds_read_b128 v[192:195], v230 offset:17408
	ds_read_b128 v[180:183], v230 offset:18432
	ds_read_b128 v[184:187], v230 offset:19456
	ds_read_b128 v[172:175], v230 offset:20480
	ds_read_b128 v[176:179], v230 offset:21504
	ds_read_b128 v[164:167], v230 offset:22528
	ds_read_b128 v[168:171], v230 offset:23552
	global_load_lds_dwordx4 v196, s[36:37]
	v_lshl_add_u64 v[224:225], s[36:37], 0, v[200:201]
	s_mov_b32 m0, s39
	v_cmp_ne_u32_e64 s[12:13], 1, v233
	global_load_lds_dwordx4 v200, s[36:37]
	s_barrier
	s_waitcnt lgkmcnt(0)
	s_andn2_b64 vcc, exec, s[28:29]
	s_cbranch_vccnz .LBB0_393
	s_setprio 1
	s_waitcnt lgkmcnt(0)
	v_mfma_f32_16x16x32_bf16 v[128:131], v[148:151], v[188:191], v[128:131]
	v_mfma_f32_16x16x32_bf16 v[124:127], v[156:159], v[188:191], v[124:127]
	v_mfma_f32_16x16x32_bf16 v[112:115], v[148:151], v[180:183], v[112:115]
	v_mfma_f32_16x16x32_bf16 v[108:111], v[156:159], v[180:183], v[108:111]
	v_mfma_f32_16x16x32_bf16 v[96:99], v[148:151], v[172:175], v[96:99]
	v_mfma_f32_16x16x32_bf16 v[92:95], v[156:159], v[172:175], v[92:95]
	v_mfma_f32_16x16x32_bf16 v[28:31], v[148:151], v[164:167], v[28:31]
	v_mfma_f32_16x16x32_bf16 v[16:19], v[156:159], v[164:167], v[16:19]
	v_mfma_f32_16x16x32_bf16 v[128:131], v[152:155], v[192:195], v[128:131]
	v_mfma_f32_16x16x32_bf16 v[124:127], v[160:163], v[192:195], v[124:127]
	v_mfma_f32_16x16x32_bf16 v[112:115], v[152:155], v[184:187], v[112:115]
	v_mfma_f32_16x16x32_bf16 v[108:111], v[160:163], v[184:187], v[108:111]
	v_mfma_f32_16x16x32_bf16 v[96:99], v[152:155], v[176:179], v[96:99]
	v_mfma_f32_16x16x32_bf16 v[92:95], v[160:163], v[176:179], v[92:95]
	v_mfma_f32_16x16x32_bf16 v[28:31], v[152:155], v[168:171], v[28:31]
	v_mfma_f32_16x16x32_bf16 v[16:19], v[160:163], v[168:171], v[16:19]
	s_setprio 0
.LBB0_393:
	s_barrier
	s_add_u32 s56, s34, 0x80000
	s_addc_u32 s57, s35, 0
	s_mov_b32 m0, s40
	s_nop 0
	global_load_lds_dwordx4 v198, s[56:57]
	s_mov_b32 m0, s41
	s_and_b64 vcc, exec, s[12:13]
	global_load_lds_dwordx4 v202, s[56:57]
	s_waitcnt vmcnt(6)
	s_barrier
	s_cbranch_vccnz .LBB0_395
	s_setprio 1
	s_waitcnt lgkmcnt(0)
	v_mfma_f32_16x16x32_bf16 v[120:123], v[132:135], v[188:191], v[120:123]
	v_mfma_f32_16x16x32_bf16 v[116:119], v[140:143], v[188:191], v[116:119]
	v_mfma_f32_16x16x32_bf16 v[104:107], v[132:135], v[180:183], v[104:107]
	v_mfma_f32_16x16x32_bf16 v[100:103], v[140:143], v[180:183], v[100:103]
	v_mfma_f32_16x16x32_bf16 v[88:91], v[132:135], v[172:175], v[88:91]
	v_mfma_f32_16x16x32_bf16 v[80:83], v[140:143], v[172:175], v[80:83]
	v_mfma_f32_16x16x32_bf16 v[8:11], v[132:135], v[164:167], v[8:11]
	v_mfma_f32_16x16x32_bf16 v[4:7], v[140:143], v[164:167], v[4:7]
	v_mfma_f32_16x16x32_bf16 v[120:123], v[136:139], v[192:195], v[120:123]
	v_mfma_f32_16x16x32_bf16 v[116:119], v[144:147], v[192:195], v[116:119]
	v_mfma_f32_16x16x32_bf16 v[104:107], v[136:139], v[184:187], v[104:107]
	v_mfma_f32_16x16x32_bf16 v[100:103], v[144:147], v[184:187], v[100:103]
	v_mfma_f32_16x16x32_bf16 v[88:91], v[136:139], v[176:179], v[88:91]
	v_mfma_f32_16x16x32_bf16 v[80:83], v[144:147], v[176:179], v[80:83]
	v_mfma_f32_16x16x32_bf16 v[8:11], v[136:139], v[168:171], v[8:11]
	v_mfma_f32_16x16x32_bf16 v[4:7], v[144:147], v[168:171], v[4:7]
	s_setprio 0
.LBB0_395:
	s_add_i32 s56, 0, 0x18000
	v_add_u32_e32 v1, s56, v226
	s_barrier
	ds_read_b128 v[148:151], v1
	ds_read_b128 v[152:155], v1 offset:1024
	ds_read_b128 v[156:159], v1 offset:2048
	ds_read_b128 v[160:163], v1 offset:3072
	s_add_u32 s36, s36, 0x80000
	s_addc_u32 s37, s37, 0
	s_mov_b32 m0, s42
	s_waitcnt lgkmcnt(0)
	ds_read_b128 v[164:167], v230 offset:32768
	ds_read_b128 v[168:171], v230 offset:33792
	ds_read_b128 v[172:175], v230 offset:34816
	ds_read_b128 v[176:179], v230 offset:35840
	ds_read_b128 v[180:183], v230 offset:36864
	ds_read_b128 v[184:187], v230 offset:37888
	ds_read_b128 v[188:191], v230 offset:38912
	ds_read_b128 v[192:195], v230 offset:39936
	global_load_lds_dwordx4 v196, s[36:37]
	s_mov_b32 m0, s43
	s_nop 0
	global_load_lds_dwordx4 v200, s[36:37]
	s_waitcnt lgkmcnt(8)
	s_barrier
	s_waitcnt lgkmcnt(0)
	s_setprio 1
	s_waitcnt lgkmcnt(0)
	v_mfma_f32_16x16x32_bf16 v[84:87], v[148:151], v[164:167], v[84:87]
	v_mfma_f32_16x16x32_bf16 v[76:79], v[156:159], v[164:167], v[76:79]
	v_mfma_f32_16x16x32_bf16 v[64:67], v[148:151], v[172:175], v[64:67]
	v_mfma_f32_16x16x32_bf16 v[60:63], v[156:159], v[172:175], v[60:63]
	v_mfma_f32_16x16x32_bf16 v[48:51], v[148:151], v[180:183], v[48:51]
	v_mfma_f32_16x16x32_bf16 v[44:47], v[156:159], v[180:183], v[44:47]
	v_mfma_f32_16x16x32_bf16 v[32:35], v[148:151], v[188:191], v[32:35]
	v_mfma_f32_16x16x32_bf16 v[24:27], v[156:159], v[188:191], v[24:27]
	v_mfma_f32_16x16x32_bf16 v[84:87], v[152:155], v[168:171], v[84:87]
	v_mfma_f32_16x16x32_bf16 v[76:79], v[160:163], v[168:171], v[76:79]
	v_mfma_f32_16x16x32_bf16 v[64:67], v[152:155], v[176:179], v[64:67]
	v_mfma_f32_16x16x32_bf16 v[60:63], v[160:163], v[176:179], v[60:63]
	v_mfma_f32_16x16x32_bf16 v[48:51], v[152:155], v[184:187], v[48:51]
	v_mfma_f32_16x16x32_bf16 v[44:47], v[160:163], v[184:187], v[44:47]
	v_mfma_f32_16x16x32_bf16 v[32:35], v[152:155], v[192:195], v[32:35]
	v_mfma_f32_16x16x32_bf16 v[24:27], v[160:163], v[192:195], v[24:27]
	s_setprio 0
	s_barrier
	s_add_i32 s36, s56, s38
	v_add_u32_e32 v1, 0x1c000, v231
	v_lshl_add_u64 v[2:3], v[2:3], 0, s[14:15]
	s_mov_b32 m0, s36
	ds_read_b128 v[132:135], v1
	ds_read_b128 v[136:139], v1 offset:1024
	ds_read_b128 v[140:143], v1 offset:2048
	ds_read_b128 v[144:147], v1 offset:3072
	global_load_lds_dwordx4 v[2:3], off
	v_lshl_add_u64 v[2:3], v[220:221], 0, s[14:15]
	s_add_i32 m0, s36, 0x2000
	s_nop 0
	global_load_lds_dwordx4 v[2:3], off
	s_barrier
	s_waitcnt lgkmcnt(0)
	s_setprio 1
	s_waitcnt lgkmcnt(0)
	v_mfma_f32_16x16x32_bf16 v[72:75], v[132:135], v[164:167], v[72:75]
	v_mfma_f32_16x16x32_bf16 v[68:71], v[140:143], v[164:167], v[68:71]
	v_mfma_f32_16x16x32_bf16 v[56:59], v[132:135], v[172:175], v[56:59]
	v_mfma_f32_16x16x32_bf16 v[52:55], v[140:143], v[172:175], v[52:55]
	v_mfma_f32_16x16x32_bf16 v[40:43], v[132:135], v[180:183], v[40:43]
	v_mfma_f32_16x16x32_bf16 v[36:39], v[140:143], v[180:183], v[36:39]
	v_mfma_f32_16x16x32_bf16 v[20:23], v[132:135], v[188:191], v[20:23]
	v_mfma_f32_16x16x32_bf16 v[12:15], v[140:143], v[188:191], v[12:15]
	v_mfma_f32_16x16x32_bf16 v[72:75], v[136:139], v[168:171], v[72:75]
	v_mfma_f32_16x16x32_bf16 v[68:71], v[144:147], v[168:171], v[68:71]
	v_mfma_f32_16x16x32_bf16 v[56:59], v[136:139], v[176:179], v[56:59]
	v_mfma_f32_16x16x32_bf16 v[52:55], v[144:147], v[176:179], v[52:55]
	v_mfma_f32_16x16x32_bf16 v[40:43], v[136:139], v[184:187], v[40:43]
	v_mfma_f32_16x16x32_bf16 v[36:39], v[144:147], v[184:187], v[36:39]
	v_mfma_f32_16x16x32_bf16 v[20:23], v[136:139], v[192:195], v[20:23]
	v_mfma_f32_16x16x32_bf16 v[12:15], v[144:147], v[192:195], v[12:15]
	s_setprio 0
	s_mov_b32 m0, s45
	v_lshl_add_u64 v[2:3], v[222:223], 0, s[14:15]
	s_barrier
	ds_read_b128 v[188:191], v230 offset:49152
	ds_read_b128 v[192:195], v230 offset:50176
	ds_read_b128 v[180:183], v230 offset:51200
	ds_read_b128 v[184:187], v230 offset:52224
	ds_read_b128 v[172:175], v230 offset:53248
	ds_read_b128 v[176:179], v230 offset:54272
	ds_read_b128 v[164:167], v230 offset:55296
	ds_read_b128 v[168:171], v230 offset:56320
	global_load_lds_dwordx4 v[2:3], off
	v_lshl_add_u64 v[2:3], v[224:225], 0, s[14:15]
	s_mov_b32 m0, s46
	s_and_b64 vcc, exec, s[12:13]
	global_load_lds_dwordx4 v[2:3], off
	s_barrier
	s_waitcnt lgkmcnt(0)
	s_cbranch_vccnz .LBB0_397
	s_setprio 1
	s_waitcnt lgkmcnt(0)
	v_mfma_f32_16x16x32_bf16 v[128:131], v[148:151], v[188:191], v[128:131]
	v_mfma_f32_16x16x32_bf16 v[124:127], v[156:159], v[188:191], v[124:127]
	v_mfma_f32_16x16x32_bf16 v[112:115], v[148:151], v[180:183], v[112:115]
	v_mfma_f32_16x16x32_bf16 v[108:111], v[156:159], v[180:183], v[108:111]
	v_mfma_f32_16x16x32_bf16 v[96:99], v[148:151], v[172:175], v[96:99]
	v_mfma_f32_16x16x32_bf16 v[92:95], v[156:159], v[172:175], v[92:95]
	v_mfma_f32_16x16x32_bf16 v[28:31], v[148:151], v[164:167], v[28:31]
	v_mfma_f32_16x16x32_bf16 v[16:19], v[156:159], v[164:167], v[16:19]
	v_mfma_f32_16x16x32_bf16 v[128:131], v[152:155], v[192:195], v[128:131]
	v_mfma_f32_16x16x32_bf16 v[124:127], v[160:163], v[192:195], v[124:127]
	v_mfma_f32_16x16x32_bf16 v[112:115], v[152:155], v[184:187], v[112:115]
	v_mfma_f32_16x16x32_bf16 v[108:111], v[160:163], v[184:187], v[108:111]
	v_mfma_f32_16x16x32_bf16 v[96:99], v[152:155], v[176:179], v[96:99]
	v_mfma_f32_16x16x32_bf16 v[92:95], v[160:163], v[176:179], v[92:95]
	v_mfma_f32_16x16x32_bf16 v[28:31], v[152:155], v[168:171], v[28:31]
	v_mfma_f32_16x16x32_bf16 v[16:19], v[160:163], v[168:171], v[16:19]
	s_setprio 0
.LBB0_397:
	s_barrier
	s_add_u32 s34, s34, 0x80080
	s_addc_u32 s35, s35, 0
	s_mov_b32 m0, s47
	s_nop 0
	global_load_lds_dwordx4 v198, s[34:35]
	s_mov_b32 m0, s48
	s_and_b64 vcc, exec, s[12:13]
	global_load_lds_dwordx4 v202, s[34:35]
	s_waitcnt vmcnt(6)
	s_barrier
	s_cbranch_vccnz .LBB0_390
	s_setprio 1
	s_waitcnt lgkmcnt(0)
	v_mfma_f32_16x16x32_bf16 v[120:123], v[132:135], v[188:191], v[120:123]
	v_mfma_f32_16x16x32_bf16 v[116:119], v[140:143], v[188:191], v[116:119]
	v_mfma_f32_16x16x32_bf16 v[104:107], v[132:135], v[180:183], v[104:107]
	v_mfma_f32_16x16x32_bf16 v[100:103], v[140:143], v[180:183], v[100:103]
	v_mfma_f32_16x16x32_bf16 v[88:91], v[132:135], v[172:175], v[88:91]
	v_mfma_f32_16x16x32_bf16 v[80:83], v[140:143], v[172:175], v[80:83]
	v_mfma_f32_16x16x32_bf16 v[8:11], v[132:135], v[164:167], v[8:11]
	v_mfma_f32_16x16x32_bf16 v[2:5], v[140:143], v[164:167], v[4:7]
	v_mfma_f32_16x16x32_bf16 v[120:123], v[136:139], v[192:195], v[120:123]
	v_mfma_f32_16x16x32_bf16 v[116:119], v[144:147], v[192:195], v[116:119]
	v_mfma_f32_16x16x32_bf16 v[104:107], v[136:139], v[184:187], v[104:107]
	v_mfma_f32_16x16x32_bf16 v[100:103], v[144:147], v[184:187], v[100:103]
	v_mfma_f32_16x16x32_bf16 v[88:91], v[136:139], v[176:179], v[88:91]
	v_mfma_f32_16x16x32_bf16 v[80:83], v[144:147], v[176:179], v[80:83]
	v_mfma_f32_16x16x32_bf16 v[8:11], v[136:139], v[168:171], v[8:11]
	v_mfma_f32_16x16x32_bf16 v[4:7], v[144:147], v[168:171], v[2:5]
	s_setprio 0
	s_branch .LBB0_390

.LBB0_573:
	ds_read_b128 v[148:151], v222
	ds_read_b128 v[152:155], v222 offset:1024
	ds_read_b128 v[156:159], v222 offset:2048
	ds_read_b128 v[160:163], v222 offset:3072
	s_add_u32 s14, s26, 0xfffc0080
	s_addc_u32 s15, s27, -1
	s_cmp_eq_u32 s50, s53
	s_cselect_b32 s31, s2, s15
	s_cselect_b32 s30, s9, s14
	s_cselect_b32 s29, s11, s52
	s_cselect_b32 s28, s21, s51
	s_add_i32 m0, s34, 0xc000
	s_waitcnt lgkmcnt(0)
	ds_read_b128 v[164:167], v223
	ds_read_b128 v[168:171], v223 offset:1024
	ds_read_b128 v[172:175], v223 offset:2048
	ds_read_b128 v[176:179], v223 offset:3072
	ds_read_b128 v[180:183], v223 offset:4096
	ds_read_b128 v[184:187], v223 offset:5120
	ds_read_b128 v[188:191], v223 offset:6144
	ds_read_b128 v[192:195], v223 offset:7168
	global_load_lds_dwordx4 v204, s[26:27]
	s_add_i32 m0, s34, 0xe000
	s_nop 0
	global_load_lds_dwordx4 v206, s[26:27]
	s_waitcnt lgkmcnt(8)
	s_barrier
	s_waitcnt lgkmcnt(0)
	s_setprio 1
	s_waitcnt lgkmcnt(0)
	v_mfma_f32_16x16x32_bf16 v[124:127], v[148:151], v[164:167], v[124:127]
	v_mfma_f32_16x16x32_bf16 v[116:119], v[156:159], v[164:167], v[116:119]
	v_mfma_f32_16x16x32_bf16 v[108:111], v[148:151], v[172:175], v[108:111]
	v_mfma_f32_16x16x32_bf16 v[100:103], v[156:159], v[172:175], v[100:103]
	v_mfma_f32_16x16x32_bf16 v[92:95], v[148:151], v[180:183], v[92:95]
	v_mfma_f32_16x16x32_bf16 v[84:87], v[156:159], v[180:183], v[84:87]
	v_mfma_f32_16x16x32_bf16 v[76:79], v[148:151], v[188:191], v[76:79]
	v_mfma_f32_16x16x32_bf16 v[72:75], v[156:159], v[188:191], v[72:75]
	v_mfma_f32_16x16x32_bf16 v[124:127], v[152:155], v[168:171], v[124:127]
	v_mfma_f32_16x16x32_bf16 v[116:119], v[160:163], v[168:171], v[116:119]
	v_mfma_f32_16x16x32_bf16 v[108:111], v[152:155], v[176:179], v[108:111]
	v_mfma_f32_16x16x32_bf16 v[100:103], v[160:163], v[176:179], v[100:103]
	v_mfma_f32_16x16x32_bf16 v[92:95], v[152:155], v[184:187], v[92:95]
	v_mfma_f32_16x16x32_bf16 v[84:87], v[160:163], v[184:187], v[84:87]
	v_mfma_f32_16x16x32_bf16 v[76:79], v[152:155], v[192:195], v[76:79]
	v_mfma_f32_16x16x32_bf16 v[72:75], v[160:163], v[192:195], v[72:75]
	s_setprio 0
	s_barrier
	s_add_i32 s14, s47, s23
	v_lshl_add_u64 v[2:3], s[28:29], 0, v[198:199]
	s_mov_b32 m0, s14
	ds_read_b128 v[132:135], v225
	ds_read_b128 v[136:139], v225 offset:1024
	ds_read_b128 v[140:143], v225 offset:2048
	ds_read_b128 v[144:147], v225 offset:3072
	global_load_lds_dwordx4 v198, s[28:29]
	v_lshl_add_u64 v[212:213], s[28:29], 0, v[202:203]
	s_add_i32 m0, s14, 0x2000
	s_nop 0
	global_load_lds_dwordx4 v202, s[28:29]
	s_barrier
	s_waitcnt lgkmcnt(0)
	s_setprio 1
	s_waitcnt lgkmcnt(0)
	v_mfma_f32_16x16x32_bf16 v[128:131], v[132:135], v[164:167], v[128:131]
	v_mfma_f32_16x16x32_bf16 v[120:123], v[140:143], v[164:167], v[120:123]
	v_mfma_f32_16x16x32_bf16 v[112:115], v[132:135], v[172:175], v[112:115]
	v_mfma_f32_16x16x32_bf16 v[104:107], v[140:143], v[172:175], v[104:107]
	v_mfma_f32_16x16x32_bf16 v[96:99], v[132:135], v[180:183], v[96:99]
	v_mfma_f32_16x16x32_bf16 v[88:91], v[140:143], v[180:183], v[88:91]
	v_mfma_f32_16x16x32_bf16 v[80:83], v[132:135], v[188:191], v[80:83]
	v_mfma_f32_16x16x32_bf16 v[68:71], v[140:143], v[188:191], v[68:71]
	v_mfma_f32_16x16x32_bf16 v[128:131], v[136:139], v[168:171], v[128:131]
	v_mfma_f32_16x16x32_bf16 v[120:123], v[144:147], v[168:171], v[120:123]
	v_mfma_f32_16x16x32_bf16 v[112:115], v[136:139], v[176:179], v[112:115]
	v_mfma_f32_16x16x32_bf16 v[104:107], v[144:147], v[176:179], v[104:107]
	v_mfma_f32_16x16x32_bf16 v[96:99], v[136:139], v[184:187], v[96:99]
	v_mfma_f32_16x16x32_bf16 v[88:91], v[144:147], v[184:187], v[88:91]
	v_mfma_f32_16x16x32_bf16 v[80:83], v[136:139], v[192:195], v[80:83]
	v_mfma_f32_16x16x32_bf16 v[68:71], v[144:147], v[192:195], v[68:71]
	s_setprio 0
	s_mov_b32 m0, s34
	v_lshl_add_u64 v[214:215], s[30:31], 0, v[196:197]
	s_barrier
	ds_read_b128 v[188:191], v223 offset:16384
	ds_read_b128 v[192:195], v223 offset:17408
	ds_read_b128 v[180:183], v223 offset:18432
	ds_read_b128 v[184:187], v223 offset:19456
	ds_read_b128 v[172:175], v223 offset:20480
	ds_read_b128 v[176:179], v223 offset:21504
	ds_read_b128 v[164:167], v223 offset:22528
	ds_read_b128 v[168:171], v223 offset:23552
	global_load_lds_dwordx4 v196, s[30:31]
	v_lshl_add_u64 v[216:217], s[30:31], 0, v[200:201]
	s_mov_b32 m0, s35
	v_cmp_ne_u32_e64 s[14:15], 1, v234
	global_load_lds_dwordx4 v200, s[30:31]
	s_barrier
	s_waitcnt lgkmcnt(0)
	s_andn2_b64 vcc, exec, s[24:25]
	s_cbranch_vccnz .LBB0_575
	s_setprio 1
	s_waitcnt lgkmcnt(0)
	v_mfma_f32_16x16x32_bf16 v[60:63], v[148:151], v[188:191], v[60:63]
	v_mfma_f32_16x16x32_bf16 v[52:55], v[156:159], v[188:191], v[52:55]
	v_mfma_f32_16x16x32_bf16 v[44:47], v[148:151], v[180:183], v[44:47]
	v_mfma_f32_16x16x32_bf16 v[36:39], v[156:159], v[180:183], v[36:39]
	v_mfma_f32_16x16x32_bf16 v[28:31], v[148:151], v[172:175], v[28:31]
	v_mfma_f32_16x16x32_bf16 v[20:23], v[156:159], v[172:175], v[20:23]
	v_mfma_f32_16x16x32_bf16 v[12:15], v[148:151], v[164:167], v[12:15]
	v_mfma_f32_16x16x32_bf16 v[4:7], v[156:159], v[164:167], v[4:7]
	v_mfma_f32_16x16x32_bf16 v[60:63], v[152:155], v[192:195], v[60:63]
	v_mfma_f32_16x16x32_bf16 v[52:55], v[160:163], v[192:195], v[52:55]
	v_mfma_f32_16x16x32_bf16 v[44:47], v[152:155], v[184:187], v[44:47]
	v_mfma_f32_16x16x32_bf16 v[36:39], v[160:163], v[184:187], v[36:39]
	v_mfma_f32_16x16x32_bf16 v[28:31], v[152:155], v[176:179], v[28:31]
	v_mfma_f32_16x16x32_bf16 v[20:23], v[160:163], v[176:179], v[20:23]
	v_mfma_f32_16x16x32_bf16 v[12:15], v[152:155], v[168:171], v[12:15]
	v_mfma_f32_16x16x32_bf16 v[4:7], v[160:163], v[168:171], v[4:7]
	s_setprio 0
.LBB0_575:
	s_barrier
	s_add_u32 s54, s28, 0x40000
	s_addc_u32 s55, s29, 0
	s_mov_b32 m0, s36
	s_nop 0
	global_load_lds_dwordx4 v198, s[54:55]
	s_mov_b32 m0, s37
	s_and_b64 vcc, exec, s[14:15]
	global_load_lds_dwordx4 v202, s[54:55]
	s_waitcnt vmcnt(6)
	s_barrier
	s_cbranch_vccnz .LBB0_577
	s_setprio 1
	s_waitcnt lgkmcnt(0)
	v_mfma_f32_16x16x32_bf16 v[64:67], v[132:135], v[188:191], v[64:67]
	v_mfma_f32_16x16x32_bf16 v[56:59], v[140:143], v[188:191], v[56:59]
	v_mfma_f32_16x16x32_bf16 v[48:51], v[132:135], v[180:183], v[48:51]
	v_mfma_f32_16x16x32_bf16 v[40:43], v[140:143], v[180:183], v[40:43]
	v_mfma_f32_16x16x32_bf16 v[32:35], v[132:135], v[172:175], v[32:35]
	v_mfma_f32_16x16x32_bf16 v[24:27], v[140:143], v[172:175], v[24:27]
	v_mfma_f32_16x16x32_bf16 v[16:19], v[132:135], v[164:167], v[16:19]
	v_mfma_f32_16x16x32_bf16 v[8:11], v[140:143], v[164:167], v[8:11]
	v_mfma_f32_16x16x32_bf16 v[64:67], v[136:139], v[192:195], v[64:67]
	v_mfma_f32_16x16x32_bf16 v[56:59], v[144:147], v[192:195], v[56:59]
	v_mfma_f32_16x16x32_bf16 v[48:51], v[136:139], v[184:187], v[48:51]
	v_mfma_f32_16x16x32_bf16 v[40:43], v[144:147], v[184:187], v[40:43]
	v_mfma_f32_16x16x32_bf16 v[32:35], v[136:139], v[176:179], v[32:35]
	v_mfma_f32_16x16x32_bf16 v[24:27], v[144:147], v[176:179], v[24:27]
	v_mfma_f32_16x16x32_bf16 v[16:19], v[136:139], v[168:171], v[16:19]
	v_mfma_f32_16x16x32_bf16 v[8:11], v[144:147], v[168:171], v[8:11]
	s_setprio 0
.LBB0_577:
	s_add_i32 s54, 0, 0x18000
	v_add_u32_e32 v1, s54, v220
	s_barrier
	ds_read_b128 v[148:151], v1
	ds_read_b128 v[152:155], v1 offset:1024
	ds_read_b128 v[156:159], v1 offset:2048
	ds_read_b128 v[160:163], v1 offset:3072
	s_add_u32 s30, s30, 0x40000
	s_addc_u32 s31, s31, 0
	s_mov_b32 m0, s38
	s_waitcnt lgkmcnt(0)
	ds_read_b128 v[164:167], v223 offset:32768
	ds_read_b128 v[168:171], v223 offset:33792
	ds_read_b128 v[172:175], v223 offset:34816
	ds_read_b128 v[176:179], v223 offset:35840
	ds_read_b128 v[180:183], v223 offset:36864
	ds_read_b128 v[184:187], v223 offset:37888
	ds_read_b128 v[188:191], v223 offset:38912
	ds_read_b128 v[192:195], v223 offset:39936
	global_load_lds_dwordx4 v196, s[30:31]
	s_mov_b32 m0, s39
	s_nop 0
	global_load_lds_dwordx4 v200, s[30:31]
	s_waitcnt lgkmcnt(8)
	s_barrier
	s_waitcnt lgkmcnt(0)
	s_setprio 1
	s_waitcnt lgkmcnt(0)
	v_mfma_f32_16x16x32_bf16 v[124:127], v[148:151], v[164:167], v[124:127]
	v_mfma_f32_16x16x32_bf16 v[116:119], v[156:159], v[164:167], v[116:119]
	v_mfma_f32_16x16x32_bf16 v[108:111], v[148:151], v[172:175], v[108:111]
	v_mfma_f32_16x16x32_bf16 v[100:103], v[156:159], v[172:175], v[100:103]
	v_mfma_f32_16x16x32_bf16 v[92:95], v[148:151], v[180:183], v[92:95]
	v_mfma_f32_16x16x32_bf16 v[84:87], v[156:159], v[180:183], v[84:87]
	v_mfma_f32_16x16x32_bf16 v[76:79], v[148:151], v[188:191], v[76:79]
	v_mfma_f32_16x16x32_bf16 v[72:75], v[156:159], v[188:191], v[72:75]
	v_mfma_f32_16x16x32_bf16 v[124:127], v[152:155], v[168:171], v[124:127]
	v_mfma_f32_16x16x32_bf16 v[116:119], v[160:163], v[168:171], v[116:119]
	v_mfma_f32_16x16x32_bf16 v[108:111], v[152:155], v[176:179], v[108:111]
	v_mfma_f32_16x16x32_bf16 v[100:103], v[160:163], v[176:179], v[100:103]
	v_mfma_f32_16x16x32_bf16 v[92:95], v[152:155], v[184:187], v[92:95]
	v_mfma_f32_16x16x32_bf16 v[84:87], v[160:163], v[184:187], v[84:87]
	v_mfma_f32_16x16x32_bf16 v[76:79], v[152:155], v[192:195], v[76:79]
	v_mfma_f32_16x16x32_bf16 v[72:75], v[160:163], v[192:195], v[72:75]
	s_setprio 0
	s_barrier
	s_add_i32 s30, s54, s23
	v_add_u32_e32 v1, 0x1c000, v224
	v_lshl_add_u64 v[2:3], v[2:3], 0, s[6:7]
	s_mov_b32 m0, s30
	ds_read_b128 v[132:135], v1
	ds_read_b128 v[136:139], v1 offset:1024
	ds_read_b128 v[140:143], v1 offset:2048
	ds_read_b128 v[144:147], v1 offset:3072
	global_load_lds_dwordx4 v[2:3], off
	v_lshl_add_u64 v[2:3], v[212:213], 0, s[6:7]
	s_add_i32 m0, s30, 0x2000
	s_nop 0
	global_load_lds_dwordx4 v[2:3], off
	s_barrier
	s_waitcnt lgkmcnt(0)
	s_setprio 1
	s_waitcnt lgkmcnt(0)
	v_mfma_f32_16x16x32_bf16 v[128:131], v[132:135], v[164:167], v[128:131]
	v_mfma_f32_16x16x32_bf16 v[120:123], v[140:143], v[164:167], v[120:123]
	v_mfma_f32_16x16x32_bf16 v[112:115], v[132:135], v[172:175], v[112:115]
	v_mfma_f32_16x16x32_bf16 v[104:107], v[140:143], v[172:175], v[104:107]
	v_mfma_f32_16x16x32_bf16 v[96:99], v[132:135], v[180:183], v[96:99]
	v_mfma_f32_16x16x32_bf16 v[88:91], v[140:143], v[180:183], v[88:91]
	v_mfma_f32_16x16x32_bf16 v[80:83], v[132:135], v[188:191], v[80:83]
	v_mfma_f32_16x16x32_bf16 v[68:71], v[140:143], v[188:191], v[68:71]
	v_mfma_f32_16x16x32_bf16 v[128:131], v[136:139], v[168:171], v[128:131]
	v_mfma_f32_16x16x32_bf16 v[120:123], v[144:147], v[168:171], v[120:123]
	v_mfma_f32_16x16x32_bf16 v[112:115], v[136:139], v[176:179], v[112:115]
	v_mfma_f32_16x16x32_bf16 v[104:107], v[144:147], v[176:179], v[104:107]
	v_mfma_f32_16x16x32_bf16 v[96:99], v[136:139], v[184:187], v[96:99]
	v_mfma_f32_16x16x32_bf16 v[88:91], v[144:147], v[184:187], v[88:91]
	v_mfma_f32_16x16x32_bf16 v[80:83], v[136:139], v[192:195], v[80:83]
	v_mfma_f32_16x16x32_bf16 v[68:71], v[144:147], v[192:195], v[68:71]
	s_setprio 0
	s_mov_b32 m0, s41
	v_lshl_add_u64 v[2:3], v[214:215], 0, s[6:7]
	s_barrier
	ds_read_b128 v[188:191], v223 offset:49152
	ds_read_b128 v[192:195], v223 offset:50176
	ds_read_b128 v[180:183], v223 offset:51200
	ds_read_b128 v[184:187], v223 offset:52224
	ds_read_b128 v[172:175], v223 offset:53248
	ds_read_b128 v[176:179], v223 offset:54272
	ds_read_b128 v[164:167], v223 offset:55296
	ds_read_b128 v[168:171], v223 offset:56320
	global_load_lds_dwordx4 v[2:3], off
	v_lshl_add_u64 v[2:3], v[216:217], 0, s[6:7]
	s_mov_b32 m0, s42
	s_and_b64 vcc, exec, s[14:15]
	global_load_lds_dwordx4 v[2:3], off
	s_barrier
	s_waitcnt lgkmcnt(0)
	s_cbranch_vccnz .LBB0_579
	s_setprio 1
	s_waitcnt lgkmcnt(0)
	v_mfma_f32_16x16x32_bf16 v[60:63], v[148:151], v[188:191], v[60:63]
	v_mfma_f32_16x16x32_bf16 v[52:55], v[156:159], v[188:191], v[52:55]
	v_mfma_f32_16x16x32_bf16 v[44:47], v[148:151], v[180:183], v[44:47]
	v_mfma_f32_16x16x32_bf16 v[36:39], v[156:159], v[180:183], v[36:39]
	v_mfma_f32_16x16x32_bf16 v[28:31], v[148:151], v[172:175], v[28:31]
	v_mfma_f32_16x16x32_bf16 v[20:23], v[156:159], v[172:175], v[20:23]
	v_mfma_f32_16x16x32_bf16 v[12:15], v[148:151], v[164:167], v[12:15]
	v_mfma_f32_16x16x32_bf16 v[2:5], v[156:159], v[164:167], v[4:7]
	v_mfma_f32_16x16x32_bf16 v[60:63], v[152:155], v[192:195], v[60:63]
	v_mfma_f32_16x16x32_bf16 v[52:55], v[160:163], v[192:195], v[52:55]
	v_mfma_f32_16x16x32_bf16 v[44:47], v[152:155], v[184:187], v[44:47]
	v_mfma_f32_16x16x32_bf16 v[36:39], v[160:163], v[184:187], v[36:39]
	v_mfma_f32_16x16x32_bf16 v[28:31], v[152:155], v[176:179], v[28:31]
	v_mfma_f32_16x16x32_bf16 v[20:23], v[160:163], v[176:179], v[20:23]
	v_mfma_f32_16x16x32_bf16 v[12:15], v[152:155], v[168:171], v[12:15]
	v_mfma_f32_16x16x32_bf16 v[4:7], v[160:163], v[168:171], v[2:5]
	s_setprio 0
.LBB0_579:
	s_barrier
	s_add_u32 s28, s28, 0x40080
	s_addc_u32 s29, s29, 0
	s_mov_b32 m0, s43
	s_nop 0
	global_load_lds_dwordx4 v198, s[28:29]
	s_mov_b32 m0, s44
	s_and_b64 vcc, exec, s[14:15]
	global_load_lds_dwordx4 v202, s[28:29]
	s_waitcnt vmcnt(6)
	s_barrier
	s_cbranch_vccnz .LBB0_572
	s_setprio 1
	s_waitcnt lgkmcnt(0)
	v_mfma_f32_16x16x32_bf16 v[64:67], v[132:135], v[188:191], v[64:67]
	v_mfma_f32_16x16x32_bf16 v[56:59], v[140:143], v[188:191], v[56:59]
	v_mfma_f32_16x16x32_bf16 v[48:51], v[132:135], v[180:183], v[48:51]
	v_mfma_f32_16x16x32_bf16 v[40:43], v[140:143], v[180:183], v[40:43]
	v_mfma_f32_16x16x32_bf16 v[32:35], v[132:135], v[172:175], v[32:35]
	v_mfma_f32_16x16x32_bf16 v[24:27], v[140:143], v[172:175], v[24:27]
	v_mfma_f32_16x16x32_bf16 v[16:19], v[132:135], v[164:167], v[16:19]
	v_mfma_f32_16x16x32_bf16 v[8:11], v[140:143], v[164:167], v[8:11]
	v_mfma_f32_16x16x32_bf16 v[64:67], v[136:139], v[192:195], v[64:67]
	v_mfma_f32_16x16x32_bf16 v[56:59], v[144:147], v[192:195], v[56:59]
	v_mfma_f32_16x16x32_bf16 v[48:51], v[136:139], v[184:187], v[48:51]
	v_mfma_f32_16x16x32_bf16 v[40:43], v[144:147], v[184:187], v[40:43]
	v_mfma_f32_16x16x32_bf16 v[32:35], v[136:139], v[176:179], v[32:35]
	v_mfma_f32_16x16x32_bf16 v[24:27], v[144:147], v[176:179], v[24:27]
	v_mfma_f32_16x16x32_bf16 v[16:19], v[136:139], v[168:171], v[16:19]
	v_mfma_f32_16x16x32_bf16 v[8:11], v[144:147], v[168:171], v[8:11]
	s_setprio 0
	s_branch .LBB0_572

.LBB0_688:
	ds_read_b128 v[148:151], v205
	ds_read_b128 v[152:155], v205 offset:1024
	ds_read_b128 v[156:159], v205 offset:2048
	ds_read_b128 v[160:163], v205 offset:3072
	s_mov_b64 s[16:17], s[22:23]
	s_add_u32 s22, s16, 0x100
	s_addc_u32 s23, s17, 0
	s_cmp_eq_u32 s5, s51
	s_cselect_b32 s29, s19, s23
	s_cselect_b32 s28, s18, s22
	s_cselect_b32 s27, s21, s11
	s_cselect_b32 s26, s20, s6
	s_add_i32 m0, s34, 0xc000
	s_waitcnt lgkmcnt(0)
	ds_read_b128 v[164:167], v230
	ds_read_b128 v[168:171], v230 offset:1024
	ds_read_b128 v[172:175], v230 offset:2048
	ds_read_b128 v[176:179], v230 offset:3072
	ds_read_b128 v[180:183], v230 offset:4096
	ds_read_b128 v[184:187], v230 offset:5120
	ds_read_b128 v[188:191], v230 offset:6144
	ds_read_b128 v[192:195], v230 offset:7168
	global_load_lds_dwordx4 v214, s[16:17]
	s_add_i32 m0, s34, 0xe000
	s_nop 0
	global_load_lds_dwordx4 v216, s[16:17]
	s_waitcnt lgkmcnt(8)
	s_barrier
	s_waitcnt lgkmcnt(0)
	s_setprio 1
	s_waitcnt lgkmcnt(0)
	v_mfma_f32_16x16x32_bf16 v[84:87], v[148:151], v[164:167], v[84:87]
	v_mfma_f32_16x16x32_bf16 v[76:79], v[156:159], v[164:167], v[76:79]
	v_mfma_f32_16x16x32_bf16 v[64:67], v[148:151], v[172:175], v[64:67]
	v_mfma_f32_16x16x32_bf16 v[60:63], v[156:159], v[172:175], v[60:63]
	v_mfma_f32_16x16x32_bf16 v[48:51], v[148:151], v[180:183], v[48:51]
	v_mfma_f32_16x16x32_bf16 v[44:47], v[156:159], v[180:183], v[44:47]
	v_mfma_f32_16x16x32_bf16 v[32:35], v[148:151], v[188:191], v[32:35]
	v_mfma_f32_16x16x32_bf16 v[24:27], v[156:159], v[188:191], v[24:27]
	v_mfma_f32_16x16x32_bf16 v[84:87], v[152:155], v[168:171], v[84:87]
	v_mfma_f32_16x16x32_bf16 v[76:79], v[160:163], v[168:171], v[76:79]
	v_mfma_f32_16x16x32_bf16 v[64:67], v[152:155], v[176:179], v[64:67]
	v_mfma_f32_16x16x32_bf16 v[60:63], v[160:163], v[176:179], v[60:63]
	v_mfma_f32_16x16x32_bf16 v[48:51], v[152:155], v[184:187], v[48:51]
	v_mfma_f32_16x16x32_bf16 v[44:47], v[160:163], v[184:187], v[44:47]
	v_mfma_f32_16x16x32_bf16 v[32:35], v[152:155], v[192:195], v[32:35]
	v_mfma_f32_16x16x32_bf16 v[24:27], v[160:163], v[192:195], v[24:27]
	s_setprio 0
	s_barrier
	s_add_i32 s16, s47, s30
	v_lshl_add_u64 v[2:3], s[26:27], 0, v[198:199]
	s_mov_b32 m0, s16
	ds_read_b128 v[132:135], v232
	ds_read_b128 v[136:139], v232 offset:1024
	ds_read_b128 v[140:143], v232 offset:2048
	ds_read_b128 v[144:147], v232 offset:3072
	global_load_lds_dwordx4 v198, s[26:27]
	v_lshl_add_u64 v[220:221], s[26:27], 0, v[202:203]
	s_add_i32 m0, s16, 0x2000
	s_nop 0
	global_load_lds_dwordx4 v202, s[26:27]
	s_barrier
	s_waitcnt lgkmcnt(0)
	s_setprio 1
	s_waitcnt lgkmcnt(0)
	v_mfma_f32_16x16x32_bf16 v[72:75], v[132:135], v[164:167], v[72:75]
	v_mfma_f32_16x16x32_bf16 v[68:71], v[140:143], v[164:167], v[68:71]
	v_mfma_f32_16x16x32_bf16 v[56:59], v[132:135], v[172:175], v[56:59]
	v_mfma_f32_16x16x32_bf16 v[52:55], v[140:143], v[172:175], v[52:55]
	v_mfma_f32_16x16x32_bf16 v[40:43], v[132:135], v[180:183], v[40:43]
	v_mfma_f32_16x16x32_bf16 v[36:39], v[140:143], v[180:183], v[36:39]
	v_mfma_f32_16x16x32_bf16 v[20:23], v[132:135], v[188:191], v[20:23]
	v_mfma_f32_16x16x32_bf16 v[12:15], v[140:143], v[188:191], v[12:15]
	v_mfma_f32_16x16x32_bf16 v[72:75], v[136:139], v[168:171], v[72:75]
	v_mfma_f32_16x16x32_bf16 v[68:71], v[144:147], v[168:171], v[68:71]
	v_mfma_f32_16x16x32_bf16 v[56:59], v[136:139], v[176:179], v[56:59]
	v_mfma_f32_16x16x32_bf16 v[52:55], v[144:147], v[176:179], v[52:55]
	v_mfma_f32_16x16x32_bf16 v[40:43], v[136:139], v[184:187], v[40:43]
	v_mfma_f32_16x16x32_bf16 v[36:39], v[144:147], v[184:187], v[36:39]
	v_mfma_f32_16x16x32_bf16 v[20:23], v[136:139], v[192:195], v[20:23]
	v_mfma_f32_16x16x32_bf16 v[12:15], v[144:147], v[192:195], v[12:15]
	s_setprio 0
	s_mov_b32 m0, s34
	v_lshl_add_u64 v[222:223], s[28:29], 0, v[196:197]
	s_barrier
	ds_read_b128 v[188:191], v230 offset:16384
	ds_read_b128 v[192:195], v230 offset:17408
	ds_read_b128 v[180:183], v230 offset:18432
	ds_read_b128 v[184:187], v230 offset:19456
	ds_read_b128 v[172:175], v230 offset:20480
	ds_read_b128 v[176:179], v230 offset:21504
	ds_read_b128 v[164:167], v230 offset:22528
	ds_read_b128 v[168:171], v230 offset:23552
	global_load_lds_dwordx4 v196, s[28:29]
	v_lshl_add_u64 v[224:225], s[28:29], 0, v[200:201]
	s_mov_b32 m0, s35
	v_cmp_ne_u32_e64 s[16:17], 1, v233
	global_load_lds_dwordx4 v200, s[28:29]
	s_barrier
	s_waitcnt lgkmcnt(0)
	s_andn2_b64 vcc, exec, s[24:25]
	s_cbranch_vccnz .LBB0_690
	s_setprio 1
	s_waitcnt lgkmcnt(0)
	v_mfma_f32_16x16x32_bf16 v[128:131], v[148:151], v[188:191], v[128:131]
	v_mfma_f32_16x16x32_bf16 v[124:127], v[156:159], v[188:191], v[124:127]
	v_mfma_f32_16x16x32_bf16 v[112:115], v[148:151], v[180:183], v[112:115]
	v_mfma_f32_16x16x32_bf16 v[108:111], v[156:159], v[180:183], v[108:111]
	v_mfma_f32_16x16x32_bf16 v[96:99], v[148:151], v[172:175], v[96:99]
	v_mfma_f32_16x16x32_bf16 v[92:95], v[156:159], v[172:175], v[92:95]
	v_mfma_f32_16x16x32_bf16 v[28:31], v[148:151], v[164:167], v[28:31]
	v_mfma_f32_16x16x32_bf16 v[16:19], v[156:159], v[164:167], v[16:19]
	v_mfma_f32_16x16x32_bf16 v[128:131], v[152:155], v[192:195], v[128:131]
	v_mfma_f32_16x16x32_bf16 v[124:127], v[160:163], v[192:195], v[124:127]
	v_mfma_f32_16x16x32_bf16 v[112:115], v[152:155], v[184:187], v[112:115]
	v_mfma_f32_16x16x32_bf16 v[108:111], v[160:163], v[184:187], v[108:111]
	v_mfma_f32_16x16x32_bf16 v[96:99], v[152:155], v[176:179], v[96:99]
	v_mfma_f32_16x16x32_bf16 v[92:95], v[160:163], v[176:179], v[92:95]
	v_mfma_f32_16x16x32_bf16 v[28:31], v[152:155], v[168:171], v[28:31]
	v_mfma_f32_16x16x32_bf16 v[16:19], v[160:163], v[168:171], v[16:19]
	s_setprio 0
.LBB0_690:
	s_barrier
	s_add_u32 s52, s26, 0xb0000
	s_addc_u32 s53, s27, 0
	s_mov_b32 m0, s36
	s_nop 0
	global_load_lds_dwordx4 v198, s[52:53]
	s_mov_b32 m0, s37
	s_and_b64 vcc, exec, s[16:17]
	global_load_lds_dwordx4 v202, s[52:53]
	s_waitcnt vmcnt(6)
	s_barrier
	s_cbranch_vccnz .LBB0_692
	s_setprio 1
	s_waitcnt lgkmcnt(0)
	v_mfma_f32_16x16x32_bf16 v[120:123], v[132:135], v[188:191], v[120:123]
	v_mfma_f32_16x16x32_bf16 v[116:119], v[140:143], v[188:191], v[116:119]
	v_mfma_f32_16x16x32_bf16 v[104:107], v[132:135], v[180:183], v[104:107]
	v_mfma_f32_16x16x32_bf16 v[100:103], v[140:143], v[180:183], v[100:103]
	v_mfma_f32_16x16x32_bf16 v[88:91], v[132:135], v[172:175], v[88:91]
	v_mfma_f32_16x16x32_bf16 v[80:83], v[140:143], v[172:175], v[80:83]
	v_mfma_f32_16x16x32_bf16 v[8:11], v[132:135], v[164:167], v[8:11]
	v_mfma_f32_16x16x32_bf16 v[4:7], v[140:143], v[164:167], v[4:7]
	v_mfma_f32_16x16x32_bf16 v[120:123], v[136:139], v[192:195], v[120:123]
	v_mfma_f32_16x16x32_bf16 v[116:119], v[144:147], v[192:195], v[116:119]
	v_mfma_f32_16x16x32_bf16 v[104:107], v[136:139], v[184:187], v[104:107]
	v_mfma_f32_16x16x32_bf16 v[100:103], v[144:147], v[184:187], v[100:103]
	v_mfma_f32_16x16x32_bf16 v[88:91], v[136:139], v[176:179], v[88:91]
	v_mfma_f32_16x16x32_bf16 v[80:83], v[144:147], v[176:179], v[80:83]
	v_mfma_f32_16x16x32_bf16 v[8:11], v[136:139], v[168:171], v[8:11]
	v_mfma_f32_16x16x32_bf16 v[4:7], v[144:147], v[168:171], v[4:7]
	s_setprio 0
.LBB0_692:
	s_add_i32 s52, 0, 0x18000
	v_add_u32_e32 v1, s52, v226
	s_barrier
	ds_read_b128 v[148:151], v1
	ds_read_b128 v[152:155], v1 offset:1024
	ds_read_b128 v[156:159], v1 offset:2048
	ds_read_b128 v[160:163], v1 offset:3072
	s_add_u32 s28, s28, 0xb0000
	s_addc_u32 s29, s29, 0
	s_mov_b32 m0, s38
	s_waitcnt lgkmcnt(0)
	ds_read_b128 v[164:167], v230 offset:32768
	ds_read_b128 v[168:171], v230 offset:33792
	ds_read_b128 v[172:175], v230 offset:34816
	ds_read_b128 v[176:179], v230 offset:35840
	ds_read_b128 v[180:183], v230 offset:36864
	ds_read_b128 v[184:187], v230 offset:37888
	ds_read_b128 v[188:191], v230 offset:38912
	ds_read_b128 v[192:195], v230 offset:39936
	global_load_lds_dwordx4 v196, s[28:29]
	s_mov_b32 m0, s39
	s_nop 0
	global_load_lds_dwordx4 v200, s[28:29]
	s_waitcnt lgkmcnt(8)
	s_barrier
	s_waitcnt lgkmcnt(0)
	s_setprio 1
	s_waitcnt lgkmcnt(0)
	v_mfma_f32_16x16x32_bf16 v[84:87], v[148:151], v[164:167], v[84:87]
	v_mfma_f32_16x16x32_bf16 v[76:79], v[156:159], v[164:167], v[76:79]
	v_mfma_f32_16x16x32_bf16 v[64:67], v[148:151], v[172:175], v[64:67]
	v_mfma_f32_16x16x32_bf16 v[60:63], v[156:159], v[172:175], v[60:63]
	v_mfma_f32_16x16x32_bf16 v[48:51], v[148:151], v[180:183], v[48:51]
	v_mfma_f32_16x16x32_bf16 v[44:47], v[156:159], v[180:183], v[44:47]
	v_mfma_f32_16x16x32_bf16 v[32:35], v[148:151], v[188:191], v[32:35]
	v_mfma_f32_16x16x32_bf16 v[24:27], v[156:159], v[188:191], v[24:27]
	v_mfma_f32_16x16x32_bf16 v[84:87], v[152:155], v[168:171], v[84:87]
	v_mfma_f32_16x16x32_bf16 v[76:79], v[160:163], v[168:171], v[76:79]
	v_mfma_f32_16x16x32_bf16 v[64:67], v[152:155], v[176:179], v[64:67]
	v_mfma_f32_16x16x32_bf16 v[60:63], v[160:163], v[176:179], v[60:63]
	v_mfma_f32_16x16x32_bf16 v[48:51], v[152:155], v[184:187], v[48:51]
	v_mfma_f32_16x16x32_bf16 v[44:47], v[160:163], v[184:187], v[44:47]
	v_mfma_f32_16x16x32_bf16 v[32:35], v[152:155], v[192:195], v[32:35]
	v_mfma_f32_16x16x32_bf16 v[24:27], v[160:163], v[192:195], v[24:27]
	s_setprio 0
	s_barrier
	s_add_i32 s28, s52, s30
	v_add_u32_e32 v1, 0x1c000, v231
	v_lshl_add_u64 v[2:3], v[2:3], 0, s[8:9]
	s_mov_b32 m0, s28
	ds_read_b128 v[132:135], v1
	ds_read_b128 v[136:139], v1 offset:1024
	ds_read_b128 v[140:143], v1 offset:2048
	ds_read_b128 v[144:147], v1 offset:3072
	global_load_lds_dwordx4 v[2:3], off
	v_lshl_add_u64 v[2:3], v[220:221], 0, s[8:9]
	s_add_i32 m0, s28, 0x2000
	s_nop 0
	global_load_lds_dwordx4 v[2:3], off
	s_barrier
	s_waitcnt lgkmcnt(0)
	s_setprio 1
	s_waitcnt lgkmcnt(0)
	v_mfma_f32_16x16x32_bf16 v[72:75], v[132:135], v[164:167], v[72:75]
	v_mfma_f32_16x16x32_bf16 v[68:71], v[140:143], v[164:167], v[68:71]
	v_mfma_f32_16x16x32_bf16 v[56:59], v[132:135], v[172:175], v[56:59]
	v_mfma_f32_16x16x32_bf16 v[52:55], v[140:143], v[172:175], v[52:55]
	v_mfma_f32_16x16x32_bf16 v[40:43], v[132:135], v[180:183], v[40:43]
	v_mfma_f32_16x16x32_bf16 v[36:39], v[140:143], v[180:183], v[36:39]
	v_mfma_f32_16x16x32_bf16 v[20:23], v[132:135], v[188:191], v[20:23]
	v_mfma_f32_16x16x32_bf16 v[12:15], v[140:143], v[188:191], v[12:15]
	v_mfma_f32_16x16x32_bf16 v[72:75], v[136:139], v[168:171], v[72:75]
	v_mfma_f32_16x16x32_bf16 v[68:71], v[144:147], v[168:171], v[68:71]
	v_mfma_f32_16x16x32_bf16 v[56:59], v[136:139], v[176:179], v[56:59]
	v_mfma_f32_16x16x32_bf16 v[52:55], v[144:147], v[176:179], v[52:55]
	v_mfma_f32_16x16x32_bf16 v[40:43], v[136:139], v[184:187], v[40:43]
	v_mfma_f32_16x16x32_bf16 v[36:39], v[144:147], v[184:187], v[36:39]
	v_mfma_f32_16x16x32_bf16 v[20:23], v[136:139], v[192:195], v[20:23]
	v_mfma_f32_16x16x32_bf16 v[12:15], v[144:147], v[192:195], v[12:15]
	s_setprio 0
	s_mov_b32 m0, s41
	v_lshl_add_u64 v[2:3], v[222:223], 0, s[8:9]
	s_barrier
	ds_read_b128 v[188:191], v230 offset:49152
	ds_read_b128 v[192:195], v230 offset:50176
	ds_read_b128 v[180:183], v230 offset:51200
	ds_read_b128 v[184:187], v230 offset:52224
	ds_read_b128 v[172:175], v230 offset:53248
	ds_read_b128 v[176:179], v230 offset:54272
	ds_read_b128 v[164:167], v230 offset:55296
	ds_read_b128 v[168:171], v230 offset:56320
	global_load_lds_dwordx4 v[2:3], off
	v_lshl_add_u64 v[2:3], v[224:225], 0, s[8:9]
	s_mov_b32 m0, s42
	s_and_b64 vcc, exec, s[16:17]
	global_load_lds_dwordx4 v[2:3], off
	s_barrier
	s_waitcnt lgkmcnt(0)
	s_cbranch_vccnz .LBB0_694
	s_setprio 1
	s_waitcnt lgkmcnt(0)
	v_mfma_f32_16x16x32_bf16 v[128:131], v[148:151], v[188:191], v[128:131]
	v_mfma_f32_16x16x32_bf16 v[124:127], v[156:159], v[188:191], v[124:127]
	v_mfma_f32_16x16x32_bf16 v[112:115], v[148:151], v[180:183], v[112:115]
	v_mfma_f32_16x16x32_bf16 v[108:111], v[156:159], v[180:183], v[108:111]
	v_mfma_f32_16x16x32_bf16 v[96:99], v[148:151], v[172:175], v[96:99]
	v_mfma_f32_16x16x32_bf16 v[92:95], v[156:159], v[172:175], v[92:95]
	v_mfma_f32_16x16x32_bf16 v[28:31], v[148:151], v[164:167], v[28:31]
	v_mfma_f32_16x16x32_bf16 v[16:19], v[156:159], v[164:167], v[16:19]
	v_mfma_f32_16x16x32_bf16 v[128:131], v[152:155], v[192:195], v[128:131]
	v_mfma_f32_16x16x32_bf16 v[124:127], v[160:163], v[192:195], v[124:127]
	v_mfma_f32_16x16x32_bf16 v[112:115], v[152:155], v[184:187], v[112:115]
	v_mfma_f32_16x16x32_bf16 v[108:111], v[160:163], v[184:187], v[108:111]
	v_mfma_f32_16x16x32_bf16 v[96:99], v[152:155], v[176:179], v[96:99]
	v_mfma_f32_16x16x32_bf16 v[92:95], v[160:163], v[176:179], v[92:95]
	v_mfma_f32_16x16x32_bf16 v[28:31], v[152:155], v[168:171], v[28:31]
	v_mfma_f32_16x16x32_bf16 v[16:19], v[160:163], v[168:171], v[16:19]
	s_setprio 0
.LBB0_694:
	s_barrier
	s_add_u32 s26, s26, 0xb0080
	s_addc_u32 s27, s27, 0
	s_mov_b32 m0, s43
	s_nop 0
	global_load_lds_dwordx4 v198, s[26:27]
	s_mov_b32 m0, s44
	s_and_b64 vcc, exec, s[16:17]
	global_load_lds_dwordx4 v202, s[26:27]
	s_waitcnt vmcnt(6)
	s_barrier
	s_cbranch_vccnz .LBB0_687
	s_setprio 1
	s_waitcnt lgkmcnt(0)
	v_mfma_f32_16x16x32_bf16 v[120:123], v[132:135], v[188:191], v[120:123]
	v_mfma_f32_16x16x32_bf16 v[116:119], v[140:143], v[188:191], v[116:119]
	v_mfma_f32_16x16x32_bf16 v[104:107], v[132:135], v[180:183], v[104:107]
	v_mfma_f32_16x16x32_bf16 v[100:103], v[140:143], v[180:183], v[100:103]
	v_mfma_f32_16x16x32_bf16 v[88:91], v[132:135], v[172:175], v[88:91]
	v_mfma_f32_16x16x32_bf16 v[80:83], v[140:143], v[172:175], v[80:83]
	v_mfma_f32_16x16x32_bf16 v[8:11], v[132:135], v[164:167], v[8:11]
	v_mfma_f32_16x16x32_bf16 v[2:5], v[140:143], v[164:167], v[4:7]
	v_mfma_f32_16x16x32_bf16 v[120:123], v[136:139], v[192:195], v[120:123]
	v_mfma_f32_16x16x32_bf16 v[116:119], v[144:147], v[192:195], v[116:119]
	v_mfma_f32_16x16x32_bf16 v[104:107], v[136:139], v[184:187], v[104:107]
	v_mfma_f32_16x16x32_bf16 v[100:103], v[144:147], v[184:187], v[100:103]
	v_mfma_f32_16x16x32_bf16 v[88:91], v[136:139], v[176:179], v[88:91]
	v_mfma_f32_16x16x32_bf16 v[80:83], v[144:147], v[176:179], v[80:83]
	v_mfma_f32_16x16x32_bf16 v[8:11], v[136:139], v[168:171], v[8:11]
	v_mfma_f32_16x16x32_bf16 v[4:7], v[144:147], v[168:171], v[2:5]
	s_setprio 0
	s_branch .LBB0_687

.LBB0_883:
	ds_read_b128 v[148:151], v234
	ds_read_b128 v[152:155], v234 offset:1024
	ds_read_b128 v[156:159], v234 offset:2048
	ds_read_b128 v[160:163], v234 offset:3072
	s_add_u32 s14, s36, 0xfffc0080
	s_addc_u32 s15, s37, -1
	s_cmp_eq_u32 s29, s61
	s_cselect_b32 s41, s2, s15
	s_cselect_b32 s40, s9, s14
	s_cselect_b32 s39, s19, s60
	s_cselect_b32 s38, s27, s31
	s_add_i32 m0, s44, 0xc000
	s_waitcnt lgkmcnt(0)
	ds_read_b128 v[164:167], v235
	ds_read_b128 v[168:171], v235 offset:1024
	ds_read_b128 v[172:175], v235 offset:2048
	ds_read_b128 v[176:179], v235 offset:3072
	ds_read_b128 v[180:183], v235 offset:4096
	ds_read_b128 v[184:187], v235 offset:5120
	ds_read_b128 v[188:191], v235 offset:6144
	ds_read_b128 v[192:195], v235 offset:7168
	global_load_lds_dwordx4 v214, s[36:37]
	s_add_i32 m0, s44, 0xe000
	s_nop 0
	global_load_lds_dwordx4 v216, s[36:37]
	s_waitcnt lgkmcnt(8)
	s_barrier
	s_waitcnt lgkmcnt(0)
	s_setprio 1
	s_waitcnt lgkmcnt(0)
	v_mfma_f32_16x16x32_bf16 v[72:75], v[148:151], v[164:167], v[72:75]
	v_mfma_f32_16x16x32_bf16 v[68:71], v[156:159], v[164:167], v[68:71]
	v_mfma_f32_16x16x32_bf16 v[56:59], v[148:151], v[172:175], v[56:59]
	v_mfma_f32_16x16x32_bf16 v[52:55], v[156:159], v[172:175], v[52:55]
	v_mfma_f32_16x16x32_bf16 v[40:43], v[148:151], v[180:183], v[40:43]
	v_mfma_f32_16x16x32_bf16 v[36:39], v[156:159], v[180:183], v[36:39]
	v_mfma_f32_16x16x32_bf16 v[24:27], v[148:151], v[188:191], v[24:27]
	v_mfma_f32_16x16x32_bf16 v[20:23], v[156:159], v[188:191], v[20:23]
	v_mfma_f32_16x16x32_bf16 v[72:75], v[152:155], v[168:171], v[72:75]
	v_mfma_f32_16x16x32_bf16 v[68:71], v[160:163], v[168:171], v[68:71]
	v_mfma_f32_16x16x32_bf16 v[56:59], v[152:155], v[176:179], v[56:59]
	v_mfma_f32_16x16x32_bf16 v[52:55], v[160:163], v[176:179], v[52:55]
	v_mfma_f32_16x16x32_bf16 v[40:43], v[152:155], v[184:187], v[40:43]
	v_mfma_f32_16x16x32_bf16 v[36:39], v[160:163], v[184:187], v[36:39]
	v_mfma_f32_16x16x32_bf16 v[24:27], v[152:155], v[192:195], v[24:27]
	v_mfma_f32_16x16x32_bf16 v[20:23], v[160:163], v[192:195], v[20:23]
	s_setprio 0
	s_barrier
	s_add_i32 s14, s57, s21
	v_lshl_add_u64 v[222:223], s[38:39], 0, v[198:199]
	s_mov_b32 m0, s14
	ds_read_b128 v[132:135], v237
	ds_read_b128 v[136:139], v237 offset:1024
	ds_read_b128 v[140:143], v237 offset:2048
	ds_read_b128 v[144:147], v237 offset:3072
	global_load_lds_dwordx4 v198, s[38:39]
	v_lshl_add_u64 v[224:225], s[38:39], 0, v[202:203]
	s_add_i32 m0, s14, 0x2000
	s_nop 0
	global_load_lds_dwordx4 v202, s[38:39]
	s_barrier
	s_waitcnt lgkmcnt(0)
	s_setprio 1
	s_waitcnt lgkmcnt(0)
	v_mfma_f32_16x16x32_bf16 v[64:67], v[132:135], v[164:167], v[64:67]
	v_mfma_f32_16x16x32_bf16 v[60:63], v[140:143], v[164:167], v[60:63]
	v_mfma_f32_16x16x32_bf16 v[48:51], v[132:135], v[172:175], v[48:51]
	v_mfma_f32_16x16x32_bf16 v[44:47], v[140:143], v[172:175], v[44:47]
	v_mfma_f32_16x16x32_bf16 v[32:35], v[132:135], v[180:183], v[32:35]
	v_mfma_f32_16x16x32_bf16 v[28:31], v[140:143], v[180:183], v[28:31]
	v_mfma_f32_16x16x32_bf16 v[16:19], v[132:135], v[188:191], v[16:19]
	v_mfma_f32_16x16x32_bf16 v[2:5], v[140:143], v[188:191], v[4:7]
	v_mfma_f32_16x16x32_bf16 v[64:67], v[136:139], v[168:171], v[64:67]
	v_mfma_f32_16x16x32_bf16 v[60:63], v[144:147], v[168:171], v[60:63]
	v_mfma_f32_16x16x32_bf16 v[48:51], v[136:139], v[176:179], v[48:51]
	v_mfma_f32_16x16x32_bf16 v[44:47], v[144:147], v[176:179], v[44:47]
	v_mfma_f32_16x16x32_bf16 v[32:35], v[136:139], v[184:187], v[32:35]
	v_mfma_f32_16x16x32_bf16 v[28:31], v[144:147], v[184:187], v[28:31]
	v_mfma_f32_16x16x32_bf16 v[16:19], v[136:139], v[192:195], v[16:19]
	v_mfma_f32_16x16x32_bf16 v[2:5], v[144:147], v[192:195], v[2:5]
	s_setprio 0
	s_mov_b32 m0, s44
	v_lshl_add_u64 v[226:227], s[40:41], 0, v[196:197]
	s_barrier
	ds_read_b128 v[188:191], v235 offset:16384
	ds_read_b128 v[192:195], v235 offset:17408
	ds_read_b128 v[180:183], v235 offset:18432
	ds_read_b128 v[184:187], v235 offset:19456
	ds_read_b128 v[172:175], v235 offset:20480
	ds_read_b128 v[176:179], v235 offset:21504
	ds_read_b128 v[164:167], v235 offset:22528
	ds_read_b128 v[168:171], v235 offset:23552
	global_load_lds_dwordx4 v196, s[40:41]
	v_lshl_add_u64 v[228:229], s[40:41], 0, v[200:201]
	s_mov_b32 m0, s45
	v_cmp_ne_u32_e64 s[14:15], 1, v245
	global_load_lds_dwordx4 v200, s[40:41]
	s_barrier
	s_waitcnt lgkmcnt(0)
	s_andn2_b64 vcc, exec, s[4:5]
	s_cbranch_vccnz .LBB0_885
	s_setprio 1
	s_waitcnt lgkmcnt(0)
	v_mfma_f32_16x16x32_bf16 v[128:131], v[148:151], v[188:191], v[128:131]
	v_mfma_f32_16x16x32_bf16 v[124:127], v[156:159], v[188:191], v[124:127]
	v_mfma_f32_16x16x32_bf16 v[112:115], v[148:151], v[180:183], v[112:115]
	v_mfma_f32_16x16x32_bf16 v[108:111], v[156:159], v[180:183], v[108:111]
	v_mfma_f32_16x16x32_bf16 v[96:99], v[148:151], v[172:175], v[96:99]
	v_mfma_f32_16x16x32_bf16 v[92:95], v[156:159], v[172:175], v[92:95]
	v_mfma_f32_16x16x32_bf16 v[80:83], v[148:151], v[164:167], v[80:83]
	v_mfma_f32_16x16x32_bf16 v[76:79], v[156:159], v[164:167], v[76:79]
	v_mfma_f32_16x16x32_bf16 v[128:131], v[152:155], v[192:195], v[128:131]
	v_mfma_f32_16x16x32_bf16 v[124:127], v[160:163], v[192:195], v[124:127]
	v_mfma_f32_16x16x32_bf16 v[112:115], v[152:155], v[184:187], v[112:115]
	v_mfma_f32_16x16x32_bf16 v[108:111], v[160:163], v[184:187], v[108:111]
	v_mfma_f32_16x16x32_bf16 v[96:99], v[152:155], v[176:179], v[96:99]
	v_mfma_f32_16x16x32_bf16 v[92:95], v[160:163], v[176:179], v[92:95]
	v_mfma_f32_16x16x32_bf16 v[80:83], v[152:155], v[168:171], v[80:83]
	v_mfma_f32_16x16x32_bf16 v[76:79], v[160:163], v[168:171], v[76:79]
	s_setprio 0
.LBB0_885:
	s_barrier
	s_add_u32 s62, s38, 0x40000
	s_addc_u32 s63, s39, 0
	s_mov_b32 m0, s46
	s_nop 0
	global_load_lds_dwordx4 v198, s[62:63]
	s_mov_b32 m0, s47
	s_and_b64 vcc, exec, s[14:15]
	global_load_lds_dwordx4 v202, s[62:63]
	s_waitcnt vmcnt(6)
	s_barrier
	s_cbranch_vccnz .LBB0_887
	s_setprio 1
	s_waitcnt lgkmcnt(0)
	v_mfma_f32_16x16x32_bf16 v[120:123], v[132:135], v[188:191], v[120:123]
	v_mfma_f32_16x16x32_bf16 v[116:119], v[140:143], v[188:191], v[116:119]
	v_mfma_f32_16x16x32_bf16 v[104:107], v[132:135], v[180:183], v[104:107]
	v_mfma_f32_16x16x32_bf16 v[100:103], v[140:143], v[180:183], v[100:103]
	v_mfma_f32_16x16x32_bf16 v[88:91], v[132:135], v[172:175], v[88:91]
	v_mfma_f32_16x16x32_bf16 v[84:87], v[140:143], v[172:175], v[84:87]
	v_mfma_f32_16x16x32_bf16 v[12:15], v[132:135], v[164:167], v[12:15]
	v_mfma_f32_16x16x32_bf16 v[6:9], v[140:143], v[164:167], v[8:11]
	v_mfma_f32_16x16x32_bf16 v[120:123], v[136:139], v[192:195], v[120:123]
	v_mfma_f32_16x16x32_bf16 v[116:119], v[144:147], v[192:195], v[116:119]
	v_mfma_f32_16x16x32_bf16 v[104:107], v[136:139], v[184:187], v[104:107]
	v_mfma_f32_16x16x32_bf16 v[100:103], v[144:147], v[184:187], v[100:103]
	v_mfma_f32_16x16x32_bf16 v[88:91], v[136:139], v[176:179], v[88:91]
	v_mfma_f32_16x16x32_bf16 v[84:87], v[144:147], v[176:179], v[84:87]
	v_mfma_f32_16x16x32_bf16 v[12:15], v[136:139], v[168:171], v[12:15]
	v_mfma_f32_16x16x32_bf16 v[8:11], v[144:147], v[168:171], v[6:9]
	s_setprio 0
.LBB0_887:
	s_add_i32 s62, 0, 0x18000
	v_add_u32_e32 v1, s62, v230
	s_barrier
	ds_read_b128 v[148:151], v1
	ds_read_b128 v[152:155], v1 offset:1024
	ds_read_b128 v[156:159], v1 offset:2048
	ds_read_b128 v[160:163], v1 offset:3072
	s_add_u32 s40, s40, 0x40000
	s_addc_u32 s41, s41, 0
	s_mov_b32 m0, s48
	s_waitcnt lgkmcnt(0)
	ds_read_b128 v[164:167], v235 offset:32768
	ds_read_b128 v[168:171], v235 offset:33792
	ds_read_b128 v[172:175], v235 offset:34816
	ds_read_b128 v[176:179], v235 offset:35840
	ds_read_b128 v[180:183], v235 offset:36864
	ds_read_b128 v[184:187], v235 offset:37888
	ds_read_b128 v[188:191], v235 offset:38912
	ds_read_b128 v[192:195], v235 offset:39936
	global_load_lds_dwordx4 v196, s[40:41]
	s_mov_b32 m0, s49
	s_nop 0
	global_load_lds_dwordx4 v200, s[40:41]
	s_waitcnt lgkmcnt(8)
	s_barrier
	s_waitcnt lgkmcnt(0)
	s_setprio 1
	s_waitcnt lgkmcnt(0)
	v_mfma_f32_16x16x32_bf16 v[72:75], v[148:151], v[164:167], v[72:75]
	v_mfma_f32_16x16x32_bf16 v[68:71], v[156:159], v[164:167], v[68:71]
	v_mfma_f32_16x16x32_bf16 v[56:59], v[148:151], v[172:175], v[56:59]
	v_mfma_f32_16x16x32_bf16 v[52:55], v[156:159], v[172:175], v[52:55]
	v_mfma_f32_16x16x32_bf16 v[40:43], v[148:151], v[180:183], v[40:43]
	v_mfma_f32_16x16x32_bf16 v[36:39], v[156:159], v[180:183], v[36:39]
	v_mfma_f32_16x16x32_bf16 v[24:27], v[148:151], v[188:191], v[24:27]
	v_mfma_f32_16x16x32_bf16 v[20:23], v[156:159], v[188:191], v[20:23]
	v_mfma_f32_16x16x32_bf16 v[72:75], v[152:155], v[168:171], v[72:75]
	v_mfma_f32_16x16x32_bf16 v[68:71], v[160:163], v[168:171], v[68:71]
	v_mfma_f32_16x16x32_bf16 v[56:59], v[152:155], v[176:179], v[56:59]
	v_mfma_f32_16x16x32_bf16 v[52:55], v[160:163], v[176:179], v[52:55]
	v_mfma_f32_16x16x32_bf16 v[40:43], v[152:155], v[184:187], v[40:43]
	v_mfma_f32_16x16x32_bf16 v[36:39], v[160:163], v[184:187], v[36:39]
	v_mfma_f32_16x16x32_bf16 v[24:27], v[152:155], v[192:195], v[24:27]
	v_mfma_f32_16x16x32_bf16 v[20:23], v[160:163], v[192:195], v[20:23]
	s_setprio 0
	s_barrier
	s_add_i32 s40, s62, s21
	v_add_u32_e32 v1, 0x1c000, v236
	v_lshl_add_u64 v[6:7], v[222:223], 0, s[24:25]
	s_mov_b32 m0, s40
	ds_read_b128 v[132:135], v1
	ds_read_b128 v[136:139], v1 offset:1024
	ds_read_b128 v[140:143], v1 offset:2048
	ds_read_b128 v[144:147], v1 offset:3072
	global_load_lds_dwordx4 v[6:7], off
	v_lshl_add_u64 v[6:7], v[224:225], 0, s[24:25]
	s_add_i32 m0, s40, 0x2000
	s_nop 0
	global_load_lds_dwordx4 v[6:7], off
	s_barrier
	s_waitcnt lgkmcnt(0)
	s_setprio 1
	s_waitcnt lgkmcnt(0)
	v_mfma_f32_16x16x32_bf16 v[64:67], v[132:135], v[164:167], v[64:67]
	v_mfma_f32_16x16x32_bf16 v[60:63], v[140:143], v[164:167], v[60:63]
	v_mfma_f32_16x16x32_bf16 v[48:51], v[132:135], v[172:175], v[48:51]
	v_mfma_f32_16x16x32_bf16 v[44:47], v[140:143], v[172:175], v[44:47]
	v_mfma_f32_16x16x32_bf16 v[32:35], v[132:135], v[180:183], v[32:35]
	v_mfma_f32_16x16x32_bf16 v[28:31], v[140:143], v[180:183], v[28:31]
	v_mfma_f32_16x16x32_bf16 v[16:19], v[132:135], v[188:191], v[16:19]
	v_mfma_f32_16x16x32_bf16 v[2:5], v[140:143], v[188:191], v[2:5]
	v_mfma_f32_16x16x32_bf16 v[64:67], v[136:139], v[168:171], v[64:67]
	v_mfma_f32_16x16x32_bf16 v[60:63], v[144:147], v[168:171], v[60:63]
	v_mfma_f32_16x16x32_bf16 v[48:51], v[136:139], v[176:179], v[48:51]
	v_mfma_f32_16x16x32_bf16 v[44:47], v[144:147], v[176:179], v[44:47]
	v_mfma_f32_16x16x32_bf16 v[32:35], v[136:139], v[184:187], v[32:35]
	v_mfma_f32_16x16x32_bf16 v[28:31], v[144:147], v[184:187], v[28:31]
	v_mfma_f32_16x16x32_bf16 v[16:19], v[136:139], v[192:195], v[16:19]
	v_mfma_f32_16x16x32_bf16 v[4:7], v[144:147], v[192:195], v[2:5]
	s_setprio 0
	s_mov_b32 m0, s51
	s_nop 0
	v_lshl_add_u64 v[2:3], v[226:227], 0, s[24:25]
	s_barrier
	ds_read_b128 v[188:191], v235 offset:49152
	ds_read_b128 v[192:195], v235 offset:50176
	ds_read_b128 v[180:183], v235 offset:51200
	ds_read_b128 v[184:187], v235 offset:52224
	ds_read_b128 v[172:175], v235 offset:53248
	ds_read_b128 v[176:179], v235 offset:54272
	ds_read_b128 v[164:167], v235 offset:55296
	ds_read_b128 v[168:171], v235 offset:56320
	global_load_lds_dwordx4 v[2:3], off
	v_lshl_add_u64 v[2:3], v[228:229], 0, s[24:25]
	s_mov_b32 m0, s52
	s_and_b64 vcc, exec, s[14:15]
	global_load_lds_dwordx4 v[2:3], off
	s_barrier
	s_waitcnt lgkmcnt(0)
	s_cbranch_vccnz .LBB0_889
	s_setprio 1
	s_waitcnt lgkmcnt(0)
	v_mfma_f32_16x16x32_bf16 v[128:131], v[148:151], v[188:191], v[128:131]
	v_mfma_f32_16x16x32_bf16 v[124:127], v[156:159], v[188:191], v[124:127]
	v_mfma_f32_16x16x32_bf16 v[112:115], v[148:151], v[180:183], v[112:115]
	v_mfma_f32_16x16x32_bf16 v[108:111], v[156:159], v[180:183], v[108:111]
	v_mfma_f32_16x16x32_bf16 v[96:99], v[148:151], v[172:175], v[96:99]
	v_mfma_f32_16x16x32_bf16 v[92:95], v[156:159], v[172:175], v[92:95]
	v_mfma_f32_16x16x32_bf16 v[80:83], v[148:151], v[164:167], v[80:83]
	v_mfma_f32_16x16x32_bf16 v[76:79], v[156:159], v[164:167], v[76:79]
	v_mfma_f32_16x16x32_bf16 v[128:131], v[152:155], v[192:195], v[128:131]
	v_mfma_f32_16x16x32_bf16 v[124:127], v[160:163], v[192:195], v[124:127]
	v_mfma_f32_16x16x32_bf16 v[112:115], v[152:155], v[184:187], v[112:115]
	v_mfma_f32_16x16x32_bf16 v[108:111], v[160:163], v[184:187], v[108:111]
	v_mfma_f32_16x16x32_bf16 v[96:99], v[152:155], v[176:179], v[96:99]
	v_mfma_f32_16x16x32_bf16 v[92:95], v[160:163], v[176:179], v[92:95]
	v_mfma_f32_16x16x32_bf16 v[80:83], v[152:155], v[168:171], v[80:83]
	v_mfma_f32_16x16x32_bf16 v[76:79], v[160:163], v[168:171], v[76:79]
	s_setprio 0
.LBB0_889:
	s_barrier
	s_add_u32 s38, s38, 0x40080
	s_addc_u32 s39, s39, 0
	s_mov_b32 m0, s53
	s_nop 0
	global_load_lds_dwordx4 v198, s[38:39]
	s_mov_b32 m0, s54
	s_and_b64 vcc, exec, s[14:15]
	global_load_lds_dwordx4 v202, s[38:39]
	s_waitcnt vmcnt(6)
	s_barrier
	s_cbranch_vccnz .LBB0_882
	s_setprio 1
	s_waitcnt lgkmcnt(0)
	v_mfma_f32_16x16x32_bf16 v[120:123], v[132:135], v[188:191], v[120:123]
	v_mfma_f32_16x16x32_bf16 v[116:119], v[140:143], v[188:191], v[116:119]
	v_mfma_f32_16x16x32_bf16 v[104:107], v[132:135], v[180:183], v[104:107]
	v_mfma_f32_16x16x32_bf16 v[100:103], v[140:143], v[180:183], v[100:103]
	v_mfma_f32_16x16x32_bf16 v[88:91], v[132:135], v[172:175], v[88:91]
	v_mfma_f32_16x16x32_bf16 v[84:87], v[140:143], v[172:175], v[84:87]
	v_mfma_f32_16x16x32_bf16 v[12:15], v[132:135], v[164:167], v[12:15]
	v_mfma_f32_16x16x32_bf16 v[8:11], v[140:143], v[164:167], v[8:11]
	v_mfma_f32_16x16x32_bf16 v[120:123], v[136:139], v[192:195], v[120:123]
	v_mfma_f32_16x16x32_bf16 v[116:119], v[144:147], v[192:195], v[116:119]
	v_mfma_f32_16x16x32_bf16 v[104:107], v[136:139], v[184:187], v[104:107]
	v_mfma_f32_16x16x32_bf16 v[100:103], v[144:147], v[184:187], v[100:103]
	v_mfma_f32_16x16x32_bf16 v[88:91], v[136:139], v[176:179], v[88:91]
	v_mfma_f32_16x16x32_bf16 v[84:87], v[144:147], v[176:179], v[84:87]
	v_mfma_f32_16x16x32_bf16 v[12:15], v[136:139], v[168:171], v[12:15]
	v_mfma_f32_16x16x32_bf16 v[8:11], v[144:147], v[168:171], v[8:11]
	s_setprio 0
	s_branch .LBB0_882

.LBB0_1147:
	ds_read_b128 v[148:151], v205
	ds_read_b128 v[152:155], v205 offset:1024
	ds_read_b128 v[156:159], v205 offset:2048
	ds_read_b128 v[160:163], v205 offset:3072
	s_add_u32 s12, s30, 0xfff80080
	s_addc_u32 s13, s31, -1
	s_cmp_eq_u32 s21, s57
	s_cselect_b32 s37, s2, s13
	s_cselect_b32 s36, s5, s12
	s_cselect_b32 s35, s17, s56
	s_cselect_b32 s34, s19, s55
	s_add_i32 m0, s7, 0xc000
	s_waitcnt lgkmcnt(0)
	ds_read_b128 v[164:167], v230
	ds_read_b128 v[168:171], v230 offset:1024
	ds_read_b128 v[172:175], v230 offset:2048
	ds_read_b128 v[176:179], v230 offset:3072
	ds_read_b128 v[180:183], v230 offset:4096
	ds_read_b128 v[184:187], v230 offset:5120
	ds_read_b128 v[188:191], v230 offset:6144
	ds_read_b128 v[192:195], v230 offset:7168
	global_load_lds_dwordx4 v214, s[30:31]
	s_add_i32 m0, s7, 0xe000
	s_nop 0
	global_load_lds_dwordx4 v216, s[30:31]
	s_waitcnt lgkmcnt(8)
	s_barrier
	s_waitcnt lgkmcnt(0)
	s_setprio 1
	s_waitcnt lgkmcnt(0)
	v_mfma_f32_16x16x32_bf16 v[84:87], v[148:151], v[164:167], v[84:87]
	v_mfma_f32_16x16x32_bf16 v[76:79], v[156:159], v[164:167], v[76:79]
	v_mfma_f32_16x16x32_bf16 v[64:67], v[148:151], v[172:175], v[64:67]
	v_mfma_f32_16x16x32_bf16 v[60:63], v[156:159], v[172:175], v[60:63]
	v_mfma_f32_16x16x32_bf16 v[48:51], v[148:151], v[180:183], v[48:51]
	v_mfma_f32_16x16x32_bf16 v[44:47], v[156:159], v[180:183], v[44:47]
	v_mfma_f32_16x16x32_bf16 v[32:35], v[148:151], v[188:191], v[32:35]
	v_mfma_f32_16x16x32_bf16 v[24:27], v[156:159], v[188:191], v[24:27]
	v_mfma_f32_16x16x32_bf16 v[84:87], v[152:155], v[168:171], v[84:87]
	v_mfma_f32_16x16x32_bf16 v[76:79], v[160:163], v[168:171], v[76:79]
	v_mfma_f32_16x16x32_bf16 v[64:67], v[152:155], v[176:179], v[64:67]
	v_mfma_f32_16x16x32_bf16 v[60:63], v[160:163], v[176:179], v[60:63]
	v_mfma_f32_16x16x32_bf16 v[48:51], v[152:155], v[184:187], v[48:51]
	v_mfma_f32_16x16x32_bf16 v[44:47], v[160:163], v[184:187], v[44:47]
	v_mfma_f32_16x16x32_bf16 v[32:35], v[152:155], v[192:195], v[32:35]
	v_mfma_f32_16x16x32_bf16 v[24:27], v[160:163], v[192:195], v[24:27]
	s_setprio 0
	s_barrier
	s_add_i32 s12, s53, s40
	v_lshl_add_u64 v[2:3], s[34:35], 0, v[198:199]
	s_mov_b32 m0, s12
	ds_read_b128 v[132:135], v232
	ds_read_b128 v[136:139], v232 offset:1024
	ds_read_b128 v[140:143], v232 offset:2048
	ds_read_b128 v[144:147], v232 offset:3072
	global_load_lds_dwordx4 v198, s[34:35]
	v_lshl_add_u64 v[220:221], s[34:35], 0, v[202:203]
	s_add_i32 m0, s12, 0x2000
	s_nop 0
	global_load_lds_dwordx4 v202, s[34:35]
	s_barrier
	s_waitcnt lgkmcnt(0)
	s_setprio 1
	s_waitcnt lgkmcnt(0)
	v_mfma_f32_16x16x32_bf16 v[72:75], v[132:135], v[164:167], v[72:75]
	v_mfma_f32_16x16x32_bf16 v[68:71], v[140:143], v[164:167], v[68:71]
	v_mfma_f32_16x16x32_bf16 v[56:59], v[132:135], v[172:175], v[56:59]
	v_mfma_f32_16x16x32_bf16 v[52:55], v[140:143], v[172:175], v[52:55]
	v_mfma_f32_16x16x32_bf16 v[40:43], v[132:135], v[180:183], v[40:43]
	v_mfma_f32_16x16x32_bf16 v[36:39], v[140:143], v[180:183], v[36:39]
	v_mfma_f32_16x16x32_bf16 v[20:23], v[132:135], v[188:191], v[20:23]
	v_mfma_f32_16x16x32_bf16 v[12:15], v[140:143], v[188:191], v[12:15]
	v_mfma_f32_16x16x32_bf16 v[72:75], v[136:139], v[168:171], v[72:75]
	v_mfma_f32_16x16x32_bf16 v[68:71], v[144:147], v[168:171], v[68:71]
	v_mfma_f32_16x16x32_bf16 v[56:59], v[136:139], v[176:179], v[56:59]
	v_mfma_f32_16x16x32_bf16 v[52:55], v[144:147], v[176:179], v[52:55]
	v_mfma_f32_16x16x32_bf16 v[40:43], v[136:139], v[184:187], v[40:43]
	v_mfma_f32_16x16x32_bf16 v[36:39], v[144:147], v[184:187], v[36:39]
	v_mfma_f32_16x16x32_bf16 v[20:23], v[136:139], v[192:195], v[20:23]
	v_mfma_f32_16x16x32_bf16 v[12:15], v[144:147], v[192:195], v[12:15]
	s_setprio 0
	s_mov_b32 m0, s7
	v_lshl_add_u64 v[222:223], s[36:37], 0, v[196:197]
	s_barrier
	ds_read_b128 v[188:191], v230 offset:16384
	ds_read_b128 v[192:195], v230 offset:17408
	ds_read_b128 v[180:183], v230 offset:18432
	ds_read_b128 v[184:187], v230 offset:19456
	ds_read_b128 v[172:175], v230 offset:20480
	ds_read_b128 v[176:179], v230 offset:21504
	ds_read_b128 v[164:167], v230 offset:22528
	ds_read_b128 v[168:171], v230 offset:23552
	global_load_lds_dwordx4 v196, s[36:37]
	v_lshl_add_u64 v[224:225], s[36:37], 0, v[200:201]
	s_mov_b32 m0, s41
	v_cmp_ne_u32_e64 s[12:13], 1, v233
	global_load_lds_dwordx4 v200, s[36:37]
	s_barrier
	s_waitcnt lgkmcnt(0)
	s_andn2_b64 vcc, exec, s[28:29]
	s_cbranch_vccnz .LBB0_1149
	s_setprio 1
	s_waitcnt lgkmcnt(0)
	v_mfma_f32_16x16x32_bf16 v[128:131], v[148:151], v[188:191], v[128:131]
	v_mfma_f32_16x16x32_bf16 v[124:127], v[156:159], v[188:191], v[124:127]
	v_mfma_f32_16x16x32_bf16 v[112:115], v[148:151], v[180:183], v[112:115]
	v_mfma_f32_16x16x32_bf16 v[108:111], v[156:159], v[180:183], v[108:111]
	v_mfma_f32_16x16x32_bf16 v[96:99], v[148:151], v[172:175], v[96:99]
	v_mfma_f32_16x16x32_bf16 v[92:95], v[156:159], v[172:175], v[92:95]
	v_mfma_f32_16x16x32_bf16 v[28:31], v[148:151], v[164:167], v[28:31]
	v_mfma_f32_16x16x32_bf16 v[16:19], v[156:159], v[164:167], v[16:19]
	v_mfma_f32_16x16x32_bf16 v[128:131], v[152:155], v[192:195], v[128:131]
	v_mfma_f32_16x16x32_bf16 v[124:127], v[160:163], v[192:195], v[124:127]
	v_mfma_f32_16x16x32_bf16 v[112:115], v[152:155], v[184:187], v[112:115]
	v_mfma_f32_16x16x32_bf16 v[108:111], v[160:163], v[184:187], v[108:111]
	v_mfma_f32_16x16x32_bf16 v[96:99], v[152:155], v[176:179], v[96:99]
	v_mfma_f32_16x16x32_bf16 v[92:95], v[160:163], v[176:179], v[92:95]
	v_mfma_f32_16x16x32_bf16 v[28:31], v[152:155], v[168:171], v[28:31]
	v_mfma_f32_16x16x32_bf16 v[16:19], v[160:163], v[168:171], v[16:19]
	s_setprio 0
.LBB0_1149:
	s_barrier
	s_add_u32 s58, s34, 0x80000
	s_addc_u32 s59, s35, 0
	s_mov_b32 m0, s42
	s_nop 0
	global_load_lds_dwordx4 v198, s[58:59]
	s_mov_b32 m0, s43
	s_and_b64 vcc, exec, s[12:13]
	global_load_lds_dwordx4 v202, s[58:59]
	s_waitcnt vmcnt(6)
	s_barrier
	s_cbranch_vccnz .LBB0_1151
	s_setprio 1
	s_waitcnt lgkmcnt(0)
	v_mfma_f32_16x16x32_bf16 v[120:123], v[132:135], v[188:191], v[120:123]
	v_mfma_f32_16x16x32_bf16 v[116:119], v[140:143], v[188:191], v[116:119]
	v_mfma_f32_16x16x32_bf16 v[104:107], v[132:135], v[180:183], v[104:107]
	v_mfma_f32_16x16x32_bf16 v[100:103], v[140:143], v[180:183], v[100:103]
	v_mfma_f32_16x16x32_bf16 v[88:91], v[132:135], v[172:175], v[88:91]
	v_mfma_f32_16x16x32_bf16 v[80:83], v[140:143], v[172:175], v[80:83]
	v_mfma_f32_16x16x32_bf16 v[8:11], v[132:135], v[164:167], v[8:11]
	v_mfma_f32_16x16x32_bf16 v[4:7], v[140:143], v[164:167], v[4:7]
	v_mfma_f32_16x16x32_bf16 v[120:123], v[136:139], v[192:195], v[120:123]
	v_mfma_f32_16x16x32_bf16 v[116:119], v[144:147], v[192:195], v[116:119]
	v_mfma_f32_16x16x32_bf16 v[104:107], v[136:139], v[184:187], v[104:107]
	v_mfma_f32_16x16x32_bf16 v[100:103], v[144:147], v[184:187], v[100:103]
	v_mfma_f32_16x16x32_bf16 v[88:91], v[136:139], v[176:179], v[88:91]
	v_mfma_f32_16x16x32_bf16 v[80:83], v[144:147], v[176:179], v[80:83]
	v_mfma_f32_16x16x32_bf16 v[8:11], v[136:139], v[168:171], v[8:11]
	v_mfma_f32_16x16x32_bf16 v[4:7], v[144:147], v[168:171], v[4:7]
	s_setprio 0
.LBB0_1151:
	s_add_i32 s58, 0, 0x18000
	v_add_u32_e32 v1, s58, v226
	s_barrier
	ds_read_b128 v[148:151], v1
	ds_read_b128 v[152:155], v1 offset:1024
	ds_read_b128 v[156:159], v1 offset:2048
	ds_read_b128 v[160:163], v1 offset:3072
	s_add_u32 s36, s36, 0x80000
	s_addc_u32 s37, s37, 0
	s_mov_b32 m0, s44
	s_waitcnt lgkmcnt(0)
	ds_read_b128 v[164:167], v230 offset:32768
	ds_read_b128 v[168:171], v230 offset:33792
	ds_read_b128 v[172:175], v230 offset:34816
	ds_read_b128 v[176:179], v230 offset:35840
	ds_read_b128 v[180:183], v230 offset:36864
	ds_read_b128 v[184:187], v230 offset:37888
	ds_read_b128 v[188:191], v230 offset:38912
	ds_read_b128 v[192:195], v230 offset:39936
	global_load_lds_dwordx4 v196, s[36:37]
	s_mov_b32 m0, s45
	s_nop 0
	global_load_lds_dwordx4 v200, s[36:37]
	s_waitcnt lgkmcnt(8)
	s_barrier
	s_waitcnt lgkmcnt(0)
	s_setprio 1
	s_waitcnt lgkmcnt(0)
	v_mfma_f32_16x16x32_bf16 v[84:87], v[148:151], v[164:167], v[84:87]
	v_mfma_f32_16x16x32_bf16 v[76:79], v[156:159], v[164:167], v[76:79]
	v_mfma_f32_16x16x32_bf16 v[64:67], v[148:151], v[172:175], v[64:67]
	v_mfma_f32_16x16x32_bf16 v[60:63], v[156:159], v[172:175], v[60:63]
	v_mfma_f32_16x16x32_bf16 v[48:51], v[148:151], v[180:183], v[48:51]
	v_mfma_f32_16x16x32_bf16 v[44:47], v[156:159], v[180:183], v[44:47]
	v_mfma_f32_16x16x32_bf16 v[32:35], v[148:151], v[188:191], v[32:35]
	v_mfma_f32_16x16x32_bf16 v[24:27], v[156:159], v[188:191], v[24:27]
	v_mfma_f32_16x16x32_bf16 v[84:87], v[152:155], v[168:171], v[84:87]
	v_mfma_f32_16x16x32_bf16 v[76:79], v[160:163], v[168:171], v[76:79]
	v_mfma_f32_16x16x32_bf16 v[64:67], v[152:155], v[176:179], v[64:67]
	v_mfma_f32_16x16x32_bf16 v[60:63], v[160:163], v[176:179], v[60:63]
	v_mfma_f32_16x16x32_bf16 v[48:51], v[152:155], v[184:187], v[48:51]
	v_mfma_f32_16x16x32_bf16 v[44:47], v[160:163], v[184:187], v[44:47]
	v_mfma_f32_16x16x32_bf16 v[32:35], v[152:155], v[192:195], v[32:35]
	v_mfma_f32_16x16x32_bf16 v[24:27], v[160:163], v[192:195], v[24:27]
	s_setprio 0
	s_barrier
	s_add_i32 s36, s58, s40
	v_add_u32_e32 v1, 0x1c000, v231
	v_lshl_add_u64 v[2:3], v[2:3], 0, s[14:15]
	s_mov_b32 m0, s36
	ds_read_b128 v[132:135], v1
	ds_read_b128 v[136:139], v1 offset:1024
	ds_read_b128 v[140:143], v1 offset:2048
	ds_read_b128 v[144:147], v1 offset:3072
	global_load_lds_dwordx4 v[2:3], off
	v_lshl_add_u64 v[2:3], v[220:221], 0, s[14:15]
	s_add_i32 m0, s36, 0x2000
	s_nop 0
	global_load_lds_dwordx4 v[2:3], off
	s_barrier
	s_waitcnt lgkmcnt(0)
	s_setprio 1
	s_waitcnt lgkmcnt(0)
	v_mfma_f32_16x16x32_bf16 v[72:75], v[132:135], v[164:167], v[72:75]
	v_mfma_f32_16x16x32_bf16 v[68:71], v[140:143], v[164:167], v[68:71]
	v_mfma_f32_16x16x32_bf16 v[56:59], v[132:135], v[172:175], v[56:59]
	v_mfma_f32_16x16x32_bf16 v[52:55], v[140:143], v[172:175], v[52:55]
	v_mfma_f32_16x16x32_bf16 v[40:43], v[132:135], v[180:183], v[40:43]
	v_mfma_f32_16x16x32_bf16 v[36:39], v[140:143], v[180:183], v[36:39]
	v_mfma_f32_16x16x32_bf16 v[20:23], v[132:135], v[188:191], v[20:23]
	v_mfma_f32_16x16x32_bf16 v[12:15], v[140:143], v[188:191], v[12:15]
	v_mfma_f32_16x16x32_bf16 v[72:75], v[136:139], v[168:171], v[72:75]
	v_mfma_f32_16x16x32_bf16 v[68:71], v[144:147], v[168:171], v[68:71]
	v_mfma_f32_16x16x32_bf16 v[56:59], v[136:139], v[176:179], v[56:59]
	v_mfma_f32_16x16x32_bf16 v[52:55], v[144:147], v[176:179], v[52:55]
	v_mfma_f32_16x16x32_bf16 v[40:43], v[136:139], v[184:187], v[40:43]
	v_mfma_f32_16x16x32_bf16 v[36:39], v[144:147], v[184:187], v[36:39]
	v_mfma_f32_16x16x32_bf16 v[20:23], v[136:139], v[192:195], v[20:23]
	v_mfma_f32_16x16x32_bf16 v[12:15], v[144:147], v[192:195], v[12:15]
	s_setprio 0
	s_mov_b32 m0, s47
	v_lshl_add_u64 v[2:3], v[222:223], 0, s[14:15]
	s_barrier
	ds_read_b128 v[188:191], v230 offset:49152
	ds_read_b128 v[192:195], v230 offset:50176
	ds_read_b128 v[180:183], v230 offset:51200
	ds_read_b128 v[184:187], v230 offset:52224
	ds_read_b128 v[172:175], v230 offset:53248
	ds_read_b128 v[176:179], v230 offset:54272
	ds_read_b128 v[164:167], v230 offset:55296
	ds_read_b128 v[168:171], v230 offset:56320
	global_load_lds_dwordx4 v[2:3], off
	v_lshl_add_u64 v[2:3], v[224:225], 0, s[14:15]
	s_mov_b32 m0, s48
	s_and_b64 vcc, exec, s[12:13]
	global_load_lds_dwordx4 v[2:3], off
	s_barrier
	s_waitcnt lgkmcnt(0)
	s_cbranch_vccnz .LBB0_1153
	s_setprio 1
	s_waitcnt lgkmcnt(0)
	v_mfma_f32_16x16x32_bf16 v[128:131], v[148:151], v[188:191], v[128:131]
	v_mfma_f32_16x16x32_bf16 v[124:127], v[156:159], v[188:191], v[124:127]
	v_mfma_f32_16x16x32_bf16 v[112:115], v[148:151], v[180:183], v[112:115]
	v_mfma_f32_16x16x32_bf16 v[108:111], v[156:159], v[180:183], v[108:111]
	v_mfma_f32_16x16x32_bf16 v[96:99], v[148:151], v[172:175], v[96:99]
	v_mfma_f32_16x16x32_bf16 v[92:95], v[156:159], v[172:175], v[92:95]
	v_mfma_f32_16x16x32_bf16 v[28:31], v[148:151], v[164:167], v[28:31]
	v_mfma_f32_16x16x32_bf16 v[16:19], v[156:159], v[164:167], v[16:19]
	v_mfma_f32_16x16x32_bf16 v[128:131], v[152:155], v[192:195], v[128:131]
	v_mfma_f32_16x16x32_bf16 v[124:127], v[160:163], v[192:195], v[124:127]
	v_mfma_f32_16x16x32_bf16 v[112:115], v[152:155], v[184:187], v[112:115]
	v_mfma_f32_16x16x32_bf16 v[108:111], v[160:163], v[184:187], v[108:111]
	v_mfma_f32_16x16x32_bf16 v[96:99], v[152:155], v[176:179], v[96:99]
	v_mfma_f32_16x16x32_bf16 v[92:95], v[160:163], v[176:179], v[92:95]
	v_mfma_f32_16x16x32_bf16 v[28:31], v[152:155], v[168:171], v[28:31]
	v_mfma_f32_16x16x32_bf16 v[16:19], v[160:163], v[168:171], v[16:19]
	s_setprio 0
.LBB0_1153:
	s_barrier
	s_add_u32 s34, s34, 0x80080
	s_addc_u32 s35, s35, 0
	s_mov_b32 m0, s49
	s_nop 0
	global_load_lds_dwordx4 v198, s[34:35]
	s_mov_b32 m0, s50
	s_and_b64 vcc, exec, s[12:13]
	global_load_lds_dwordx4 v202, s[34:35]
	s_waitcnt vmcnt(6)
	s_barrier
	s_cbranch_vccnz .LBB0_1146
	s_setprio 1
	s_waitcnt lgkmcnt(0)
	v_mfma_f32_16x16x32_bf16 v[120:123], v[132:135], v[188:191], v[120:123]
	v_mfma_f32_16x16x32_bf16 v[116:119], v[140:143], v[188:191], v[116:119]
	v_mfma_f32_16x16x32_bf16 v[104:107], v[132:135], v[180:183], v[104:107]
	v_mfma_f32_16x16x32_bf16 v[100:103], v[140:143], v[180:183], v[100:103]
	v_mfma_f32_16x16x32_bf16 v[88:91], v[132:135], v[172:175], v[88:91]
	v_mfma_f32_16x16x32_bf16 v[80:83], v[140:143], v[172:175], v[80:83]
	v_mfma_f32_16x16x32_bf16 v[8:11], v[132:135], v[164:167], v[8:11]
	v_mfma_f32_16x16x32_bf16 v[2:5], v[140:143], v[164:167], v[4:7]
	v_mfma_f32_16x16x32_bf16 v[120:123], v[136:139], v[192:195], v[120:123]
	v_mfma_f32_16x16x32_bf16 v[116:119], v[144:147], v[192:195], v[116:119]
	v_mfma_f32_16x16x32_bf16 v[104:107], v[136:139], v[184:187], v[104:107]
	v_mfma_f32_16x16x32_bf16 v[100:103], v[144:147], v[184:187], v[100:103]
	v_mfma_f32_16x16x32_bf16 v[88:91], v[136:139], v[176:179], v[88:91]
	v_mfma_f32_16x16x32_bf16 v[80:83], v[144:147], v[176:179], v[80:83]
	v_mfma_f32_16x16x32_bf16 v[8:11], v[136:139], v[168:171], v[8:11]
	v_mfma_f32_16x16x32_bf16 v[4:7], v[144:147], v[168:171], v[2:5]
	s_setprio 0
	s_branch .LBB0_1146

.LBB0_1346:
	ds_read_b128 v[148:151], v222
	ds_read_b128 v[152:155], v222 offset:1024
	ds_read_b128 v[156:159], v222 offset:2048
	ds_read_b128 v[160:163], v222 offset:3072
	s_add_u32 s12, s26, 0xfffc0080
	s_addc_u32 s13, s27, -1
	s_cmp_eq_u32 s52, s55
	s_cselect_b32 s31, s2, s13
	s_cselect_b32 s30, s9, s12
	s_cselect_b32 s29, s15, s54
	s_cselect_b32 s28, s21, s53
	s_add_i32 m0, s36, 0xc000
	s_waitcnt lgkmcnt(0)
	ds_read_b128 v[164:167], v223
	ds_read_b128 v[168:171], v223 offset:1024
	ds_read_b128 v[172:175], v223 offset:2048
	ds_read_b128 v[176:179], v223 offset:3072
	ds_read_b128 v[180:183], v223 offset:4096
	ds_read_b128 v[184:187], v223 offset:5120
	ds_read_b128 v[188:191], v223 offset:6144
	ds_read_b128 v[192:195], v223 offset:7168
	global_load_lds_dwordx4 v204, s[26:27]
	s_add_i32 m0, s36, 0xe000
	s_nop 0
	global_load_lds_dwordx4 v206, s[26:27]
	s_waitcnt lgkmcnt(8)
	s_barrier
	s_waitcnt lgkmcnt(0)
	s_setprio 1
	s_waitcnt lgkmcnt(0)
	v_mfma_f32_16x16x32_bf16 v[124:127], v[148:151], v[164:167], v[124:127]
	v_mfma_f32_16x16x32_bf16 v[116:119], v[156:159], v[164:167], v[116:119]
	v_mfma_f32_16x16x32_bf16 v[108:111], v[148:151], v[172:175], v[108:111]
	v_mfma_f32_16x16x32_bf16 v[100:103], v[156:159], v[172:175], v[100:103]
	v_mfma_f32_16x16x32_bf16 v[92:95], v[148:151], v[180:183], v[92:95]
	v_mfma_f32_16x16x32_bf16 v[84:87], v[156:159], v[180:183], v[84:87]
	v_mfma_f32_16x16x32_bf16 v[76:79], v[148:151], v[188:191], v[76:79]
	v_mfma_f32_16x16x32_bf16 v[72:75], v[156:159], v[188:191], v[72:75]
	v_mfma_f32_16x16x32_bf16 v[124:127], v[152:155], v[168:171], v[124:127]
	v_mfma_f32_16x16x32_bf16 v[116:119], v[160:163], v[168:171], v[116:119]
	v_mfma_f32_16x16x32_bf16 v[108:111], v[152:155], v[176:179], v[108:111]
	v_mfma_f32_16x16x32_bf16 v[100:103], v[160:163], v[176:179], v[100:103]
	v_mfma_f32_16x16x32_bf16 v[92:95], v[152:155], v[184:187], v[92:95]
	v_mfma_f32_16x16x32_bf16 v[84:87], v[160:163], v[184:187], v[84:87]
	v_mfma_f32_16x16x32_bf16 v[76:79], v[152:155], v[192:195], v[76:79]
	v_mfma_f32_16x16x32_bf16 v[72:75], v[160:163], v[192:195], v[72:75]
	s_setprio 0
	s_barrier
	s_add_i32 s12, s49, s23
	v_lshl_add_u64 v[2:3], s[28:29], 0, v[198:199]
	s_mov_b32 m0, s12
	ds_read_b128 v[132:135], v225
	ds_read_b128 v[136:139], v225 offset:1024
	ds_read_b128 v[140:143], v225 offset:2048
	ds_read_b128 v[144:147], v225 offset:3072
	global_load_lds_dwordx4 v198, s[28:29]
	v_lshl_add_u64 v[212:213], s[28:29], 0, v[202:203]
	s_add_i32 m0, s12, 0x2000
	s_nop 0
	global_load_lds_dwordx4 v202, s[28:29]
	s_barrier
	s_waitcnt lgkmcnt(0)
	s_setprio 1
	s_waitcnt lgkmcnt(0)
	v_mfma_f32_16x16x32_bf16 v[128:131], v[132:135], v[164:167], v[128:131]
	v_mfma_f32_16x16x32_bf16 v[120:123], v[140:143], v[164:167], v[120:123]
	v_mfma_f32_16x16x32_bf16 v[112:115], v[132:135], v[172:175], v[112:115]
	v_mfma_f32_16x16x32_bf16 v[104:107], v[140:143], v[172:175], v[104:107]
	v_mfma_f32_16x16x32_bf16 v[96:99], v[132:135], v[180:183], v[96:99]
	v_mfma_f32_16x16x32_bf16 v[88:91], v[140:143], v[180:183], v[88:91]
	v_mfma_f32_16x16x32_bf16 v[80:83], v[132:135], v[188:191], v[80:83]
	v_mfma_f32_16x16x32_bf16 v[68:71], v[140:143], v[188:191], v[68:71]
	v_mfma_f32_16x16x32_bf16 v[128:131], v[136:139], v[168:171], v[128:131]
	v_mfma_f32_16x16x32_bf16 v[120:123], v[144:147], v[168:171], v[120:123]
	v_mfma_f32_16x16x32_bf16 v[112:115], v[136:139], v[176:179], v[112:115]
	v_mfma_f32_16x16x32_bf16 v[104:107], v[144:147], v[176:179], v[104:107]
	v_mfma_f32_16x16x32_bf16 v[96:99], v[136:139], v[184:187], v[96:99]
	v_mfma_f32_16x16x32_bf16 v[88:91], v[144:147], v[184:187], v[88:91]
	v_mfma_f32_16x16x32_bf16 v[80:83], v[136:139], v[192:195], v[80:83]
	v_mfma_f32_16x16x32_bf16 v[68:71], v[144:147], v[192:195], v[68:71]
	s_setprio 0
	s_mov_b32 m0, s36
	v_lshl_add_u64 v[214:215], s[30:31], 0, v[196:197]
	s_barrier
	ds_read_b128 v[188:191], v223 offset:16384
	ds_read_b128 v[192:195], v223 offset:17408
	ds_read_b128 v[180:183], v223 offset:18432
	ds_read_b128 v[184:187], v223 offset:19456
	ds_read_b128 v[172:175], v223 offset:20480
	ds_read_b128 v[176:179], v223 offset:21504
	ds_read_b128 v[164:167], v223 offset:22528
	ds_read_b128 v[168:171], v223 offset:23552
	global_load_lds_dwordx4 v196, s[30:31]
	v_lshl_add_u64 v[216:217], s[30:31], 0, v[200:201]
	s_mov_b32 m0, s37
	v_cmp_ne_u32_e64 s[12:13], 1, v234
	global_load_lds_dwordx4 v200, s[30:31]
	s_barrier
	s_waitcnt lgkmcnt(0)
	s_andn2_b64 vcc, exec, s[24:25]
	s_cbranch_vccnz .LBB0_1348
	s_setprio 1
	s_waitcnt lgkmcnt(0)
	v_mfma_f32_16x16x32_bf16 v[60:63], v[148:151], v[188:191], v[60:63]
	v_mfma_f32_16x16x32_bf16 v[52:55], v[156:159], v[188:191], v[52:55]
	v_mfma_f32_16x16x32_bf16 v[44:47], v[148:151], v[180:183], v[44:47]
	v_mfma_f32_16x16x32_bf16 v[36:39], v[156:159], v[180:183], v[36:39]
	v_mfma_f32_16x16x32_bf16 v[28:31], v[148:151], v[172:175], v[28:31]
	v_mfma_f32_16x16x32_bf16 v[20:23], v[156:159], v[172:175], v[20:23]
	v_mfma_f32_16x16x32_bf16 v[12:15], v[148:151], v[164:167], v[12:15]
	v_mfma_f32_16x16x32_bf16 v[4:7], v[156:159], v[164:167], v[4:7]
	v_mfma_f32_16x16x32_bf16 v[60:63], v[152:155], v[192:195], v[60:63]
	v_mfma_f32_16x16x32_bf16 v[52:55], v[160:163], v[192:195], v[52:55]
	v_mfma_f32_16x16x32_bf16 v[44:47], v[152:155], v[184:187], v[44:47]
	v_mfma_f32_16x16x32_bf16 v[36:39], v[160:163], v[184:187], v[36:39]
	v_mfma_f32_16x16x32_bf16 v[28:31], v[152:155], v[176:179], v[28:31]
	v_mfma_f32_16x16x32_bf16 v[20:23], v[160:163], v[176:179], v[20:23]
	v_mfma_f32_16x16x32_bf16 v[12:15], v[152:155], v[168:171], v[12:15]
	v_mfma_f32_16x16x32_bf16 v[4:7], v[160:163], v[168:171], v[4:7]
	s_setprio 0
.LBB0_1348:
	s_barrier
	s_add_u32 s56, s28, 0x40000
	s_addc_u32 s57, s29, 0
	s_mov_b32 m0, s38
	s_nop 0
	global_load_lds_dwordx4 v198, s[56:57]
	s_mov_b32 m0, s39
	s_and_b64 vcc, exec, s[12:13]
	global_load_lds_dwordx4 v202, s[56:57]
	s_waitcnt vmcnt(6)
	s_barrier
	s_cbranch_vccnz .LBB0_1350
	s_setprio 1
	s_waitcnt lgkmcnt(0)
	v_mfma_f32_16x16x32_bf16 v[64:67], v[132:135], v[188:191], v[64:67]
	v_mfma_f32_16x16x32_bf16 v[56:59], v[140:143], v[188:191], v[56:59]
	v_mfma_f32_16x16x32_bf16 v[48:51], v[132:135], v[180:183], v[48:51]
	v_mfma_f32_16x16x32_bf16 v[40:43], v[140:143], v[180:183], v[40:43]
	v_mfma_f32_16x16x32_bf16 v[32:35], v[132:135], v[172:175], v[32:35]
	v_mfma_f32_16x16x32_bf16 v[24:27], v[140:143], v[172:175], v[24:27]
	v_mfma_f32_16x16x32_bf16 v[16:19], v[132:135], v[164:167], v[16:19]
	v_mfma_f32_16x16x32_bf16 v[8:11], v[140:143], v[164:167], v[8:11]
	v_mfma_f32_16x16x32_bf16 v[64:67], v[136:139], v[192:195], v[64:67]
	v_mfma_f32_16x16x32_bf16 v[56:59], v[144:147], v[192:195], v[56:59]
	v_mfma_f32_16x16x32_bf16 v[48:51], v[136:139], v[184:187], v[48:51]
	v_mfma_f32_16x16x32_bf16 v[40:43], v[144:147], v[184:187], v[40:43]
	v_mfma_f32_16x16x32_bf16 v[32:35], v[136:139], v[176:179], v[32:35]
	v_mfma_f32_16x16x32_bf16 v[24:27], v[144:147], v[176:179], v[24:27]
	v_mfma_f32_16x16x32_bf16 v[16:19], v[136:139], v[168:171], v[16:19]
	v_mfma_f32_16x16x32_bf16 v[8:11], v[144:147], v[168:171], v[8:11]
	s_setprio 0
.LBB0_1350:
	s_add_i32 s56, 0, 0x18000
	v_add_u32_e32 v1, s56, v220
	s_barrier
	ds_read_b128 v[148:151], v1
	ds_read_b128 v[152:155], v1 offset:1024
	ds_read_b128 v[156:159], v1 offset:2048
	ds_read_b128 v[160:163], v1 offset:3072
	s_add_u32 s30, s30, 0x40000
	s_addc_u32 s31, s31, 0
	s_mov_b32 m0, s40
	s_waitcnt lgkmcnt(0)
	ds_read_b128 v[164:167], v223 offset:32768
	ds_read_b128 v[168:171], v223 offset:33792
	ds_read_b128 v[172:175], v223 offset:34816
	ds_read_b128 v[176:179], v223 offset:35840
	ds_read_b128 v[180:183], v223 offset:36864
	ds_read_b128 v[184:187], v223 offset:37888
	ds_read_b128 v[188:191], v223 offset:38912
	ds_read_b128 v[192:195], v223 offset:39936
	global_load_lds_dwordx4 v196, s[30:31]
	s_mov_b32 m0, s41
	s_nop 0
	global_load_lds_dwordx4 v200, s[30:31]
	s_waitcnt lgkmcnt(8)
	s_barrier
	s_waitcnt lgkmcnt(0)
	s_setprio 1
	s_waitcnt lgkmcnt(0)
	v_mfma_f32_16x16x32_bf16 v[124:127], v[148:151], v[164:167], v[124:127]
	v_mfma_f32_16x16x32_bf16 v[116:119], v[156:159], v[164:167], v[116:119]
	v_mfma_f32_16x16x32_bf16 v[108:111], v[148:151], v[172:175], v[108:111]
	v_mfma_f32_16x16x32_bf16 v[100:103], v[156:159], v[172:175], v[100:103]
	v_mfma_f32_16x16x32_bf16 v[92:95], v[148:151], v[180:183], v[92:95]
	v_mfma_f32_16x16x32_bf16 v[84:87], v[156:159], v[180:183], v[84:87]
	v_mfma_f32_16x16x32_bf16 v[76:79], v[148:151], v[188:191], v[76:79]
	v_mfma_f32_16x16x32_bf16 v[72:75], v[156:159], v[188:191], v[72:75]
	v_mfma_f32_16x16x32_bf16 v[124:127], v[152:155], v[168:171], v[124:127]
	v_mfma_f32_16x16x32_bf16 v[116:119], v[160:163], v[168:171], v[116:119]
	v_mfma_f32_16x16x32_bf16 v[108:111], v[152:155], v[176:179], v[108:111]
	v_mfma_f32_16x16x32_bf16 v[100:103], v[160:163], v[176:179], v[100:103]
	v_mfma_f32_16x16x32_bf16 v[92:95], v[152:155], v[184:187], v[92:95]
	v_mfma_f32_16x16x32_bf16 v[84:87], v[160:163], v[184:187], v[84:87]
	v_mfma_f32_16x16x32_bf16 v[76:79], v[152:155], v[192:195], v[76:79]
	v_mfma_f32_16x16x32_bf16 v[72:75], v[160:163], v[192:195], v[72:75]
	s_setprio 0
	s_barrier
	s_add_i32 s30, s56, s23
	v_add_u32_e32 v1, 0x1c000, v224
	v_lshl_add_u64 v[2:3], v[2:3], 0, s[6:7]
	s_mov_b32 m0, s30
	ds_read_b128 v[132:135], v1
	ds_read_b128 v[136:139], v1 offset:1024
	ds_read_b128 v[140:143], v1 offset:2048
	ds_read_b128 v[144:147], v1 offset:3072
	global_load_lds_dwordx4 v[2:3], off
	v_lshl_add_u64 v[2:3], v[212:213], 0, s[6:7]
	s_add_i32 m0, s30, 0x2000
	s_nop 0
	global_load_lds_dwordx4 v[2:3], off
	s_barrier
	s_waitcnt lgkmcnt(0)
	s_setprio 1
	s_waitcnt lgkmcnt(0)
	v_mfma_f32_16x16x32_bf16 v[128:131], v[132:135], v[164:167], v[128:131]
	v_mfma_f32_16x16x32_bf16 v[120:123], v[140:143], v[164:167], v[120:123]
	v_mfma_f32_16x16x32_bf16 v[112:115], v[132:135], v[172:175], v[112:115]
	v_mfma_f32_16x16x32_bf16 v[104:107], v[140:143], v[172:175], v[104:107]
	v_mfma_f32_16x16x32_bf16 v[96:99], v[132:135], v[180:183], v[96:99]
	v_mfma_f32_16x16x32_bf16 v[88:91], v[140:143], v[180:183], v[88:91]
	v_mfma_f32_16x16x32_bf16 v[80:83], v[132:135], v[188:191], v[80:83]
	v_mfma_f32_16x16x32_bf16 v[68:71], v[140:143], v[188:191], v[68:71]
	v_mfma_f32_16x16x32_bf16 v[128:131], v[136:139], v[168:171], v[128:131]
	v_mfma_f32_16x16x32_bf16 v[120:123], v[144:147], v[168:171], v[120:123]
	v_mfma_f32_16x16x32_bf16 v[112:115], v[136:139], v[176:179], v[112:115]
	v_mfma_f32_16x16x32_bf16 v[104:107], v[144:147], v[176:179], v[104:107]
	v_mfma_f32_16x16x32_bf16 v[96:99], v[136:139], v[184:187], v[96:99]
	v_mfma_f32_16x16x32_bf16 v[88:91], v[144:147], v[184:187], v[88:91]
	v_mfma_f32_16x16x32_bf16 v[80:83], v[136:139], v[192:195], v[80:83]
	v_mfma_f32_16x16x32_bf16 v[68:71], v[144:147], v[192:195], v[68:71]
	s_setprio 0
	s_mov_b32 m0, s43
	v_lshl_add_u64 v[2:3], v[214:215], 0, s[6:7]
	s_barrier
	ds_read_b128 v[188:191], v223 offset:49152
	ds_read_b128 v[192:195], v223 offset:50176
	ds_read_b128 v[180:183], v223 offset:51200
	ds_read_b128 v[184:187], v223 offset:52224
	ds_read_b128 v[172:175], v223 offset:53248
	ds_read_b128 v[176:179], v223 offset:54272
	ds_read_b128 v[164:167], v223 offset:55296
	ds_read_b128 v[168:171], v223 offset:56320
	global_load_lds_dwordx4 v[2:3], off
	v_lshl_add_u64 v[2:3], v[216:217], 0, s[6:7]
	s_mov_b32 m0, s44
	s_and_b64 vcc, exec, s[12:13]
	global_load_lds_dwordx4 v[2:3], off
	s_barrier
	s_waitcnt lgkmcnt(0)
	s_cbranch_vccnz .LBB0_1352
	s_setprio 1
	s_waitcnt lgkmcnt(0)
	v_mfma_f32_16x16x32_bf16 v[60:63], v[148:151], v[188:191], v[60:63]
	v_mfma_f32_16x16x32_bf16 v[52:55], v[156:159], v[188:191], v[52:55]
	v_mfma_f32_16x16x32_bf16 v[44:47], v[148:151], v[180:183], v[44:47]
	v_mfma_f32_16x16x32_bf16 v[36:39], v[156:159], v[180:183], v[36:39]
	v_mfma_f32_16x16x32_bf16 v[28:31], v[148:151], v[172:175], v[28:31]
	v_mfma_f32_16x16x32_bf16 v[20:23], v[156:159], v[172:175], v[20:23]
	v_mfma_f32_16x16x32_bf16 v[12:15], v[148:151], v[164:167], v[12:15]
	v_mfma_f32_16x16x32_bf16 v[2:5], v[156:159], v[164:167], v[4:7]
	v_mfma_f32_16x16x32_bf16 v[60:63], v[152:155], v[192:195], v[60:63]
	v_mfma_f32_16x16x32_bf16 v[52:55], v[160:163], v[192:195], v[52:55]
	v_mfma_f32_16x16x32_bf16 v[44:47], v[152:155], v[184:187], v[44:47]
	v_mfma_f32_16x16x32_bf16 v[36:39], v[160:163], v[184:187], v[36:39]
	v_mfma_f32_16x16x32_bf16 v[28:31], v[152:155], v[176:179], v[28:31]
	v_mfma_f32_16x16x32_bf16 v[20:23], v[160:163], v[176:179], v[20:23]
	v_mfma_f32_16x16x32_bf16 v[12:15], v[152:155], v[168:171], v[12:15]
	v_mfma_f32_16x16x32_bf16 v[4:7], v[160:163], v[168:171], v[2:5]
	s_setprio 0
.LBB0_1352:
	s_barrier
	s_add_u32 s28, s28, 0x40080
	s_addc_u32 s29, s29, 0
	s_mov_b32 m0, s45
	s_nop 0
	global_load_lds_dwordx4 v198, s[28:29]
	s_mov_b32 m0, s46
	s_and_b64 vcc, exec, s[12:13]
	global_load_lds_dwordx4 v202, s[28:29]
	s_waitcnt vmcnt(6)
	s_barrier
	s_cbranch_vccnz .LBB0_1345
	s_setprio 1
	s_waitcnt lgkmcnt(0)
	v_mfma_f32_16x16x32_bf16 v[64:67], v[132:135], v[188:191], v[64:67]
	v_mfma_f32_16x16x32_bf16 v[56:59], v[140:143], v[188:191], v[56:59]
	v_mfma_f32_16x16x32_bf16 v[48:51], v[132:135], v[180:183], v[48:51]
	v_mfma_f32_16x16x32_bf16 v[40:43], v[140:143], v[180:183], v[40:43]
	v_mfma_f32_16x16x32_bf16 v[32:35], v[132:135], v[172:175], v[32:35]
	v_mfma_f32_16x16x32_bf16 v[24:27], v[140:143], v[172:175], v[24:27]
	v_mfma_f32_16x16x32_bf16 v[16:19], v[132:135], v[164:167], v[16:19]
	v_mfma_f32_16x16x32_bf16 v[8:11], v[140:143], v[164:167], v[8:11]
	v_mfma_f32_16x16x32_bf16 v[64:67], v[136:139], v[192:195], v[64:67]
	v_mfma_f32_16x16x32_bf16 v[56:59], v[144:147], v[192:195], v[56:59]
	v_mfma_f32_16x16x32_bf16 v[48:51], v[136:139], v[184:187], v[48:51]
	v_mfma_f32_16x16x32_bf16 v[40:43], v[144:147], v[184:187], v[40:43]
	v_mfma_f32_16x16x32_bf16 v[32:35], v[136:139], v[176:179], v[32:35]
	v_mfma_f32_16x16x32_bf16 v[24:27], v[144:147], v[176:179], v[24:27]
	v_mfma_f32_16x16x32_bf16 v[16:19], v[136:139], v[168:171], v[16:19]
	v_mfma_f32_16x16x32_bf16 v[8:11], v[144:147], v[168:171], v[8:11]
	s_setprio 0
	s_branch .LBB0_1345

.LBB0_1461:
	ds_read_b128 v[148:151], v205
	ds_read_b128 v[152:155], v205 offset:1024
	ds_read_b128 v[156:159], v205 offset:2048
	ds_read_b128 v[160:163], v205 offset:3072
	s_mov_b64 s[16:17], s[24:25]
	s_add_u32 s24, s16, 0x100
	s_addc_u32 s25, s17, 0
	s_cmp_eq_u32 s5, s53
	s_cselect_b32 s31, s21, s25
	s_cselect_b32 s30, s20, s24
	s_cselect_b32 s29, s23, s19
	s_cselect_b32 s28, s22, s6
	s_add_i32 m0, s36, 0xc000
	s_waitcnt lgkmcnt(0)
	ds_read_b128 v[164:167], v230
	ds_read_b128 v[168:171], v230 offset:1024
	ds_read_b128 v[172:175], v230 offset:2048
	ds_read_b128 v[176:179], v230 offset:3072
	ds_read_b128 v[180:183], v230 offset:4096
	ds_read_b128 v[184:187], v230 offset:5120
	ds_read_b128 v[188:191], v230 offset:6144
	ds_read_b128 v[192:195], v230 offset:7168
	global_load_lds_dwordx4 v214, s[16:17]
	s_add_i32 m0, s36, 0xe000
	s_nop 0
	global_load_lds_dwordx4 v216, s[16:17]
	s_waitcnt lgkmcnt(8)
	s_barrier
	s_waitcnt lgkmcnt(0)
	s_setprio 1
	s_waitcnt lgkmcnt(0)
	v_mfma_f32_16x16x32_bf16 v[84:87], v[148:151], v[164:167], v[84:87]
	v_mfma_f32_16x16x32_bf16 v[76:79], v[156:159], v[164:167], v[76:79]
	v_mfma_f32_16x16x32_bf16 v[64:67], v[148:151], v[172:175], v[64:67]
	v_mfma_f32_16x16x32_bf16 v[60:63], v[156:159], v[172:175], v[60:63]
	v_mfma_f32_16x16x32_bf16 v[48:51], v[148:151], v[180:183], v[48:51]
	v_mfma_f32_16x16x32_bf16 v[44:47], v[156:159], v[180:183], v[44:47]
	v_mfma_f32_16x16x32_bf16 v[32:35], v[148:151], v[188:191], v[32:35]
	v_mfma_f32_16x16x32_bf16 v[24:27], v[156:159], v[188:191], v[24:27]
	v_mfma_f32_16x16x32_bf16 v[84:87], v[152:155], v[168:171], v[84:87]
	v_mfma_f32_16x16x32_bf16 v[76:79], v[160:163], v[168:171], v[76:79]
	v_mfma_f32_16x16x32_bf16 v[64:67], v[152:155], v[176:179], v[64:67]
	v_mfma_f32_16x16x32_bf16 v[60:63], v[160:163], v[176:179], v[60:63]
	v_mfma_f32_16x16x32_bf16 v[48:51], v[152:155], v[184:187], v[48:51]
	v_mfma_f32_16x16x32_bf16 v[44:47], v[160:163], v[184:187], v[44:47]
	v_mfma_f32_16x16x32_bf16 v[32:35], v[152:155], v[192:195], v[32:35]
	v_mfma_f32_16x16x32_bf16 v[24:27], v[160:163], v[192:195], v[24:27]
	s_setprio 0
	s_barrier
	s_add_i32 s16, s49, s34
	v_lshl_add_u64 v[2:3], s[28:29], 0, v[198:199]
	s_mov_b32 m0, s16
	ds_read_b128 v[132:135], v232
	ds_read_b128 v[136:139], v232 offset:1024
	ds_read_b128 v[140:143], v232 offset:2048
	ds_read_b128 v[144:147], v232 offset:3072
	global_load_lds_dwordx4 v198, s[28:29]
	v_lshl_add_u64 v[220:221], s[28:29], 0, v[202:203]
	s_add_i32 m0, s16, 0x2000
	s_nop 0
	global_load_lds_dwordx4 v202, s[28:29]
	s_barrier
	s_waitcnt lgkmcnt(0)
	s_setprio 1
	s_waitcnt lgkmcnt(0)
	v_mfma_f32_16x16x32_bf16 v[72:75], v[132:135], v[164:167], v[72:75]
	v_mfma_f32_16x16x32_bf16 v[68:71], v[140:143], v[164:167], v[68:71]
	v_mfma_f32_16x16x32_bf16 v[56:59], v[132:135], v[172:175], v[56:59]
	v_mfma_f32_16x16x32_bf16 v[52:55], v[140:143], v[172:175], v[52:55]
	v_mfma_f32_16x16x32_bf16 v[40:43], v[132:135], v[180:183], v[40:43]
	v_mfma_f32_16x16x32_bf16 v[36:39], v[140:143], v[180:183], v[36:39]
	v_mfma_f32_16x16x32_bf16 v[20:23], v[132:135], v[188:191], v[20:23]
	v_mfma_f32_16x16x32_bf16 v[12:15], v[140:143], v[188:191], v[12:15]
	v_mfma_f32_16x16x32_bf16 v[72:75], v[136:139], v[168:171], v[72:75]
	v_mfma_f32_16x16x32_bf16 v[68:71], v[144:147], v[168:171], v[68:71]
	v_mfma_f32_16x16x32_bf16 v[56:59], v[136:139], v[176:179], v[56:59]
	v_mfma_f32_16x16x32_bf16 v[52:55], v[144:147], v[176:179], v[52:55]
	v_mfma_f32_16x16x32_bf16 v[40:43], v[136:139], v[184:187], v[40:43]
	v_mfma_f32_16x16x32_bf16 v[36:39], v[144:147], v[184:187], v[36:39]
	v_mfma_f32_16x16x32_bf16 v[20:23], v[136:139], v[192:195], v[20:23]
	v_mfma_f32_16x16x32_bf16 v[12:15], v[144:147], v[192:195], v[12:15]
	s_setprio 0
	s_mov_b32 m0, s36
	v_lshl_add_u64 v[222:223], s[30:31], 0, v[196:197]
	s_barrier
	ds_read_b128 v[188:191], v230 offset:16384
	ds_read_b128 v[192:195], v230 offset:17408
	ds_read_b128 v[180:183], v230 offset:18432
	ds_read_b128 v[184:187], v230 offset:19456
	ds_read_b128 v[172:175], v230 offset:20480
	ds_read_b128 v[176:179], v230 offset:21504
	ds_read_b128 v[164:167], v230 offset:22528
	ds_read_b128 v[168:171], v230 offset:23552
	global_load_lds_dwordx4 v196, s[30:31]
	v_lshl_add_u64 v[224:225], s[30:31], 0, v[200:201]
	s_mov_b32 m0, s37
	v_cmp_ne_u32_e64 s[16:17], 1, v233
	global_load_lds_dwordx4 v200, s[30:31]
	s_barrier
	s_waitcnt lgkmcnt(0)
	s_andn2_b64 vcc, exec, s[26:27]
	s_cbranch_vccnz .LBB0_1463
	s_setprio 1
	s_waitcnt lgkmcnt(0)
	v_mfma_f32_16x16x32_bf16 v[128:131], v[148:151], v[188:191], v[128:131]
	v_mfma_f32_16x16x32_bf16 v[124:127], v[156:159], v[188:191], v[124:127]
	v_mfma_f32_16x16x32_bf16 v[112:115], v[148:151], v[180:183], v[112:115]
	v_mfma_f32_16x16x32_bf16 v[108:111], v[156:159], v[180:183], v[108:111]
	v_mfma_f32_16x16x32_bf16 v[96:99], v[148:151], v[172:175], v[96:99]
	v_mfma_f32_16x16x32_bf16 v[92:95], v[156:159], v[172:175], v[92:95]
	v_mfma_f32_16x16x32_bf16 v[28:31], v[148:151], v[164:167], v[28:31]
	v_mfma_f32_16x16x32_bf16 v[16:19], v[156:159], v[164:167], v[16:19]
	v_mfma_f32_16x16x32_bf16 v[128:131], v[152:155], v[192:195], v[128:131]
	v_mfma_f32_16x16x32_bf16 v[124:127], v[160:163], v[192:195], v[124:127]
	v_mfma_f32_16x16x32_bf16 v[112:115], v[152:155], v[184:187], v[112:115]
	v_mfma_f32_16x16x32_bf16 v[108:111], v[160:163], v[184:187], v[108:111]
	v_mfma_f32_16x16x32_bf16 v[96:99], v[152:155], v[176:179], v[96:99]
	v_mfma_f32_16x16x32_bf16 v[92:95], v[160:163], v[176:179], v[92:95]
	v_mfma_f32_16x16x32_bf16 v[28:31], v[152:155], v[168:171], v[28:31]
	v_mfma_f32_16x16x32_bf16 v[16:19], v[160:163], v[168:171], v[16:19]
	s_setprio 0
.LBB0_1463:
	s_barrier
	s_add_u32 s54, s28, 0xb0000
	s_addc_u32 s55, s29, 0
	s_mov_b32 m0, s38
	s_nop 0
	global_load_lds_dwordx4 v198, s[54:55]
	s_mov_b32 m0, s39
	s_and_b64 vcc, exec, s[16:17]
	global_load_lds_dwordx4 v202, s[54:55]
	s_waitcnt vmcnt(6)
	s_barrier
	s_cbranch_vccnz .LBB0_1465
	s_setprio 1
	s_waitcnt lgkmcnt(0)
	v_mfma_f32_16x16x32_bf16 v[120:123], v[132:135], v[188:191], v[120:123]
	v_mfma_f32_16x16x32_bf16 v[116:119], v[140:143], v[188:191], v[116:119]
	v_mfma_f32_16x16x32_bf16 v[104:107], v[132:135], v[180:183], v[104:107]
	v_mfma_f32_16x16x32_bf16 v[100:103], v[140:143], v[180:183], v[100:103]
	v_mfma_f32_16x16x32_bf16 v[88:91], v[132:135], v[172:175], v[88:91]
	v_mfma_f32_16x16x32_bf16 v[80:83], v[140:143], v[172:175], v[80:83]
	v_mfma_f32_16x16x32_bf16 v[8:11], v[132:135], v[164:167], v[8:11]
	v_mfma_f32_16x16x32_bf16 v[4:7], v[140:143], v[164:167], v[4:7]
	v_mfma_f32_16x16x32_bf16 v[120:123], v[136:139], v[192:195], v[120:123]
	v_mfma_f32_16x16x32_bf16 v[116:119], v[144:147], v[192:195], v[116:119]
	v_mfma_f32_16x16x32_bf16 v[104:107], v[136:139], v[184:187], v[104:107]
	v_mfma_f32_16x16x32_bf16 v[100:103], v[144:147], v[184:187], v[100:103]
	v_mfma_f32_16x16x32_bf16 v[88:91], v[136:139], v[176:179], v[88:91]
	v_mfma_f32_16x16x32_bf16 v[80:83], v[144:147], v[176:179], v[80:83]
	v_mfma_f32_16x16x32_bf16 v[8:11], v[136:139], v[168:171], v[8:11]
	v_mfma_f32_16x16x32_bf16 v[4:7], v[144:147], v[168:171], v[4:7]
	s_setprio 0
.LBB0_1465:
	s_add_i32 s54, 0, 0x18000
	v_add_u32_e32 v1, s54, v226
	s_barrier
	ds_read_b128 v[148:151], v1
	ds_read_b128 v[152:155], v1 offset:1024
	ds_read_b128 v[156:159], v1 offset:2048
	ds_read_b128 v[160:163], v1 offset:3072
	s_add_u32 s30, s30, 0xb0000
	s_addc_u32 s31, s31, 0
	s_mov_b32 m0, s40
	s_waitcnt lgkmcnt(0)
	ds_read_b128 v[164:167], v230 offset:32768
	ds_read_b128 v[168:171], v230 offset:33792
	ds_read_b128 v[172:175], v230 offset:34816
	ds_read_b128 v[176:179], v230 offset:35840
	ds_read_b128 v[180:183], v230 offset:36864
	ds_read_b128 v[184:187], v230 offset:37888
	ds_read_b128 v[188:191], v230 offset:38912
	ds_read_b128 v[192:195], v230 offset:39936
	global_load_lds_dwordx4 v196, s[30:31]
	s_mov_b32 m0, s41
	s_nop 0
	global_load_lds_dwordx4 v200, s[30:31]
	s_waitcnt lgkmcnt(8)
	s_barrier
	s_waitcnt lgkmcnt(0)
	s_setprio 1
	s_waitcnt lgkmcnt(0)
	v_mfma_f32_16x16x32_bf16 v[84:87], v[148:151], v[164:167], v[84:87]
	v_mfma_f32_16x16x32_bf16 v[76:79], v[156:159], v[164:167], v[76:79]
	v_mfma_f32_16x16x32_bf16 v[64:67], v[148:151], v[172:175], v[64:67]
	v_mfma_f32_16x16x32_bf16 v[60:63], v[156:159], v[172:175], v[60:63]
	v_mfma_f32_16x16x32_bf16 v[48:51], v[148:151], v[180:183], v[48:51]
	v_mfma_f32_16x16x32_bf16 v[44:47], v[156:159], v[180:183], v[44:47]
	v_mfma_f32_16x16x32_bf16 v[32:35], v[148:151], v[188:191], v[32:35]
	v_mfma_f32_16x16x32_bf16 v[24:27], v[156:159], v[188:191], v[24:27]
	v_mfma_f32_16x16x32_bf16 v[84:87], v[152:155], v[168:171], v[84:87]
	v_mfma_f32_16x16x32_bf16 v[76:79], v[160:163], v[168:171], v[76:79]
	v_mfma_f32_16x16x32_bf16 v[64:67], v[152:155], v[176:179], v[64:67]
	v_mfma_f32_16x16x32_bf16 v[60:63], v[160:163], v[176:179], v[60:63]
	v_mfma_f32_16x16x32_bf16 v[48:51], v[152:155], v[184:187], v[48:51]
	v_mfma_f32_16x16x32_bf16 v[44:47], v[160:163], v[184:187], v[44:47]
	v_mfma_f32_16x16x32_bf16 v[32:35], v[152:155], v[192:195], v[32:35]
	v_mfma_f32_16x16x32_bf16 v[24:27], v[160:163], v[192:195], v[24:27]
	s_setprio 0
	s_barrier
	s_add_i32 s30, s54, s34
	v_add_u32_e32 v1, 0x1c000, v231
	v_lshl_add_u64 v[2:3], v[2:3], 0, s[8:9]
	s_mov_b32 m0, s30
	ds_read_b128 v[132:135], v1
	ds_read_b128 v[136:139], v1 offset:1024
	ds_read_b128 v[140:143], v1 offset:2048
	ds_read_b128 v[144:147], v1 offset:3072
	global_load_lds_dwordx4 v[2:3], off
	v_lshl_add_u64 v[2:3], v[220:221], 0, s[8:9]
	s_add_i32 m0, s30, 0x2000
	s_nop 0
	global_load_lds_dwordx4 v[2:3], off
	s_barrier
	s_waitcnt lgkmcnt(0)
	s_setprio 1
	s_waitcnt lgkmcnt(0)
	v_mfma_f32_16x16x32_bf16 v[72:75], v[132:135], v[164:167], v[72:75]
	v_mfma_f32_16x16x32_bf16 v[68:71], v[140:143], v[164:167], v[68:71]
	v_mfma_f32_16x16x32_bf16 v[56:59], v[132:135], v[172:175], v[56:59]
	v_mfma_f32_16x16x32_bf16 v[52:55], v[140:143], v[172:175], v[52:55]
	v_mfma_f32_16x16x32_bf16 v[40:43], v[132:135], v[180:183], v[40:43]
	v_mfma_f32_16x16x32_bf16 v[36:39], v[140:143], v[180:183], v[36:39]
	v_mfma_f32_16x16x32_bf16 v[20:23], v[132:135], v[188:191], v[20:23]
	v_mfma_f32_16x16x32_bf16 v[12:15], v[140:143], v[188:191], v[12:15]
	v_mfma_f32_16x16x32_bf16 v[72:75], v[136:139], v[168:171], v[72:75]
	v_mfma_f32_16x16x32_bf16 v[68:71], v[144:147], v[168:171], v[68:71]
	v_mfma_f32_16x16x32_bf16 v[56:59], v[136:139], v[176:179], v[56:59]
	v_mfma_f32_16x16x32_bf16 v[52:55], v[144:147], v[176:179], v[52:55]
	v_mfma_f32_16x16x32_bf16 v[40:43], v[136:139], v[184:187], v[40:43]
	v_mfma_f32_16x16x32_bf16 v[36:39], v[144:147], v[184:187], v[36:39]
	v_mfma_f32_16x16x32_bf16 v[20:23], v[136:139], v[192:195], v[20:23]
	v_mfma_f32_16x16x32_bf16 v[12:15], v[144:147], v[192:195], v[12:15]
	s_setprio 0
	s_mov_b32 m0, s43
	v_lshl_add_u64 v[2:3], v[222:223], 0, s[8:9]
	s_barrier
	ds_read_b128 v[188:191], v230 offset:49152
	ds_read_b128 v[192:195], v230 offset:50176
	ds_read_b128 v[180:183], v230 offset:51200
	ds_read_b128 v[184:187], v230 offset:52224
	ds_read_b128 v[172:175], v230 offset:53248
	ds_read_b128 v[176:179], v230 offset:54272
	ds_read_b128 v[164:167], v230 offset:55296
	ds_read_b128 v[168:171], v230 offset:56320
	global_load_lds_dwordx4 v[2:3], off
	v_lshl_add_u64 v[2:3], v[224:225], 0, s[8:9]
	s_mov_b32 m0, s44
	s_and_b64 vcc, exec, s[16:17]
	global_load_lds_dwordx4 v[2:3], off
	s_barrier
	s_waitcnt lgkmcnt(0)
	s_cbranch_vccnz .LBB0_1467
	s_setprio 1
	s_waitcnt lgkmcnt(0)
	v_mfma_f32_16x16x32_bf16 v[128:131], v[148:151], v[188:191], v[128:131]
	v_mfma_f32_16x16x32_bf16 v[124:127], v[156:159], v[188:191], v[124:127]
	v_mfma_f32_16x16x32_bf16 v[112:115], v[148:151], v[180:183], v[112:115]
	v_mfma_f32_16x16x32_bf16 v[108:111], v[156:159], v[180:183], v[108:111]
	v_mfma_f32_16x16x32_bf16 v[96:99], v[148:151], v[172:175], v[96:99]
	v_mfma_f32_16x16x32_bf16 v[92:95], v[156:159], v[172:175], v[92:95]
	v_mfma_f32_16x16x32_bf16 v[28:31], v[148:151], v[164:167], v[28:31]
	v_mfma_f32_16x16x32_bf16 v[16:19], v[156:159], v[164:167], v[16:19]
	v_mfma_f32_16x16x32_bf16 v[128:131], v[152:155], v[192:195], v[128:131]
	v_mfma_f32_16x16x32_bf16 v[124:127], v[160:163], v[192:195], v[124:127]
	v_mfma_f32_16x16x32_bf16 v[112:115], v[152:155], v[184:187], v[112:115]
	v_mfma_f32_16x16x32_bf16 v[108:111], v[160:163], v[184:187], v[108:111]
	v_mfma_f32_16x16x32_bf16 v[96:99], v[152:155], v[176:179], v[96:99]
	v_mfma_f32_16x16x32_bf16 v[92:95], v[160:163], v[176:179], v[92:95]
	v_mfma_f32_16x16x32_bf16 v[28:31], v[152:155], v[168:171], v[28:31]
	v_mfma_f32_16x16x32_bf16 v[16:19], v[160:163], v[168:171], v[16:19]
	s_setprio 0
.LBB0_1467:
	s_barrier
	s_add_u32 s28, s28, 0xb0080
	s_addc_u32 s29, s29, 0
	s_mov_b32 m0, s45
	s_nop 0
	global_load_lds_dwordx4 v198, s[28:29]
	s_mov_b32 m0, s46
	s_and_b64 vcc, exec, s[16:17]
	global_load_lds_dwordx4 v202, s[28:29]
	s_waitcnt vmcnt(6)
	s_barrier
	s_cbranch_vccnz .LBB0_1460
	s_setprio 1
	s_waitcnt lgkmcnt(0)
	v_mfma_f32_16x16x32_bf16 v[120:123], v[132:135], v[188:191], v[120:123]
	v_mfma_f32_16x16x32_bf16 v[116:119], v[140:143], v[188:191], v[116:119]
	v_mfma_f32_16x16x32_bf16 v[104:107], v[132:135], v[180:183], v[104:107]
	v_mfma_f32_16x16x32_bf16 v[100:103], v[140:143], v[180:183], v[100:103]
	v_mfma_f32_16x16x32_bf16 v[88:91], v[132:135], v[172:175], v[88:91]
	v_mfma_f32_16x16x32_bf16 v[80:83], v[140:143], v[172:175], v[80:83]
	v_mfma_f32_16x16x32_bf16 v[8:11], v[132:135], v[164:167], v[8:11]
	v_mfma_f32_16x16x32_bf16 v[2:5], v[140:143], v[164:167], v[4:7]
	v_mfma_f32_16x16x32_bf16 v[120:123], v[136:139], v[192:195], v[120:123]
	v_mfma_f32_16x16x32_bf16 v[116:119], v[144:147], v[192:195], v[116:119]
	v_mfma_f32_16x16x32_bf16 v[104:107], v[136:139], v[184:187], v[104:107]
	v_mfma_f32_16x16x32_bf16 v[100:103], v[144:147], v[184:187], v[100:103]
	v_mfma_f32_16x16x32_bf16 v[88:91], v[136:139], v[176:179], v[88:91]
	v_mfma_f32_16x16x32_bf16 v[80:83], v[144:147], v[176:179], v[80:83]
	v_mfma_f32_16x16x32_bf16 v[8:11], v[136:139], v[168:171], v[8:11]
	v_mfma_f32_16x16x32_bf16 v[4:7], v[144:147], v[168:171], v[2:5]
	s_setprio 0
	s_branch .LBB0_1460

.LBB0_1682:
	ds_read_b128 v[148:151], v223
	ds_read_b128 v[152:155], v223 offset:1024
	ds_read_b128 v[156:159], v223 offset:2048
	ds_read_b128 v[160:163], v223 offset:3072
	s_add_u32 s16, s20, 0xfffc0080
	s_addc_u32 s17, s21, -1
	s_cmp_eq_u32 s35, s48
	s_cselect_b32 s41, s2, s17
	s_cselect_b32 s40, s5, s16
	s_cselect_b32 s23, s24, s43
	s_cselect_b32 s22, s31, s42
	s_add_i32 m0, s44, 0xc000
	s_waitcnt lgkmcnt(0)
	ds_read_b128 v[164:167], v224
	ds_read_b128 v[168:171], v224 offset:1024
	ds_read_b128 v[172:175], v224 offset:2048
	ds_read_b128 v[176:179], v224 offset:3072
	ds_read_b128 v[180:183], v224 offset:4096
	ds_read_b128 v[184:187], v224 offset:5120
	ds_read_b128 v[188:191], v224 offset:6144
	ds_read_b128 v[192:195], v224 offset:7168
	global_load_lds_dwordx4 v204, s[20:21]
	s_add_i32 m0, s44, 0xe000
	s_nop 0
	global_load_lds_dwordx4 v206, s[20:21]
	s_waitcnt lgkmcnt(8)
	s_barrier
	s_waitcnt lgkmcnt(0)
	s_setprio 1
	s_waitcnt lgkmcnt(0)
	v_mfma_f32_16x16x32_bf16 v[128:131], v[148:151], v[164:167], v[128:131]
	v_mfma_f32_16x16x32_bf16 v[124:127], v[156:159], v[164:167], v[124:127]
	v_mfma_f32_16x16x32_bf16 v[112:115], v[148:151], v[172:175], v[112:115]
	v_mfma_f32_16x16x32_bf16 v[108:111], v[156:159], v[172:175], v[108:111]
	v_mfma_f32_16x16x32_bf16 v[96:99], v[148:151], v[180:183], v[96:99]
	v_mfma_f32_16x16x32_bf16 v[92:95], v[156:159], v[180:183], v[92:95]
	v_mfma_f32_16x16x32_bf16 v[80:83], v[148:151], v[188:191], v[80:83]
	v_mfma_f32_16x16x32_bf16 v[76:79], v[156:159], v[188:191], v[76:79]
	v_mfma_f32_16x16x32_bf16 v[128:131], v[152:155], v[168:171], v[128:131]
	v_mfma_f32_16x16x32_bf16 v[124:127], v[160:163], v[168:171], v[124:127]
	v_mfma_f32_16x16x32_bf16 v[112:115], v[152:155], v[176:179], v[112:115]
	v_mfma_f32_16x16x32_bf16 v[108:111], v[160:163], v[176:179], v[108:111]
	v_mfma_f32_16x16x32_bf16 v[96:99], v[152:155], v[184:187], v[96:99]
	v_mfma_f32_16x16x32_bf16 v[92:95], v[160:163], v[184:187], v[92:95]
	v_mfma_f32_16x16x32_bf16 v[80:83], v[152:155], v[192:195], v[80:83]
	v_mfma_f32_16x16x32_bf16 v[76:79], v[160:163], v[192:195], v[76:79]
	s_setprio 0
	s_barrier
	s_add_i32 s16, s61, s9
	v_lshl_add_u64 v[2:3], s[22:23], 0, v[198:199]
	s_mov_b32 m0, s16
	ds_read_b128 v[132:135], v226
	ds_read_b128 v[136:139], v226 offset:1024
	ds_read_b128 v[140:143], v226 offset:2048
	ds_read_b128 v[144:147], v226 offset:3072
	global_load_lds_dwordx4 v198, s[22:23]
	v_lshl_add_u64 v[212:213], s[22:23], 0, v[202:203]
	s_add_i32 m0, s16, 0x2000
	s_nop 0
	global_load_lds_dwordx4 v202, s[22:23]
	s_barrier
	s_waitcnt lgkmcnt(0)
	s_setprio 1
	s_waitcnt lgkmcnt(0)
	v_mfma_f32_16x16x32_bf16 v[120:123], v[132:135], v[164:167], v[120:123]
	v_mfma_f32_16x16x32_bf16 v[116:119], v[140:143], v[164:167], v[116:119]
	v_mfma_f32_16x16x32_bf16 v[104:107], v[132:135], v[172:175], v[104:107]
	v_mfma_f32_16x16x32_bf16 v[100:103], v[140:143], v[172:175], v[100:103]
	v_mfma_f32_16x16x32_bf16 v[88:91], v[132:135], v[180:183], v[88:91]
	v_mfma_f32_16x16x32_bf16 v[84:87], v[140:143], v[180:183], v[84:87]
	v_mfma_f32_16x16x32_bf16 v[72:75], v[132:135], v[188:191], v[72:75]
	v_mfma_f32_16x16x32_bf16 v[68:71], v[140:143], v[188:191], v[68:71]
	v_mfma_f32_16x16x32_bf16 v[120:123], v[136:139], v[168:171], v[120:123]
	v_mfma_f32_16x16x32_bf16 v[116:119], v[144:147], v[168:171], v[116:119]
	v_mfma_f32_16x16x32_bf16 v[104:107], v[136:139], v[176:179], v[104:107]
	v_mfma_f32_16x16x32_bf16 v[100:103], v[144:147], v[176:179], v[100:103]
	v_mfma_f32_16x16x32_bf16 v[88:91], v[136:139], v[184:187], v[88:91]
	v_mfma_f32_16x16x32_bf16 v[84:87], v[144:147], v[184:187], v[84:87]
	v_mfma_f32_16x16x32_bf16 v[72:75], v[136:139], v[192:195], v[72:75]
	v_mfma_f32_16x16x32_bf16 v[68:71], v[144:147], v[192:195], v[68:71]
	s_setprio 0
	s_mov_b32 m0, s44
	v_lshl_add_u64 v[214:215], s[40:41], 0, v[196:197]
	s_barrier
	ds_read_b128 v[188:191], v224 offset:16384
	ds_read_b128 v[192:195], v224 offset:17408
	ds_read_b128 v[180:183], v224 offset:18432
	ds_read_b128 v[184:187], v224 offset:19456
	ds_read_b128 v[172:175], v224 offset:20480
	ds_read_b128 v[176:179], v224 offset:21504
	ds_read_b128 v[164:167], v224 offset:22528
	ds_read_b128 v[168:171], v224 offset:23552
	global_load_lds_dwordx4 v196, s[40:41]
	v_lshl_add_u64 v[216:217], s[40:41], 0, v[200:201]
	s_mov_b32 m0, s45
	v_cmp_ne_u32_e64 s[16:17], 1, v236
	global_load_lds_dwordx4 v200, s[40:41]
	s_barrier
	s_waitcnt lgkmcnt(0)
	s_andn2_b64 vcc, exec, s[18:19]
	s_cbranch_vccnz .LBB0_1684
	s_setprio 1
	s_waitcnt lgkmcnt(0)
	v_mfma_f32_16x16x32_bf16 v[64:67], v[148:151], v[188:191], v[64:67]
	v_mfma_f32_16x16x32_bf16 v[60:63], v[156:159], v[188:191], v[60:63]
	v_mfma_f32_16x16x32_bf16 v[48:51], v[148:151], v[180:183], v[48:51]
	v_mfma_f32_16x16x32_bf16 v[44:47], v[156:159], v[180:183], v[44:47]
	v_mfma_f32_16x16x32_bf16 v[32:35], v[148:151], v[172:175], v[32:35]
	v_mfma_f32_16x16x32_bf16 v[28:31], v[156:159], v[172:175], v[28:31]
	v_mfma_f32_16x16x32_bf16 v[16:19], v[148:151], v[164:167], v[16:19]
	v_mfma_f32_16x16x32_bf16 v[12:15], v[156:159], v[164:167], v[12:15]
	v_mfma_f32_16x16x32_bf16 v[64:67], v[152:155], v[192:195], v[64:67]
	v_mfma_f32_16x16x32_bf16 v[60:63], v[160:163], v[192:195], v[60:63]
	v_mfma_f32_16x16x32_bf16 v[48:51], v[152:155], v[184:187], v[48:51]
	v_mfma_f32_16x16x32_bf16 v[44:47], v[160:163], v[184:187], v[44:47]
	v_mfma_f32_16x16x32_bf16 v[32:35], v[152:155], v[176:179], v[32:35]
	v_mfma_f32_16x16x32_bf16 v[28:31], v[160:163], v[176:179], v[28:31]
	v_mfma_f32_16x16x32_bf16 v[16:19], v[152:155], v[168:171], v[16:19]
	v_mfma_f32_16x16x32_bf16 v[12:15], v[160:163], v[168:171], v[12:15]
	s_setprio 0
.LBB0_1684:
	s_barrier
	s_add_u32 s50, s22, 0x40000
	s_addc_u32 s51, s23, 0
	s_mov_b32 m0, s46
	s_nop 0
	global_load_lds_dwordx4 v198, s[50:51]
	s_mov_b32 m0, s47
	s_and_b64 vcc, exec, s[16:17]
	global_load_lds_dwordx4 v202, s[50:51]
	s_waitcnt vmcnt(6)
	s_barrier
	s_cbranch_vccnz .LBB0_1686
	s_setprio 1
	s_waitcnt lgkmcnt(0)
	v_mfma_f32_16x16x32_bf16 v[56:59], v[132:135], v[188:191], v[56:59]
	v_mfma_f32_16x16x32_bf16 v[52:55], v[140:143], v[188:191], v[52:55]
	v_mfma_f32_16x16x32_bf16 v[40:43], v[132:135], v[180:183], v[40:43]
	v_mfma_f32_16x16x32_bf16 v[36:39], v[140:143], v[180:183], v[36:39]
	v_mfma_f32_16x16x32_bf16 v[24:27], v[132:135], v[172:175], v[24:27]
	v_mfma_f32_16x16x32_bf16 v[20:23], v[140:143], v[172:175], v[20:23]
	v_mfma_f32_16x16x32_bf16 v[8:11], v[132:135], v[164:167], v[8:11]
	v_mfma_f32_16x16x32_bf16 v[4:7], v[140:143], v[164:167], v[4:7]
	v_mfma_f32_16x16x32_bf16 v[56:59], v[136:139], v[192:195], v[56:59]
	v_mfma_f32_16x16x32_bf16 v[52:55], v[144:147], v[192:195], v[52:55]
	v_mfma_f32_16x16x32_bf16 v[40:43], v[136:139], v[184:187], v[40:43]
	v_mfma_f32_16x16x32_bf16 v[36:39], v[144:147], v[184:187], v[36:39]
	v_mfma_f32_16x16x32_bf16 v[24:27], v[136:139], v[176:179], v[24:27]
	v_mfma_f32_16x16x32_bf16 v[20:23], v[144:147], v[176:179], v[20:23]
	v_mfma_f32_16x16x32_bf16 v[8:11], v[136:139], v[168:171], v[8:11]
	v_mfma_f32_16x16x32_bf16 v[4:7], v[144:147], v[168:171], v[4:7]
	s_setprio 0
.LBB0_1686:
	s_add_i32 s49, 0, 0x18000
	v_add_u32_e32 v1, s49, v219
	s_barrier
	ds_read_b128 v[148:151], v1
	ds_read_b128 v[152:155], v1 offset:1024
	ds_read_b128 v[156:159], v1 offset:2048
	ds_read_b128 v[160:163], v1 offset:3072
	s_add_u32 s40, s40, 0x40000
	s_addc_u32 s41, s41, 0
	s_mov_b32 m0, s52
	s_waitcnt lgkmcnt(0)
	ds_read_b128 v[164:167], v224 offset:32768
	ds_read_b128 v[168:171], v224 offset:33792
	ds_read_b128 v[172:175], v224 offset:34816
	ds_read_b128 v[176:179], v224 offset:35840
	ds_read_b128 v[180:183], v224 offset:36864
	ds_read_b128 v[184:187], v224 offset:37888
	ds_read_b128 v[188:191], v224 offset:38912
	ds_read_b128 v[192:195], v224 offset:39936
	global_load_lds_dwordx4 v196, s[40:41]
	s_mov_b32 m0, s53
	s_nop 0
	global_load_lds_dwordx4 v200, s[40:41]
	s_waitcnt lgkmcnt(8)
	s_barrier
	s_waitcnt lgkmcnt(0)
	s_setprio 1
	s_waitcnt lgkmcnt(0)
	v_mfma_f32_16x16x32_bf16 v[128:131], v[148:151], v[164:167], v[128:131]
	v_mfma_f32_16x16x32_bf16 v[124:127], v[156:159], v[164:167], v[124:127]
	v_mfma_f32_16x16x32_bf16 v[112:115], v[148:151], v[172:175], v[112:115]
	v_mfma_f32_16x16x32_bf16 v[108:111], v[156:159], v[172:175], v[108:111]
	v_mfma_f32_16x16x32_bf16 v[96:99], v[148:151], v[180:183], v[96:99]
	v_mfma_f32_16x16x32_bf16 v[92:95], v[156:159], v[180:183], v[92:95]
	v_mfma_f32_16x16x32_bf16 v[80:83], v[148:151], v[188:191], v[80:83]
	v_mfma_f32_16x16x32_bf16 v[76:79], v[156:159], v[188:191], v[76:79]
	v_mfma_f32_16x16x32_bf16 v[128:131], v[152:155], v[168:171], v[128:131]
	v_mfma_f32_16x16x32_bf16 v[124:127], v[160:163], v[168:171], v[124:127]
	v_mfma_f32_16x16x32_bf16 v[112:115], v[152:155], v[176:179], v[112:115]
	v_mfma_f32_16x16x32_bf16 v[108:111], v[160:163], v[176:179], v[108:111]
	v_mfma_f32_16x16x32_bf16 v[96:99], v[152:155], v[184:187], v[96:99]
	v_mfma_f32_16x16x32_bf16 v[92:95], v[160:163], v[184:187], v[92:95]
	v_mfma_f32_16x16x32_bf16 v[80:83], v[152:155], v[192:195], v[80:83]
	v_mfma_f32_16x16x32_bf16 v[76:79], v[160:163], v[192:195], v[76:79]
	s_setprio 0
	s_barrier
	s_add_i32 s40, s49, s9
	v_add_u32_e32 v1, 0x1c000, v225
	v_lshl_add_u64 v[2:3], v[2:3], 0, s[26:27]
	s_mov_b32 m0, s40
	ds_read_b128 v[132:135], v1
	ds_read_b128 v[136:139], v1 offset:1024
	ds_read_b128 v[140:143], v1 offset:2048
	ds_read_b128 v[144:147], v1 offset:3072
	global_load_lds_dwordx4 v[2:3], off
	v_lshl_add_u64 v[2:3], v[212:213], 0, s[26:27]
	s_add_i32 m0, s40, 0x2000
	s_nop 0
	global_load_lds_dwordx4 v[2:3], off
	s_barrier
	s_waitcnt lgkmcnt(0)
	s_setprio 1
	s_waitcnt lgkmcnt(0)
	v_mfma_f32_16x16x32_bf16 v[120:123], v[132:135], v[164:167], v[120:123]
	v_mfma_f32_16x16x32_bf16 v[116:119], v[140:143], v[164:167], v[116:119]
	v_mfma_f32_16x16x32_bf16 v[104:107], v[132:135], v[172:175], v[104:107]
	v_mfma_f32_16x16x32_bf16 v[100:103], v[140:143], v[172:175], v[100:103]
	v_mfma_f32_16x16x32_bf16 v[88:91], v[132:135], v[180:183], v[88:91]
	v_mfma_f32_16x16x32_bf16 v[84:87], v[140:143], v[180:183], v[84:87]
	v_mfma_f32_16x16x32_bf16 v[72:75], v[132:135], v[188:191], v[72:75]
	v_mfma_f32_16x16x32_bf16 v[68:71], v[140:143], v[188:191], v[68:71]
	v_mfma_f32_16x16x32_bf16 v[120:123], v[136:139], v[168:171], v[120:123]
	v_mfma_f32_16x16x32_bf16 v[116:119], v[144:147], v[168:171], v[116:119]
	v_mfma_f32_16x16x32_bf16 v[104:107], v[136:139], v[176:179], v[104:107]
	v_mfma_f32_16x16x32_bf16 v[100:103], v[144:147], v[176:179], v[100:103]
	v_mfma_f32_16x16x32_bf16 v[88:91], v[136:139], v[184:187], v[88:91]
	v_mfma_f32_16x16x32_bf16 v[84:87], v[144:147], v[184:187], v[84:87]
	v_mfma_f32_16x16x32_bf16 v[72:75], v[136:139], v[192:195], v[72:75]
	v_mfma_f32_16x16x32_bf16 v[68:71], v[144:147], v[192:195], v[68:71]
	s_setprio 0
	s_mov_b32 m0, s55
	v_lshl_add_u64 v[2:3], v[214:215], 0, s[26:27]
	s_barrier
	ds_read_b128 v[188:191], v224 offset:49152
	ds_read_b128 v[192:195], v224 offset:50176
	ds_read_b128 v[180:183], v224 offset:51200
	ds_read_b128 v[184:187], v224 offset:52224
	ds_read_b128 v[172:175], v224 offset:53248
	ds_read_b128 v[176:179], v224 offset:54272
	ds_read_b128 v[164:167], v224 offset:55296
	ds_read_b128 v[168:171], v224 offset:56320
	global_load_lds_dwordx4 v[2:3], off
	v_lshl_add_u64 v[2:3], v[216:217], 0, s[26:27]
	s_mov_b32 m0, s56
	s_and_b64 vcc, exec, s[16:17]
	global_load_lds_dwordx4 v[2:3], off
	s_barrier
	s_waitcnt lgkmcnt(0)
	s_cbranch_vccnz .LBB0_1688
	s_setprio 1
	s_waitcnt lgkmcnt(0)
	v_mfma_f32_16x16x32_bf16 v[64:67], v[148:151], v[188:191], v[64:67]
	v_mfma_f32_16x16x32_bf16 v[60:63], v[156:159], v[188:191], v[60:63]
	v_mfma_f32_16x16x32_bf16 v[48:51], v[148:151], v[180:183], v[48:51]
	v_mfma_f32_16x16x32_bf16 v[44:47], v[156:159], v[180:183], v[44:47]
	v_mfma_f32_16x16x32_bf16 v[32:35], v[148:151], v[172:175], v[32:35]
	v_mfma_f32_16x16x32_bf16 v[28:31], v[156:159], v[172:175], v[28:31]
	v_mfma_f32_16x16x32_bf16 v[16:19], v[148:151], v[164:167], v[16:19]
	v_mfma_f32_16x16x32_bf16 v[12:15], v[156:159], v[164:167], v[12:15]
	v_mfma_f32_16x16x32_bf16 v[64:67], v[152:155], v[192:195], v[64:67]
	v_mfma_f32_16x16x32_bf16 v[60:63], v[160:163], v[192:195], v[60:63]
	v_mfma_f32_16x16x32_bf16 v[48:51], v[152:155], v[184:187], v[48:51]
	v_mfma_f32_16x16x32_bf16 v[44:47], v[160:163], v[184:187], v[44:47]
	v_mfma_f32_16x16x32_bf16 v[32:35], v[152:155], v[176:179], v[32:35]
	v_mfma_f32_16x16x32_bf16 v[28:31], v[160:163], v[176:179], v[28:31]
	v_mfma_f32_16x16x32_bf16 v[16:19], v[152:155], v[168:171], v[16:19]
	v_mfma_f32_16x16x32_bf16 v[12:15], v[160:163], v[168:171], v[12:15]
	s_setprio 0
.LBB0_1688:
	s_barrier
	s_add_u32 s22, s22, 0x40080
	s_addc_u32 s23, s23, 0
	s_mov_b32 m0, s57
	s_nop 0
	global_load_lds_dwordx4 v198, s[22:23]
	s_mov_b32 m0, s58
	s_and_b64 vcc, exec, s[16:17]
	global_load_lds_dwordx4 v202, s[22:23]
	s_waitcnt vmcnt(6)
	s_barrier
	s_cbranch_vccnz .LBB0_1681
	s_setprio 1
	s_waitcnt lgkmcnt(0)
	v_mfma_f32_16x16x32_bf16 v[56:59], v[132:135], v[188:191], v[56:59]
	v_mfma_f32_16x16x32_bf16 v[52:55], v[140:143], v[188:191], v[52:55]
	v_mfma_f32_16x16x32_bf16 v[40:43], v[132:135], v[180:183], v[40:43]
	v_mfma_f32_16x16x32_bf16 v[36:39], v[140:143], v[180:183], v[36:39]
	v_mfma_f32_16x16x32_bf16 v[24:27], v[132:135], v[172:175], v[24:27]
	v_mfma_f32_16x16x32_bf16 v[20:23], v[140:143], v[172:175], v[20:23]
	v_mfma_f32_16x16x32_bf16 v[8:11], v[132:135], v[164:167], v[8:11]
	v_mfma_f32_16x16x32_bf16 v[2:5], v[140:143], v[164:167], v[4:7]
	v_mfma_f32_16x16x32_bf16 v[56:59], v[136:139], v[192:195], v[56:59]
	v_mfma_f32_16x16x32_bf16 v[52:55], v[144:147], v[192:195], v[52:55]
	v_mfma_f32_16x16x32_bf16 v[40:43], v[136:139], v[184:187], v[40:43]
	v_mfma_f32_16x16x32_bf16 v[36:39], v[144:147], v[184:187], v[36:39]
	v_mfma_f32_16x16x32_bf16 v[24:27], v[136:139], v[176:179], v[24:27]
	v_mfma_f32_16x16x32_bf16 v[20:23], v[144:147], v[176:179], v[20:23]
	v_mfma_f32_16x16x32_bf16 v[8:11], v[136:139], v[168:171], v[8:11]
	v_mfma_f32_16x16x32_bf16 v[4:7], v[144:147], v[168:171], v[2:5]
	s_setprio 0
	s_branch .LBB0_1681

.LBB0_1888:
	ds_read_b128 v[148:151], v232
	ds_read_b128 v[152:155], v232 offset:1024
	ds_read_b128 v[156:159], v232 offset:2048
	ds_read_b128 v[160:163], v232 offset:3072
	s_add_u32 s12, s20, 0xffff0080
	s_addc_u32 s13, s21, -1
	s_cmp_eq_u32 s52, s55
	s_cselect_b32 s25, s17, s13
	s_cselect_b32 s24, s49, s12
	s_cselect_b32 s23, s50, s54
	s_cselect_b32 s22, s51, s53
	s_add_i32 m0, s30, 0xc000
	s_waitcnt lgkmcnt(0)
	ds_read_b128 v[164:167], v233
	ds_read_b128 v[168:171], v233 offset:1024
	ds_read_b128 v[172:175], v233 offset:2048
	ds_read_b128 v[176:179], v233 offset:3072
	ds_read_b128 v[180:183], v233 offset:4096
	ds_read_b128 v[184:187], v233 offset:5120
	ds_read_b128 v[188:191], v233 offset:6144
	ds_read_b128 v[192:195], v233 offset:7168
	global_load_lds_dwordx4 v220, s[20:21]
	s_add_i32 m0, s30, 0xe000
	s_nop 0
	global_load_lds_dwordx4 v222, s[20:21]
	s_waitcnt lgkmcnt(8)
	s_barrier
	s_waitcnt lgkmcnt(0)
	s_setprio 1
	s_waitcnt lgkmcnt(0)
	v_mfma_f32_16x16x32_bf16 v[128:131], v[148:151], v[164:167], v[128:131]
	v_mfma_f32_16x16x32_bf16 v[124:127], v[156:159], v[164:167], v[124:127]
	v_mfma_f32_16x16x32_bf16 v[112:115], v[148:151], v[172:175], v[112:115]
	v_mfma_f32_16x16x32_bf16 v[108:111], v[156:159], v[172:175], v[108:111]
	v_mfma_f32_16x16x32_bf16 v[96:99], v[148:151], v[180:183], v[96:99]
	v_mfma_f32_16x16x32_bf16 v[92:95], v[156:159], v[180:183], v[92:95]
	v_mfma_f32_16x16x32_bf16 v[80:83], v[148:151], v[188:191], v[80:83]
	v_mfma_f32_16x16x32_bf16 v[76:79], v[156:159], v[188:191], v[76:79]
	v_mfma_f32_16x16x32_bf16 v[128:131], v[152:155], v[168:171], v[128:131]
	v_mfma_f32_16x16x32_bf16 v[124:127], v[160:163], v[168:171], v[124:127]
	v_mfma_f32_16x16x32_bf16 v[112:115], v[152:155], v[176:179], v[112:115]
	v_mfma_f32_16x16x32_bf16 v[108:111], v[160:163], v[176:179], v[108:111]
	v_mfma_f32_16x16x32_bf16 v[96:99], v[152:155], v[184:187], v[96:99]
	v_mfma_f32_16x16x32_bf16 v[92:95], v[160:163], v[184:187], v[92:95]
	v_mfma_f32_16x16x32_bf16 v[80:83], v[152:155], v[192:195], v[80:83]
	v_mfma_f32_16x16x32_bf16 v[76:79], v[160:163], v[192:195], v[76:79]
	s_setprio 0
	s_barrier
	s_add_i32 s12, s43, s29
	v_add_u32_e32 v0, 0x14000, v234
	v_lshl_add_u64 v[2:3], s[22:23], 0, v[196:197]
	s_mov_b32 m0, s12
	ds_read_b128 v[132:135], v0
	ds_read_b128 v[136:139], v0 offset:1024
	ds_read_b128 v[140:143], v0 offset:2048
	ds_read_b128 v[144:147], v0 offset:3072
	global_load_lds_dwordx4 v196, s[22:23]
	v_lshl_add_u64 v[224:225], s[22:23], 0, v[198:199]
	s_add_i32 m0, s12, 0x2000
	s_nop 0
	global_load_lds_dwordx4 v198, s[22:23]
	s_barrier
	s_waitcnt lgkmcnt(0)
	s_setprio 1
	s_waitcnt lgkmcnt(0)
	v_mfma_f32_16x16x32_bf16 v[120:123], v[132:135], v[164:167], v[120:123]
	v_mfma_f32_16x16x32_bf16 v[116:119], v[140:143], v[164:167], v[116:119]
	v_mfma_f32_16x16x32_bf16 v[104:107], v[132:135], v[172:175], v[104:107]
	v_mfma_f32_16x16x32_bf16 v[100:103], v[140:143], v[172:175], v[100:103]
	v_mfma_f32_16x16x32_bf16 v[88:91], v[132:135], v[180:183], v[88:91]
	v_mfma_f32_16x16x32_bf16 v[84:87], v[140:143], v[180:183], v[84:87]
	v_mfma_f32_16x16x32_bf16 v[72:75], v[132:135], v[188:191], v[72:75]
	v_mfma_f32_16x16x32_bf16 v[68:71], v[140:143], v[188:191], v[68:71]
	v_mfma_f32_16x16x32_bf16 v[120:123], v[136:139], v[168:171], v[120:123]
	v_mfma_f32_16x16x32_bf16 v[116:119], v[144:147], v[168:171], v[116:119]
	v_mfma_f32_16x16x32_bf16 v[104:107], v[136:139], v[176:179], v[104:107]
	v_mfma_f32_16x16x32_bf16 v[100:103], v[144:147], v[176:179], v[100:103]
	v_mfma_f32_16x16x32_bf16 v[88:91], v[136:139], v[184:187], v[88:91]
	v_mfma_f32_16x16x32_bf16 v[84:87], v[144:147], v[184:187], v[84:87]
	v_mfma_f32_16x16x32_bf16 v[72:75], v[136:139], v[192:195], v[72:75]
	v_mfma_f32_16x16x32_bf16 v[68:71], v[144:147], v[192:195], v[68:71]
	s_setprio 0
	s_mov_b32 m0, s30
	v_lshl_add_u64 v[226:227], s[24:25], 0, v[202:203]
	s_barrier
	ds_read_b128 v[188:191], v233 offset:16384
	ds_read_b128 v[192:195], v233 offset:17408
	ds_read_b128 v[180:183], v233 offset:18432
	ds_read_b128 v[184:187], v233 offset:19456
	ds_read_b128 v[172:175], v233 offset:20480
	ds_read_b128 v[176:179], v233 offset:21504
	ds_read_b128 v[164:167], v233 offset:22528
	ds_read_b128 v[168:171], v233 offset:23552
	global_load_lds_dwordx4 v202, s[24:25]
	v_lshl_add_u64 v[228:229], s[24:25], 0, v[200:201]
	s_mov_b32 m0, s31
	v_cndmask_b32_e64 v0, 0, 1, s[18:19]
	global_load_lds_dwordx4 v200, s[24:25]
	s_barrier
	s_waitcnt lgkmcnt(0)
	v_cmp_ne_u32_e64 s[12:13], 1, v0
	s_andn2_b64 vcc, exec, s[18:19]
	s_cbranch_vccnz .LBB0_1890
	s_setprio 1
	s_waitcnt lgkmcnt(0)
	v_mfma_f32_16x16x32_bf16 v[64:67], v[148:151], v[188:191], v[64:67]
	v_mfma_f32_16x16x32_bf16 v[60:63], v[156:159], v[188:191], v[60:63]
	v_mfma_f32_16x16x32_bf16 v[48:51], v[148:151], v[180:183], v[48:51]
	v_mfma_f32_16x16x32_bf16 v[44:47], v[156:159], v[180:183], v[44:47]
	v_mfma_f32_16x16x32_bf16 v[32:35], v[148:151], v[172:175], v[32:35]
	v_mfma_f32_16x16x32_bf16 v[28:31], v[156:159], v[172:175], v[28:31]
	v_mfma_f32_16x16x32_bf16 v[16:19], v[148:151], v[164:167], v[16:19]
	v_mfma_f32_16x16x32_bf16 v[12:15], v[156:159], v[164:167], v[12:15]
	v_mfma_f32_16x16x32_bf16 v[64:67], v[152:155], v[192:195], v[64:67]
	v_mfma_f32_16x16x32_bf16 v[60:63], v[160:163], v[192:195], v[60:63]
	v_mfma_f32_16x16x32_bf16 v[48:51], v[152:155], v[184:187], v[48:51]
	v_mfma_f32_16x16x32_bf16 v[44:47], v[160:163], v[184:187], v[44:47]
	v_mfma_f32_16x16x32_bf16 v[32:35], v[152:155], v[176:179], v[32:35]
	v_mfma_f32_16x16x32_bf16 v[28:31], v[160:163], v[176:179], v[28:31]
	v_mfma_f32_16x16x32_bf16 v[16:19], v[152:155], v[168:171], v[16:19]
	v_mfma_f32_16x16x32_bf16 v[12:15], v[160:163], v[168:171], v[12:15]
	s_setprio 0
.LBB0_1890:
	s_barrier
	s_add_u32 s56, s22, 0x10000
	s_addc_u32 s57, s23, 0
	s_mov_b32 m0, s34
	s_nop 0
	global_load_lds_dwordx4 v196, s[56:57]
	s_mov_b32 m0, s35
	s_and_b64 vcc, exec, s[12:13]
	global_load_lds_dwordx4 v198, s[56:57]
	s_waitcnt vmcnt(6)
	s_barrier
	s_cbranch_vccnz .LBB0_1892
	s_setprio 1
	s_waitcnt lgkmcnt(0)
	v_mfma_f32_16x16x32_bf16 v[56:59], v[132:135], v[188:191], v[56:59]
	v_mfma_f32_16x16x32_bf16 v[52:55], v[140:143], v[188:191], v[52:55]
	v_mfma_f32_16x16x32_bf16 v[40:43], v[132:135], v[180:183], v[40:43]
	v_mfma_f32_16x16x32_bf16 v[36:39], v[140:143], v[180:183], v[36:39]
	v_mfma_f32_16x16x32_bf16 v[24:27], v[132:135], v[172:175], v[24:27]
	v_mfma_f32_16x16x32_bf16 v[20:23], v[140:143], v[172:175], v[20:23]
	v_mfma_f32_16x16x32_bf16 v[8:11], v[132:135], v[164:167], v[8:11]
	v_mfma_f32_16x16x32_bf16 v[4:7], v[140:143], v[164:167], v[4:7]
	v_mfma_f32_16x16x32_bf16 v[56:59], v[136:139], v[192:195], v[56:59]
	v_mfma_f32_16x16x32_bf16 v[52:55], v[144:147], v[192:195], v[52:55]
	v_mfma_f32_16x16x32_bf16 v[40:43], v[136:139], v[184:187], v[40:43]
	v_mfma_f32_16x16x32_bf16 v[36:39], v[144:147], v[184:187], v[36:39]
	v_mfma_f32_16x16x32_bf16 v[24:27], v[136:139], v[176:179], v[24:27]
	v_mfma_f32_16x16x32_bf16 v[20:23], v[144:147], v[176:179], v[20:23]
	v_mfma_f32_16x16x32_bf16 v[8:11], v[136:139], v[168:171], v[8:11]
	v_mfma_f32_16x16x32_bf16 v[4:7], v[144:147], v[168:171], v[4:7]
	s_setprio 0
.LBB0_1892:
	s_add_i32 s56, 0, 0x18000
	v_add_u32_e32 v0, s56, v230
	s_barrier
	ds_read_b128 v[148:151], v0
	ds_read_b128 v[152:155], v0 offset:1024
	ds_read_b128 v[156:159], v0 offset:2048
	ds_read_b128 v[160:163], v0 offset:3072
	s_add_u32 s24, s24, 0x10000
	s_addc_u32 s25, s25, 0
	s_mov_b32 m0, s36
	s_waitcnt lgkmcnt(0)
	ds_read_b128 v[164:167], v233 offset:32768
	ds_read_b128 v[168:171], v233 offset:33792
	ds_read_b128 v[172:175], v233 offset:34816
	ds_read_b128 v[176:179], v233 offset:35840
	ds_read_b128 v[180:183], v233 offset:36864
	ds_read_b128 v[184:187], v233 offset:37888
	ds_read_b128 v[188:191], v233 offset:38912
	ds_read_b128 v[192:195], v233 offset:39936
	global_load_lds_dwordx4 v202, s[24:25]
	s_mov_b32 m0, s37
	s_nop 0
	global_load_lds_dwordx4 v200, s[24:25]
	s_waitcnt lgkmcnt(8)
	s_barrier
	s_waitcnt lgkmcnt(0)
	s_setprio 1
	s_waitcnt lgkmcnt(0)
	v_mfma_f32_16x16x32_bf16 v[128:131], v[148:151], v[164:167], v[128:131]
	v_mfma_f32_16x16x32_bf16 v[124:127], v[156:159], v[164:167], v[124:127]
	v_mfma_f32_16x16x32_bf16 v[112:115], v[148:151], v[172:175], v[112:115]
	v_mfma_f32_16x16x32_bf16 v[108:111], v[156:159], v[172:175], v[108:111]
	v_mfma_f32_16x16x32_bf16 v[96:99], v[148:151], v[180:183], v[96:99]
	v_mfma_f32_16x16x32_bf16 v[92:95], v[156:159], v[180:183], v[92:95]
	v_mfma_f32_16x16x32_bf16 v[80:83], v[148:151], v[188:191], v[80:83]
	v_mfma_f32_16x16x32_bf16 v[76:79], v[156:159], v[188:191], v[76:79]
	v_mfma_f32_16x16x32_bf16 v[128:131], v[152:155], v[168:171], v[128:131]
	v_mfma_f32_16x16x32_bf16 v[124:127], v[160:163], v[168:171], v[124:127]
	v_mfma_f32_16x16x32_bf16 v[112:115], v[152:155], v[176:179], v[112:115]
	v_mfma_f32_16x16x32_bf16 v[108:111], v[160:163], v[176:179], v[108:111]
	v_mfma_f32_16x16x32_bf16 v[96:99], v[152:155], v[184:187], v[96:99]
	v_mfma_f32_16x16x32_bf16 v[92:95], v[160:163], v[184:187], v[92:95]
	v_mfma_f32_16x16x32_bf16 v[80:83], v[152:155], v[192:195], v[80:83]
	v_mfma_f32_16x16x32_bf16 v[76:79], v[160:163], v[192:195], v[76:79]
	s_setprio 0
	s_barrier
	s_add_i32 s24, s56, s29
	v_add_u32_e32 v0, 0x1c000, v234
	v_lshl_add_u64 v[2:3], v[2:3], 0, s[4:5]
	s_mov_b32 m0, s24
	ds_read_b128 v[132:135], v0
	ds_read_b128 v[136:139], v0 offset:1024
	ds_read_b128 v[140:143], v0 offset:2048
	ds_read_b128 v[144:147], v0 offset:3072
	global_load_lds_dwordx4 v[2:3], off
	v_lshl_add_u64 v[2:3], v[224:225], 0, s[4:5]
	s_add_i32 m0, s24, 0x2000
	s_nop 0
	global_load_lds_dwordx4 v[2:3], off
	s_barrier
	s_waitcnt lgkmcnt(0)
	s_setprio 1
	s_waitcnt lgkmcnt(0)
	v_mfma_f32_16x16x32_bf16 v[120:123], v[132:135], v[164:167], v[120:123]
	v_mfma_f32_16x16x32_bf16 v[116:119], v[140:143], v[164:167], v[116:119]
	v_mfma_f32_16x16x32_bf16 v[104:107], v[132:135], v[172:175], v[104:107]
	v_mfma_f32_16x16x32_bf16 v[100:103], v[140:143], v[172:175], v[100:103]
	v_mfma_f32_16x16x32_bf16 v[88:91], v[132:135], v[180:183], v[88:91]
	v_mfma_f32_16x16x32_bf16 v[84:87], v[140:143], v[180:183], v[84:87]
	v_mfma_f32_16x16x32_bf16 v[72:75], v[132:135], v[188:191], v[72:75]
	v_mfma_f32_16x16x32_bf16 v[68:71], v[140:143], v[188:191], v[68:71]
	v_mfma_f32_16x16x32_bf16 v[120:123], v[136:139], v[168:171], v[120:123]
	v_mfma_f32_16x16x32_bf16 v[116:119], v[144:147], v[168:171], v[116:119]
	v_mfma_f32_16x16x32_bf16 v[104:107], v[136:139], v[176:179], v[104:107]
	v_mfma_f32_16x16x32_bf16 v[100:103], v[144:147], v[176:179], v[100:103]
	v_mfma_f32_16x16x32_bf16 v[88:91], v[136:139], v[184:187], v[88:91]
	v_mfma_f32_16x16x32_bf16 v[84:87], v[144:147], v[184:187], v[84:87]
	v_mfma_f32_16x16x32_bf16 v[72:75], v[136:139], v[192:195], v[72:75]
	v_mfma_f32_16x16x32_bf16 v[68:71], v[144:147], v[192:195], v[68:71]
	s_setprio 0
	s_mov_b32 m0, s39
	v_lshl_add_u64 v[2:3], v[226:227], 0, s[4:5]
	s_barrier
	ds_read_b128 v[188:191], v233 offset:49152
	ds_read_b128 v[192:195], v233 offset:50176
	ds_read_b128 v[180:183], v233 offset:51200
	ds_read_b128 v[184:187], v233 offset:52224
	ds_read_b128 v[172:175], v233 offset:53248
	ds_read_b128 v[176:179], v233 offset:54272
	ds_read_b128 v[164:167], v233 offset:55296
	ds_read_b128 v[168:171], v233 offset:56320
	global_load_lds_dwordx4 v[2:3], off
	v_lshl_add_u64 v[2:3], v[228:229], 0, s[4:5]
	s_mov_b32 m0, s40
	s_and_b64 vcc, exec, s[12:13]
	global_load_lds_dwordx4 v[2:3], off
	s_barrier
	s_waitcnt lgkmcnt(0)
	s_cbranch_vccnz .LBB0_1894
	s_setprio 1
	s_waitcnt lgkmcnt(0)
	v_mfma_f32_16x16x32_bf16 v[64:67], v[148:151], v[188:191], v[64:67]
	v_mfma_f32_16x16x32_bf16 v[60:63], v[156:159], v[188:191], v[60:63]
	v_mfma_f32_16x16x32_bf16 v[48:51], v[148:151], v[180:183], v[48:51]
	v_mfma_f32_16x16x32_bf16 v[44:47], v[156:159], v[180:183], v[44:47]
	v_mfma_f32_16x16x32_bf16 v[32:35], v[148:151], v[172:175], v[32:35]
	v_mfma_f32_16x16x32_bf16 v[28:31], v[156:159], v[172:175], v[28:31]
	v_mfma_f32_16x16x32_bf16 v[16:19], v[148:151], v[164:167], v[16:19]
	v_mfma_f32_16x16x32_bf16 v[12:15], v[156:159], v[164:167], v[12:15]
	v_mfma_f32_16x16x32_bf16 v[64:67], v[152:155], v[192:195], v[64:67]
	v_mfma_f32_16x16x32_bf16 v[60:63], v[160:163], v[192:195], v[60:63]
	v_mfma_f32_16x16x32_bf16 v[48:51], v[152:155], v[184:187], v[48:51]
	v_mfma_f32_16x16x32_bf16 v[44:47], v[160:163], v[184:187], v[44:47]
	v_mfma_f32_16x16x32_bf16 v[32:35], v[152:155], v[176:179], v[32:35]
	v_mfma_f32_16x16x32_bf16 v[28:31], v[160:163], v[176:179], v[28:31]
	v_mfma_f32_16x16x32_bf16 v[16:19], v[152:155], v[168:171], v[16:19]
	v_mfma_f32_16x16x32_bf16 v[12:15], v[160:163], v[168:171], v[12:15]
	s_setprio 0
.LBB0_1894:
	s_barrier
	s_add_u32 s22, s22, 0x10080
	s_addc_u32 s23, s23, 0
	s_mov_b32 m0, s41
	s_nop 0
	global_load_lds_dwordx4 v196, s[22:23]
	s_mov_b32 m0, s42
	s_and_b64 vcc, exec, s[12:13]
	global_load_lds_dwordx4 v198, s[22:23]
	s_waitcnt vmcnt(6)
	s_barrier
	s_cbranch_vccnz .LBB0_1887
	s_setprio 1
	s_waitcnt lgkmcnt(0)
	v_mfma_f32_16x16x32_bf16 v[56:59], v[132:135], v[188:191], v[56:59]
	v_mfma_f32_16x16x32_bf16 v[52:55], v[140:143], v[188:191], v[52:55]
	v_mfma_f32_16x16x32_bf16 v[40:43], v[132:135], v[180:183], v[40:43]
	v_mfma_f32_16x16x32_bf16 v[36:39], v[140:143], v[180:183], v[36:39]
	v_mfma_f32_16x16x32_bf16 v[24:27], v[132:135], v[172:175], v[24:27]
	v_mfma_f32_16x16x32_bf16 v[20:23], v[140:143], v[172:175], v[20:23]
	v_mfma_f32_16x16x32_bf16 v[8:11], v[132:135], v[164:167], v[8:11]
	v_mfma_f32_16x16x32_bf16 v[2:5], v[140:143], v[164:167], v[4:7]
	v_mfma_f32_16x16x32_bf16 v[56:59], v[136:139], v[192:195], v[56:59]
	v_mfma_f32_16x16x32_bf16 v[52:55], v[144:147], v[192:195], v[52:55]
	v_mfma_f32_16x16x32_bf16 v[40:43], v[136:139], v[184:187], v[40:43]
	v_mfma_f32_16x16x32_bf16 v[36:39], v[144:147], v[184:187], v[36:39]
	v_mfma_f32_16x16x32_bf16 v[24:27], v[136:139], v[176:179], v[24:27]
	v_mfma_f32_16x16x32_bf16 v[20:23], v[144:147], v[176:179], v[20:23]
	v_mfma_f32_16x16x32_bf16 v[8:11], v[136:139], v[168:171], v[8:11]
	v_mfma_f32_16x16x32_bf16 v[4:7], v[144:147], v[168:171], v[2:5]
	s_setprio 0
	s_branch .LBB0_1887

.LBB0_1996:
	ds_read_b128 v[156:159], v219
	ds_read_b128 v[160:163], v219 offset:1024
	ds_read_b128 v[164:167], v219 offset:2048
	ds_read_b128 v[168:171], v219 offset:3072
	s_mov_b64 s[14:15], s[4:5]
	s_add_u32 s4, s14, 0x100
	s_addc_u32 s5, s15, 0
	s_cmp_eq_u32 s47, s50
	s_cselect_b32 s25, s19, s5
	s_cselect_b32 s24, s18, s4
	s_cselect_b32 s23, s21, s49
	s_cselect_b32 s22, s20, s48
	s_add_i32 m0, s29, 0xc000
	s_waitcnt lgkmcnt(0)
	ds_read_b128 v[104:107], v220
	ds_read_b128 v[172:175], v220 offset:1024
	ds_read_b128 v[176:179], v220 offset:2048
	ds_read_b128 v[180:183], v220 offset:3072
	ds_read_b128 v[184:187], v220 offset:4096
	ds_read_b128 v[188:191], v220 offset:5120
	ds_read_b128 v[192:195], v220 offset:6144
	ds_read_b128 v[212:215], v220 offset:7168
	global_load_lds_dwordx4 v204, s[14:15]
	s_add_i32 m0, s29, 0xe000
	s_nop 0
	global_load_lds_dwordx4 v206, s[14:15]
	s_waitcnt lgkmcnt(8)
	s_barrier
	s_waitcnt lgkmcnt(0)
	s_setprio 1
	s_waitcnt lgkmcnt(0)
	v_mfma_f32_16x16x32_bf16 v[100:103], v[156:159], v[104:107], v[152:155]
	v_mfma_f32_16x16x32_bf16 v[124:127], v[160:163], v[172:175], v[100:103]
	v_mfma_f32_16x16x32_bf16 v[100:103], v[164:167], v[104:107], v[148:151]
	v_mfma_f32_16x16x32_bf16 v[128:131], v[168:171], v[172:175], v[100:103]
	v_mfma_f32_16x16x32_bf16 v[100:103], v[156:159], v[176:179], v[120:123]
	v_mfma_f32_16x16x32_bf16 v[120:123], v[160:163], v[180:183], v[100:103]
	v_mfma_f32_16x16x32_bf16 v[100:103], v[164:167], v[176:179], v[116:119]
	v_mfma_f32_16x16x32_bf16 v[96:99], v[156:159], v[184:187], v[96:99]
	v_mfma_f32_16x16x32_bf16 v[92:95], v[164:167], v[184:187], v[92:95]
	v_mfma_f32_16x16x32_bf16 v[80:83], v[156:159], v[192:195], v[80:83]
	v_mfma_f32_16x16x32_bf16 v[76:79], v[164:167], v[192:195], v[76:79]
	v_mfma_f32_16x16x32_bf16 v[116:119], v[168:171], v[180:183], v[100:103]
	v_mfma_f32_16x16x32_bf16 v[96:99], v[160:163], v[188:191], v[96:99]
	v_mfma_f32_16x16x32_bf16 v[92:95], v[168:171], v[188:191], v[92:95]
	v_mfma_f32_16x16x32_bf16 v[80:83], v[160:163], v[212:215], v[80:83]
	v_mfma_f32_16x16x32_bf16 v[76:79], v[168:171], v[212:215], v[76:79]
	s_setprio 0
	s_barrier
	s_add_i32 s14, s55, s28
	v_lshl_add_u64 v[2:3], s[22:23], 0, v[198:199]
	s_mov_b32 m0, s14
	ds_read_b128 v[140:143], v222
	ds_read_b128 v[144:147], v222 offset:1024
	ds_read_b128 v[148:151], v222 offset:2048
	ds_read_b128 v[152:155], v222 offset:3072
	global_load_lds_dwordx4 v198, s[22:23]
	v_lshl_add_u64 v[210:211], s[22:23], 0, v[202:203]
	s_add_i32 m0, s14, 0x2000
	s_nop 0
	global_load_lds_dwordx4 v202, s[22:23]
	s_barrier
	s_waitcnt lgkmcnt(0)
	s_setprio 1
	s_waitcnt lgkmcnt(0)
	v_mfma_f32_16x16x32_bf16 v[100:103], v[140:143], v[104:107], v[136:139]
	v_mfma_f32_16x16x32_bf16 v[104:107], v[148:151], v[104:107], v[132:135]
	v_mfma_f32_16x16x32_bf16 v[112:115], v[140:143], v[176:179], v[112:115]
	v_mfma_f32_16x16x32_bf16 v[108:111], v[148:151], v[176:179], v[108:111]
	v_mfma_f32_16x16x32_bf16 v[88:91], v[140:143], v[184:187], v[88:91]
	v_mfma_f32_16x16x32_bf16 v[84:87], v[148:151], v[184:187], v[84:87]
	v_mfma_f32_16x16x32_bf16 v[72:75], v[140:143], v[192:195], v[72:75]
	v_mfma_f32_16x16x32_bf16 v[68:71], v[148:151], v[192:195], v[68:71]
	v_mfma_f32_16x16x32_bf16 v[100:103], v[144:147], v[172:175], v[100:103]
	v_mfma_f32_16x16x32_bf16 v[104:107], v[152:155], v[172:175], v[104:107]
	v_mfma_f32_16x16x32_bf16 v[112:115], v[144:147], v[180:183], v[112:115]
	v_mfma_f32_16x16x32_bf16 v[108:111], v[152:155], v[180:183], v[108:111]
	v_mfma_f32_16x16x32_bf16 v[88:91], v[144:147], v[188:191], v[88:91]
	v_mfma_f32_16x16x32_bf16 v[84:87], v[152:155], v[188:191], v[84:87]
	v_mfma_f32_16x16x32_bf16 v[72:75], v[144:147], v[212:215], v[72:75]
	v_mfma_f32_16x16x32_bf16 v[68:71], v[152:155], v[212:215], v[68:71]
	s_setprio 0
	s_mov_b32 m0, s29
	v_lshl_add_u64 v[212:213], s[24:25], 0, v[196:197]
	s_barrier
	ds_read_b128 v[188:191], v220 offset:16384
	ds_read_b128 v[192:195], v220 offset:17408
	ds_read_b128 v[180:183], v220 offset:18432
	ds_read_b128 v[184:187], v220 offset:19456
	ds_read_b128 v[172:175], v220 offset:20480
	ds_read_b128 v[176:179], v220 offset:21504
	ds_read_b128 v[132:135], v220 offset:22528
	ds_read_b128 v[136:139], v220 offset:23552
	global_load_lds_dwordx4 v196, s[24:25]
	v_lshl_add_u64 v[214:215], s[24:25], 0, v[200:201]
	s_mov_b32 m0, s30
	v_cmp_ne_u32_e64 s[14:15], 1, v224
	global_load_lds_dwordx4 v200, s[24:25]
	s_barrier
	s_waitcnt lgkmcnt(0)
	s_andn2_b64 vcc, exec, s[16:17]
	s_cbranch_vccnz .LBB0_1998
	s_setprio 1
	s_waitcnt lgkmcnt(0)
	v_mfma_f32_16x16x32_bf16 v[64:67], v[156:159], v[188:191], v[64:67]
	v_mfma_f32_16x16x32_bf16 v[60:63], v[164:167], v[188:191], v[60:63]
	v_mfma_f32_16x16x32_bf16 v[48:51], v[156:159], v[180:183], v[48:51]
	v_mfma_f32_16x16x32_bf16 v[44:47], v[164:167], v[180:183], v[44:47]
	v_mfma_f32_16x16x32_bf16 v[32:35], v[156:159], v[172:175], v[32:35]
	v_mfma_f32_16x16x32_bf16 v[28:31], v[164:167], v[172:175], v[28:31]
	v_mfma_f32_16x16x32_bf16 v[16:19], v[156:159], v[132:135], v[16:19]
	v_mfma_f32_16x16x32_bf16 v[12:15], v[164:167], v[132:135], v[12:15]
	v_mfma_f32_16x16x32_bf16 v[64:67], v[160:163], v[192:195], v[64:67]
	v_mfma_f32_16x16x32_bf16 v[60:63], v[168:171], v[192:195], v[60:63]
	v_mfma_f32_16x16x32_bf16 v[48:51], v[160:163], v[184:187], v[48:51]
	v_mfma_f32_16x16x32_bf16 v[44:47], v[168:171], v[184:187], v[44:47]
	v_mfma_f32_16x16x32_bf16 v[32:35], v[160:163], v[176:179], v[32:35]
	v_mfma_f32_16x16x32_bf16 v[28:31], v[168:171], v[176:179], v[28:31]
	v_mfma_f32_16x16x32_bf16 v[16:19], v[160:163], v[136:139], v[16:19]
	v_mfma_f32_16x16x32_bf16 v[12:15], v[168:171], v[136:139], v[12:15]
	s_setprio 0
.LBB0_1998:
	s_barrier
	s_add_u32 s64, s22, 0x18000
	s_addc_u32 s65, s23, 0
	s_mov_b32 m0, s31
	s_nop 0
	global_load_lds_dwordx4 v198, s[64:65]
	s_mov_b32 m0, s34
	s_and_b64 vcc, exec, s[14:15]
	global_load_lds_dwordx4 v202, s[64:65]
	s_waitcnt vmcnt(6)
	s_barrier
	s_cbranch_vccnz .LBB0_2000
	s_setprio 1
	s_waitcnt lgkmcnt(0)
	v_mfma_f32_16x16x32_bf16 v[56:59], v[140:143], v[188:191], v[56:59]
	v_mfma_f32_16x16x32_bf16 v[52:55], v[148:151], v[188:191], v[52:55]
	v_mfma_f32_16x16x32_bf16 v[40:43], v[140:143], v[180:183], v[40:43]
	v_mfma_f32_16x16x32_bf16 v[36:39], v[148:151], v[180:183], v[36:39]
	v_mfma_f32_16x16x32_bf16 v[24:27], v[140:143], v[172:175], v[24:27]
	v_mfma_f32_16x16x32_bf16 v[20:23], v[148:151], v[172:175], v[20:23]
	v_mfma_f32_16x16x32_bf16 v[8:11], v[140:143], v[132:135], v[8:11]
	v_mfma_f32_16x16x32_bf16 v[4:7], v[148:151], v[132:135], v[4:7]
	v_mfma_f32_16x16x32_bf16 v[56:59], v[144:147], v[192:195], v[56:59]
	v_mfma_f32_16x16x32_bf16 v[52:55], v[152:155], v[192:195], v[52:55]
	v_mfma_f32_16x16x32_bf16 v[40:43], v[144:147], v[184:187], v[40:43]
	v_mfma_f32_16x16x32_bf16 v[36:39], v[152:155], v[184:187], v[36:39]
	v_mfma_f32_16x16x32_bf16 v[24:27], v[144:147], v[176:179], v[24:27]
	v_mfma_f32_16x16x32_bf16 v[20:23], v[152:155], v[176:179], v[20:23]
	v_mfma_f32_16x16x32_bf16 v[8:11], v[144:147], v[136:139], v[8:11]
	v_mfma_f32_16x16x32_bf16 v[4:7], v[152:155], v[136:139], v[4:7]
	s_setprio 0
.LBB0_2000:
	s_add_i32 s51, 0, 0x18000
	v_add_u32_e32 v1, s51, v217
	s_barrier
	ds_read_b128 v[156:159], v1
	ds_read_b128 v[160:163], v1 offset:1024
	ds_read_b128 v[164:167], v1 offset:2048
	ds_read_b128 v[168:171], v1 offset:3072
	s_add_u32 s24, s24, 0x18000
	s_addc_u32 s25, s25, 0
	s_mov_b32 m0, s35
	s_waitcnt lgkmcnt(0)
	ds_read_b128 v[132:135], v220 offset:32768
	ds_read_b128 v[172:175], v220 offset:33792
	ds_read_b128 v[176:179], v220 offset:34816
	ds_read_b128 v[180:183], v220 offset:35840
	ds_read_b128 v[184:187], v220 offset:36864
	ds_read_b128 v[188:191], v220 offset:37888
	ds_read_b128 v[192:195], v220 offset:38912
	ds_read_b128 v[226:229], v220 offset:39936
	global_load_lds_dwordx4 v196, s[24:25]
	s_mov_b32 m0, s36
	s_nop 0
	global_load_lds_dwordx4 v200, s[24:25]
	s_waitcnt lgkmcnt(8)
	s_barrier
	s_waitcnt lgkmcnt(0)
	s_setprio 1
	s_waitcnt lgkmcnt(0)
	v_mfma_f32_16x16x32_bf16 v[124:127], v[156:159], v[132:135], v[124:127]
	v_mfma_f32_16x16x32_bf16 v[152:155], v[160:163], v[172:175], v[124:127]
	v_mfma_f32_16x16x32_bf16 v[124:127], v[164:167], v[132:135], v[128:131]
	v_mfma_f32_16x16x32_bf16 v[120:123], v[156:159], v[176:179], v[120:123]
	v_mfma_f32_16x16x32_bf16 v[116:119], v[164:167], v[176:179], v[116:119]
	v_mfma_f32_16x16x32_bf16 v[96:99], v[156:159], v[184:187], v[96:99]
	v_mfma_f32_16x16x32_bf16 v[92:95], v[164:167], v[184:187], v[92:95]
	v_mfma_f32_16x16x32_bf16 v[80:83], v[156:159], v[192:195], v[80:83]
	v_mfma_f32_16x16x32_bf16 v[76:79], v[164:167], v[192:195], v[76:79]
	v_mfma_f32_16x16x32_bf16 v[148:151], v[168:171], v[172:175], v[124:127]
	v_mfma_f32_16x16x32_bf16 v[120:123], v[160:163], v[180:183], v[120:123]
	v_mfma_f32_16x16x32_bf16 v[116:119], v[168:171], v[180:183], v[116:119]
	v_mfma_f32_16x16x32_bf16 v[96:99], v[160:163], v[188:191], v[96:99]
	v_mfma_f32_16x16x32_bf16 v[92:95], v[168:171], v[188:191], v[92:95]
	v_mfma_f32_16x16x32_bf16 v[80:83], v[160:163], v[226:229], v[80:83]
	v_mfma_f32_16x16x32_bf16 v[76:79], v[168:171], v[226:229], v[76:79]
	s_setprio 0
	s_barrier
	s_add_i32 s24, s51, s28
	v_add_u32_e32 v1, 0x1c000, v221
	v_lshl_add_u64 v[2:3], v[2:3], 0, s[6:7]
	s_mov_b32 m0, s24
	ds_read_b128 v[124:127], v1
	ds_read_b128 v[128:131], v1 offset:1024
	ds_read_b128 v[140:143], v1 offset:2048
	ds_read_b128 v[144:147], v1 offset:3072
	global_load_lds_dwordx4 v[2:3], off
	v_lshl_add_u64 v[2:3], v[210:211], 0, s[6:7]
	s_add_i32 m0, s24, 0x2000
	s_nop 0
	global_load_lds_dwordx4 v[2:3], off
	s_barrier
	s_waitcnt lgkmcnt(0)
	s_setprio 1
	s_waitcnt lgkmcnt(0)
	v_mfma_f32_16x16x32_bf16 v[100:103], v[124:127], v[132:135], v[100:103]
	v_mfma_f32_16x16x32_bf16 v[136:139], v[128:131], v[172:175], v[100:103]
	v_mfma_f32_16x16x32_bf16 v[100:103], v[140:143], v[132:135], v[104:107]
	v_mfma_f32_16x16x32_bf16 v[132:135], v[144:147], v[172:175], v[100:103]
	v_mfma_f32_16x16x32_bf16 v[100:103], v[124:127], v[176:179], v[112:115]
	v_mfma_f32_16x16x32_bf16 v[112:115], v[128:131], v[180:183], v[100:103]
	v_mfma_f32_16x16x32_bf16 v[100:103], v[140:143], v[176:179], v[108:111]
	v_mfma_f32_16x16x32_bf16 v[88:91], v[124:127], v[184:187], v[88:91]
	v_mfma_f32_16x16x32_bf16 v[84:87], v[140:143], v[184:187], v[84:87]
	v_mfma_f32_16x16x32_bf16 v[72:75], v[124:127], v[192:195], v[72:75]
	v_mfma_f32_16x16x32_bf16 v[68:71], v[140:143], v[192:195], v[68:71]
	v_mfma_f32_16x16x32_bf16 v[108:111], v[144:147], v[180:183], v[100:103]
	v_mfma_f32_16x16x32_bf16 v[88:91], v[128:131], v[188:191], v[88:91]
	v_mfma_f32_16x16x32_bf16 v[84:87], v[144:147], v[188:191], v[84:87]
	v_mfma_f32_16x16x32_bf16 v[72:75], v[128:131], v[226:229], v[72:75]
	v_mfma_f32_16x16x32_bf16 v[68:71], v[144:147], v[226:229], v[68:71]
	s_setprio 0
	s_mov_b32 m0, s39
	v_lshl_add_u64 v[2:3], v[212:213], 0, s[6:7]
	s_barrier
	ds_read_b128 v[188:191], v220 offset:49152
	ds_read_b128 v[192:195], v220 offset:50176
	ds_read_b128 v[180:183], v220 offset:51200
	ds_read_b128 v[184:187], v220 offset:52224
	ds_read_b128 v[172:175], v220 offset:53248
	ds_read_b128 v[176:179], v220 offset:54272
	ds_read_b128 v[100:103], v220 offset:55296
	ds_read_b128 v[104:107], v220 offset:56320
	global_load_lds_dwordx4 v[2:3], off
	v_lshl_add_u64 v[2:3], v[214:215], 0, s[6:7]
	s_mov_b32 m0, s40
	s_and_b64 vcc, exec, s[14:15]
	global_load_lds_dwordx4 v[2:3], off
	s_barrier
	s_waitcnt lgkmcnt(0)
	s_cbranch_vccnz .LBB0_2002
	s_setprio 1
	s_waitcnt lgkmcnt(0)
	v_mfma_f32_16x16x32_bf16 v[64:67], v[156:159], v[188:191], v[64:67]
	v_mfma_f32_16x16x32_bf16 v[60:63], v[164:167], v[188:191], v[60:63]
	v_mfma_f32_16x16x32_bf16 v[48:51], v[156:159], v[180:183], v[48:51]
	v_mfma_f32_16x16x32_bf16 v[44:47], v[164:167], v[180:183], v[44:47]
	v_mfma_f32_16x16x32_bf16 v[32:35], v[156:159], v[172:175], v[32:35]
	v_mfma_f32_16x16x32_bf16 v[28:31], v[164:167], v[172:175], v[28:31]
	v_mfma_f32_16x16x32_bf16 v[16:19], v[156:159], v[100:103], v[16:19]
	v_mfma_f32_16x16x32_bf16 v[12:15], v[164:167], v[100:103], v[12:15]
	v_mfma_f32_16x16x32_bf16 v[64:67], v[160:163], v[192:195], v[64:67]
	v_mfma_f32_16x16x32_bf16 v[60:63], v[168:171], v[192:195], v[60:63]
	v_mfma_f32_16x16x32_bf16 v[48:51], v[160:163], v[184:187], v[48:51]
	v_mfma_f32_16x16x32_bf16 v[44:47], v[168:171], v[184:187], v[44:47]
	v_mfma_f32_16x16x32_bf16 v[32:35], v[160:163], v[176:179], v[32:35]
	v_mfma_f32_16x16x32_bf16 v[28:31], v[168:171], v[176:179], v[28:31]
	v_mfma_f32_16x16x32_bf16 v[16:19], v[160:163], v[104:107], v[16:19]
	v_mfma_f32_16x16x32_bf16 v[12:15], v[168:171], v[104:107], v[12:15]
	s_setprio 0
.LBB0_2002:
	s_barrier
	s_add_u32 s22, s22, 0x18080
	s_addc_u32 s23, s23, 0
	s_mov_b32 m0, s41
	s_nop 0
	global_load_lds_dwordx4 v198, s[22:23]
	s_mov_b32 m0, s42
	s_and_b64 vcc, exec, s[14:15]
	global_load_lds_dwordx4 v202, s[22:23]
	s_waitcnt vmcnt(6)
	s_barrier
	s_cbranch_vccnz .LBB0_1995
	s_setprio 1
	s_waitcnt lgkmcnt(0)
	v_mfma_f32_16x16x32_bf16 v[56:59], v[124:127], v[188:191], v[56:59]
	v_mfma_f32_16x16x32_bf16 v[52:55], v[140:143], v[188:191], v[52:55]
	v_mfma_f32_16x16x32_bf16 v[40:43], v[124:127], v[180:183], v[40:43]
	v_mfma_f32_16x16x32_bf16 v[36:39], v[140:143], v[180:183], v[36:39]
	v_mfma_f32_16x16x32_bf16 v[24:27], v[124:127], v[172:175], v[24:27]
	v_mfma_f32_16x16x32_bf16 v[20:23], v[140:143], v[172:175], v[20:23]
	v_mfma_f32_16x16x32_bf16 v[8:11], v[124:127], v[100:103], v[8:11]
	v_mfma_f32_16x16x32_bf16 v[2:5], v[140:143], v[100:103], v[4:7]
	v_mfma_f32_16x16x32_bf16 v[56:59], v[128:131], v[192:195], v[56:59]
	v_mfma_f32_16x16x32_bf16 v[52:55], v[144:147], v[192:195], v[52:55]
	v_mfma_f32_16x16x32_bf16 v[40:43], v[128:131], v[184:187], v[40:43]
	v_mfma_f32_16x16x32_bf16 v[36:39], v[144:147], v[184:187], v[36:39]
	v_mfma_f32_16x16x32_bf16 v[24:27], v[128:131], v[176:179], v[24:27]
	v_mfma_f32_16x16x32_bf16 v[20:23], v[144:147], v[176:179], v[20:23]
	v_mfma_f32_16x16x32_bf16 v[8:11], v[128:131], v[104:107], v[8:11]
	v_mfma_f32_16x16x32_bf16 v[4:7], v[144:147], v[104:107], v[2:5]
	s_setprio 0
	s_branch .LBB0_1995

.LBB0_2191:
	ds_read_b128 v[148:151], v222
	ds_read_b128 v[152:155], v222 offset:1024
	ds_read_b128 v[156:159], v222 offset:2048
	ds_read_b128 v[160:163], v222 offset:3072
	s_mov_b64 s[12:13], s[24:25]
	s_add_u32 s24, s12, 0x100
	s_addc_u32 s25, s13, 0
	s_cmp_eq_u32 s57, s60
	s_cselect_b32 s31, s21, s25
	s_cselect_b32 s30, s20, s24
	s_cselect_b32 s29, s19, s59
	s_cselect_b32 s28, s56, s58
	s_add_i32 m0, s36, 0xc000
	s_waitcnt lgkmcnt(0)
	ds_read_b128 v[164:167], v223
	ds_read_b128 v[168:171], v223 offset:1024
	ds_read_b128 v[172:175], v223 offset:2048
	ds_read_b128 v[176:179], v223 offset:3072
	ds_read_b128 v[180:183], v223 offset:4096
	ds_read_b128 v[184:187], v223 offset:5120
	ds_read_b128 v[188:191], v223 offset:6144
	ds_read_b128 v[192:195], v223 offset:7168
	global_load_lds_dwordx4 v204, s[12:13]
	s_add_i32 m0, s36, 0xe000
	s_nop 0
	global_load_lds_dwordx4 v206, s[12:13]
	s_waitcnt lgkmcnt(8)
	s_barrier
	s_waitcnt lgkmcnt(0)
	s_setprio 1
	s_waitcnt lgkmcnt(0)
	v_mfma_f32_16x16x32_bf16 v[128:131], v[148:151], v[164:167], v[128:131]
	v_mfma_f32_16x16x32_bf16 v[124:127], v[156:159], v[164:167], v[124:127]
	v_mfma_f32_16x16x32_bf16 v[112:115], v[148:151], v[172:175], v[112:115]
	v_mfma_f32_16x16x32_bf16 v[108:111], v[156:159], v[172:175], v[108:111]
	v_mfma_f32_16x16x32_bf16 v[96:99], v[148:151], v[180:183], v[96:99]
	v_mfma_f32_16x16x32_bf16 v[92:95], v[156:159], v[180:183], v[92:95]
	v_mfma_f32_16x16x32_bf16 v[80:83], v[148:151], v[188:191], v[80:83]
	v_mfma_f32_16x16x32_bf16 v[76:79], v[156:159], v[188:191], v[76:79]
	v_mfma_f32_16x16x32_bf16 v[128:131], v[152:155], v[168:171], v[128:131]
	v_mfma_f32_16x16x32_bf16 v[124:127], v[160:163], v[168:171], v[124:127]
	v_mfma_f32_16x16x32_bf16 v[112:115], v[152:155], v[176:179], v[112:115]
	v_mfma_f32_16x16x32_bf16 v[108:111], v[160:163], v[176:179], v[108:111]
	v_mfma_f32_16x16x32_bf16 v[96:99], v[152:155], v[184:187], v[96:99]
	v_mfma_f32_16x16x32_bf16 v[92:95], v[160:163], v[184:187], v[92:95]
	v_mfma_f32_16x16x32_bf16 v[80:83], v[152:155], v[192:195], v[80:83]
	v_mfma_f32_16x16x32_bf16 v[76:79], v[160:163], v[192:195], v[76:79]
	s_setprio 0
	s_barrier
	s_add_i32 s12, s50, s11
	v_lshl_add_u64 v[2:3], s[28:29], 0, v[198:199]
	s_mov_b32 m0, s12
	ds_read_b128 v[132:135], v225
	ds_read_b128 v[136:139], v225 offset:1024
	ds_read_b128 v[140:143], v225 offset:2048
	ds_read_b128 v[144:147], v225 offset:3072
	global_load_lds_dwordx4 v198, s[28:29]
	v_lshl_add_u64 v[214:215], s[28:29], 0, v[202:203]
	s_add_i32 m0, s12, 0x2000
	s_nop 0
	global_load_lds_dwordx4 v202, s[28:29]
	s_barrier
	s_waitcnt lgkmcnt(0)
	s_setprio 1
	s_waitcnt lgkmcnt(0)
	v_mfma_f32_16x16x32_bf16 v[120:123], v[132:135], v[164:167], v[120:123]
	v_mfma_f32_16x16x32_bf16 v[116:119], v[140:143], v[164:167], v[116:119]
	v_mfma_f32_16x16x32_bf16 v[104:107], v[132:135], v[172:175], v[104:107]
	v_mfma_f32_16x16x32_bf16 v[100:103], v[140:143], v[172:175], v[100:103]
	v_mfma_f32_16x16x32_bf16 v[88:91], v[132:135], v[180:183], v[88:91]
	v_mfma_f32_16x16x32_bf16 v[84:87], v[140:143], v[180:183], v[84:87]
	v_mfma_f32_16x16x32_bf16 v[72:75], v[132:135], v[188:191], v[72:75]
	v_mfma_f32_16x16x32_bf16 v[68:71], v[140:143], v[188:191], v[68:71]
	v_mfma_f32_16x16x32_bf16 v[120:123], v[136:139], v[168:171], v[120:123]
	v_mfma_f32_16x16x32_bf16 v[116:119], v[144:147], v[168:171], v[116:119]
	v_mfma_f32_16x16x32_bf16 v[104:107], v[136:139], v[176:179], v[104:107]
	v_mfma_f32_16x16x32_bf16 v[100:103], v[144:147], v[176:179], v[100:103]
	v_mfma_f32_16x16x32_bf16 v[88:91], v[136:139], v[184:187], v[88:91]
	v_mfma_f32_16x16x32_bf16 v[84:87], v[144:147], v[184:187], v[84:87]
	v_mfma_f32_16x16x32_bf16 v[72:75], v[136:139], v[192:195], v[72:75]
	v_mfma_f32_16x16x32_bf16 v[68:71], v[144:147], v[192:195], v[68:71]
	s_setprio 0
	s_mov_b32 m0, s36
	v_lshl_add_u64 v[216:217], s[30:31], 0, v[196:197]
	s_barrier
	ds_read_b128 v[188:191], v223 offset:16384
	ds_read_b128 v[192:195], v223 offset:17408
	ds_read_b128 v[180:183], v223 offset:18432
	ds_read_b128 v[184:187], v223 offset:19456
	ds_read_b128 v[172:175], v223 offset:20480
	ds_read_b128 v[176:179], v223 offset:21504
	ds_read_b128 v[164:167], v223 offset:22528
	ds_read_b128 v[168:171], v223 offset:23552
	global_load_lds_dwordx4 v196, s[30:31]
	v_lshl_add_u64 v[218:219], s[30:31], 0, v[200:201]
	s_mov_b32 m0, s37
	v_cmp_ne_u32_e64 s[12:13], 1, v213
	global_load_lds_dwordx4 v200, s[30:31]
	s_barrier
	s_waitcnt lgkmcnt(0)
	s_andn2_b64 vcc, exec, s[26:27]
	s_cbranch_vccnz .LBB0_2193
	s_setprio 1
	s_waitcnt lgkmcnt(0)
	v_mfma_f32_16x16x32_bf16 v[64:67], v[148:151], v[188:191], v[64:67]
	v_mfma_f32_16x16x32_bf16 v[60:63], v[156:159], v[188:191], v[60:63]
	v_mfma_f32_16x16x32_bf16 v[48:51], v[148:151], v[180:183], v[48:51]
	v_mfma_f32_16x16x32_bf16 v[44:47], v[156:159], v[180:183], v[44:47]
	v_mfma_f32_16x16x32_bf16 v[32:35], v[148:151], v[172:175], v[32:35]
	v_mfma_f32_16x16x32_bf16 v[28:31], v[156:159], v[172:175], v[28:31]
	v_mfma_f32_16x16x32_bf16 v[16:19], v[148:151], v[164:167], v[16:19]
	v_mfma_f32_16x16x32_bf16 v[12:15], v[156:159], v[164:167], v[12:15]
	v_mfma_f32_16x16x32_bf16 v[64:67], v[152:155], v[192:195], v[64:67]
	v_mfma_f32_16x16x32_bf16 v[60:63], v[160:163], v[192:195], v[60:63]
	v_mfma_f32_16x16x32_bf16 v[48:51], v[152:155], v[184:187], v[48:51]
	v_mfma_f32_16x16x32_bf16 v[44:47], v[160:163], v[184:187], v[44:47]
	v_mfma_f32_16x16x32_bf16 v[32:35], v[152:155], v[176:179], v[32:35]
	v_mfma_f32_16x16x32_bf16 v[28:31], v[160:163], v[176:179], v[28:31]
	v_mfma_f32_16x16x32_bf16 v[16:19], v[152:155], v[168:171], v[16:19]
	v_mfma_f32_16x16x32_bf16 v[12:15], v[160:163], v[168:171], v[12:15]
	s_setprio 0
.LBB0_2193:
	s_barrier
	s_add_u32 s62, s28, 0x10000
	s_addc_u32 s63, s29, 0
	s_mov_b32 m0, s38
	s_nop 0
	global_load_lds_dwordx4 v198, s[62:63]
	s_mov_b32 m0, s39
	s_and_b64 vcc, exec, s[12:13]
	global_load_lds_dwordx4 v202, s[62:63]
	s_waitcnt vmcnt(6)
	s_barrier
	s_cbranch_vccnz .LBB0_2195
	s_setprio 1
	s_waitcnt lgkmcnt(0)
	v_mfma_f32_16x16x32_bf16 v[56:59], v[132:135], v[188:191], v[56:59]
	v_mfma_f32_16x16x32_bf16 v[52:55], v[140:143], v[188:191], v[52:55]
	v_mfma_f32_16x16x32_bf16 v[40:43], v[132:135], v[180:183], v[40:43]
	v_mfma_f32_16x16x32_bf16 v[36:39], v[140:143], v[180:183], v[36:39]
	v_mfma_f32_16x16x32_bf16 v[24:27], v[132:135], v[172:175], v[24:27]
	v_mfma_f32_16x16x32_bf16 v[20:23], v[140:143], v[172:175], v[20:23]
	v_mfma_f32_16x16x32_bf16 v[8:11], v[132:135], v[164:167], v[8:11]
	v_mfma_f32_16x16x32_bf16 v[4:7], v[140:143], v[164:167], v[4:7]
	v_mfma_f32_16x16x32_bf16 v[56:59], v[136:139], v[192:195], v[56:59]
	v_mfma_f32_16x16x32_bf16 v[52:55], v[144:147], v[192:195], v[52:55]
	v_mfma_f32_16x16x32_bf16 v[40:43], v[136:139], v[184:187], v[40:43]
	v_mfma_f32_16x16x32_bf16 v[36:39], v[144:147], v[184:187], v[36:39]
	v_mfma_f32_16x16x32_bf16 v[24:27], v[136:139], v[176:179], v[24:27]
	v_mfma_f32_16x16x32_bf16 v[20:23], v[144:147], v[176:179], v[20:23]
	v_mfma_f32_16x16x32_bf16 v[8:11], v[136:139], v[168:171], v[8:11]
	v_mfma_f32_16x16x32_bf16 v[4:7], v[144:147], v[168:171], v[4:7]
	s_setprio 0
.LBB0_2195:
	s_add_i32 s61, 0, 0x18000
	v_add_u32_e32 v0, s61, v221
	s_barrier
	ds_read_b128 v[148:151], v0
	ds_read_b128 v[152:155], v0 offset:1024
	ds_read_b128 v[156:159], v0 offset:2048
	ds_read_b128 v[160:163], v0 offset:3072
	s_add_u32 s30, s30, 0x14000
	s_addc_u32 s31, s31, 0
	s_mov_b32 m0, s40
	s_waitcnt lgkmcnt(0)
	ds_read_b128 v[164:167], v223 offset:32768
	ds_read_b128 v[168:171], v223 offset:33792
	ds_read_b128 v[172:175], v223 offset:34816
	ds_read_b128 v[176:179], v223 offset:35840
	ds_read_b128 v[180:183], v223 offset:36864
	ds_read_b128 v[184:187], v223 offset:37888
	ds_read_b128 v[188:191], v223 offset:38912
	ds_read_b128 v[192:195], v223 offset:39936
	global_load_lds_dwordx4 v196, s[30:31]
	s_mov_b32 m0, s41
	s_nop 0
	global_load_lds_dwordx4 v200, s[30:31]
	s_waitcnt lgkmcnt(8)
	s_barrier
	s_waitcnt lgkmcnt(0)
	s_setprio 1
	s_waitcnt lgkmcnt(0)
	v_mfma_f32_16x16x32_bf16 v[128:131], v[148:151], v[164:167], v[128:131]
	v_mfma_f32_16x16x32_bf16 v[124:127], v[156:159], v[164:167], v[124:127]
	v_mfma_f32_16x16x32_bf16 v[112:115], v[148:151], v[172:175], v[112:115]
	v_mfma_f32_16x16x32_bf16 v[108:111], v[156:159], v[172:175], v[108:111]
	v_mfma_f32_16x16x32_bf16 v[96:99], v[148:151], v[180:183], v[96:99]
	v_mfma_f32_16x16x32_bf16 v[92:95], v[156:159], v[180:183], v[92:95]
	v_mfma_f32_16x16x32_bf16 v[80:83], v[148:151], v[188:191], v[80:83]
	v_mfma_f32_16x16x32_bf16 v[76:79], v[156:159], v[188:191], v[76:79]
	v_mfma_f32_16x16x32_bf16 v[128:131], v[152:155], v[168:171], v[128:131]
	v_mfma_f32_16x16x32_bf16 v[124:127], v[160:163], v[168:171], v[124:127]
	v_mfma_f32_16x16x32_bf16 v[112:115], v[152:155], v[176:179], v[112:115]
	v_mfma_f32_16x16x32_bf16 v[108:111], v[160:163], v[176:179], v[108:111]
	v_mfma_f32_16x16x32_bf16 v[96:99], v[152:155], v[184:187], v[96:99]
	v_mfma_f32_16x16x32_bf16 v[92:95], v[160:163], v[184:187], v[92:95]
	v_mfma_f32_16x16x32_bf16 v[80:83], v[152:155], v[192:195], v[80:83]
	v_mfma_f32_16x16x32_bf16 v[76:79], v[160:163], v[192:195], v[76:79]
	s_setprio 0
	s_barrier
	s_add_i32 s30, s61, s11
	v_add_u32_e32 v0, 0x1c000, v224
	v_lshl_add_u64 v[2:3], v[2:3], 0, s[16:17]
	s_mov_b32 m0, s30
	ds_read_b128 v[132:135], v0
	ds_read_b128 v[136:139], v0 offset:1024
	ds_read_b128 v[140:143], v0 offset:2048
	ds_read_b128 v[144:147], v0 offset:3072
	global_load_lds_dwordx4 v[2:3], off
	v_lshl_add_u64 v[2:3], v[214:215], 0, s[16:17]
	s_add_i32 m0, s30, 0x2000
	s_nop 0
	global_load_lds_dwordx4 v[2:3], off
	s_barrier
	s_waitcnt lgkmcnt(0)
	s_setprio 1
	s_waitcnt lgkmcnt(0)
	v_mfma_f32_16x16x32_bf16 v[120:123], v[132:135], v[164:167], v[120:123]
	v_mfma_f32_16x16x32_bf16 v[116:119], v[140:143], v[164:167], v[116:119]
	v_mfma_f32_16x16x32_bf16 v[104:107], v[132:135], v[172:175], v[104:107]
	v_mfma_f32_16x16x32_bf16 v[100:103], v[140:143], v[172:175], v[100:103]
	v_mfma_f32_16x16x32_bf16 v[88:91], v[132:135], v[180:183], v[88:91]
	v_mfma_f32_16x16x32_bf16 v[84:87], v[140:143], v[180:183], v[84:87]
	v_mfma_f32_16x16x32_bf16 v[72:75], v[132:135], v[188:191], v[72:75]
	v_mfma_f32_16x16x32_bf16 v[68:71], v[140:143], v[188:191], v[68:71]
	v_mfma_f32_16x16x32_bf16 v[120:123], v[136:139], v[168:171], v[120:123]
	v_mfma_f32_16x16x32_bf16 v[116:119], v[144:147], v[168:171], v[116:119]
	v_mfma_f32_16x16x32_bf16 v[104:107], v[136:139], v[176:179], v[104:107]
	v_mfma_f32_16x16x32_bf16 v[100:103], v[144:147], v[176:179], v[100:103]
	v_mfma_f32_16x16x32_bf16 v[88:91], v[136:139], v[184:187], v[88:91]
	v_mfma_f32_16x16x32_bf16 v[84:87], v[144:147], v[184:187], v[84:87]
	v_mfma_f32_16x16x32_bf16 v[72:75], v[136:139], v[192:195], v[72:75]
	v_mfma_f32_16x16x32_bf16 v[68:71], v[144:147], v[192:195], v[68:71]
	s_setprio 0
	s_mov_b32 m0, s43
	v_lshl_add_u64 v[2:3], v[216:217], 0, s[16:17]
	s_barrier
	ds_read_b128 v[188:191], v223 offset:49152
	ds_read_b128 v[192:195], v223 offset:50176
	ds_read_b128 v[180:183], v223 offset:51200
	ds_read_b128 v[184:187], v223 offset:52224
	ds_read_b128 v[172:175], v223 offset:53248
	ds_read_b128 v[176:179], v223 offset:54272
	ds_read_b128 v[164:167], v223 offset:55296
	ds_read_b128 v[168:171], v223 offset:56320
	global_load_lds_dwordx4 v[2:3], off
	v_lshl_add_u64 v[2:3], v[218:219], 0, s[16:17]
	s_mov_b32 m0, s46
	s_and_b64 vcc, exec, s[12:13]
	global_load_lds_dwordx4 v[2:3], off
	s_barrier
	s_waitcnt lgkmcnt(0)
	s_cbranch_vccnz .LBB0_2197
	s_setprio 1
	s_waitcnt lgkmcnt(0)
	v_mfma_f32_16x16x32_bf16 v[64:67], v[148:151], v[188:191], v[64:67]
	v_mfma_f32_16x16x32_bf16 v[60:63], v[156:159], v[188:191], v[60:63]
	v_mfma_f32_16x16x32_bf16 v[48:51], v[148:151], v[180:183], v[48:51]
	v_mfma_f32_16x16x32_bf16 v[44:47], v[156:159], v[180:183], v[44:47]
	v_mfma_f32_16x16x32_bf16 v[32:35], v[148:151], v[172:175], v[32:35]
	v_mfma_f32_16x16x32_bf16 v[28:31], v[156:159], v[172:175], v[28:31]
	v_mfma_f32_16x16x32_bf16 v[16:19], v[148:151], v[164:167], v[16:19]
	v_mfma_f32_16x16x32_bf16 v[12:15], v[156:159], v[164:167], v[12:15]
	v_mfma_f32_16x16x32_bf16 v[64:67], v[152:155], v[192:195], v[64:67]
	v_mfma_f32_16x16x32_bf16 v[60:63], v[160:163], v[192:195], v[60:63]
	v_mfma_f32_16x16x32_bf16 v[48:51], v[152:155], v[184:187], v[48:51]
	v_mfma_f32_16x16x32_bf16 v[44:47], v[160:163], v[184:187], v[44:47]
	v_mfma_f32_16x16x32_bf16 v[32:35], v[152:155], v[176:179], v[32:35]
	v_mfma_f32_16x16x32_bf16 v[28:31], v[160:163], v[176:179], v[28:31]
	v_mfma_f32_16x16x32_bf16 v[16:19], v[152:155], v[168:171], v[16:19]
	v_mfma_f32_16x16x32_bf16 v[12:15], v[160:163], v[168:171], v[12:15]
	s_setprio 0
.LBB0_2197:
	s_barrier
	s_add_u32 s28, s28, 0x10080
	s_addc_u32 s29, s29, 0
	s_mov_b32 m0, s47
	s_nop 0
	global_load_lds_dwordx4 v198, s[28:29]
	s_mov_b32 m0, s48
	s_and_b64 vcc, exec, s[12:13]
	global_load_lds_dwordx4 v202, s[28:29]
	s_waitcnt vmcnt(6)
	s_barrier
	s_cbranch_vccnz .LBB0_2190
	s_setprio 1
	s_waitcnt lgkmcnt(0)
	v_mfma_f32_16x16x32_bf16 v[56:59], v[132:135], v[188:191], v[56:59]
	v_mfma_f32_16x16x32_bf16 v[52:55], v[140:143], v[188:191], v[52:55]
	v_mfma_f32_16x16x32_bf16 v[40:43], v[132:135], v[180:183], v[40:43]
	v_mfma_f32_16x16x32_bf16 v[36:39], v[140:143], v[180:183], v[36:39]
	v_mfma_f32_16x16x32_bf16 v[24:27], v[132:135], v[172:175], v[24:27]
	v_mfma_f32_16x16x32_bf16 v[20:23], v[140:143], v[172:175], v[20:23]
	v_mfma_f32_16x16x32_bf16 v[8:11], v[132:135], v[164:167], v[8:11]
	v_mfma_f32_16x16x32_bf16 v[2:5], v[140:143], v[164:167], v[4:7]
	v_mfma_f32_16x16x32_bf16 v[56:59], v[136:139], v[192:195], v[56:59]
	v_mfma_f32_16x16x32_bf16 v[52:55], v[144:147], v[192:195], v[52:55]
	v_mfma_f32_16x16x32_bf16 v[40:43], v[136:139], v[184:187], v[40:43]
	v_mfma_f32_16x16x32_bf16 v[36:39], v[144:147], v[184:187], v[36:39]
	v_mfma_f32_16x16x32_bf16 v[24:27], v[136:139], v[176:179], v[24:27]
	v_mfma_f32_16x16x32_bf16 v[20:23], v[144:147], v[176:179], v[20:23]
	v_mfma_f32_16x16x32_bf16 v[8:11], v[136:139], v[168:171], v[8:11]
	v_mfma_f32_16x16x32_bf16 v[4:7], v[144:147], v[168:171], v[2:5]
	s_setprio 0
	s_branch .LBB0_2190

.LBB0_2717:
	ds_read_b128 v[148:151], v205
	ds_read_b128 v[152:155], v205 offset:1024
	ds_read_b128 v[156:159], v205 offset:2048
	ds_read_b128 v[160:163], v205 offset:3072
	s_add_u32 s12, s34, 0xfff80080
	s_addc_u32 s13, s35, -1
	s_cmp_eq_u32 s23, s48
	s_cselect_b32 s39, s2, s13
	s_cselect_b32 s38, s5, s12
	s_cselect_b32 s37, s19, s47
	s_cselect_b32 s36, s21, s46
	s_add_i32 m0, s7, 0xc000
	s_waitcnt lgkmcnt(0)
	ds_read_b128 v[164:167], v230
	ds_read_b128 v[168:171], v230 offset:1024
	ds_read_b128 v[172:175], v230 offset:2048
	ds_read_b128 v[176:179], v230 offset:3072
	ds_read_b128 v[180:183], v230 offset:4096
	ds_read_b128 v[184:187], v230 offset:5120
	ds_read_b128 v[188:191], v230 offset:6144
	ds_read_b128 v[192:195], v230 offset:7168
	global_load_lds_dwordx4 v214, s[34:35]
	s_add_i32 m0, s7, 0xe000
	s_nop 0
	global_load_lds_dwordx4 v216, s[34:35]
	s_waitcnt lgkmcnt(8)
	s_barrier
	s_waitcnt lgkmcnt(0)
	s_setprio 1
	s_waitcnt lgkmcnt(0)
	v_mfma_f32_16x16x32_bf16 v[84:87], v[148:151], v[164:167], v[84:87]
	v_mfma_f32_16x16x32_bf16 v[76:79], v[156:159], v[164:167], v[76:79]
	v_mfma_f32_16x16x32_bf16 v[64:67], v[148:151], v[172:175], v[64:67]
	v_mfma_f32_16x16x32_bf16 v[60:63], v[156:159], v[172:175], v[60:63]
	v_mfma_f32_16x16x32_bf16 v[48:51], v[148:151], v[180:183], v[48:51]
	v_mfma_f32_16x16x32_bf16 v[44:47], v[156:159], v[180:183], v[44:47]
	v_mfma_f32_16x16x32_bf16 v[32:35], v[148:151], v[188:191], v[32:35]
	v_mfma_f32_16x16x32_bf16 v[24:27], v[156:159], v[188:191], v[24:27]
	v_mfma_f32_16x16x32_bf16 v[84:87], v[152:155], v[168:171], v[84:87]
	v_mfma_f32_16x16x32_bf16 v[76:79], v[160:163], v[168:171], v[76:79]
	v_mfma_f32_16x16x32_bf16 v[64:67], v[152:155], v[176:179], v[64:67]
	v_mfma_f32_16x16x32_bf16 v[60:63], v[160:163], v[176:179], v[60:63]
	v_mfma_f32_16x16x32_bf16 v[48:51], v[152:155], v[184:187], v[48:51]
	v_mfma_f32_16x16x32_bf16 v[44:47], v[160:163], v[184:187], v[44:47]
	v_mfma_f32_16x16x32_bf16 v[32:35], v[152:155], v[192:195], v[32:35]
	v_mfma_f32_16x16x32_bf16 v[24:27], v[160:163], v[192:195], v[24:27]
	s_setprio 0
	s_barrier
	s_add_i32 s12, s63, s40
	v_lshl_add_u64 v[2:3], s[36:37], 0, v[198:199]
	s_mov_b32 m0, s12
	ds_read_b128 v[132:135], v232
	ds_read_b128 v[136:139], v232 offset:1024
	ds_read_b128 v[140:143], v232 offset:2048
	ds_read_b128 v[144:147], v232 offset:3072
	global_load_lds_dwordx4 v198, s[36:37]
	v_lshl_add_u64 v[220:221], s[36:37], 0, v[202:203]
	s_add_i32 m0, s12, 0x2000
	s_nop 0
	global_load_lds_dwordx4 v202, s[36:37]
	s_barrier
	s_waitcnt lgkmcnt(0)
	s_setprio 1
	s_waitcnt lgkmcnt(0)
	v_mfma_f32_16x16x32_bf16 v[72:75], v[132:135], v[164:167], v[72:75]
	v_mfma_f32_16x16x32_bf16 v[68:71], v[140:143], v[164:167], v[68:71]
	v_mfma_f32_16x16x32_bf16 v[56:59], v[132:135], v[172:175], v[56:59]
	v_mfma_f32_16x16x32_bf16 v[52:55], v[140:143], v[172:175], v[52:55]
	v_mfma_f32_16x16x32_bf16 v[40:43], v[132:135], v[180:183], v[40:43]
	v_mfma_f32_16x16x32_bf16 v[36:39], v[140:143], v[180:183], v[36:39]
	v_mfma_f32_16x16x32_bf16 v[20:23], v[132:135], v[188:191], v[20:23]
	v_mfma_f32_16x16x32_bf16 v[12:15], v[140:143], v[188:191], v[12:15]
	v_mfma_f32_16x16x32_bf16 v[72:75], v[136:139], v[168:171], v[72:75]
	v_mfma_f32_16x16x32_bf16 v[68:71], v[144:147], v[168:171], v[68:71]
	v_mfma_f32_16x16x32_bf16 v[56:59], v[136:139], v[176:179], v[56:59]
	v_mfma_f32_16x16x32_bf16 v[52:55], v[144:147], v[176:179], v[52:55]
	v_mfma_f32_16x16x32_bf16 v[40:43], v[136:139], v[184:187], v[40:43]
	v_mfma_f32_16x16x32_bf16 v[36:39], v[144:147], v[184:187], v[36:39]
	v_mfma_f32_16x16x32_bf16 v[20:23], v[136:139], v[192:195], v[20:23]
	v_mfma_f32_16x16x32_bf16 v[12:15], v[144:147], v[192:195], v[12:15]
	s_setprio 0
	s_mov_b32 m0, s7
	v_lshl_add_u64 v[222:223], s[38:39], 0, v[196:197]
	s_barrier
	ds_read_b128 v[188:191], v230 offset:16384
	ds_read_b128 v[192:195], v230 offset:17408
	ds_read_b128 v[180:183], v230 offset:18432
	ds_read_b128 v[184:187], v230 offset:19456
	ds_read_b128 v[172:175], v230 offset:20480
	ds_read_b128 v[176:179], v230 offset:21504
	ds_read_b128 v[164:167], v230 offset:22528
	ds_read_b128 v[168:171], v230 offset:23552
	global_load_lds_dwordx4 v196, s[38:39]
	v_lshl_add_u64 v[224:225], s[38:39], 0, v[200:201]
	s_mov_b32 m0, s41
	v_cmp_ne_u32_e64 s[12:13], 1, v233
	global_load_lds_dwordx4 v200, s[38:39]
	s_barrier
	s_waitcnt lgkmcnt(0)
	s_andn2_b64 vcc, exec, s[30:31]
	s_cbranch_vccnz .LBB0_2719
	s_setprio 1
	s_waitcnt lgkmcnt(0)
	v_mfma_f32_16x16x32_bf16 v[128:131], v[148:151], v[188:191], v[128:131]
	v_mfma_f32_16x16x32_bf16 v[124:127], v[156:159], v[188:191], v[124:127]
	v_mfma_f32_16x16x32_bf16 v[112:115], v[148:151], v[180:183], v[112:115]
	v_mfma_f32_16x16x32_bf16 v[108:111], v[156:159], v[180:183], v[108:111]
	v_mfma_f32_16x16x32_bf16 v[96:99], v[148:151], v[172:175], v[96:99]
	v_mfma_f32_16x16x32_bf16 v[92:95], v[156:159], v[172:175], v[92:95]
	v_mfma_f32_16x16x32_bf16 v[28:31], v[148:151], v[164:167], v[28:31]
	v_mfma_f32_16x16x32_bf16 v[16:19], v[156:159], v[164:167], v[16:19]
	v_mfma_f32_16x16x32_bf16 v[128:131], v[152:155], v[192:195], v[128:131]
	v_mfma_f32_16x16x32_bf16 v[124:127], v[160:163], v[192:195], v[124:127]
	v_mfma_f32_16x16x32_bf16 v[112:115], v[152:155], v[184:187], v[112:115]
	v_mfma_f32_16x16x32_bf16 v[108:111], v[160:163], v[184:187], v[108:111]
	v_mfma_f32_16x16x32_bf16 v[96:99], v[152:155], v[176:179], v[96:99]
	v_mfma_f32_16x16x32_bf16 v[92:95], v[160:163], v[176:179], v[92:95]
	v_mfma_f32_16x16x32_bf16 v[28:31], v[152:155], v[168:171], v[28:31]
	v_mfma_f32_16x16x32_bf16 v[16:19], v[160:163], v[168:171], v[16:19]
	s_setprio 0
.LBB0_2719:
	s_barrier
	s_add_u32 s50, s36, 0x80000
	s_addc_u32 s51, s37, 0
	s_mov_b32 m0, s52
	s_nop 0
	global_load_lds_dwordx4 v198, s[50:51]
	s_mov_b32 m0, s53
	s_and_b64 vcc, exec, s[12:13]
	global_load_lds_dwordx4 v202, s[50:51]
	s_waitcnt vmcnt(6)
	s_barrier
	s_cbranch_vccnz .LBB0_2721
	s_setprio 1
	s_waitcnt lgkmcnt(0)
	v_mfma_f32_16x16x32_bf16 v[120:123], v[132:135], v[188:191], v[120:123]
	v_mfma_f32_16x16x32_bf16 v[116:119], v[140:143], v[188:191], v[116:119]
	v_mfma_f32_16x16x32_bf16 v[104:107], v[132:135], v[180:183], v[104:107]
	v_mfma_f32_16x16x32_bf16 v[100:103], v[140:143], v[180:183], v[100:103]
	v_mfma_f32_16x16x32_bf16 v[88:91], v[132:135], v[172:175], v[88:91]
	v_mfma_f32_16x16x32_bf16 v[80:83], v[140:143], v[172:175], v[80:83]
	v_mfma_f32_16x16x32_bf16 v[8:11], v[132:135], v[164:167], v[8:11]
	v_mfma_f32_16x16x32_bf16 v[4:7], v[140:143], v[164:167], v[4:7]
	v_mfma_f32_16x16x32_bf16 v[120:123], v[136:139], v[192:195], v[120:123]
	v_mfma_f32_16x16x32_bf16 v[116:119], v[144:147], v[192:195], v[116:119]
	v_mfma_f32_16x16x32_bf16 v[104:107], v[136:139], v[184:187], v[104:107]
	v_mfma_f32_16x16x32_bf16 v[100:103], v[144:147], v[184:187], v[100:103]
	v_mfma_f32_16x16x32_bf16 v[88:91], v[136:139], v[176:179], v[88:91]
	v_mfma_f32_16x16x32_bf16 v[80:83], v[144:147], v[176:179], v[80:83]
	v_mfma_f32_16x16x32_bf16 v[8:11], v[136:139], v[168:171], v[8:11]
	v_mfma_f32_16x16x32_bf16 v[4:7], v[144:147], v[168:171], v[4:7]
	s_setprio 0
.LBB0_2721:
	s_add_i32 s49, 0, 0x18000
	v_add_u32_e32 v1, s49, v226
	s_barrier
	ds_read_b128 v[148:151], v1
	ds_read_b128 v[152:155], v1 offset:1024
	ds_read_b128 v[156:159], v1 offset:2048
	ds_read_b128 v[160:163], v1 offset:3072
	s_add_u32 s38, s38, 0x80000
	s_addc_u32 s39, s39, 0
	s_mov_b32 m0, s54
	s_waitcnt lgkmcnt(0)
	ds_read_b128 v[164:167], v230 offset:32768
	ds_read_b128 v[168:171], v230 offset:33792
	ds_read_b128 v[172:175], v230 offset:34816
	ds_read_b128 v[176:179], v230 offset:35840
	ds_read_b128 v[180:183], v230 offset:36864
	ds_read_b128 v[184:187], v230 offset:37888
	ds_read_b128 v[188:191], v230 offset:38912
	ds_read_b128 v[192:195], v230 offset:39936
	global_load_lds_dwordx4 v196, s[38:39]
	s_mov_b32 m0, s55
	s_nop 0
	global_load_lds_dwordx4 v200, s[38:39]
	s_waitcnt lgkmcnt(8)
	s_barrier
	s_waitcnt lgkmcnt(0)
	s_setprio 1
	s_waitcnt lgkmcnt(0)
	v_mfma_f32_16x16x32_bf16 v[84:87], v[148:151], v[164:167], v[84:87]
	v_mfma_f32_16x16x32_bf16 v[76:79], v[156:159], v[164:167], v[76:79]
	v_mfma_f32_16x16x32_bf16 v[64:67], v[148:151], v[172:175], v[64:67]
	v_mfma_f32_16x16x32_bf16 v[60:63], v[156:159], v[172:175], v[60:63]
	v_mfma_f32_16x16x32_bf16 v[48:51], v[148:151], v[180:183], v[48:51]
	v_mfma_f32_16x16x32_bf16 v[44:47], v[156:159], v[180:183], v[44:47]
	v_mfma_f32_16x16x32_bf16 v[32:35], v[148:151], v[188:191], v[32:35]
	v_mfma_f32_16x16x32_bf16 v[24:27], v[156:159], v[188:191], v[24:27]
	v_mfma_f32_16x16x32_bf16 v[84:87], v[152:155], v[168:171], v[84:87]
	v_mfma_f32_16x16x32_bf16 v[76:79], v[160:163], v[168:171], v[76:79]
	v_mfma_f32_16x16x32_bf16 v[64:67], v[152:155], v[176:179], v[64:67]
	v_mfma_f32_16x16x32_bf16 v[60:63], v[160:163], v[176:179], v[60:63]
	v_mfma_f32_16x16x32_bf16 v[48:51], v[152:155], v[184:187], v[48:51]
	v_mfma_f32_16x16x32_bf16 v[44:47], v[160:163], v[184:187], v[44:47]
	v_mfma_f32_16x16x32_bf16 v[32:35], v[152:155], v[192:195], v[32:35]
	v_mfma_f32_16x16x32_bf16 v[24:27], v[160:163], v[192:195], v[24:27]
	s_setprio 0
	s_barrier
	s_add_i32 s38, s49, s40
	v_add_u32_e32 v1, 0x1c000, v231
	v_lshl_add_u64 v[2:3], v[2:3], 0, s[16:17]
	s_mov_b32 m0, s38
	ds_read_b128 v[132:135], v1
	ds_read_b128 v[136:139], v1 offset:1024
	ds_read_b128 v[140:143], v1 offset:2048
	ds_read_b128 v[144:147], v1 offset:3072
	global_load_lds_dwordx4 v[2:3], off
	v_lshl_add_u64 v[2:3], v[220:221], 0, s[16:17]
	s_add_i32 m0, s38, 0x2000
	s_nop 0
	global_load_lds_dwordx4 v[2:3], off
	s_barrier
	s_waitcnt lgkmcnt(0)
	s_setprio 1
	s_waitcnt lgkmcnt(0)
	v_mfma_f32_16x16x32_bf16 v[72:75], v[132:135], v[164:167], v[72:75]
	v_mfma_f32_16x16x32_bf16 v[68:71], v[140:143], v[164:167], v[68:71]
	v_mfma_f32_16x16x32_bf16 v[56:59], v[132:135], v[172:175], v[56:59]
	v_mfma_f32_16x16x32_bf16 v[52:55], v[140:143], v[172:175], v[52:55]
	v_mfma_f32_16x16x32_bf16 v[40:43], v[132:135], v[180:183], v[40:43]
	v_mfma_f32_16x16x32_bf16 v[36:39], v[140:143], v[180:183], v[36:39]
	v_mfma_f32_16x16x32_bf16 v[20:23], v[132:135], v[188:191], v[20:23]
	v_mfma_f32_16x16x32_bf16 v[12:15], v[140:143], v[188:191], v[12:15]
	v_mfma_f32_16x16x32_bf16 v[72:75], v[136:139], v[168:171], v[72:75]
	v_mfma_f32_16x16x32_bf16 v[68:71], v[144:147], v[168:171], v[68:71]
	v_mfma_f32_16x16x32_bf16 v[56:59], v[136:139], v[176:179], v[56:59]
	v_mfma_f32_16x16x32_bf16 v[52:55], v[144:147], v[176:179], v[52:55]
	v_mfma_f32_16x16x32_bf16 v[40:43], v[136:139], v[184:187], v[40:43]
	v_mfma_f32_16x16x32_bf16 v[36:39], v[144:147], v[184:187], v[36:39]
	v_mfma_f32_16x16x32_bf16 v[20:23], v[136:139], v[192:195], v[20:23]
	v_mfma_f32_16x16x32_bf16 v[12:15], v[144:147], v[192:195], v[12:15]
	s_setprio 0
	s_mov_b32 m0, s57
	v_lshl_add_u64 v[2:3], v[222:223], 0, s[16:17]
	s_barrier
	ds_read_b128 v[188:191], v230 offset:49152
	ds_read_b128 v[192:195], v230 offset:50176
	ds_read_b128 v[180:183], v230 offset:51200
	ds_read_b128 v[184:187], v230 offset:52224
	ds_read_b128 v[172:175], v230 offset:53248
	ds_read_b128 v[176:179], v230 offset:54272
	ds_read_b128 v[164:167], v230 offset:55296
	ds_read_b128 v[168:171], v230 offset:56320
	global_load_lds_dwordx4 v[2:3], off
	v_lshl_add_u64 v[2:3], v[224:225], 0, s[16:17]
	s_mov_b32 m0, s58
	s_and_b64 vcc, exec, s[12:13]
	global_load_lds_dwordx4 v[2:3], off
	s_barrier
	s_waitcnt lgkmcnt(0)
	s_cbranch_vccnz .LBB0_2723
	s_setprio 1
	s_waitcnt lgkmcnt(0)
	v_mfma_f32_16x16x32_bf16 v[128:131], v[148:151], v[188:191], v[128:131]
	v_mfma_f32_16x16x32_bf16 v[124:127], v[156:159], v[188:191], v[124:127]
	v_mfma_f32_16x16x32_bf16 v[112:115], v[148:151], v[180:183], v[112:115]
	v_mfma_f32_16x16x32_bf16 v[108:111], v[156:159], v[180:183], v[108:111]
	v_mfma_f32_16x16x32_bf16 v[96:99], v[148:151], v[172:175], v[96:99]
	v_mfma_f32_16x16x32_bf16 v[92:95], v[156:159], v[172:175], v[92:95]
	v_mfma_f32_16x16x32_bf16 v[28:31], v[148:151], v[164:167], v[28:31]
	v_mfma_f32_16x16x32_bf16 v[16:19], v[156:159], v[164:167], v[16:19]
	v_mfma_f32_16x16x32_bf16 v[128:131], v[152:155], v[192:195], v[128:131]
	v_mfma_f32_16x16x32_bf16 v[124:127], v[160:163], v[192:195], v[124:127]
	v_mfma_f32_16x16x32_bf16 v[112:115], v[152:155], v[184:187], v[112:115]
	v_mfma_f32_16x16x32_bf16 v[108:111], v[160:163], v[184:187], v[108:111]
	v_mfma_f32_16x16x32_bf16 v[96:99], v[152:155], v[176:179], v[96:99]
	v_mfma_f32_16x16x32_bf16 v[92:95], v[160:163], v[176:179], v[92:95]
	v_mfma_f32_16x16x32_bf16 v[28:31], v[152:155], v[168:171], v[28:31]
	v_mfma_f32_16x16x32_bf16 v[16:19], v[160:163], v[168:171], v[16:19]
	s_setprio 0
.LBB0_2723:
	s_barrier
	s_add_u32 s36, s36, 0x80080
	s_addc_u32 s37, s37, 0
	s_mov_b32 m0, s59
	s_nop 0
	global_load_lds_dwordx4 v198, s[36:37]
	s_mov_b32 m0, s60
	s_and_b64 vcc, exec, s[12:13]
	global_load_lds_dwordx4 v202, s[36:37]
	s_waitcnt vmcnt(6)
	s_barrier
	s_cbranch_vccnz .LBB0_2716
	s_setprio 1
	s_waitcnt lgkmcnt(0)
	v_mfma_f32_16x16x32_bf16 v[120:123], v[132:135], v[188:191], v[120:123]
	v_mfma_f32_16x16x32_bf16 v[116:119], v[140:143], v[188:191], v[116:119]
	v_mfma_f32_16x16x32_bf16 v[104:107], v[132:135], v[180:183], v[104:107]
	v_mfma_f32_16x16x32_bf16 v[100:103], v[140:143], v[180:183], v[100:103]
	v_mfma_f32_16x16x32_bf16 v[88:91], v[132:135], v[172:175], v[88:91]
	v_mfma_f32_16x16x32_bf16 v[80:83], v[140:143], v[172:175], v[80:83]
	v_mfma_f32_16x16x32_bf16 v[8:11], v[132:135], v[164:167], v[8:11]
	v_mfma_f32_16x16x32_bf16 v[2:5], v[140:143], v[164:167], v[4:7]
	v_mfma_f32_16x16x32_bf16 v[120:123], v[136:139], v[192:195], v[120:123]
	v_mfma_f32_16x16x32_bf16 v[116:119], v[144:147], v[192:195], v[116:119]
	v_mfma_f32_16x16x32_bf16 v[104:107], v[136:139], v[184:187], v[104:107]
	v_mfma_f32_16x16x32_bf16 v[100:103], v[144:147], v[184:187], v[100:103]
	v_mfma_f32_16x16x32_bf16 v[88:91], v[136:139], v[176:179], v[88:91]
	v_mfma_f32_16x16x32_bf16 v[80:83], v[144:147], v[176:179], v[80:83]
	v_mfma_f32_16x16x32_bf16 v[8:11], v[136:139], v[168:171], v[8:11]
	v_mfma_f32_16x16x32_bf16 v[4:7], v[144:147], v[168:171], v[2:5]
	s_setprio 0
	s_branch .LBB0_2716

.LBB0_2892:
	ds_read_b128 v[148:151], v222
	ds_read_b128 v[152:155], v222 offset:1024
	ds_read_b128 v[156:159], v222 offset:2048
	ds_read_b128 v[160:163], v222 offset:3072
	s_add_u32 s12, s28, 0xfffc0080
	s_addc_u32 s13, s29, -1
	s_cmp_eq_u32 s56, s59
	s_cselect_b32 s35, s2, s13
	s_cselect_b32 s34, s15, s12
	s_cselect_b32 s31, s17, s58
	s_cselect_b32 s30, s23, s57
	s_add_i32 m0, s36, 0xc000
	s_waitcnt lgkmcnt(0)
	ds_read_b128 v[164:167], v223
	ds_read_b128 v[168:171], v223 offset:1024
	ds_read_b128 v[172:175], v223 offset:2048
	ds_read_b128 v[176:179], v223 offset:3072
	ds_read_b128 v[180:183], v223 offset:4096
	ds_read_b128 v[184:187], v223 offset:5120
	ds_read_b128 v[188:191], v223 offset:6144
	ds_read_b128 v[192:195], v223 offset:7168
	global_load_lds_dwordx4 v204, s[28:29]
	s_add_i32 m0, s36, 0xe000
	s_nop 0
	global_load_lds_dwordx4 v206, s[28:29]
	s_waitcnt lgkmcnt(8)
	s_barrier
	s_waitcnt lgkmcnt(0)
	s_setprio 1
	s_waitcnt lgkmcnt(0)
	v_mfma_f32_16x16x32_bf16 v[124:127], v[148:151], v[164:167], v[124:127]
	v_mfma_f32_16x16x32_bf16 v[116:119], v[156:159], v[164:167], v[116:119]
	v_mfma_f32_16x16x32_bf16 v[108:111], v[148:151], v[172:175], v[108:111]
	v_mfma_f32_16x16x32_bf16 v[100:103], v[156:159], v[172:175], v[100:103]
	v_mfma_f32_16x16x32_bf16 v[92:95], v[148:151], v[180:183], v[92:95]
	v_mfma_f32_16x16x32_bf16 v[84:87], v[156:159], v[180:183], v[84:87]
	v_mfma_f32_16x16x32_bf16 v[76:79], v[148:151], v[188:191], v[76:79]
	v_mfma_f32_16x16x32_bf16 v[72:75], v[156:159], v[188:191], v[72:75]
	v_mfma_f32_16x16x32_bf16 v[124:127], v[152:155], v[168:171], v[124:127]
	v_mfma_f32_16x16x32_bf16 v[116:119], v[160:163], v[168:171], v[116:119]
	v_mfma_f32_16x16x32_bf16 v[108:111], v[152:155], v[176:179], v[108:111]
	v_mfma_f32_16x16x32_bf16 v[100:103], v[160:163], v[176:179], v[100:103]
	v_mfma_f32_16x16x32_bf16 v[92:95], v[152:155], v[184:187], v[92:95]
	v_mfma_f32_16x16x32_bf16 v[84:87], v[160:163], v[184:187], v[84:87]
	v_mfma_f32_16x16x32_bf16 v[76:79], v[152:155], v[192:195], v[76:79]
	v_mfma_f32_16x16x32_bf16 v[72:75], v[160:163], v[192:195], v[72:75]
	s_setprio 0
	s_barrier
	s_add_i32 s12, s46, s25
	v_lshl_add_u64 v[2:3], s[30:31], 0, v[198:199]
	s_mov_b32 m0, s12
	ds_read_b128 v[132:135], v225
	ds_read_b128 v[136:139], v225 offset:1024
	ds_read_b128 v[140:143], v225 offset:2048
	ds_read_b128 v[144:147], v225 offset:3072
	global_load_lds_dwordx4 v198, s[30:31]
	v_lshl_add_u64 v[212:213], s[30:31], 0, v[202:203]
	s_add_i32 m0, s12, 0x2000
	s_nop 0
	global_load_lds_dwordx4 v202, s[30:31]
	s_barrier
	s_waitcnt lgkmcnt(0)
	s_setprio 1
	s_waitcnt lgkmcnt(0)
	v_mfma_f32_16x16x32_bf16 v[128:131], v[132:135], v[164:167], v[128:131]
	v_mfma_f32_16x16x32_bf16 v[120:123], v[140:143], v[164:167], v[120:123]
	v_mfma_f32_16x16x32_bf16 v[112:115], v[132:135], v[172:175], v[112:115]
	v_mfma_f32_16x16x32_bf16 v[104:107], v[140:143], v[172:175], v[104:107]
	v_mfma_f32_16x16x32_bf16 v[96:99], v[132:135], v[180:183], v[96:99]
	v_mfma_f32_16x16x32_bf16 v[88:91], v[140:143], v[180:183], v[88:91]
	v_mfma_f32_16x16x32_bf16 v[80:83], v[132:135], v[188:191], v[80:83]
	v_mfma_f32_16x16x32_bf16 v[68:71], v[140:143], v[188:191], v[68:71]
	v_mfma_f32_16x16x32_bf16 v[128:131], v[136:139], v[168:171], v[128:131]
	v_mfma_f32_16x16x32_bf16 v[120:123], v[144:147], v[168:171], v[120:123]
	v_mfma_f32_16x16x32_bf16 v[112:115], v[136:139], v[176:179], v[112:115]
	v_mfma_f32_16x16x32_bf16 v[104:107], v[144:147], v[176:179], v[104:107]
	v_mfma_f32_16x16x32_bf16 v[96:99], v[136:139], v[184:187], v[96:99]
	v_mfma_f32_16x16x32_bf16 v[88:91], v[144:147], v[184:187], v[88:91]
	v_mfma_f32_16x16x32_bf16 v[80:83], v[136:139], v[192:195], v[80:83]
	v_mfma_f32_16x16x32_bf16 v[68:71], v[144:147], v[192:195], v[68:71]
	s_setprio 0
	s_mov_b32 m0, s36
	v_lshl_add_u64 v[214:215], s[34:35], 0, v[196:197]
	s_barrier
	ds_read_b128 v[188:191], v223 offset:16384
	ds_read_b128 v[192:195], v223 offset:17408
	ds_read_b128 v[180:183], v223 offset:18432
	ds_read_b128 v[184:187], v223 offset:19456
	ds_read_b128 v[172:175], v223 offset:20480
	ds_read_b128 v[176:179], v223 offset:21504
	ds_read_b128 v[164:167], v223 offset:22528
	ds_read_b128 v[168:171], v223 offset:23552
	global_load_lds_dwordx4 v196, s[34:35]
	v_lshl_add_u64 v[216:217], s[34:35], 0, v[200:201]
	s_mov_b32 m0, s37
	v_cmp_ne_u32_e64 s[12:13], 1, v234
	global_load_lds_dwordx4 v200, s[34:35]
	s_barrier
	s_waitcnt lgkmcnt(0)
	s_andn2_b64 vcc, exec, s[26:27]
	s_cbranch_vccnz .LBB0_2894
	s_setprio 1
	s_waitcnt lgkmcnt(0)
	v_mfma_f32_16x16x32_bf16 v[60:63], v[148:151], v[188:191], v[60:63]
	v_mfma_f32_16x16x32_bf16 v[52:55], v[156:159], v[188:191], v[52:55]
	v_mfma_f32_16x16x32_bf16 v[44:47], v[148:151], v[180:183], v[44:47]
	v_mfma_f32_16x16x32_bf16 v[36:39], v[156:159], v[180:183], v[36:39]
	v_mfma_f32_16x16x32_bf16 v[28:31], v[148:151], v[172:175], v[28:31]
	v_mfma_f32_16x16x32_bf16 v[20:23], v[156:159], v[172:175], v[20:23]
	v_mfma_f32_16x16x32_bf16 v[12:15], v[148:151], v[164:167], v[12:15]
	v_mfma_f32_16x16x32_bf16 v[4:7], v[156:159], v[164:167], v[4:7]
	v_mfma_f32_16x16x32_bf16 v[60:63], v[152:155], v[192:195], v[60:63]
	v_mfma_f32_16x16x32_bf16 v[52:55], v[160:163], v[192:195], v[52:55]
	v_mfma_f32_16x16x32_bf16 v[44:47], v[152:155], v[184:187], v[44:47]
	v_mfma_f32_16x16x32_bf16 v[36:39], v[160:163], v[184:187], v[36:39]
	v_mfma_f32_16x16x32_bf16 v[28:31], v[152:155], v[176:179], v[28:31]
	v_mfma_f32_16x16x32_bf16 v[20:23], v[160:163], v[176:179], v[20:23]
	v_mfma_f32_16x16x32_bf16 v[12:15], v[152:155], v[168:171], v[12:15]
	v_mfma_f32_16x16x32_bf16 v[4:7], v[160:163], v[168:171], v[4:7]
	s_setprio 0
.LBB0_2894:
	s_barrier
	s_add_u32 s60, s30, 0x40000
	s_addc_u32 s61, s31, 0
	s_mov_b32 m0, s38
	s_nop 0
	global_load_lds_dwordx4 v198, s[60:61]
	s_mov_b32 m0, s39
	s_and_b64 vcc, exec, s[12:13]
	global_load_lds_dwordx4 v202, s[60:61]
	s_waitcnt vmcnt(6)
	s_barrier
	s_cbranch_vccnz .LBB0_2896
	s_setprio 1
	s_waitcnt lgkmcnt(0)
	v_mfma_f32_16x16x32_bf16 v[64:67], v[132:135], v[188:191], v[64:67]
	v_mfma_f32_16x16x32_bf16 v[56:59], v[140:143], v[188:191], v[56:59]
	v_mfma_f32_16x16x32_bf16 v[48:51], v[132:135], v[180:183], v[48:51]
	v_mfma_f32_16x16x32_bf16 v[40:43], v[140:143], v[180:183], v[40:43]
	v_mfma_f32_16x16x32_bf16 v[32:35], v[132:135], v[172:175], v[32:35]
	v_mfma_f32_16x16x32_bf16 v[24:27], v[140:143], v[172:175], v[24:27]
	v_mfma_f32_16x16x32_bf16 v[16:19], v[132:135], v[164:167], v[16:19]
	v_mfma_f32_16x16x32_bf16 v[8:11], v[140:143], v[164:167], v[8:11]
	v_mfma_f32_16x16x32_bf16 v[64:67], v[136:139], v[192:195], v[64:67]
	v_mfma_f32_16x16x32_bf16 v[56:59], v[144:147], v[192:195], v[56:59]
	v_mfma_f32_16x16x32_bf16 v[48:51], v[136:139], v[184:187], v[48:51]
	v_mfma_f32_16x16x32_bf16 v[40:43], v[144:147], v[184:187], v[40:43]
	v_mfma_f32_16x16x32_bf16 v[32:35], v[136:139], v[176:179], v[32:35]
	v_mfma_f32_16x16x32_bf16 v[24:27], v[144:147], v[176:179], v[24:27]
	v_mfma_f32_16x16x32_bf16 v[16:19], v[136:139], v[168:171], v[16:19]
	v_mfma_f32_16x16x32_bf16 v[8:11], v[144:147], v[168:171], v[8:11]
	s_setprio 0
.LBB0_2896:
	s_add_i32 s60, 0, 0x18000
	v_add_u32_e32 v1, s60, v220
	s_barrier
	ds_read_b128 v[148:151], v1
	ds_read_b128 v[152:155], v1 offset:1024
	ds_read_b128 v[156:159], v1 offset:2048
	ds_read_b128 v[160:163], v1 offset:3072
	s_add_u32 s34, s34, 0x40000
	s_addc_u32 s35, s35, 0
	s_mov_b32 m0, s40
	s_waitcnt lgkmcnt(0)
	ds_read_b128 v[164:167], v223 offset:32768
	ds_read_b128 v[168:171], v223 offset:33792
	ds_read_b128 v[172:175], v223 offset:34816
	ds_read_b128 v[176:179], v223 offset:35840
	ds_read_b128 v[180:183], v223 offset:36864
	ds_read_b128 v[184:187], v223 offset:37888
	ds_read_b128 v[188:191], v223 offset:38912
	ds_read_b128 v[192:195], v223 offset:39936
	global_load_lds_dwordx4 v196, s[34:35]
	s_mov_b32 m0, s41
	s_nop 0
	global_load_lds_dwordx4 v200, s[34:35]
	s_waitcnt lgkmcnt(8)
	s_barrier
	s_waitcnt lgkmcnt(0)
	s_setprio 1
	s_waitcnt lgkmcnt(0)
	v_mfma_f32_16x16x32_bf16 v[124:127], v[148:151], v[164:167], v[124:127]
	v_mfma_f32_16x16x32_bf16 v[116:119], v[156:159], v[164:167], v[116:119]
	v_mfma_f32_16x16x32_bf16 v[108:111], v[148:151], v[172:175], v[108:111]
	v_mfma_f32_16x16x32_bf16 v[100:103], v[156:159], v[172:175], v[100:103]
	v_mfma_f32_16x16x32_bf16 v[92:95], v[148:151], v[180:183], v[92:95]
	v_mfma_f32_16x16x32_bf16 v[84:87], v[156:159], v[180:183], v[84:87]
	v_mfma_f32_16x16x32_bf16 v[76:79], v[148:151], v[188:191], v[76:79]
	v_mfma_f32_16x16x32_bf16 v[72:75], v[156:159], v[188:191], v[72:75]
	v_mfma_f32_16x16x32_bf16 v[124:127], v[152:155], v[168:171], v[124:127]
	v_mfma_f32_16x16x32_bf16 v[116:119], v[160:163], v[168:171], v[116:119]
	v_mfma_f32_16x16x32_bf16 v[108:111], v[152:155], v[176:179], v[108:111]
	v_mfma_f32_16x16x32_bf16 v[100:103], v[160:163], v[176:179], v[100:103]
	v_mfma_f32_16x16x32_bf16 v[92:95], v[152:155], v[184:187], v[92:95]
	v_mfma_f32_16x16x32_bf16 v[84:87], v[160:163], v[184:187], v[84:87]
	v_mfma_f32_16x16x32_bf16 v[76:79], v[152:155], v[192:195], v[76:79]
	v_mfma_f32_16x16x32_bf16 v[72:75], v[160:163], v[192:195], v[72:75]
	s_setprio 0
	s_barrier
	s_add_i32 s34, s60, s25
	v_add_u32_e32 v1, 0x1c000, v224
	v_lshl_add_u64 v[2:3], v[2:3], 0, s[6:7]
	s_mov_b32 m0, s34
	ds_read_b128 v[132:135], v1
	ds_read_b128 v[136:139], v1 offset:1024
	ds_read_b128 v[140:143], v1 offset:2048
	ds_read_b128 v[144:147], v1 offset:3072
	global_load_lds_dwordx4 v[2:3], off
	v_lshl_add_u64 v[2:3], v[212:213], 0, s[6:7]
	s_add_i32 m0, s34, 0x2000
	s_nop 0
	global_load_lds_dwordx4 v[2:3], off
	s_barrier
	s_waitcnt lgkmcnt(0)
	s_setprio 1
	s_waitcnt lgkmcnt(0)
	v_mfma_f32_16x16x32_bf16 v[128:131], v[132:135], v[164:167], v[128:131]
	v_mfma_f32_16x16x32_bf16 v[120:123], v[140:143], v[164:167], v[120:123]
	v_mfma_f32_16x16x32_bf16 v[112:115], v[132:135], v[172:175], v[112:115]
	v_mfma_f32_16x16x32_bf16 v[104:107], v[140:143], v[172:175], v[104:107]
	v_mfma_f32_16x16x32_bf16 v[96:99], v[132:135], v[180:183], v[96:99]
	v_mfma_f32_16x16x32_bf16 v[88:91], v[140:143], v[180:183], v[88:91]
	v_mfma_f32_16x16x32_bf16 v[80:83], v[132:135], v[188:191], v[80:83]
	v_mfma_f32_16x16x32_bf16 v[68:71], v[140:143], v[188:191], v[68:71]
	v_mfma_f32_16x16x32_bf16 v[128:131], v[136:139], v[168:171], v[128:131]
	v_mfma_f32_16x16x32_bf16 v[120:123], v[144:147], v[168:171], v[120:123]
	v_mfma_f32_16x16x32_bf16 v[112:115], v[136:139], v[176:179], v[112:115]
	v_mfma_f32_16x16x32_bf16 v[104:107], v[144:147], v[176:179], v[104:107]
	v_mfma_f32_16x16x32_bf16 v[96:99], v[136:139], v[184:187], v[96:99]
	v_mfma_f32_16x16x32_bf16 v[88:91], v[144:147], v[184:187], v[88:91]
	v_mfma_f32_16x16x32_bf16 v[80:83], v[136:139], v[192:195], v[80:83]
	v_mfma_f32_16x16x32_bf16 v[68:71], v[144:147], v[192:195], v[68:71]
	s_setprio 0
	s_mov_b32 m0, s48
	v_lshl_add_u64 v[2:3], v[214:215], 0, s[6:7]
	s_barrier
	ds_read_b128 v[188:191], v223 offset:49152
	ds_read_b128 v[192:195], v223 offset:50176
	ds_read_b128 v[180:183], v223 offset:51200
	ds_read_b128 v[184:187], v223 offset:52224
	ds_read_b128 v[172:175], v223 offset:53248
	ds_read_b128 v[176:179], v223 offset:54272
	ds_read_b128 v[164:167], v223 offset:55296
	ds_read_b128 v[168:171], v223 offset:56320
	global_load_lds_dwordx4 v[2:3], off
	v_lshl_add_u64 v[2:3], v[216:217], 0, s[6:7]
	s_mov_b32 m0, s49
	s_and_b64 vcc, exec, s[12:13]
	global_load_lds_dwordx4 v[2:3], off
	s_barrier
	s_waitcnt lgkmcnt(0)
	s_cbranch_vccnz .LBB0_2898
	s_setprio 1
	s_waitcnt lgkmcnt(0)
	v_mfma_f32_16x16x32_bf16 v[60:63], v[148:151], v[188:191], v[60:63]
	v_mfma_f32_16x16x32_bf16 v[52:55], v[156:159], v[188:191], v[52:55]
	v_mfma_f32_16x16x32_bf16 v[44:47], v[148:151], v[180:183], v[44:47]
	v_mfma_f32_16x16x32_bf16 v[36:39], v[156:159], v[180:183], v[36:39]
	v_mfma_f32_16x16x32_bf16 v[28:31], v[148:151], v[172:175], v[28:31]
	v_mfma_f32_16x16x32_bf16 v[20:23], v[156:159], v[172:175], v[20:23]
	v_mfma_f32_16x16x32_bf16 v[12:15], v[148:151], v[164:167], v[12:15]
	v_mfma_f32_16x16x32_bf16 v[2:5], v[156:159], v[164:167], v[4:7]
	v_mfma_f32_16x16x32_bf16 v[60:63], v[152:155], v[192:195], v[60:63]
	v_mfma_f32_16x16x32_bf16 v[52:55], v[160:163], v[192:195], v[52:55]
	v_mfma_f32_16x16x32_bf16 v[44:47], v[152:155], v[184:187], v[44:47]
	v_mfma_f32_16x16x32_bf16 v[36:39], v[160:163], v[184:187], v[36:39]
	v_mfma_f32_16x16x32_bf16 v[28:31], v[152:155], v[176:179], v[28:31]
	v_mfma_f32_16x16x32_bf16 v[20:23], v[160:163], v[176:179], v[20:23]
	v_mfma_f32_16x16x32_bf16 v[12:15], v[152:155], v[168:171], v[12:15]
	v_mfma_f32_16x16x32_bf16 v[4:7], v[160:163], v[168:171], v[2:5]
	s_setprio 0
.LBB0_2898:
	s_barrier
	s_add_u32 s30, s30, 0x40080
	s_addc_u32 s31, s31, 0
	s_mov_b32 m0, s53
	s_nop 0
	global_load_lds_dwordx4 v198, s[30:31]
	s_mov_b32 m0, s54
	s_and_b64 vcc, exec, s[12:13]
	global_load_lds_dwordx4 v202, s[30:31]
	s_waitcnt vmcnt(6)
	s_barrier
	s_cbranch_vccnz .LBB0_2891
	s_setprio 1
	s_waitcnt lgkmcnt(0)
	v_mfma_f32_16x16x32_bf16 v[64:67], v[132:135], v[188:191], v[64:67]
	v_mfma_f32_16x16x32_bf16 v[56:59], v[140:143], v[188:191], v[56:59]
	v_mfma_f32_16x16x32_bf16 v[48:51], v[132:135], v[180:183], v[48:51]
	v_mfma_f32_16x16x32_bf16 v[40:43], v[140:143], v[180:183], v[40:43]
	v_mfma_f32_16x16x32_bf16 v[32:35], v[132:135], v[172:175], v[32:35]
	v_mfma_f32_16x16x32_bf16 v[24:27], v[140:143], v[172:175], v[24:27]
	v_mfma_f32_16x16x32_bf16 v[16:19], v[132:135], v[164:167], v[16:19]
	v_mfma_f32_16x16x32_bf16 v[8:11], v[140:143], v[164:167], v[8:11]
	v_mfma_f32_16x16x32_bf16 v[64:67], v[136:139], v[192:195], v[64:67]
	v_mfma_f32_16x16x32_bf16 v[56:59], v[144:147], v[192:195], v[56:59]
	v_mfma_f32_16x16x32_bf16 v[48:51], v[136:139], v[184:187], v[48:51]
	v_mfma_f32_16x16x32_bf16 v[40:43], v[144:147], v[184:187], v[40:43]
	v_mfma_f32_16x16x32_bf16 v[32:35], v[136:139], v[176:179], v[32:35]
	v_mfma_f32_16x16x32_bf16 v[24:27], v[144:147], v[176:179], v[24:27]
	v_mfma_f32_16x16x32_bf16 v[16:19], v[136:139], v[168:171], v[16:19]
	v_mfma_f32_16x16x32_bf16 v[8:11], v[144:147], v[168:171], v[8:11]
	s_setprio 0
	s_branch .LBB0_2891

.LBB0_3007:
	ds_read_b128 v[148:151], v205
	ds_read_b128 v[152:155], v205 offset:1024
	ds_read_b128 v[156:159], v205 offset:2048
	ds_read_b128 v[160:163], v205 offset:3072
	s_mov_b64 s[12:13], s[22:23]
	s_add_u32 s22, s12, 0x100
	s_addc_u32 s23, s13, 0
	s_cmp_eq_u32 s5, s46
	s_cselect_b32 s29, s19, s23
	s_cselect_b32 s28, s18, s22
	s_cselect_b32 s27, s21, s17
	s_cselect_b32 s26, s20, s6
	s_add_i32 m0, s36, 0xc000
	s_waitcnt lgkmcnt(0)
	ds_read_b128 v[164:167], v230
	ds_read_b128 v[168:171], v230 offset:1024
	ds_read_b128 v[172:175], v230 offset:2048
	ds_read_b128 v[176:179], v230 offset:3072
	ds_read_b128 v[180:183], v230 offset:4096
	ds_read_b128 v[184:187], v230 offset:5120
	ds_read_b128 v[188:191], v230 offset:6144
	ds_read_b128 v[192:195], v230 offset:7168
	global_load_lds_dwordx4 v214, s[12:13]
	s_add_i32 m0, s36, 0xe000
	s_nop 0
	global_load_lds_dwordx4 v216, s[12:13]
	s_waitcnt lgkmcnt(8)
	s_barrier
	s_waitcnt lgkmcnt(0)
	s_setprio 1
	s_waitcnt lgkmcnt(0)
	v_mfma_f32_16x16x32_bf16 v[84:87], v[148:151], v[164:167], v[84:87]
	v_mfma_f32_16x16x32_bf16 v[76:79], v[156:159], v[164:167], v[76:79]
	v_mfma_f32_16x16x32_bf16 v[64:67], v[148:151], v[172:175], v[64:67]
	v_mfma_f32_16x16x32_bf16 v[60:63], v[156:159], v[172:175], v[60:63]
	v_mfma_f32_16x16x32_bf16 v[48:51], v[148:151], v[180:183], v[48:51]
	v_mfma_f32_16x16x32_bf16 v[44:47], v[156:159], v[180:183], v[44:47]
	v_mfma_f32_16x16x32_bf16 v[32:35], v[148:151], v[188:191], v[32:35]
	v_mfma_f32_16x16x32_bf16 v[24:27], v[156:159], v[188:191], v[24:27]
	v_mfma_f32_16x16x32_bf16 v[84:87], v[152:155], v[168:171], v[84:87]
	v_mfma_f32_16x16x32_bf16 v[76:79], v[160:163], v[168:171], v[76:79]
	v_mfma_f32_16x16x32_bf16 v[64:67], v[152:155], v[176:179], v[64:67]
	v_mfma_f32_16x16x32_bf16 v[60:63], v[160:163], v[176:179], v[60:63]
	v_mfma_f32_16x16x32_bf16 v[48:51], v[152:155], v[184:187], v[48:51]
	v_mfma_f32_16x16x32_bf16 v[44:47], v[160:163], v[184:187], v[44:47]
	v_mfma_f32_16x16x32_bf16 v[32:35], v[152:155], v[192:195], v[32:35]
	v_mfma_f32_16x16x32_bf16 v[24:27], v[160:163], v[192:195], v[24:27]
	s_setprio 0
	s_barrier
	s_add_i32 s12, s59, s34
	v_lshl_add_u64 v[2:3], s[26:27], 0, v[198:199]
	s_mov_b32 m0, s12
	ds_read_b128 v[132:135], v232
	ds_read_b128 v[136:139], v232 offset:1024
	ds_read_b128 v[140:143], v232 offset:2048
	ds_read_b128 v[144:147], v232 offset:3072
	global_load_lds_dwordx4 v198, s[26:27]
	v_lshl_add_u64 v[220:221], s[26:27], 0, v[202:203]
	s_add_i32 m0, s12, 0x2000
	s_nop 0
	global_load_lds_dwordx4 v202, s[26:27]
	s_barrier
	s_waitcnt lgkmcnt(0)
	s_setprio 1
	s_waitcnt lgkmcnt(0)
	v_mfma_f32_16x16x32_bf16 v[72:75], v[132:135], v[164:167], v[72:75]
	v_mfma_f32_16x16x32_bf16 v[68:71], v[140:143], v[164:167], v[68:71]
	v_mfma_f32_16x16x32_bf16 v[56:59], v[132:135], v[172:175], v[56:59]
	v_mfma_f32_16x16x32_bf16 v[52:55], v[140:143], v[172:175], v[52:55]
	v_mfma_f32_16x16x32_bf16 v[40:43], v[132:135], v[180:183], v[40:43]
	v_mfma_f32_16x16x32_bf16 v[36:39], v[140:143], v[180:183], v[36:39]
	v_mfma_f32_16x16x32_bf16 v[20:23], v[132:135], v[188:191], v[20:23]
	v_mfma_f32_16x16x32_bf16 v[12:15], v[140:143], v[188:191], v[12:15]
	v_mfma_f32_16x16x32_bf16 v[72:75], v[136:139], v[168:171], v[72:75]
	v_mfma_f32_16x16x32_bf16 v[68:71], v[144:147], v[168:171], v[68:71]
	v_mfma_f32_16x16x32_bf16 v[56:59], v[136:139], v[176:179], v[56:59]
	v_mfma_f32_16x16x32_bf16 v[52:55], v[144:147], v[176:179], v[52:55]
	v_mfma_f32_16x16x32_bf16 v[40:43], v[136:139], v[184:187], v[40:43]
	v_mfma_f32_16x16x32_bf16 v[36:39], v[144:147], v[184:187], v[36:39]
	v_mfma_f32_16x16x32_bf16 v[20:23], v[136:139], v[192:195], v[20:23]
	v_mfma_f32_16x16x32_bf16 v[12:15], v[144:147], v[192:195], v[12:15]
	s_setprio 0
	s_mov_b32 m0, s36
	v_lshl_add_u64 v[222:223], s[28:29], 0, v[196:197]
	s_barrier
	ds_read_b128 v[188:191], v230 offset:16384
	ds_read_b128 v[192:195], v230 offset:17408
	ds_read_b128 v[180:183], v230 offset:18432
	ds_read_b128 v[184:187], v230 offset:19456
	ds_read_b128 v[172:175], v230 offset:20480
	ds_read_b128 v[176:179], v230 offset:21504
	ds_read_b128 v[164:167], v230 offset:22528
	ds_read_b128 v[168:171], v230 offset:23552
	global_load_lds_dwordx4 v196, s[28:29]
	v_lshl_add_u64 v[224:225], s[28:29], 0, v[200:201]
	s_mov_b32 m0, s37
	v_cmp_ne_u32_e64 s[12:13], 1, v233
	global_load_lds_dwordx4 v200, s[28:29]
	s_barrier
	s_waitcnt lgkmcnt(0)
	s_andn2_b64 vcc, exec, s[24:25]
	s_cbranch_vccnz .LBB0_3009
	s_setprio 1
	s_waitcnt lgkmcnt(0)
	v_mfma_f32_16x16x32_bf16 v[128:131], v[148:151], v[188:191], v[128:131]
	v_mfma_f32_16x16x32_bf16 v[124:127], v[156:159], v[188:191], v[124:127]
	v_mfma_f32_16x16x32_bf16 v[112:115], v[148:151], v[180:183], v[112:115]
	v_mfma_f32_16x16x32_bf16 v[108:111], v[156:159], v[180:183], v[108:111]
	v_mfma_f32_16x16x32_bf16 v[96:99], v[148:151], v[172:175], v[96:99]
	v_mfma_f32_16x16x32_bf16 v[92:95], v[156:159], v[172:175], v[92:95]
	v_mfma_f32_16x16x32_bf16 v[28:31], v[148:151], v[164:167], v[28:31]
	v_mfma_f32_16x16x32_bf16 v[16:19], v[156:159], v[164:167], v[16:19]
	v_mfma_f32_16x16x32_bf16 v[128:131], v[152:155], v[192:195], v[128:131]
	v_mfma_f32_16x16x32_bf16 v[124:127], v[160:163], v[192:195], v[124:127]
	v_mfma_f32_16x16x32_bf16 v[112:115], v[152:155], v[184:187], v[112:115]
	v_mfma_f32_16x16x32_bf16 v[108:111], v[160:163], v[184:187], v[108:111]
	v_mfma_f32_16x16x32_bf16 v[96:99], v[152:155], v[176:179], v[96:99]
	v_mfma_f32_16x16x32_bf16 v[92:95], v[160:163], v[176:179], v[92:95]
	v_mfma_f32_16x16x32_bf16 v[28:31], v[152:155], v[168:171], v[28:31]
	v_mfma_f32_16x16x32_bf16 v[16:19], v[160:163], v[168:171], v[16:19]
	s_setprio 0
.LBB0_3009:
	s_barrier
	s_add_u32 s50, s26, 0xb0000
	s_addc_u32 s51, s27, 0
	s_mov_b32 m0, s38
	s_nop 0
	global_load_lds_dwordx4 v198, s[50:51]
	s_mov_b32 m0, s39
	s_and_b64 vcc, exec, s[12:13]
	global_load_lds_dwordx4 v202, s[50:51]
	s_waitcnt vmcnt(6)
	s_barrier
	s_cbranch_vccnz .LBB0_3011
	s_setprio 1
	s_waitcnt lgkmcnt(0)
	v_mfma_f32_16x16x32_bf16 v[120:123], v[132:135], v[188:191], v[120:123]
	v_mfma_f32_16x16x32_bf16 v[116:119], v[140:143], v[188:191], v[116:119]
	v_mfma_f32_16x16x32_bf16 v[104:107], v[132:135], v[180:183], v[104:107]
	v_mfma_f32_16x16x32_bf16 v[100:103], v[140:143], v[180:183], v[100:103]
	v_mfma_f32_16x16x32_bf16 v[88:91], v[132:135], v[172:175], v[88:91]
	v_mfma_f32_16x16x32_bf16 v[80:83], v[140:143], v[172:175], v[80:83]
	v_mfma_f32_16x16x32_bf16 v[8:11], v[132:135], v[164:167], v[8:11]
	v_mfma_f32_16x16x32_bf16 v[4:7], v[140:143], v[164:167], v[4:7]
	v_mfma_f32_16x16x32_bf16 v[120:123], v[136:139], v[192:195], v[120:123]
	v_mfma_f32_16x16x32_bf16 v[116:119], v[144:147], v[192:195], v[116:119]
	v_mfma_f32_16x16x32_bf16 v[104:107], v[136:139], v[184:187], v[104:107]
	v_mfma_f32_16x16x32_bf16 v[100:103], v[144:147], v[184:187], v[100:103]
	v_mfma_f32_16x16x32_bf16 v[88:91], v[136:139], v[176:179], v[88:91]
	v_mfma_f32_16x16x32_bf16 v[80:83], v[144:147], v[176:179], v[80:83]
	v_mfma_f32_16x16x32_bf16 v[8:11], v[136:139], v[168:171], v[8:11]
	v_mfma_f32_16x16x32_bf16 v[4:7], v[144:147], v[168:171], v[4:7]
	s_setprio 0
.LBB0_3011:
	s_add_i32 s47, 0, 0x18000
	v_add_u32_e32 v1, s47, v226
	s_barrier
	ds_read_b128 v[148:151], v1
	ds_read_b128 v[152:155], v1 offset:1024
	ds_read_b128 v[156:159], v1 offset:2048
	ds_read_b128 v[160:163], v1 offset:3072
	s_add_u32 s28, s28, 0xb0000
	s_addc_u32 s29, s29, 0
	s_mov_b32 m0, s40
	s_waitcnt lgkmcnt(0)
	ds_read_b128 v[164:167], v230 offset:32768
	ds_read_b128 v[168:171], v230 offset:33792
	ds_read_b128 v[172:175], v230 offset:34816
	ds_read_b128 v[176:179], v230 offset:35840
	ds_read_b128 v[180:183], v230 offset:36864
	ds_read_b128 v[184:187], v230 offset:37888
	ds_read_b128 v[188:191], v230 offset:38912
	ds_read_b128 v[192:195], v230 offset:39936
	global_load_lds_dwordx4 v196, s[28:29]
	s_mov_b32 m0, s41
	s_nop 0
	global_load_lds_dwordx4 v200, s[28:29]
	s_waitcnt lgkmcnt(8)
	s_barrier
	s_waitcnt lgkmcnt(0)
	s_setprio 1
	s_waitcnt lgkmcnt(0)
	v_mfma_f32_16x16x32_bf16 v[84:87], v[148:151], v[164:167], v[84:87]
	v_mfma_f32_16x16x32_bf16 v[76:79], v[156:159], v[164:167], v[76:79]
	v_mfma_f32_16x16x32_bf16 v[64:67], v[148:151], v[172:175], v[64:67]
	v_mfma_f32_16x16x32_bf16 v[60:63], v[156:159], v[172:175], v[60:63]
	v_mfma_f32_16x16x32_bf16 v[48:51], v[148:151], v[180:183], v[48:51]
	v_mfma_f32_16x16x32_bf16 v[44:47], v[156:159], v[180:183], v[44:47]
	v_mfma_f32_16x16x32_bf16 v[32:35], v[148:151], v[188:191], v[32:35]
	v_mfma_f32_16x16x32_bf16 v[24:27], v[156:159], v[188:191], v[24:27]
	v_mfma_f32_16x16x32_bf16 v[84:87], v[152:155], v[168:171], v[84:87]
	v_mfma_f32_16x16x32_bf16 v[76:79], v[160:163], v[168:171], v[76:79]
	v_mfma_f32_16x16x32_bf16 v[64:67], v[152:155], v[176:179], v[64:67]
	v_mfma_f32_16x16x32_bf16 v[60:63], v[160:163], v[176:179], v[60:63]
	v_mfma_f32_16x16x32_bf16 v[48:51], v[152:155], v[184:187], v[48:51]
	v_mfma_f32_16x16x32_bf16 v[44:47], v[160:163], v[184:187], v[44:47]
	v_mfma_f32_16x16x32_bf16 v[32:35], v[152:155], v[192:195], v[32:35]
	v_mfma_f32_16x16x32_bf16 v[24:27], v[160:163], v[192:195], v[24:27]
	s_setprio 0
	s_barrier
	s_add_i32 s28, s47, s34
	v_add_u32_e32 v1, 0x1c000, v231
	v_lshl_add_u64 v[2:3], v[2:3], 0, s[14:15]
	s_mov_b32 m0, s28
	ds_read_b128 v[132:135], v1
	ds_read_b128 v[136:139], v1 offset:1024
	ds_read_b128 v[140:143], v1 offset:2048
	ds_read_b128 v[144:147], v1 offset:3072
	global_load_lds_dwordx4 v[2:3], off
	v_lshl_add_u64 v[2:3], v[220:221], 0, s[14:15]
	s_add_i32 m0, s28, 0x2000
	s_nop 0
	global_load_lds_dwordx4 v[2:3], off
	s_barrier
	s_waitcnt lgkmcnt(0)
	s_setprio 1
	s_waitcnt lgkmcnt(0)
	v_mfma_f32_16x16x32_bf16 v[72:75], v[132:135], v[164:167], v[72:75]
	v_mfma_f32_16x16x32_bf16 v[68:71], v[140:143], v[164:167], v[68:71]
	v_mfma_f32_16x16x32_bf16 v[56:59], v[132:135], v[172:175], v[56:59]
	v_mfma_f32_16x16x32_bf16 v[52:55], v[140:143], v[172:175], v[52:55]
	v_mfma_f32_16x16x32_bf16 v[40:43], v[132:135], v[180:183], v[40:43]
	v_mfma_f32_16x16x32_bf16 v[36:39], v[140:143], v[180:183], v[36:39]
	v_mfma_f32_16x16x32_bf16 v[20:23], v[132:135], v[188:191], v[20:23]
	v_mfma_f32_16x16x32_bf16 v[12:15], v[140:143], v[188:191], v[12:15]
	v_mfma_f32_16x16x32_bf16 v[72:75], v[136:139], v[168:171], v[72:75]
	v_mfma_f32_16x16x32_bf16 v[68:71], v[144:147], v[168:171], v[68:71]
	v_mfma_f32_16x16x32_bf16 v[56:59], v[136:139], v[176:179], v[56:59]
	v_mfma_f32_16x16x32_bf16 v[52:55], v[144:147], v[176:179], v[52:55]
	v_mfma_f32_16x16x32_bf16 v[40:43], v[136:139], v[184:187], v[40:43]
	v_mfma_f32_16x16x32_bf16 v[36:39], v[144:147], v[184:187], v[36:39]
	v_mfma_f32_16x16x32_bf16 v[20:23], v[136:139], v[192:195], v[20:23]
	v_mfma_f32_16x16x32_bf16 v[12:15], v[144:147], v[192:195], v[12:15]
	s_setprio 0
	s_mov_b32 m0, s53
	v_lshl_add_u64 v[2:3], v[222:223], 0, s[14:15]
	s_barrier
	ds_read_b128 v[188:191], v230 offset:49152
	ds_read_b128 v[192:195], v230 offset:50176
	ds_read_b128 v[180:183], v230 offset:51200
	ds_read_b128 v[184:187], v230 offset:52224
	ds_read_b128 v[172:175], v230 offset:53248
	ds_read_b128 v[176:179], v230 offset:54272
	ds_read_b128 v[164:167], v230 offset:55296
	ds_read_b128 v[168:171], v230 offset:56320
	global_load_lds_dwordx4 v[2:3], off
	v_lshl_add_u64 v[2:3], v[224:225], 0, s[14:15]
	s_mov_b32 m0, s54
	s_and_b64 vcc, exec, s[12:13]
	global_load_lds_dwordx4 v[2:3], off
	s_barrier
	s_waitcnt lgkmcnt(0)
	s_cbranch_vccnz .LBB0_3013
	s_setprio 1
	s_waitcnt lgkmcnt(0)
	v_mfma_f32_16x16x32_bf16 v[128:131], v[148:151], v[188:191], v[128:131]
	v_mfma_f32_16x16x32_bf16 v[124:127], v[156:159], v[188:191], v[124:127]
	v_mfma_f32_16x16x32_bf16 v[112:115], v[148:151], v[180:183], v[112:115]
	v_mfma_f32_16x16x32_bf16 v[108:111], v[156:159], v[180:183], v[108:111]
	v_mfma_f32_16x16x32_bf16 v[96:99], v[148:151], v[172:175], v[96:99]
	v_mfma_f32_16x16x32_bf16 v[92:95], v[156:159], v[172:175], v[92:95]
	v_mfma_f32_16x16x32_bf16 v[28:31], v[148:151], v[164:167], v[28:31]
	v_mfma_f32_16x16x32_bf16 v[16:19], v[156:159], v[164:167], v[16:19]
	v_mfma_f32_16x16x32_bf16 v[128:131], v[152:155], v[192:195], v[128:131]
	v_mfma_f32_16x16x32_bf16 v[124:127], v[160:163], v[192:195], v[124:127]
	v_mfma_f32_16x16x32_bf16 v[112:115], v[152:155], v[184:187], v[112:115]
	v_mfma_f32_16x16x32_bf16 v[108:111], v[160:163], v[184:187], v[108:111]
	v_mfma_f32_16x16x32_bf16 v[96:99], v[152:155], v[176:179], v[96:99]
	v_mfma_f32_16x16x32_bf16 v[92:95], v[160:163], v[176:179], v[92:95]
	v_mfma_f32_16x16x32_bf16 v[28:31], v[152:155], v[168:171], v[28:31]
	v_mfma_f32_16x16x32_bf16 v[16:19], v[160:163], v[168:171], v[16:19]
	s_setprio 0
.LBB0_3013:
	s_barrier
	s_add_u32 s26, s26, 0xb0080
	s_addc_u32 s27, s27, 0
	s_mov_b32 m0, s55
	s_nop 0
	global_load_lds_dwordx4 v198, s[26:27]
	s_mov_b32 m0, s56
	s_and_b64 vcc, exec, s[12:13]
	global_load_lds_dwordx4 v202, s[26:27]
	s_waitcnt vmcnt(6)
	s_barrier
	s_cbranch_vccnz .LBB0_3006
	s_setprio 1
	s_waitcnt lgkmcnt(0)
	v_mfma_f32_16x16x32_bf16 v[120:123], v[132:135], v[188:191], v[120:123]
	v_mfma_f32_16x16x32_bf16 v[116:119], v[140:143], v[188:191], v[116:119]
	v_mfma_f32_16x16x32_bf16 v[104:107], v[132:135], v[180:183], v[104:107]
	v_mfma_f32_16x16x32_bf16 v[100:103], v[140:143], v[180:183], v[100:103]
	v_mfma_f32_16x16x32_bf16 v[88:91], v[132:135], v[172:175], v[88:91]
	v_mfma_f32_16x16x32_bf16 v[80:83], v[140:143], v[172:175], v[80:83]
	v_mfma_f32_16x16x32_bf16 v[8:11], v[132:135], v[164:167], v[8:11]
	v_mfma_f32_16x16x32_bf16 v[2:5], v[140:143], v[164:167], v[4:7]
	v_mfma_f32_16x16x32_bf16 v[120:123], v[136:139], v[192:195], v[120:123]
	v_mfma_f32_16x16x32_bf16 v[116:119], v[144:147], v[192:195], v[116:119]
	v_mfma_f32_16x16x32_bf16 v[104:107], v[136:139], v[184:187], v[104:107]
	v_mfma_f32_16x16x32_bf16 v[100:103], v[144:147], v[184:187], v[100:103]
	v_mfma_f32_16x16x32_bf16 v[88:91], v[136:139], v[176:179], v[88:91]
	v_mfma_f32_16x16x32_bf16 v[80:83], v[144:147], v[176:179], v[80:83]
	v_mfma_f32_16x16x32_bf16 v[8:11], v[136:139], v[168:171], v[8:11]
	v_mfma_f32_16x16x32_bf16 v[4:7], v[144:147], v[168:171], v[2:5]
	s_setprio 0
	s_branch .LBB0_3006

.LBB0_3184:
	ds_read_b128 v[148:151], v223
	ds_read_b128 v[152:155], v223 offset:1024
	ds_read_b128 v[156:159], v223 offset:2048
	ds_read_b128 v[160:163], v223 offset:3072
	s_add_u32 s12, s16, 0xfffc0080
	s_addc_u32 s13, s17, -1
	s_cmp_eq_u32 s29, s48
	s_cselect_b32 s39, s2, s13
	s_cselect_b32 s38, s5, s12
	s_cselect_b32 s37, s20, s47
	s_cselect_b32 s36, s27, s46
	s_add_i32 m0, s52, 0xc000
	s_waitcnt lgkmcnt(0)
	ds_read_b128 v[164:167], v224
	ds_read_b128 v[168:171], v224 offset:1024
	ds_read_b128 v[172:175], v224 offset:2048
	ds_read_b128 v[176:179], v224 offset:3072
	ds_read_b128 v[180:183], v224 offset:4096
	ds_read_b128 v[184:187], v224 offset:5120
	ds_read_b128 v[188:191], v224 offset:6144
	ds_read_b128 v[192:195], v224 offset:7168
	global_load_lds_dwordx4 v204, s[16:17]
	s_add_i32 m0, s52, 0xe000
	s_nop 0
	global_load_lds_dwordx4 v206, s[16:17]
	s_waitcnt lgkmcnt(8)
	s_barrier
	s_waitcnt lgkmcnt(0)
	s_setprio 1
	s_waitcnt lgkmcnt(0)
	v_mfma_f32_16x16x32_bf16 v[128:131], v[148:151], v[164:167], v[128:131]
	v_mfma_f32_16x16x32_bf16 v[124:127], v[156:159], v[164:167], v[124:127]
	v_mfma_f32_16x16x32_bf16 v[112:115], v[148:151], v[172:175], v[112:115]
	v_mfma_f32_16x16x32_bf16 v[108:111], v[156:159], v[172:175], v[108:111]
	v_mfma_f32_16x16x32_bf16 v[96:99], v[148:151], v[180:183], v[96:99]
	v_mfma_f32_16x16x32_bf16 v[92:95], v[156:159], v[180:183], v[92:95]
	v_mfma_f32_16x16x32_bf16 v[80:83], v[148:151], v[188:191], v[80:83]
	v_mfma_f32_16x16x32_bf16 v[76:79], v[156:159], v[188:191], v[76:79]
	v_mfma_f32_16x16x32_bf16 v[128:131], v[152:155], v[168:171], v[128:131]
	v_mfma_f32_16x16x32_bf16 v[124:127], v[160:163], v[168:171], v[124:127]
	v_mfma_f32_16x16x32_bf16 v[112:115], v[152:155], v[176:179], v[112:115]
	v_mfma_f32_16x16x32_bf16 v[108:111], v[160:163], v[176:179], v[108:111]
	v_mfma_f32_16x16x32_bf16 v[96:99], v[152:155], v[184:187], v[96:99]
	v_mfma_f32_16x16x32_bf16 v[92:95], v[160:163], v[184:187], v[92:95]
	v_mfma_f32_16x16x32_bf16 v[80:83], v[152:155], v[192:195], v[80:83]
	v_mfma_f32_16x16x32_bf16 v[76:79], v[160:163], v[192:195], v[76:79]
	s_setprio 0
	s_barrier
	s_add_i32 s12, s65, s19
	v_lshl_add_u64 v[2:3], s[36:37], 0, v[198:199]
	s_mov_b32 m0, s12
	ds_read_b128 v[132:135], v226
	ds_read_b128 v[136:139], v226 offset:1024
	ds_read_b128 v[140:143], v226 offset:2048
	ds_read_b128 v[144:147], v226 offset:3072
	global_load_lds_dwordx4 v198, s[36:37]
	v_lshl_add_u64 v[212:213], s[36:37], 0, v[202:203]
	s_add_i32 m0, s12, 0x2000
	s_nop 0
	global_load_lds_dwordx4 v202, s[36:37]
	s_barrier
	s_waitcnt lgkmcnt(0)
	s_setprio 1
	s_waitcnt lgkmcnt(0)
	v_mfma_f32_16x16x32_bf16 v[120:123], v[132:135], v[164:167], v[120:123]
	v_mfma_f32_16x16x32_bf16 v[116:119], v[140:143], v[164:167], v[116:119]
	v_mfma_f32_16x16x32_bf16 v[104:107], v[132:135], v[172:175], v[104:107]
	v_mfma_f32_16x16x32_bf16 v[100:103], v[140:143], v[172:175], v[100:103]
	v_mfma_f32_16x16x32_bf16 v[88:91], v[132:135], v[180:183], v[88:91]
	v_mfma_f32_16x16x32_bf16 v[84:87], v[140:143], v[180:183], v[84:87]
	v_mfma_f32_16x16x32_bf16 v[72:75], v[132:135], v[188:191], v[72:75]
	v_mfma_f32_16x16x32_bf16 v[68:71], v[140:143], v[188:191], v[68:71]
	v_mfma_f32_16x16x32_bf16 v[120:123], v[136:139], v[168:171], v[120:123]
	v_mfma_f32_16x16x32_bf16 v[116:119], v[144:147], v[168:171], v[116:119]
	v_mfma_f32_16x16x32_bf16 v[104:107], v[136:139], v[176:179], v[104:107]
	v_mfma_f32_16x16x32_bf16 v[100:103], v[144:147], v[176:179], v[100:103]
	v_mfma_f32_16x16x32_bf16 v[88:91], v[136:139], v[184:187], v[88:91]
	v_mfma_f32_16x16x32_bf16 v[84:87], v[144:147], v[184:187], v[84:87]
	v_mfma_f32_16x16x32_bf16 v[72:75], v[136:139], v[192:195], v[72:75]
	v_mfma_f32_16x16x32_bf16 v[68:71], v[144:147], v[192:195], v[68:71]
	s_setprio 0
	s_mov_b32 m0, s52
	v_lshl_add_u64 v[214:215], s[38:39], 0, v[196:197]
	s_barrier
	ds_read_b128 v[188:191], v224 offset:16384
	ds_read_b128 v[192:195], v224 offset:17408
	ds_read_b128 v[180:183], v224 offset:18432
	ds_read_b128 v[184:187], v224 offset:19456
	ds_read_b128 v[172:175], v224 offset:20480
	ds_read_b128 v[176:179], v224 offset:21504
	ds_read_b128 v[164:167], v224 offset:22528
	ds_read_b128 v[168:171], v224 offset:23552
	global_load_lds_dwordx4 v196, s[38:39]
	v_lshl_add_u64 v[216:217], s[38:39], 0, v[200:201]
	s_mov_b32 m0, s53
	v_cmp_ne_u32_e64 s[12:13], 1, v236
	global_load_lds_dwordx4 v200, s[38:39]
	s_barrier
	s_waitcnt lgkmcnt(0)
	s_andn2_b64 vcc, exec, s[14:15]
	s_cbranch_vccnz .LBB0_3186
	s_setprio 1
	s_waitcnt lgkmcnt(0)
	v_mfma_f32_16x16x32_bf16 v[64:67], v[148:151], v[188:191], v[64:67]
	v_mfma_f32_16x16x32_bf16 v[60:63], v[156:159], v[188:191], v[60:63]
	v_mfma_f32_16x16x32_bf16 v[48:51], v[148:151], v[180:183], v[48:51]
	v_mfma_f32_16x16x32_bf16 v[44:47], v[156:159], v[180:183], v[44:47]
	v_mfma_f32_16x16x32_bf16 v[32:35], v[148:151], v[172:175], v[32:35]
	v_mfma_f32_16x16x32_bf16 v[28:31], v[156:159], v[172:175], v[28:31]
	v_mfma_f32_16x16x32_bf16 v[16:19], v[148:151], v[164:167], v[16:19]
	v_mfma_f32_16x16x32_bf16 v[12:15], v[156:159], v[164:167], v[12:15]
	v_mfma_f32_16x16x32_bf16 v[64:67], v[152:155], v[192:195], v[64:67]
	v_mfma_f32_16x16x32_bf16 v[60:63], v[160:163], v[192:195], v[60:63]
	v_mfma_f32_16x16x32_bf16 v[48:51], v[152:155], v[184:187], v[48:51]
	v_mfma_f32_16x16x32_bf16 v[44:47], v[160:163], v[184:187], v[44:47]
	v_mfma_f32_16x16x32_bf16 v[32:35], v[152:155], v[176:179], v[32:35]
	v_mfma_f32_16x16x32_bf16 v[28:31], v[160:163], v[176:179], v[28:31]
	v_mfma_f32_16x16x32_bf16 v[16:19], v[152:155], v[168:171], v[16:19]
	v_mfma_f32_16x16x32_bf16 v[12:15], v[160:163], v[168:171], v[12:15]
	s_setprio 0
.LBB0_3186:
	s_barrier
	s_add_u32 s50, s36, 0x40000
	s_addc_u32 s51, s37, 0
	s_mov_b32 m0, s54
	s_nop 0
	global_load_lds_dwordx4 v198, s[50:51]
	s_mov_b32 m0, s55
	s_and_b64 vcc, exec, s[12:13]
	global_load_lds_dwordx4 v202, s[50:51]
	s_waitcnt vmcnt(6)
	s_barrier
	s_cbranch_vccnz .LBB0_3188
	s_setprio 1
	s_waitcnt lgkmcnt(0)
	v_mfma_f32_16x16x32_bf16 v[56:59], v[132:135], v[188:191], v[56:59]
	v_mfma_f32_16x16x32_bf16 v[52:55], v[140:143], v[188:191], v[52:55]
	v_mfma_f32_16x16x32_bf16 v[40:43], v[132:135], v[180:183], v[40:43]
	v_mfma_f32_16x16x32_bf16 v[36:39], v[140:143], v[180:183], v[36:39]
	v_mfma_f32_16x16x32_bf16 v[24:27], v[132:135], v[172:175], v[24:27]
	v_mfma_f32_16x16x32_bf16 v[20:23], v[140:143], v[172:175], v[20:23]
	v_mfma_f32_16x16x32_bf16 v[8:11], v[132:135], v[164:167], v[8:11]
	v_mfma_f32_16x16x32_bf16 v[4:7], v[140:143], v[164:167], v[4:7]
	v_mfma_f32_16x16x32_bf16 v[56:59], v[136:139], v[192:195], v[56:59]
	v_mfma_f32_16x16x32_bf16 v[52:55], v[144:147], v[192:195], v[52:55]
	v_mfma_f32_16x16x32_bf16 v[40:43], v[136:139], v[184:187], v[40:43]
	v_mfma_f32_16x16x32_bf16 v[36:39], v[144:147], v[184:187], v[36:39]
	v_mfma_f32_16x16x32_bf16 v[24:27], v[136:139], v[176:179], v[24:27]
	v_mfma_f32_16x16x32_bf16 v[20:23], v[144:147], v[176:179], v[20:23]
	v_mfma_f32_16x16x32_bf16 v[8:11], v[136:139], v[168:171], v[8:11]
	v_mfma_f32_16x16x32_bf16 v[4:7], v[144:147], v[168:171], v[4:7]
	s_setprio 0
.LBB0_3188:
	s_add_i32 s49, 0, 0x18000
	v_add_u32_e32 v1, s49, v219
	s_barrier
	ds_read_b128 v[148:151], v1
	ds_read_b128 v[152:155], v1 offset:1024
	ds_read_b128 v[156:159], v1 offset:2048
	ds_read_b128 v[160:163], v1 offset:3072
	s_add_u32 s38, s38, 0x40000
	s_addc_u32 s39, s39, 0
	s_mov_b32 m0, s56
	s_waitcnt lgkmcnt(0)
	ds_read_b128 v[164:167], v224 offset:32768
	ds_read_b128 v[168:171], v224 offset:33792
	ds_read_b128 v[172:175], v224 offset:34816
	ds_read_b128 v[176:179], v224 offset:35840
	ds_read_b128 v[180:183], v224 offset:36864
	ds_read_b128 v[184:187], v224 offset:37888
	ds_read_b128 v[188:191], v224 offset:38912
	ds_read_b128 v[192:195], v224 offset:39936
	global_load_lds_dwordx4 v196, s[38:39]
	s_mov_b32 m0, s57
	s_nop 0
	global_load_lds_dwordx4 v200, s[38:39]
	s_waitcnt lgkmcnt(8)
	s_barrier
	s_waitcnt lgkmcnt(0)
	s_setprio 1
	s_waitcnt lgkmcnt(0)
	v_mfma_f32_16x16x32_bf16 v[128:131], v[148:151], v[164:167], v[128:131]
	v_mfma_f32_16x16x32_bf16 v[124:127], v[156:159], v[164:167], v[124:127]
	v_mfma_f32_16x16x32_bf16 v[112:115], v[148:151], v[172:175], v[112:115]
	v_mfma_f32_16x16x32_bf16 v[108:111], v[156:159], v[172:175], v[108:111]
	v_mfma_f32_16x16x32_bf16 v[96:99], v[148:151], v[180:183], v[96:99]
	v_mfma_f32_16x16x32_bf16 v[92:95], v[156:159], v[180:183], v[92:95]
	v_mfma_f32_16x16x32_bf16 v[80:83], v[148:151], v[188:191], v[80:83]
	v_mfma_f32_16x16x32_bf16 v[76:79], v[156:159], v[188:191], v[76:79]
	v_mfma_f32_16x16x32_bf16 v[128:131], v[152:155], v[168:171], v[128:131]
	v_mfma_f32_16x16x32_bf16 v[124:127], v[160:163], v[168:171], v[124:127]
	v_mfma_f32_16x16x32_bf16 v[112:115], v[152:155], v[176:179], v[112:115]
	v_mfma_f32_16x16x32_bf16 v[108:111], v[160:163], v[176:179], v[108:111]
	v_mfma_f32_16x16x32_bf16 v[96:99], v[152:155], v[184:187], v[96:99]
	v_mfma_f32_16x16x32_bf16 v[92:95], v[160:163], v[184:187], v[92:95]
	v_mfma_f32_16x16x32_bf16 v[80:83], v[152:155], v[192:195], v[80:83]
	v_mfma_f32_16x16x32_bf16 v[76:79], v[160:163], v[192:195], v[76:79]
	s_setprio 0
	s_barrier
	s_add_i32 s38, s49, s19
	v_add_u32_e32 v1, 0x1c000, v225
	v_lshl_add_u64 v[2:3], v[2:3], 0, s[22:23]
	s_mov_b32 m0, s38
	ds_read_b128 v[132:135], v1
	ds_read_b128 v[136:139], v1 offset:1024
	ds_read_b128 v[140:143], v1 offset:2048
	ds_read_b128 v[144:147], v1 offset:3072
	global_load_lds_dwordx4 v[2:3], off
	v_lshl_add_u64 v[2:3], v[212:213], 0, s[22:23]
	s_add_i32 m0, s38, 0x2000
	s_nop 0
	global_load_lds_dwordx4 v[2:3], off
	s_barrier
	s_waitcnt lgkmcnt(0)
	s_setprio 1
	s_waitcnt lgkmcnt(0)
	v_mfma_f32_16x16x32_bf16 v[120:123], v[132:135], v[164:167], v[120:123]
	v_mfma_f32_16x16x32_bf16 v[116:119], v[140:143], v[164:167], v[116:119]
	v_mfma_f32_16x16x32_bf16 v[104:107], v[132:135], v[172:175], v[104:107]
	v_mfma_f32_16x16x32_bf16 v[100:103], v[140:143], v[172:175], v[100:103]
	v_mfma_f32_16x16x32_bf16 v[88:91], v[132:135], v[180:183], v[88:91]
	v_mfma_f32_16x16x32_bf16 v[84:87], v[140:143], v[180:183], v[84:87]
	v_mfma_f32_16x16x32_bf16 v[72:75], v[132:135], v[188:191], v[72:75]
	v_mfma_f32_16x16x32_bf16 v[68:71], v[140:143], v[188:191], v[68:71]
	v_mfma_f32_16x16x32_bf16 v[120:123], v[136:139], v[168:171], v[120:123]
	v_mfma_f32_16x16x32_bf16 v[116:119], v[144:147], v[168:171], v[116:119]
	v_mfma_f32_16x16x32_bf16 v[104:107], v[136:139], v[176:179], v[104:107]
	v_mfma_f32_16x16x32_bf16 v[100:103], v[144:147], v[176:179], v[100:103]
	v_mfma_f32_16x16x32_bf16 v[88:91], v[136:139], v[184:187], v[88:91]
	v_mfma_f32_16x16x32_bf16 v[84:87], v[144:147], v[184:187], v[84:87]
	v_mfma_f32_16x16x32_bf16 v[72:75], v[136:139], v[192:195], v[72:75]
	v_mfma_f32_16x16x32_bf16 v[68:71], v[144:147], v[192:195], v[68:71]
	s_setprio 0
	s_mov_b32 m0, s59
	v_lshl_add_u64 v[2:3], v[214:215], 0, s[22:23]
	s_barrier
	ds_read_b128 v[188:191], v224 offset:49152
	ds_read_b128 v[192:195], v224 offset:50176
	ds_read_b128 v[180:183], v224 offset:51200
	ds_read_b128 v[184:187], v224 offset:52224
	ds_read_b128 v[172:175], v224 offset:53248
	ds_read_b128 v[176:179], v224 offset:54272
	ds_read_b128 v[164:167], v224 offset:55296
	ds_read_b128 v[168:171], v224 offset:56320
	global_load_lds_dwordx4 v[2:3], off
	v_lshl_add_u64 v[2:3], v[216:217], 0, s[22:23]
	s_mov_b32 m0, s60
	s_and_b64 vcc, exec, s[12:13]
	global_load_lds_dwordx4 v[2:3], off
	s_barrier
	s_waitcnt lgkmcnt(0)
	s_cbranch_vccnz .LBB0_3190
	s_setprio 1
	s_waitcnt lgkmcnt(0)
	v_mfma_f32_16x16x32_bf16 v[64:67], v[148:151], v[188:191], v[64:67]
	v_mfma_f32_16x16x32_bf16 v[60:63], v[156:159], v[188:191], v[60:63]
	v_mfma_f32_16x16x32_bf16 v[48:51], v[148:151], v[180:183], v[48:51]
	v_mfma_f32_16x16x32_bf16 v[44:47], v[156:159], v[180:183], v[44:47]
	v_mfma_f32_16x16x32_bf16 v[32:35], v[148:151], v[172:175], v[32:35]
	v_mfma_f32_16x16x32_bf16 v[28:31], v[156:159], v[172:175], v[28:31]
	v_mfma_f32_16x16x32_bf16 v[16:19], v[148:151], v[164:167], v[16:19]
	v_mfma_f32_16x16x32_bf16 v[12:15], v[156:159], v[164:167], v[12:15]
	v_mfma_f32_16x16x32_bf16 v[64:67], v[152:155], v[192:195], v[64:67]
	v_mfma_f32_16x16x32_bf16 v[60:63], v[160:163], v[192:195], v[60:63]
	v_mfma_f32_16x16x32_bf16 v[48:51], v[152:155], v[184:187], v[48:51]
	v_mfma_f32_16x16x32_bf16 v[44:47], v[160:163], v[184:187], v[44:47]
	v_mfma_f32_16x16x32_bf16 v[32:35], v[152:155], v[176:179], v[32:35]
	v_mfma_f32_16x16x32_bf16 v[28:31], v[160:163], v[176:179], v[28:31]
	v_mfma_f32_16x16x32_bf16 v[16:19], v[152:155], v[168:171], v[16:19]
	v_mfma_f32_16x16x32_bf16 v[12:15], v[160:163], v[168:171], v[12:15]
	s_setprio 0
.LBB0_3190:
	s_barrier
	s_add_u32 s36, s36, 0x40080
	s_addc_u32 s37, s37, 0
	s_mov_b32 m0, s61
	s_nop 0
	global_load_lds_dwordx4 v198, s[36:37]
	s_mov_b32 m0, s62
	s_and_b64 vcc, exec, s[12:13]
	global_load_lds_dwordx4 v202, s[36:37]
	s_waitcnt vmcnt(6)
	s_barrier
	s_cbranch_vccnz .LBB0_3183
	s_setprio 1
	s_waitcnt lgkmcnt(0)
	v_mfma_f32_16x16x32_bf16 v[56:59], v[132:135], v[188:191], v[56:59]
	v_mfma_f32_16x16x32_bf16 v[52:55], v[140:143], v[188:191], v[52:55]
	v_mfma_f32_16x16x32_bf16 v[40:43], v[132:135], v[180:183], v[40:43]
	v_mfma_f32_16x16x32_bf16 v[36:39], v[140:143], v[180:183], v[36:39]
	v_mfma_f32_16x16x32_bf16 v[24:27], v[132:135], v[172:175], v[24:27]
	v_mfma_f32_16x16x32_bf16 v[20:23], v[140:143], v[172:175], v[20:23]
	v_mfma_f32_16x16x32_bf16 v[8:11], v[132:135], v[164:167], v[8:11]
	v_mfma_f32_16x16x32_bf16 v[2:5], v[140:143], v[164:167], v[4:7]
	v_mfma_f32_16x16x32_bf16 v[56:59], v[136:139], v[192:195], v[56:59]
	v_mfma_f32_16x16x32_bf16 v[52:55], v[144:147], v[192:195], v[52:55]
	v_mfma_f32_16x16x32_bf16 v[40:43], v[136:139], v[184:187], v[40:43]
	v_mfma_f32_16x16x32_bf16 v[36:39], v[144:147], v[184:187], v[36:39]
	v_mfma_f32_16x16x32_bf16 v[24:27], v[136:139], v[176:179], v[24:27]
	v_mfma_f32_16x16x32_bf16 v[20:23], v[144:147], v[176:179], v[20:23]
	v_mfma_f32_16x16x32_bf16 v[8:11], v[136:139], v[168:171], v[8:11]
	v_mfma_f32_16x16x32_bf16 v[4:7], v[144:147], v[168:171], v[2:5]
	s_setprio 0
	s_branch .LBB0_3183

.LBB0_3442:
	ds_read_b128 v[156:159], v219
	ds_read_b128 v[160:163], v219 offset:1024
	ds_read_b128 v[164:167], v219 offset:2048
	ds_read_b128 v[168:171], v219 offset:3072
	s_mov_b64 s[10:11], s[4:5]
	s_add_u32 s4, s10, 0x100
	s_addc_u32 s5, s11, 0
	s_cmp_eq_u32 s47, s56
	s_cselect_b32 s23, s17, s5
	s_cselect_b32 s22, s16, s4
	s_cselect_b32 s21, s19, s49
	s_cselect_b32 s20, s18, s48
	s_add_i32 m0, s29, 0xc000
	s_waitcnt lgkmcnt(0)
	ds_read_b128 v[104:107], v220
	ds_read_b128 v[172:175], v220 offset:1024
	ds_read_b128 v[176:179], v220 offset:2048
	ds_read_b128 v[180:183], v220 offset:3072
	ds_read_b128 v[184:187], v220 offset:4096
	ds_read_b128 v[188:191], v220 offset:5120
	ds_read_b128 v[192:195], v220 offset:6144
	ds_read_b128 v[212:215], v220 offset:7168
	global_load_lds_dwordx4 v204, s[10:11]
	s_add_i32 m0, s29, 0xe000
	s_nop 0
	global_load_lds_dwordx4 v206, s[10:11]
	s_waitcnt lgkmcnt(8)
	s_barrier
	s_waitcnt lgkmcnt(0)
	s_setprio 1
	s_waitcnt lgkmcnt(0)
	v_mfma_f32_16x16x32_bf16 v[100:103], v[156:159], v[104:107], v[152:155]
	v_mfma_f32_16x16x32_bf16 v[124:127], v[160:163], v[172:175], v[100:103]
	v_mfma_f32_16x16x32_bf16 v[100:103], v[164:167], v[104:107], v[148:151]
	v_mfma_f32_16x16x32_bf16 v[128:131], v[168:171], v[172:175], v[100:103]
	v_mfma_f32_16x16x32_bf16 v[100:103], v[156:159], v[176:179], v[120:123]
	v_mfma_f32_16x16x32_bf16 v[120:123], v[160:163], v[180:183], v[100:103]
	v_mfma_f32_16x16x32_bf16 v[100:103], v[164:167], v[176:179], v[116:119]
	v_mfma_f32_16x16x32_bf16 v[96:99], v[156:159], v[184:187], v[96:99]
	v_mfma_f32_16x16x32_bf16 v[92:95], v[164:167], v[184:187], v[92:95]
	v_mfma_f32_16x16x32_bf16 v[80:83], v[156:159], v[192:195], v[80:83]
	v_mfma_f32_16x16x32_bf16 v[76:79], v[164:167], v[192:195], v[76:79]
	v_mfma_f32_16x16x32_bf16 v[116:119], v[168:171], v[180:183], v[100:103]
	v_mfma_f32_16x16x32_bf16 v[96:99], v[160:163], v[188:191], v[96:99]
	v_mfma_f32_16x16x32_bf16 v[92:95], v[168:171], v[188:191], v[92:95]
	v_mfma_f32_16x16x32_bf16 v[80:83], v[160:163], v[212:215], v[80:83]
	v_mfma_f32_16x16x32_bf16 v[76:79], v[168:171], v[212:215], v[76:79]
	s_setprio 0
	s_barrier
	s_add_i32 s10, s55, s28
	v_lshl_add_u64 v[2:3], s[20:21], 0, v[198:199]
	s_mov_b32 m0, s10
	ds_read_b128 v[140:143], v222
	ds_read_b128 v[144:147], v222 offset:1024
	ds_read_b128 v[148:151], v222 offset:2048
	ds_read_b128 v[152:155], v222 offset:3072
	global_load_lds_dwordx4 v198, s[20:21]
	v_lshl_add_u64 v[210:211], s[20:21], 0, v[202:203]
	s_add_i32 m0, s10, 0x2000
	s_nop 0
	global_load_lds_dwordx4 v202, s[20:21]
	s_barrier
	s_waitcnt lgkmcnt(0)
	s_setprio 1
	s_waitcnt lgkmcnt(0)
	v_mfma_f32_16x16x32_bf16 v[100:103], v[140:143], v[104:107], v[136:139]
	v_mfma_f32_16x16x32_bf16 v[104:107], v[148:151], v[104:107], v[132:135]
	v_mfma_f32_16x16x32_bf16 v[112:115], v[140:143], v[176:179], v[112:115]
	v_mfma_f32_16x16x32_bf16 v[108:111], v[148:151], v[176:179], v[108:111]
	v_mfma_f32_16x16x32_bf16 v[88:91], v[140:143], v[184:187], v[88:91]
	v_mfma_f32_16x16x32_bf16 v[84:87], v[148:151], v[184:187], v[84:87]
	v_mfma_f32_16x16x32_bf16 v[72:75], v[140:143], v[192:195], v[72:75]
	v_mfma_f32_16x16x32_bf16 v[68:71], v[148:151], v[192:195], v[68:71]
	v_mfma_f32_16x16x32_bf16 v[100:103], v[144:147], v[172:175], v[100:103]
	v_mfma_f32_16x16x32_bf16 v[104:107], v[152:155], v[172:175], v[104:107]
	v_mfma_f32_16x16x32_bf16 v[112:115], v[144:147], v[180:183], v[112:115]
	v_mfma_f32_16x16x32_bf16 v[108:111], v[152:155], v[180:183], v[108:111]
	v_mfma_f32_16x16x32_bf16 v[88:91], v[144:147], v[188:191], v[88:91]
	v_mfma_f32_16x16x32_bf16 v[84:87], v[152:155], v[188:191], v[84:87]
	v_mfma_f32_16x16x32_bf16 v[72:75], v[144:147], v[212:215], v[72:75]
	v_mfma_f32_16x16x32_bf16 v[68:71], v[152:155], v[212:215], v[68:71]
	s_setprio 0
	s_mov_b32 m0, s29
	v_lshl_add_u64 v[212:213], s[22:23], 0, v[196:197]
	s_barrier
	ds_read_b128 v[188:191], v220 offset:16384
	ds_read_b128 v[192:195], v220 offset:17408
	ds_read_b128 v[180:183], v220 offset:18432
	ds_read_b128 v[184:187], v220 offset:19456
	ds_read_b128 v[172:175], v220 offset:20480
	ds_read_b128 v[176:179], v220 offset:21504
	ds_read_b128 v[132:135], v220 offset:22528
	ds_read_b128 v[136:139], v220 offset:23552
	global_load_lds_dwordx4 v196, s[22:23]
	v_lshl_add_u64 v[214:215], s[22:23], 0, v[200:201]
	s_mov_b32 m0, s30
	v_cmp_ne_u32_e64 s[10:11], 1, v224
	global_load_lds_dwordx4 v200, s[22:23]
	s_barrier
	s_waitcnt lgkmcnt(0)
	s_andn2_b64 vcc, exec, s[12:13]
	s_cbranch_vccnz .LBB0_3444
	s_setprio 1
	s_waitcnt lgkmcnt(0)
	v_mfma_f32_16x16x32_bf16 v[64:67], v[156:159], v[188:191], v[64:67]
	v_mfma_f32_16x16x32_bf16 v[60:63], v[164:167], v[188:191], v[60:63]
	v_mfma_f32_16x16x32_bf16 v[48:51], v[156:159], v[180:183], v[48:51]
	v_mfma_f32_16x16x32_bf16 v[44:47], v[164:167], v[180:183], v[44:47]
	v_mfma_f32_16x16x32_bf16 v[32:35], v[156:159], v[172:175], v[32:35]
	v_mfma_f32_16x16x32_bf16 v[28:31], v[164:167], v[172:175], v[28:31]
	v_mfma_f32_16x16x32_bf16 v[16:19], v[156:159], v[132:135], v[16:19]
	v_mfma_f32_16x16x32_bf16 v[12:15], v[164:167], v[132:135], v[12:15]
	v_mfma_f32_16x16x32_bf16 v[64:67], v[160:163], v[192:195], v[64:67]
	v_mfma_f32_16x16x32_bf16 v[60:63], v[168:171], v[192:195], v[60:63]
	v_mfma_f32_16x16x32_bf16 v[48:51], v[160:163], v[184:187], v[48:51]
	v_mfma_f32_16x16x32_bf16 v[44:47], v[168:171], v[184:187], v[44:47]
	v_mfma_f32_16x16x32_bf16 v[32:35], v[160:163], v[176:179], v[32:35]
	v_mfma_f32_16x16x32_bf16 v[28:31], v[168:171], v[176:179], v[28:31]
	v_mfma_f32_16x16x32_bf16 v[16:19], v[160:163], v[136:139], v[16:19]
	v_mfma_f32_16x16x32_bf16 v[12:15], v[168:171], v[136:139], v[12:15]
	s_setprio 0
.LBB0_3444:
	s_barrier
	s_add_u32 s66, s20, 0x18000
	s_addc_u32 s67, s21, 0
	s_mov_b32 m0, s31
	s_nop 0
	global_load_lds_dwordx4 v198, s[66:67]
	s_mov_b32 m0, s34
	s_and_b64 vcc, exec, s[10:11]
	global_load_lds_dwordx4 v202, s[66:67]
	s_waitcnt vmcnt(6)
	s_barrier
	s_cbranch_vccnz .LBB0_3446
	s_setprio 1
	s_waitcnt lgkmcnt(0)
	v_mfma_f32_16x16x32_bf16 v[56:59], v[140:143], v[188:191], v[56:59]
	v_mfma_f32_16x16x32_bf16 v[52:55], v[148:151], v[188:191], v[52:55]
	v_mfma_f32_16x16x32_bf16 v[40:43], v[140:143], v[180:183], v[40:43]
	v_mfma_f32_16x16x32_bf16 v[36:39], v[148:151], v[180:183], v[36:39]
	v_mfma_f32_16x16x32_bf16 v[24:27], v[140:143], v[172:175], v[24:27]
	v_mfma_f32_16x16x32_bf16 v[20:23], v[148:151], v[172:175], v[20:23]
	v_mfma_f32_16x16x32_bf16 v[8:11], v[140:143], v[132:135], v[8:11]
	v_mfma_f32_16x16x32_bf16 v[4:7], v[148:151], v[132:135], v[4:7]
	v_mfma_f32_16x16x32_bf16 v[56:59], v[144:147], v[192:195], v[56:59]
	v_mfma_f32_16x16x32_bf16 v[52:55], v[152:155], v[192:195], v[52:55]
	v_mfma_f32_16x16x32_bf16 v[40:43], v[144:147], v[184:187], v[40:43]
	v_mfma_f32_16x16x32_bf16 v[36:39], v[152:155], v[184:187], v[36:39]
	v_mfma_f32_16x16x32_bf16 v[24:27], v[144:147], v[176:179], v[24:27]
	v_mfma_f32_16x16x32_bf16 v[20:23], v[152:155], v[176:179], v[20:23]
	v_mfma_f32_16x16x32_bf16 v[8:11], v[144:147], v[136:139], v[8:11]
	v_mfma_f32_16x16x32_bf16 v[4:7], v[152:155], v[136:139], v[4:7]
	s_setprio 0
.LBB0_3446:
	s_add_i32 s57, 0, 0x18000
	v_add_u32_e32 v1, s57, v217
	s_barrier
	ds_read_b128 v[156:159], v1
	ds_read_b128 v[160:163], v1 offset:1024
	ds_read_b128 v[164:167], v1 offset:2048
	ds_read_b128 v[168:171], v1 offset:3072
	s_add_u32 s22, s22, 0x18000
	s_addc_u32 s23, s23, 0
	s_mov_b32 m0, s35
	s_waitcnt lgkmcnt(0)
	ds_read_b128 v[132:135], v220 offset:32768
	ds_read_b128 v[172:175], v220 offset:33792
	ds_read_b128 v[176:179], v220 offset:34816
	ds_read_b128 v[180:183], v220 offset:35840
	ds_read_b128 v[184:187], v220 offset:36864
	ds_read_b128 v[188:191], v220 offset:37888
	ds_read_b128 v[192:195], v220 offset:38912
	ds_read_b128 v[226:229], v220 offset:39936
	global_load_lds_dwordx4 v196, s[22:23]
	s_mov_b32 m0, s36
	s_nop 0
	global_load_lds_dwordx4 v200, s[22:23]
	s_waitcnt lgkmcnt(8)
	s_barrier
	s_waitcnt lgkmcnt(0)
	s_setprio 1
	s_waitcnt lgkmcnt(0)
	v_mfma_f32_16x16x32_bf16 v[124:127], v[156:159], v[132:135], v[124:127]
	v_mfma_f32_16x16x32_bf16 v[152:155], v[160:163], v[172:175], v[124:127]
	v_mfma_f32_16x16x32_bf16 v[124:127], v[164:167], v[132:135], v[128:131]
	v_mfma_f32_16x16x32_bf16 v[120:123], v[156:159], v[176:179], v[120:123]
	v_mfma_f32_16x16x32_bf16 v[116:119], v[164:167], v[176:179], v[116:119]
	v_mfma_f32_16x16x32_bf16 v[96:99], v[156:159], v[184:187], v[96:99]
	v_mfma_f32_16x16x32_bf16 v[92:95], v[164:167], v[184:187], v[92:95]
	v_mfma_f32_16x16x32_bf16 v[80:83], v[156:159], v[192:195], v[80:83]
	v_mfma_f32_16x16x32_bf16 v[76:79], v[164:167], v[192:195], v[76:79]
	v_mfma_f32_16x16x32_bf16 v[148:151], v[168:171], v[172:175], v[124:127]
	v_mfma_f32_16x16x32_bf16 v[120:123], v[160:163], v[180:183], v[120:123]
	v_mfma_f32_16x16x32_bf16 v[116:119], v[168:171], v[180:183], v[116:119]
	v_mfma_f32_16x16x32_bf16 v[96:99], v[160:163], v[188:191], v[96:99]
	v_mfma_f32_16x16x32_bf16 v[92:95], v[168:171], v[188:191], v[92:95]
	v_mfma_f32_16x16x32_bf16 v[80:83], v[160:163], v[226:229], v[80:83]
	v_mfma_f32_16x16x32_bf16 v[76:79], v[168:171], v[226:229], v[76:79]
	s_setprio 0
	s_barrier
	s_add_i32 s22, s57, s28
	v_add_u32_e32 v1, 0x1c000, v221
	v_lshl_add_u64 v[2:3], v[2:3], 0, s[6:7]
	s_mov_b32 m0, s22
	ds_read_b128 v[124:127], v1
	ds_read_b128 v[128:131], v1 offset:1024
	ds_read_b128 v[140:143], v1 offset:2048
	ds_read_b128 v[144:147], v1 offset:3072
	global_load_lds_dwordx4 v[2:3], off
	v_lshl_add_u64 v[2:3], v[210:211], 0, s[6:7]
	s_add_i32 m0, s22, 0x2000
	s_nop 0
	global_load_lds_dwordx4 v[2:3], off
	s_barrier
	s_waitcnt lgkmcnt(0)
	s_setprio 1
	s_waitcnt lgkmcnt(0)
	v_mfma_f32_16x16x32_bf16 v[100:103], v[124:127], v[132:135], v[100:103]
	v_mfma_f32_16x16x32_bf16 v[136:139], v[128:131], v[172:175], v[100:103]
	v_mfma_f32_16x16x32_bf16 v[100:103], v[140:143], v[132:135], v[104:107]
	v_mfma_f32_16x16x32_bf16 v[132:135], v[144:147], v[172:175], v[100:103]
	v_mfma_f32_16x16x32_bf16 v[100:103], v[124:127], v[176:179], v[112:115]
	v_mfma_f32_16x16x32_bf16 v[112:115], v[128:131], v[180:183], v[100:103]
	v_mfma_f32_16x16x32_bf16 v[100:103], v[140:143], v[176:179], v[108:111]
	v_mfma_f32_16x16x32_bf16 v[88:91], v[124:127], v[184:187], v[88:91]
	v_mfma_f32_16x16x32_bf16 v[84:87], v[140:143], v[184:187], v[84:87]
	v_mfma_f32_16x16x32_bf16 v[72:75], v[124:127], v[192:195], v[72:75]
	v_mfma_f32_16x16x32_bf16 v[68:71], v[140:143], v[192:195], v[68:71]
	v_mfma_f32_16x16x32_bf16 v[108:111], v[144:147], v[180:183], v[100:103]
	v_mfma_f32_16x16x32_bf16 v[88:91], v[128:131], v[188:191], v[88:91]
	v_mfma_f32_16x16x32_bf16 v[84:87], v[144:147], v[188:191], v[84:87]
	v_mfma_f32_16x16x32_bf16 v[72:75], v[128:131], v[226:229], v[72:75]
	v_mfma_f32_16x16x32_bf16 v[68:71], v[144:147], v[226:229], v[68:71]
	s_setprio 0
	s_mov_b32 m0, s39
	v_lshl_add_u64 v[2:3], v[212:213], 0, s[6:7]
	s_barrier
	ds_read_b128 v[188:191], v220 offset:49152
	ds_read_b128 v[192:195], v220 offset:50176
	ds_read_b128 v[180:183], v220 offset:51200
	ds_read_b128 v[184:187], v220 offset:52224
	ds_read_b128 v[172:175], v220 offset:53248
	ds_read_b128 v[176:179], v220 offset:54272
	ds_read_b128 v[100:103], v220 offset:55296
	ds_read_b128 v[104:107], v220 offset:56320
	global_load_lds_dwordx4 v[2:3], off
	v_lshl_add_u64 v[2:3], v[214:215], 0, s[6:7]
	s_mov_b32 m0, s40
	s_and_b64 vcc, exec, s[10:11]
	global_load_lds_dwordx4 v[2:3], off
	s_barrier
	s_waitcnt lgkmcnt(0)
	s_cbranch_vccnz .LBB0_3448
	s_setprio 1
	s_waitcnt lgkmcnt(0)
	v_mfma_f32_16x16x32_bf16 v[64:67], v[156:159], v[188:191], v[64:67]
	v_mfma_f32_16x16x32_bf16 v[60:63], v[164:167], v[188:191], v[60:63]
	v_mfma_f32_16x16x32_bf16 v[48:51], v[156:159], v[180:183], v[48:51]
	v_mfma_f32_16x16x32_bf16 v[44:47], v[164:167], v[180:183], v[44:47]
	v_mfma_f32_16x16x32_bf16 v[32:35], v[156:159], v[172:175], v[32:35]
	v_mfma_f32_16x16x32_bf16 v[28:31], v[164:167], v[172:175], v[28:31]
	v_mfma_f32_16x16x32_bf16 v[16:19], v[156:159], v[100:103], v[16:19]
	v_mfma_f32_16x16x32_bf16 v[12:15], v[164:167], v[100:103], v[12:15]
	v_mfma_f32_16x16x32_bf16 v[64:67], v[160:163], v[192:195], v[64:67]
	v_mfma_f32_16x16x32_bf16 v[60:63], v[168:171], v[192:195], v[60:63]
	v_mfma_f32_16x16x32_bf16 v[48:51], v[160:163], v[184:187], v[48:51]
	v_mfma_f32_16x16x32_bf16 v[44:47], v[168:171], v[184:187], v[44:47]
	v_mfma_f32_16x16x32_bf16 v[32:35], v[160:163], v[176:179], v[32:35]
	v_mfma_f32_16x16x32_bf16 v[28:31], v[168:171], v[176:179], v[28:31]
	v_mfma_f32_16x16x32_bf16 v[16:19], v[160:163], v[104:107], v[16:19]
	v_mfma_f32_16x16x32_bf16 v[12:15], v[168:171], v[104:107], v[12:15]
	s_setprio 0
.LBB0_3448:
	s_barrier
	s_add_u32 s20, s20, 0x18080
	s_addc_u32 s21, s21, 0
	s_mov_b32 m0, s41
	s_nop 0
	global_load_lds_dwordx4 v198, s[20:21]
	s_mov_b32 m0, s50
	s_and_b64 vcc, exec, s[10:11]
	global_load_lds_dwordx4 v202, s[20:21]
	s_waitcnt vmcnt(6)
	s_barrier
	s_cbranch_vccnz .LBB0_3441
	s_setprio 1
	s_waitcnt lgkmcnt(0)
	v_mfma_f32_16x16x32_bf16 v[56:59], v[124:127], v[188:191], v[56:59]
	v_mfma_f32_16x16x32_bf16 v[52:55], v[140:143], v[188:191], v[52:55]
	v_mfma_f32_16x16x32_bf16 v[40:43], v[124:127], v[180:183], v[40:43]
	v_mfma_f32_16x16x32_bf16 v[36:39], v[140:143], v[180:183], v[36:39]
	v_mfma_f32_16x16x32_bf16 v[24:27], v[124:127], v[172:175], v[24:27]
	v_mfma_f32_16x16x32_bf16 v[20:23], v[140:143], v[172:175], v[20:23]
	v_mfma_f32_16x16x32_bf16 v[8:11], v[124:127], v[100:103], v[8:11]
	v_mfma_f32_16x16x32_bf16 v[2:5], v[140:143], v[100:103], v[4:7]
	v_mfma_f32_16x16x32_bf16 v[56:59], v[128:131], v[192:195], v[56:59]
	v_mfma_f32_16x16x32_bf16 v[52:55], v[144:147], v[192:195], v[52:55]
	v_mfma_f32_16x16x32_bf16 v[40:43], v[128:131], v[184:187], v[40:43]
	v_mfma_f32_16x16x32_bf16 v[36:39], v[144:147], v[184:187], v[36:39]
	v_mfma_f32_16x16x32_bf16 v[24:27], v[128:131], v[176:179], v[24:27]
	v_mfma_f32_16x16x32_bf16 v[20:23], v[144:147], v[176:179], v[20:23]
	v_mfma_f32_16x16x32_bf16 v[8:11], v[128:131], v[104:107], v[8:11]
	v_mfma_f32_16x16x32_bf16 v[4:7], v[144:147], v[104:107], v[2:5]
	s_setprio 0
	s_branch .LBB0_3441

.LBB0_3977:
	ds_read_b128 v[148:151], v205
	ds_read_b128 v[152:155], v205 offset:1024
	ds_read_b128 v[156:159], v205 offset:2048
	ds_read_b128 v[160:163], v205 offset:3072
	s_add_u32 s10, s30, 0xfff80080
	s_addc_u32 s11, s31, -1
	s_cmp_eq_u32 s21, s59
	s_cselect_b32 s37, s2, s11
	s_cselect_b32 s36, s5, s10
	s_cselect_b32 s35, s17, s58
	s_cselect_b32 s34, s19, s57
	s_add_i32 m0, s7, 0xc000
	s_waitcnt lgkmcnt(0)
	ds_read_b128 v[164:167], v230
	ds_read_b128 v[168:171], v230 offset:1024
	ds_read_b128 v[172:175], v230 offset:2048
	ds_read_b128 v[176:179], v230 offset:3072
	ds_read_b128 v[180:183], v230 offset:4096
	ds_read_b128 v[184:187], v230 offset:5120
	ds_read_b128 v[188:191], v230 offset:6144
	ds_read_b128 v[192:195], v230 offset:7168
	global_load_lds_dwordx4 v214, s[30:31]
	s_add_i32 m0, s7, 0xe000
	s_nop 0
	global_load_lds_dwordx4 v216, s[30:31]
	s_waitcnt lgkmcnt(8)
	s_barrier
	s_waitcnt lgkmcnt(0)
	s_setprio 1
	s_waitcnt lgkmcnt(0)
	v_mfma_f32_16x16x32_bf16 v[84:87], v[148:151], v[164:167], v[84:87]
	v_mfma_f32_16x16x32_bf16 v[76:79], v[156:159], v[164:167], v[76:79]
	v_mfma_f32_16x16x32_bf16 v[64:67], v[148:151], v[172:175], v[64:67]
	v_mfma_f32_16x16x32_bf16 v[60:63], v[156:159], v[172:175], v[60:63]
	v_mfma_f32_16x16x32_bf16 v[48:51], v[148:151], v[180:183], v[48:51]
	v_mfma_f32_16x16x32_bf16 v[44:47], v[156:159], v[180:183], v[44:47]
	v_mfma_f32_16x16x32_bf16 v[32:35], v[148:151], v[188:191], v[32:35]
	v_mfma_f32_16x16x32_bf16 v[24:27], v[156:159], v[188:191], v[24:27]
	v_mfma_f32_16x16x32_bf16 v[84:87], v[152:155], v[168:171], v[84:87]
	v_mfma_f32_16x16x32_bf16 v[76:79], v[160:163], v[168:171], v[76:79]
	v_mfma_f32_16x16x32_bf16 v[64:67], v[152:155], v[176:179], v[64:67]
	v_mfma_f32_16x16x32_bf16 v[60:63], v[160:163], v[176:179], v[60:63]
	v_mfma_f32_16x16x32_bf16 v[48:51], v[152:155], v[184:187], v[48:51]
	v_mfma_f32_16x16x32_bf16 v[44:47], v[160:163], v[184:187], v[44:47]
	v_mfma_f32_16x16x32_bf16 v[32:35], v[152:155], v[192:195], v[32:35]
	v_mfma_f32_16x16x32_bf16 v[24:27], v[160:163], v[192:195], v[24:27]
	s_setprio 0
	s_barrier
	s_add_i32 s10, s55, s40
	v_lshl_add_u64 v[2:3], s[34:35], 0, v[198:199]
	s_mov_b32 m0, s10
	ds_read_b128 v[132:135], v232
	ds_read_b128 v[136:139], v232 offset:1024
	ds_read_b128 v[140:143], v232 offset:2048
	ds_read_b128 v[144:147], v232 offset:3072
	global_load_lds_dwordx4 v198, s[34:35]
	v_lshl_add_u64 v[220:221], s[34:35], 0, v[202:203]
	s_add_i32 m0, s10, 0x2000
	s_nop 0
	global_load_lds_dwordx4 v202, s[34:35]
	s_barrier
	s_waitcnt lgkmcnt(0)
	s_setprio 1
	s_waitcnt lgkmcnt(0)
	v_mfma_f32_16x16x32_bf16 v[72:75], v[132:135], v[164:167], v[72:75]
	v_mfma_f32_16x16x32_bf16 v[68:71], v[140:143], v[164:167], v[68:71]
	v_mfma_f32_16x16x32_bf16 v[56:59], v[132:135], v[172:175], v[56:59]
	v_mfma_f32_16x16x32_bf16 v[52:55], v[140:143], v[172:175], v[52:55]
	v_mfma_f32_16x16x32_bf16 v[40:43], v[132:135], v[180:183], v[40:43]
	v_mfma_f32_16x16x32_bf16 v[36:39], v[140:143], v[180:183], v[36:39]
	v_mfma_f32_16x16x32_bf16 v[20:23], v[132:135], v[188:191], v[20:23]
	v_mfma_f32_16x16x32_bf16 v[12:15], v[140:143], v[188:191], v[12:15]
	v_mfma_f32_16x16x32_bf16 v[72:75], v[136:139], v[168:171], v[72:75]
	v_mfma_f32_16x16x32_bf16 v[68:71], v[144:147], v[168:171], v[68:71]
	v_mfma_f32_16x16x32_bf16 v[56:59], v[136:139], v[176:179], v[56:59]
	v_mfma_f32_16x16x32_bf16 v[52:55], v[144:147], v[176:179], v[52:55]
	v_mfma_f32_16x16x32_bf16 v[40:43], v[136:139], v[184:187], v[40:43]
	v_mfma_f32_16x16x32_bf16 v[36:39], v[144:147], v[184:187], v[36:39]
	v_mfma_f32_16x16x32_bf16 v[20:23], v[136:139], v[192:195], v[20:23]
	v_mfma_f32_16x16x32_bf16 v[12:15], v[144:147], v[192:195], v[12:15]
	s_setprio 0
	s_mov_b32 m0, s7
	v_lshl_add_u64 v[222:223], s[36:37], 0, v[196:197]
	s_barrier
	ds_read_b128 v[188:191], v230 offset:16384
	ds_read_b128 v[192:195], v230 offset:17408
	ds_read_b128 v[180:183], v230 offset:18432
	ds_read_b128 v[184:187], v230 offset:19456
	ds_read_b128 v[172:175], v230 offset:20480
	ds_read_b128 v[176:179], v230 offset:21504
	ds_read_b128 v[164:167], v230 offset:22528
	ds_read_b128 v[168:171], v230 offset:23552
	global_load_lds_dwordx4 v196, s[36:37]
	v_lshl_add_u64 v[224:225], s[36:37], 0, v[200:201]
	s_mov_b32 m0, s41
	v_cmp_ne_u32_e64 s[10:11], 1, v233
	global_load_lds_dwordx4 v200, s[36:37]
	s_barrier
	s_waitcnt lgkmcnt(0)
	s_andn2_b64 vcc, exec, s[28:29]
	s_cbranch_vccnz .LBB0_3979
	s_setprio 1
	s_waitcnt lgkmcnt(0)
	v_mfma_f32_16x16x32_bf16 v[128:131], v[148:151], v[188:191], v[128:131]
	v_mfma_f32_16x16x32_bf16 v[124:127], v[156:159], v[188:191], v[124:127]
	v_mfma_f32_16x16x32_bf16 v[112:115], v[148:151], v[180:183], v[112:115]
	v_mfma_f32_16x16x32_bf16 v[108:111], v[156:159], v[180:183], v[108:111]
	v_mfma_f32_16x16x32_bf16 v[96:99], v[148:151], v[172:175], v[96:99]
	v_mfma_f32_16x16x32_bf16 v[92:95], v[156:159], v[172:175], v[92:95]
	v_mfma_f32_16x16x32_bf16 v[28:31], v[148:151], v[164:167], v[28:31]
	v_mfma_f32_16x16x32_bf16 v[16:19], v[156:159], v[164:167], v[16:19]
	v_mfma_f32_16x16x32_bf16 v[128:131], v[152:155], v[192:195], v[128:131]
	v_mfma_f32_16x16x32_bf16 v[124:127], v[160:163], v[192:195], v[124:127]
	v_mfma_f32_16x16x32_bf16 v[112:115], v[152:155], v[184:187], v[112:115]
	v_mfma_f32_16x16x32_bf16 v[108:111], v[160:163], v[184:187], v[108:111]
	v_mfma_f32_16x16x32_bf16 v[96:99], v[152:155], v[176:179], v[96:99]
	v_mfma_f32_16x16x32_bf16 v[92:95], v[160:163], v[176:179], v[92:95]
	v_mfma_f32_16x16x32_bf16 v[28:31], v[152:155], v[168:171], v[28:31]
	v_mfma_f32_16x16x32_bf16 v[16:19], v[160:163], v[168:171], v[16:19]
	s_setprio 0
.LBB0_3979:
	s_barrier
	s_add_u32 s60, s34, 0x80000
	s_addc_u32 s61, s35, 0
	s_mov_b32 m0, s44
	s_nop 0
	global_load_lds_dwordx4 v198, s[60:61]
	s_mov_b32 m0, s45
	s_and_b64 vcc, exec, s[10:11]
	global_load_lds_dwordx4 v202, s[60:61]
	s_waitcnt vmcnt(6)
	s_barrier
	s_cbranch_vccnz .LBB0_3981
	s_setprio 1
	s_waitcnt lgkmcnt(0)
	v_mfma_f32_16x16x32_bf16 v[120:123], v[132:135], v[188:191], v[120:123]
	v_mfma_f32_16x16x32_bf16 v[116:119], v[140:143], v[188:191], v[116:119]
	v_mfma_f32_16x16x32_bf16 v[104:107], v[132:135], v[180:183], v[104:107]
	v_mfma_f32_16x16x32_bf16 v[100:103], v[140:143], v[180:183], v[100:103]
	v_mfma_f32_16x16x32_bf16 v[88:91], v[132:135], v[172:175], v[88:91]
	v_mfma_f32_16x16x32_bf16 v[80:83], v[140:143], v[172:175], v[80:83]
	v_mfma_f32_16x16x32_bf16 v[8:11], v[132:135], v[164:167], v[8:11]
	v_mfma_f32_16x16x32_bf16 v[4:7], v[140:143], v[164:167], v[4:7]
	v_mfma_f32_16x16x32_bf16 v[120:123], v[136:139], v[192:195], v[120:123]
	v_mfma_f32_16x16x32_bf16 v[116:119], v[144:147], v[192:195], v[116:119]
	v_mfma_f32_16x16x32_bf16 v[104:107], v[136:139], v[184:187], v[104:107]
	v_mfma_f32_16x16x32_bf16 v[100:103], v[144:147], v[184:187], v[100:103]
	v_mfma_f32_16x16x32_bf16 v[88:91], v[136:139], v[176:179], v[88:91]
	v_mfma_f32_16x16x32_bf16 v[80:83], v[144:147], v[176:179], v[80:83]
	v_mfma_f32_16x16x32_bf16 v[8:11], v[136:139], v[168:171], v[8:11]
	v_mfma_f32_16x16x32_bf16 v[4:7], v[144:147], v[168:171], v[4:7]
	s_setprio 0
.LBB0_3981:
	s_add_i32 s60, 0, 0x18000
	v_add_u32_e32 v1, s60, v226
	s_barrier
	ds_read_b128 v[148:151], v1
	ds_read_b128 v[152:155], v1 offset:1024
	ds_read_b128 v[156:159], v1 offset:2048
	ds_read_b128 v[160:163], v1 offset:3072
	s_add_u32 s36, s36, 0x80000
	s_addc_u32 s37, s37, 0
	s_mov_b32 m0, s46
	s_waitcnt lgkmcnt(0)
	ds_read_b128 v[164:167], v230 offset:32768
	ds_read_b128 v[168:171], v230 offset:33792
	ds_read_b128 v[172:175], v230 offset:34816
	ds_read_b128 v[176:179], v230 offset:35840
	ds_read_b128 v[180:183], v230 offset:36864
	ds_read_b128 v[184:187], v230 offset:37888
	ds_read_b128 v[188:191], v230 offset:38912
	ds_read_b128 v[192:195], v230 offset:39936
	global_load_lds_dwordx4 v196, s[36:37]
	s_mov_b32 m0, s47
	s_nop 0
	global_load_lds_dwordx4 v200, s[36:37]
	s_waitcnt lgkmcnt(8)
	s_barrier
	s_waitcnt lgkmcnt(0)
	s_setprio 1
	s_waitcnt lgkmcnt(0)
	v_mfma_f32_16x16x32_bf16 v[84:87], v[148:151], v[164:167], v[84:87]
	v_mfma_f32_16x16x32_bf16 v[76:79], v[156:159], v[164:167], v[76:79]
	v_mfma_f32_16x16x32_bf16 v[64:67], v[148:151], v[172:175], v[64:67]
	v_mfma_f32_16x16x32_bf16 v[60:63], v[156:159], v[172:175], v[60:63]
	v_mfma_f32_16x16x32_bf16 v[48:51], v[148:151], v[180:183], v[48:51]
	v_mfma_f32_16x16x32_bf16 v[44:47], v[156:159], v[180:183], v[44:47]
	v_mfma_f32_16x16x32_bf16 v[32:35], v[148:151], v[188:191], v[32:35]
	v_mfma_f32_16x16x32_bf16 v[24:27], v[156:159], v[188:191], v[24:27]
	v_mfma_f32_16x16x32_bf16 v[84:87], v[152:155], v[168:171], v[84:87]
	v_mfma_f32_16x16x32_bf16 v[76:79], v[160:163], v[168:171], v[76:79]
	v_mfma_f32_16x16x32_bf16 v[64:67], v[152:155], v[176:179], v[64:67]
	v_mfma_f32_16x16x32_bf16 v[60:63], v[160:163], v[176:179], v[60:63]
	v_mfma_f32_16x16x32_bf16 v[48:51], v[152:155], v[184:187], v[48:51]
	v_mfma_f32_16x16x32_bf16 v[44:47], v[160:163], v[184:187], v[44:47]
	v_mfma_f32_16x16x32_bf16 v[32:35], v[152:155], v[192:195], v[32:35]
	v_mfma_f32_16x16x32_bf16 v[24:27], v[160:163], v[192:195], v[24:27]
	s_setprio 0
	s_barrier
	s_add_i32 s36, s60, s40
	v_add_u32_e32 v1, 0x1c000, v231
	v_lshl_add_u64 v[2:3], v[2:3], 0, s[14:15]
	s_mov_b32 m0, s36
	ds_read_b128 v[132:135], v1
	ds_read_b128 v[136:139], v1 offset:1024
	ds_read_b128 v[140:143], v1 offset:2048
	ds_read_b128 v[144:147], v1 offset:3072
	global_load_lds_dwordx4 v[2:3], off
	v_lshl_add_u64 v[2:3], v[220:221], 0, s[14:15]
	s_add_i32 m0, s36, 0x2000
	s_nop 0
	global_load_lds_dwordx4 v[2:3], off
	s_barrier
	s_waitcnt lgkmcnt(0)
	s_setprio 1
	s_waitcnt lgkmcnt(0)
	v_mfma_f32_16x16x32_bf16 v[72:75], v[132:135], v[164:167], v[72:75]
	v_mfma_f32_16x16x32_bf16 v[68:71], v[140:143], v[164:167], v[68:71]
	v_mfma_f32_16x16x32_bf16 v[56:59], v[132:135], v[172:175], v[56:59]
	v_mfma_f32_16x16x32_bf16 v[52:55], v[140:143], v[172:175], v[52:55]
	v_mfma_f32_16x16x32_bf16 v[40:43], v[132:135], v[180:183], v[40:43]
	v_mfma_f32_16x16x32_bf16 v[36:39], v[140:143], v[180:183], v[36:39]
	v_mfma_f32_16x16x32_bf16 v[20:23], v[132:135], v[188:191], v[20:23]
	v_mfma_f32_16x16x32_bf16 v[12:15], v[140:143], v[188:191], v[12:15]
	v_mfma_f32_16x16x32_bf16 v[72:75], v[136:139], v[168:171], v[72:75]
	v_mfma_f32_16x16x32_bf16 v[68:71], v[144:147], v[168:171], v[68:71]
	v_mfma_f32_16x16x32_bf16 v[56:59], v[136:139], v[176:179], v[56:59]
	v_mfma_f32_16x16x32_bf16 v[52:55], v[144:147], v[176:179], v[52:55]
	v_mfma_f32_16x16x32_bf16 v[40:43], v[136:139], v[184:187], v[40:43]
	v_mfma_f32_16x16x32_bf16 v[36:39], v[144:147], v[184:187], v[36:39]
	v_mfma_f32_16x16x32_bf16 v[20:23], v[136:139], v[192:195], v[20:23]
	v_mfma_f32_16x16x32_bf16 v[12:15], v[144:147], v[192:195], v[12:15]
	s_setprio 0
	s_mov_b32 m0, s49
	v_lshl_add_u64 v[2:3], v[222:223], 0, s[14:15]
	s_barrier
	ds_read_b128 v[188:191], v230 offset:49152
	ds_read_b128 v[192:195], v230 offset:50176
	ds_read_b128 v[180:183], v230 offset:51200
	ds_read_b128 v[184:187], v230 offset:52224
	ds_read_b128 v[172:175], v230 offset:53248
	ds_read_b128 v[176:179], v230 offset:54272
	ds_read_b128 v[164:167], v230 offset:55296
	ds_read_b128 v[168:171], v230 offset:56320
	global_load_lds_dwordx4 v[2:3], off
	v_lshl_add_u64 v[2:3], v[224:225], 0, s[14:15]
	s_mov_b32 m0, s50
	s_and_b64 vcc, exec, s[10:11]
	global_load_lds_dwordx4 v[2:3], off
	s_barrier
	s_waitcnt lgkmcnt(0)
	s_cbranch_vccnz .LBB0_3983
	s_setprio 1
	s_waitcnt lgkmcnt(0)
	v_mfma_f32_16x16x32_bf16 v[128:131], v[148:151], v[188:191], v[128:131]
	v_mfma_f32_16x16x32_bf16 v[124:127], v[156:159], v[188:191], v[124:127]
	v_mfma_f32_16x16x32_bf16 v[112:115], v[148:151], v[180:183], v[112:115]
	v_mfma_f32_16x16x32_bf16 v[108:111], v[156:159], v[180:183], v[108:111]
	v_mfma_f32_16x16x32_bf16 v[96:99], v[148:151], v[172:175], v[96:99]
	v_mfma_f32_16x16x32_bf16 v[92:95], v[156:159], v[172:175], v[92:95]
	v_mfma_f32_16x16x32_bf16 v[28:31], v[148:151], v[164:167], v[28:31]
	v_mfma_f32_16x16x32_bf16 v[16:19], v[156:159], v[164:167], v[16:19]
	v_mfma_f32_16x16x32_bf16 v[128:131], v[152:155], v[192:195], v[128:131]
	v_mfma_f32_16x16x32_bf16 v[124:127], v[160:163], v[192:195], v[124:127]
	v_mfma_f32_16x16x32_bf16 v[112:115], v[152:155], v[184:187], v[112:115]
	v_mfma_f32_16x16x32_bf16 v[108:111], v[160:163], v[184:187], v[108:111]
	v_mfma_f32_16x16x32_bf16 v[96:99], v[152:155], v[176:179], v[96:99]
	v_mfma_f32_16x16x32_bf16 v[92:95], v[160:163], v[176:179], v[92:95]
	v_mfma_f32_16x16x32_bf16 v[28:31], v[152:155], v[168:171], v[28:31]
	v_mfma_f32_16x16x32_bf16 v[16:19], v[160:163], v[168:171], v[16:19]
	s_setprio 0
.LBB0_3983:
	s_barrier
	s_add_u32 s34, s34, 0x80080
	s_addc_u32 s35, s35, 0
	s_mov_b32 m0, s51
	s_nop 0
	global_load_lds_dwordx4 v198, s[34:35]
	s_mov_b32 m0, s52
	s_and_b64 vcc, exec, s[10:11]
	global_load_lds_dwordx4 v202, s[34:35]
	s_waitcnt vmcnt(6)
	s_barrier
	s_cbranch_vccnz .LBB0_3976
	s_setprio 1
	s_waitcnt lgkmcnt(0)
	v_mfma_f32_16x16x32_bf16 v[120:123], v[132:135], v[188:191], v[120:123]
	v_mfma_f32_16x16x32_bf16 v[116:119], v[140:143], v[188:191], v[116:119]
	v_mfma_f32_16x16x32_bf16 v[104:107], v[132:135], v[180:183], v[104:107]
	v_mfma_f32_16x16x32_bf16 v[100:103], v[140:143], v[180:183], v[100:103]
	v_mfma_f32_16x16x32_bf16 v[88:91], v[132:135], v[172:175], v[88:91]
	v_mfma_f32_16x16x32_bf16 v[80:83], v[140:143], v[172:175], v[80:83]
	v_mfma_f32_16x16x32_bf16 v[8:11], v[132:135], v[164:167], v[8:11]
	v_mfma_f32_16x16x32_bf16 v[2:5], v[140:143], v[164:167], v[4:7]
	v_mfma_f32_16x16x32_bf16 v[120:123], v[136:139], v[192:195], v[120:123]
	v_mfma_f32_16x16x32_bf16 v[116:119], v[144:147], v[192:195], v[116:119]
	v_mfma_f32_16x16x32_bf16 v[104:107], v[136:139], v[184:187], v[104:107]
	v_mfma_f32_16x16x32_bf16 v[100:103], v[144:147], v[184:187], v[100:103]
	v_mfma_f32_16x16x32_bf16 v[88:91], v[136:139], v[176:179], v[88:91]
	v_mfma_f32_16x16x32_bf16 v[80:83], v[144:147], v[176:179], v[80:83]
	v_mfma_f32_16x16x32_bf16 v[8:11], v[136:139], v[168:171], v[8:11]
	v_mfma_f32_16x16x32_bf16 v[4:7], v[144:147], v[168:171], v[2:5]
	s_setprio 0
	s_branch .LBB0_3976

.LBB0_4152:
	ds_read_b128 v[148:151], v222
	ds_read_b128 v[152:155], v222 offset:1024
	ds_read_b128 v[156:159], v222 offset:2048
	ds_read_b128 v[160:163], v222 offset:3072
	s_add_u32 s8, s26, 0xfffc0080
	s_addc_u32 s9, s27, -1
	s_cmp_eq_u32 s52, s55
	s_cselect_b32 s31, s2, s9
	s_cselect_b32 s30, s13, s8
	s_cselect_b32 s29, s15, s54
	s_cselect_b32 s28, s21, s53
	s_add_i32 m0, s36, 0xc000
	s_waitcnt lgkmcnt(0)
	ds_read_b128 v[164:167], v223
	ds_read_b128 v[168:171], v223 offset:1024
	ds_read_b128 v[172:175], v223 offset:2048
	ds_read_b128 v[176:179], v223 offset:3072
	ds_read_b128 v[180:183], v223 offset:4096
	ds_read_b128 v[184:187], v223 offset:5120
	ds_read_b128 v[188:191], v223 offset:6144
	ds_read_b128 v[192:195], v223 offset:7168
	global_load_lds_dwordx4 v204, s[26:27]
	s_add_i32 m0, s36, 0xe000
	s_nop 0
	global_load_lds_dwordx4 v206, s[26:27]
	s_waitcnt lgkmcnt(8)
	s_barrier
	s_waitcnt lgkmcnt(0)
	s_setprio 1
	s_waitcnt lgkmcnt(0)
	v_mfma_f32_16x16x32_bf16 v[124:127], v[148:151], v[164:167], v[124:127]
	v_mfma_f32_16x16x32_bf16 v[116:119], v[156:159], v[164:167], v[116:119]
	v_mfma_f32_16x16x32_bf16 v[108:111], v[148:151], v[172:175], v[108:111]
	v_mfma_f32_16x16x32_bf16 v[100:103], v[156:159], v[172:175], v[100:103]
	v_mfma_f32_16x16x32_bf16 v[92:95], v[148:151], v[180:183], v[92:95]
	v_mfma_f32_16x16x32_bf16 v[84:87], v[156:159], v[180:183], v[84:87]
	v_mfma_f32_16x16x32_bf16 v[76:79], v[148:151], v[188:191], v[76:79]
	v_mfma_f32_16x16x32_bf16 v[72:75], v[156:159], v[188:191], v[72:75]
	v_mfma_f32_16x16x32_bf16 v[124:127], v[152:155], v[168:171], v[124:127]
	v_mfma_f32_16x16x32_bf16 v[116:119], v[160:163], v[168:171], v[116:119]
	v_mfma_f32_16x16x32_bf16 v[108:111], v[152:155], v[176:179], v[108:111]
	v_mfma_f32_16x16x32_bf16 v[100:103], v[160:163], v[176:179], v[100:103]
	v_mfma_f32_16x16x32_bf16 v[92:95], v[152:155], v[184:187], v[92:95]
	v_mfma_f32_16x16x32_bf16 v[84:87], v[160:163], v[184:187], v[84:87]
	v_mfma_f32_16x16x32_bf16 v[76:79], v[152:155], v[192:195], v[76:79]
	v_mfma_f32_16x16x32_bf16 v[72:75], v[160:163], v[192:195], v[72:75]
	s_setprio 0
	s_barrier
	s_add_i32 s8, s49, s23
	v_lshl_add_u64 v[2:3], s[28:29], 0, v[198:199]
	s_mov_b32 m0, s8
	ds_read_b128 v[132:135], v225
	ds_read_b128 v[136:139], v225 offset:1024
	ds_read_b128 v[140:143], v225 offset:2048
	ds_read_b128 v[144:147], v225 offset:3072
	global_load_lds_dwordx4 v198, s[28:29]
	v_lshl_add_u64 v[212:213], s[28:29], 0, v[202:203]
	s_add_i32 m0, s8, 0x2000
	s_nop 0
	global_load_lds_dwordx4 v202, s[28:29]
	s_barrier
	s_waitcnt lgkmcnt(0)
	s_setprio 1
	s_waitcnt lgkmcnt(0)
	v_mfma_f32_16x16x32_bf16 v[128:131], v[132:135], v[164:167], v[128:131]
	v_mfma_f32_16x16x32_bf16 v[120:123], v[140:143], v[164:167], v[120:123]
	v_mfma_f32_16x16x32_bf16 v[112:115], v[132:135], v[172:175], v[112:115]
	v_mfma_f32_16x16x32_bf16 v[104:107], v[140:143], v[172:175], v[104:107]
	v_mfma_f32_16x16x32_bf16 v[96:99], v[132:135], v[180:183], v[96:99]
	v_mfma_f32_16x16x32_bf16 v[88:91], v[140:143], v[180:183], v[88:91]
	v_mfma_f32_16x16x32_bf16 v[80:83], v[132:135], v[188:191], v[80:83]
	v_mfma_f32_16x16x32_bf16 v[68:71], v[140:143], v[188:191], v[68:71]
	v_mfma_f32_16x16x32_bf16 v[128:131], v[136:139], v[168:171], v[128:131]
	v_mfma_f32_16x16x32_bf16 v[120:123], v[144:147], v[168:171], v[120:123]
	v_mfma_f32_16x16x32_bf16 v[112:115], v[136:139], v[176:179], v[112:115]
	v_mfma_f32_16x16x32_bf16 v[104:107], v[144:147], v[176:179], v[104:107]
	v_mfma_f32_16x16x32_bf16 v[96:99], v[136:139], v[184:187], v[96:99]
	v_mfma_f32_16x16x32_bf16 v[88:91], v[144:147], v[184:187], v[88:91]
	v_mfma_f32_16x16x32_bf16 v[80:83], v[136:139], v[192:195], v[80:83]
	v_mfma_f32_16x16x32_bf16 v[68:71], v[144:147], v[192:195], v[68:71]
	s_setprio 0
	s_mov_b32 m0, s36
	v_lshl_add_u64 v[214:215], s[30:31], 0, v[196:197]
	s_barrier
	ds_read_b128 v[188:191], v223 offset:16384
	ds_read_b128 v[192:195], v223 offset:17408
	ds_read_b128 v[180:183], v223 offset:18432
	ds_read_b128 v[184:187], v223 offset:19456
	ds_read_b128 v[172:175], v223 offset:20480
	ds_read_b128 v[176:179], v223 offset:21504
	ds_read_b128 v[164:167], v223 offset:22528
	ds_read_b128 v[168:171], v223 offset:23552
	global_load_lds_dwordx4 v196, s[30:31]
	v_lshl_add_u64 v[216:217], s[30:31], 0, v[200:201]
	s_mov_b32 m0, s37
	v_cmp_ne_u32_e64 s[8:9], 1, v234
	global_load_lds_dwordx4 v200, s[30:31]
	s_barrier
	s_waitcnt lgkmcnt(0)
	s_andn2_b64 vcc, exec, s[24:25]
	s_cbranch_vccnz .LBB0_4154
	s_setprio 1
	s_waitcnt lgkmcnt(0)
	v_mfma_f32_16x16x32_bf16 v[60:63], v[148:151], v[188:191], v[60:63]
	v_mfma_f32_16x16x32_bf16 v[52:55], v[156:159], v[188:191], v[52:55]
	v_mfma_f32_16x16x32_bf16 v[44:47], v[148:151], v[180:183], v[44:47]
	v_mfma_f32_16x16x32_bf16 v[36:39], v[156:159], v[180:183], v[36:39]
	v_mfma_f32_16x16x32_bf16 v[28:31], v[148:151], v[172:175], v[28:31]
	v_mfma_f32_16x16x32_bf16 v[20:23], v[156:159], v[172:175], v[20:23]
	v_mfma_f32_16x16x32_bf16 v[12:15], v[148:151], v[164:167], v[12:15]
	v_mfma_f32_16x16x32_bf16 v[4:7], v[156:159], v[164:167], v[4:7]
	v_mfma_f32_16x16x32_bf16 v[60:63], v[152:155], v[192:195], v[60:63]
	v_mfma_f32_16x16x32_bf16 v[52:55], v[160:163], v[192:195], v[52:55]
	v_mfma_f32_16x16x32_bf16 v[44:47], v[152:155], v[184:187], v[44:47]
	v_mfma_f32_16x16x32_bf16 v[36:39], v[160:163], v[184:187], v[36:39]
	v_mfma_f32_16x16x32_bf16 v[28:31], v[152:155], v[176:179], v[28:31]
	v_mfma_f32_16x16x32_bf16 v[20:23], v[160:163], v[176:179], v[20:23]
	v_mfma_f32_16x16x32_bf16 v[12:15], v[152:155], v[168:171], v[12:15]
	v_mfma_f32_16x16x32_bf16 v[4:7], v[160:163], v[168:171], v[4:7]
	s_setprio 0
.LBB0_4154:
	s_barrier
	s_add_u32 s56, s28, 0x40000
	s_addc_u32 s57, s29, 0
	s_mov_b32 m0, s38
	s_nop 0
	global_load_lds_dwordx4 v198, s[56:57]
	s_mov_b32 m0, s39
	s_and_b64 vcc, exec, s[8:9]
	global_load_lds_dwordx4 v202, s[56:57]
	s_waitcnt vmcnt(6)
	s_barrier
	s_cbranch_vccnz .LBB0_4156
	s_setprio 1
	s_waitcnt lgkmcnt(0)
	v_mfma_f32_16x16x32_bf16 v[64:67], v[132:135], v[188:191], v[64:67]
	v_mfma_f32_16x16x32_bf16 v[56:59], v[140:143], v[188:191], v[56:59]
	v_mfma_f32_16x16x32_bf16 v[48:51], v[132:135], v[180:183], v[48:51]
	v_mfma_f32_16x16x32_bf16 v[40:43], v[140:143], v[180:183], v[40:43]
	v_mfma_f32_16x16x32_bf16 v[32:35], v[132:135], v[172:175], v[32:35]
	v_mfma_f32_16x16x32_bf16 v[24:27], v[140:143], v[172:175], v[24:27]
	v_mfma_f32_16x16x32_bf16 v[16:19], v[132:135], v[164:167], v[16:19]
	v_mfma_f32_16x16x32_bf16 v[8:11], v[140:143], v[164:167], v[8:11]
	v_mfma_f32_16x16x32_bf16 v[64:67], v[136:139], v[192:195], v[64:67]
	v_mfma_f32_16x16x32_bf16 v[56:59], v[144:147], v[192:195], v[56:59]
	v_mfma_f32_16x16x32_bf16 v[48:51], v[136:139], v[184:187], v[48:51]
	v_mfma_f32_16x16x32_bf16 v[40:43], v[144:147], v[184:187], v[40:43]
	v_mfma_f32_16x16x32_bf16 v[32:35], v[136:139], v[176:179], v[32:35]
	v_mfma_f32_16x16x32_bf16 v[24:27], v[144:147], v[176:179], v[24:27]
	v_mfma_f32_16x16x32_bf16 v[16:19], v[136:139], v[168:171], v[16:19]
	v_mfma_f32_16x16x32_bf16 v[8:11], v[144:147], v[168:171], v[8:11]
	s_setprio 0
.LBB0_4156:
	s_add_i32 s56, 0, 0x18000
	v_add_u32_e32 v1, s56, v220
	s_barrier
	ds_read_b128 v[148:151], v1
	ds_read_b128 v[152:155], v1 offset:1024
	ds_read_b128 v[156:159], v1 offset:2048
	ds_read_b128 v[160:163], v1 offset:3072
	s_add_u32 s30, s30, 0x40000
	s_addc_u32 s31, s31, 0
	s_mov_b32 m0, s40
	s_waitcnt lgkmcnt(0)
	ds_read_b128 v[164:167], v223 offset:32768
	ds_read_b128 v[168:171], v223 offset:33792
	ds_read_b128 v[172:175], v223 offset:34816
	ds_read_b128 v[176:179], v223 offset:35840
	ds_read_b128 v[180:183], v223 offset:36864
	ds_read_b128 v[184:187], v223 offset:37888
	ds_read_b128 v[188:191], v223 offset:38912
	ds_read_b128 v[192:195], v223 offset:39936
	global_load_lds_dwordx4 v196, s[30:31]
	s_mov_b32 m0, s41
	s_nop 0
	global_load_lds_dwordx4 v200, s[30:31]
	s_waitcnt lgkmcnt(8)
	s_barrier
	s_waitcnt lgkmcnt(0)
	s_setprio 1
	s_waitcnt lgkmcnt(0)
	v_mfma_f32_16x16x32_bf16 v[124:127], v[148:151], v[164:167], v[124:127]
	v_mfma_f32_16x16x32_bf16 v[116:119], v[156:159], v[164:167], v[116:119]
	v_mfma_f32_16x16x32_bf16 v[108:111], v[148:151], v[172:175], v[108:111]
	v_mfma_f32_16x16x32_bf16 v[100:103], v[156:159], v[172:175], v[100:103]
	v_mfma_f32_16x16x32_bf16 v[92:95], v[148:151], v[180:183], v[92:95]
	v_mfma_f32_16x16x32_bf16 v[84:87], v[156:159], v[180:183], v[84:87]
	v_mfma_f32_16x16x32_bf16 v[76:79], v[148:151], v[188:191], v[76:79]
	v_mfma_f32_16x16x32_bf16 v[72:75], v[156:159], v[188:191], v[72:75]
	v_mfma_f32_16x16x32_bf16 v[124:127], v[152:155], v[168:171], v[124:127]
	v_mfma_f32_16x16x32_bf16 v[116:119], v[160:163], v[168:171], v[116:119]
	v_mfma_f32_16x16x32_bf16 v[108:111], v[152:155], v[176:179], v[108:111]
	v_mfma_f32_16x16x32_bf16 v[100:103], v[160:163], v[176:179], v[100:103]
	v_mfma_f32_16x16x32_bf16 v[92:95], v[152:155], v[184:187], v[92:95]
	v_mfma_f32_16x16x32_bf16 v[84:87], v[160:163], v[184:187], v[84:87]
	v_mfma_f32_16x16x32_bf16 v[76:79], v[152:155], v[192:195], v[76:79]
	v_mfma_f32_16x16x32_bf16 v[72:75], v[160:163], v[192:195], v[72:75]
	s_setprio 0
	s_barrier
	s_add_i32 s30, s56, s23
	v_add_u32_e32 v1, 0x1c000, v224
	v_lshl_add_u64 v[2:3], v[2:3], 0, s[10:11]
	s_mov_b32 m0, s30
	ds_read_b128 v[132:135], v1
	ds_read_b128 v[136:139], v1 offset:1024
	ds_read_b128 v[140:143], v1 offset:2048
	ds_read_b128 v[144:147], v1 offset:3072
	global_load_lds_dwordx4 v[2:3], off
	v_lshl_add_u64 v[2:3], v[212:213], 0, s[10:11]
	s_add_i32 m0, s30, 0x2000
	s_nop 0
	global_load_lds_dwordx4 v[2:3], off
	s_barrier
	s_waitcnt lgkmcnt(0)
	s_setprio 1
	s_waitcnt lgkmcnt(0)
	v_mfma_f32_16x16x32_bf16 v[128:131], v[132:135], v[164:167], v[128:131]
	v_mfma_f32_16x16x32_bf16 v[120:123], v[140:143], v[164:167], v[120:123]
	v_mfma_f32_16x16x32_bf16 v[112:115], v[132:135], v[172:175], v[112:115]
	v_mfma_f32_16x16x32_bf16 v[104:107], v[140:143], v[172:175], v[104:107]
	v_mfma_f32_16x16x32_bf16 v[96:99], v[132:135], v[180:183], v[96:99]
	v_mfma_f32_16x16x32_bf16 v[88:91], v[140:143], v[180:183], v[88:91]
	v_mfma_f32_16x16x32_bf16 v[80:83], v[132:135], v[188:191], v[80:83]
	v_mfma_f32_16x16x32_bf16 v[68:71], v[140:143], v[188:191], v[68:71]
	v_mfma_f32_16x16x32_bf16 v[128:131], v[136:139], v[168:171], v[128:131]
	v_mfma_f32_16x16x32_bf16 v[120:123], v[144:147], v[168:171], v[120:123]
	v_mfma_f32_16x16x32_bf16 v[112:115], v[136:139], v[176:179], v[112:115]
	v_mfma_f32_16x16x32_bf16 v[104:107], v[144:147], v[176:179], v[104:107]
	v_mfma_f32_16x16x32_bf16 v[96:99], v[136:139], v[184:187], v[96:99]
	v_mfma_f32_16x16x32_bf16 v[88:91], v[144:147], v[184:187], v[88:91]
	v_mfma_f32_16x16x32_bf16 v[80:83], v[136:139], v[192:195], v[80:83]
	v_mfma_f32_16x16x32_bf16 v[68:71], v[144:147], v[192:195], v[68:71]
	s_setprio 0
	s_mov_b32 m0, s43
	v_lshl_add_u64 v[2:3], v[214:215], 0, s[10:11]
	s_barrier
	ds_read_b128 v[188:191], v223 offset:49152
	ds_read_b128 v[192:195], v223 offset:50176
	ds_read_b128 v[180:183], v223 offset:51200
	ds_read_b128 v[184:187], v223 offset:52224
	ds_read_b128 v[172:175], v223 offset:53248
	ds_read_b128 v[176:179], v223 offset:54272
	ds_read_b128 v[164:167], v223 offset:55296
	ds_read_b128 v[168:171], v223 offset:56320
	global_load_lds_dwordx4 v[2:3], off
	v_lshl_add_u64 v[2:3], v[216:217], 0, s[10:11]
	s_mov_b32 m0, s44
	s_and_b64 vcc, exec, s[8:9]
	global_load_lds_dwordx4 v[2:3], off
	s_barrier
	s_waitcnt lgkmcnt(0)
	s_cbranch_vccnz .LBB0_4158
	s_setprio 1
	s_waitcnt lgkmcnt(0)
	v_mfma_f32_16x16x32_bf16 v[60:63], v[148:151], v[188:191], v[60:63]
	v_mfma_f32_16x16x32_bf16 v[52:55], v[156:159], v[188:191], v[52:55]
	v_mfma_f32_16x16x32_bf16 v[44:47], v[148:151], v[180:183], v[44:47]
	v_mfma_f32_16x16x32_bf16 v[36:39], v[156:159], v[180:183], v[36:39]
	v_mfma_f32_16x16x32_bf16 v[28:31], v[148:151], v[172:175], v[28:31]
	v_mfma_f32_16x16x32_bf16 v[20:23], v[156:159], v[172:175], v[20:23]
	v_mfma_f32_16x16x32_bf16 v[12:15], v[148:151], v[164:167], v[12:15]
	v_mfma_f32_16x16x32_bf16 v[2:5], v[156:159], v[164:167], v[4:7]
	v_mfma_f32_16x16x32_bf16 v[60:63], v[152:155], v[192:195], v[60:63]
	v_mfma_f32_16x16x32_bf16 v[52:55], v[160:163], v[192:195], v[52:55]
	v_mfma_f32_16x16x32_bf16 v[44:47], v[152:155], v[184:187], v[44:47]
	v_mfma_f32_16x16x32_bf16 v[36:39], v[160:163], v[184:187], v[36:39]
	v_mfma_f32_16x16x32_bf16 v[28:31], v[152:155], v[176:179], v[28:31]
	v_mfma_f32_16x16x32_bf16 v[20:23], v[160:163], v[176:179], v[20:23]
	v_mfma_f32_16x16x32_bf16 v[12:15], v[152:155], v[168:171], v[12:15]
	v_mfma_f32_16x16x32_bf16 v[4:7], v[160:163], v[168:171], v[2:5]
	s_setprio 0
.LBB0_4158:
	s_barrier
	s_add_u32 s28, s28, 0x40080
	s_addc_u32 s29, s29, 0
	s_mov_b32 m0, s45
	s_nop 0
	global_load_lds_dwordx4 v198, s[28:29]
	s_mov_b32 m0, s46
	s_and_b64 vcc, exec, s[8:9]
	global_load_lds_dwordx4 v202, s[28:29]
	s_waitcnt vmcnt(6)
	s_barrier
	s_cbranch_vccnz .LBB0_4151
	s_setprio 1
	s_waitcnt lgkmcnt(0)
	v_mfma_f32_16x16x32_bf16 v[64:67], v[132:135], v[188:191], v[64:67]
	v_mfma_f32_16x16x32_bf16 v[56:59], v[140:143], v[188:191], v[56:59]
	v_mfma_f32_16x16x32_bf16 v[48:51], v[132:135], v[180:183], v[48:51]
	v_mfma_f32_16x16x32_bf16 v[40:43], v[140:143], v[180:183], v[40:43]
	v_mfma_f32_16x16x32_bf16 v[32:35], v[132:135], v[172:175], v[32:35]
	v_mfma_f32_16x16x32_bf16 v[24:27], v[140:143], v[172:175], v[24:27]
	v_mfma_f32_16x16x32_bf16 v[16:19], v[132:135], v[164:167], v[16:19]
	v_mfma_f32_16x16x32_bf16 v[8:11], v[140:143], v[164:167], v[8:11]
	v_mfma_f32_16x16x32_bf16 v[64:67], v[136:139], v[192:195], v[64:67]
	v_mfma_f32_16x16x32_bf16 v[56:59], v[144:147], v[192:195], v[56:59]
	v_mfma_f32_16x16x32_bf16 v[48:51], v[136:139], v[184:187], v[48:51]
	v_mfma_f32_16x16x32_bf16 v[40:43], v[144:147], v[184:187], v[40:43]
	v_mfma_f32_16x16x32_bf16 v[32:35], v[136:139], v[176:179], v[32:35]
	v_mfma_f32_16x16x32_bf16 v[24:27], v[144:147], v[176:179], v[24:27]
	v_mfma_f32_16x16x32_bf16 v[16:19], v[136:139], v[168:171], v[16:19]
	v_mfma_f32_16x16x32_bf16 v[8:11], v[144:147], v[168:171], v[8:11]
	s_setprio 0
	s_branch .LBB0_4151

.LBB0_4258:
	ds_read_b128 v[148:151], v205
	ds_read_b128 v[152:155], v205 offset:1024
	ds_read_b128 v[156:159], v205 offset:2048
	ds_read_b128 v[160:163], v205 offset:3072
	s_mov_b64 s[10:11], s[22:23]
	s_add_u32 s22, s10, 0x100
	s_addc_u32 s23, s11, 0
	s_cmp_eq_u32 s5, s53
	s_cselect_b32 s29, s19, s23
	s_cselect_b32 s28, s18, s22
	s_cselect_b32 s27, s21, s17
	s_cselect_b32 s26, s20, s12
	s_add_i32 m0, s36, 0xc000
	s_waitcnt lgkmcnt(0)
	ds_read_b128 v[164:167], v230
	ds_read_b128 v[168:171], v230 offset:1024
	ds_read_b128 v[172:175], v230 offset:2048
	ds_read_b128 v[176:179], v230 offset:3072
	ds_read_b128 v[180:183], v230 offset:4096
	ds_read_b128 v[184:187], v230 offset:5120
	ds_read_b128 v[188:191], v230 offset:6144
	ds_read_b128 v[192:195], v230 offset:7168
	global_load_lds_dwordx4 v214, s[10:11]
	s_add_i32 m0, s36, 0xe000
	s_nop 0
	global_load_lds_dwordx4 v216, s[10:11]
	s_waitcnt lgkmcnt(8)
	s_barrier
	s_waitcnt lgkmcnt(0)
	s_setprio 1
	s_waitcnt lgkmcnt(0)
	v_mfma_f32_16x16x32_bf16 v[84:87], v[148:151], v[164:167], v[84:87]
	v_mfma_f32_16x16x32_bf16 v[76:79], v[156:159], v[164:167], v[76:79]
	v_mfma_f32_16x16x32_bf16 v[64:67], v[148:151], v[172:175], v[64:67]
	v_mfma_f32_16x16x32_bf16 v[60:63], v[156:159], v[172:175], v[60:63]
	v_mfma_f32_16x16x32_bf16 v[48:51], v[148:151], v[180:183], v[48:51]
	v_mfma_f32_16x16x32_bf16 v[44:47], v[156:159], v[180:183], v[44:47]
	v_mfma_f32_16x16x32_bf16 v[32:35], v[148:151], v[188:191], v[32:35]
	v_mfma_f32_16x16x32_bf16 v[24:27], v[156:159], v[188:191], v[24:27]
	v_mfma_f32_16x16x32_bf16 v[84:87], v[152:155], v[168:171], v[84:87]
	v_mfma_f32_16x16x32_bf16 v[76:79], v[160:163], v[168:171], v[76:79]
	v_mfma_f32_16x16x32_bf16 v[64:67], v[152:155], v[176:179], v[64:67]
	v_mfma_f32_16x16x32_bf16 v[60:63], v[160:163], v[176:179], v[60:63]
	v_mfma_f32_16x16x32_bf16 v[48:51], v[152:155], v[184:187], v[48:51]
	v_mfma_f32_16x16x32_bf16 v[44:47], v[160:163], v[184:187], v[44:47]
	v_mfma_f32_16x16x32_bf16 v[32:35], v[152:155], v[192:195], v[32:35]
	v_mfma_f32_16x16x32_bf16 v[24:27], v[160:163], v[192:195], v[24:27]
	s_setprio 0
	s_barrier
	s_add_i32 s10, s49, s34
	v_lshl_add_u64 v[2:3], s[26:27], 0, v[198:199]
	s_mov_b32 m0, s10
	ds_read_b128 v[132:135], v232
	ds_read_b128 v[136:139], v232 offset:1024
	ds_read_b128 v[140:143], v232 offset:2048
	ds_read_b128 v[144:147], v232 offset:3072
	global_load_lds_dwordx4 v198, s[26:27]
	v_lshl_add_u64 v[220:221], s[26:27], 0, v[202:203]
	s_add_i32 m0, s10, 0x2000
	s_nop 0
	global_load_lds_dwordx4 v202, s[26:27]
	s_barrier
	s_waitcnt lgkmcnt(0)
	s_setprio 1
	s_waitcnt lgkmcnt(0)
	v_mfma_f32_16x16x32_bf16 v[72:75], v[132:135], v[164:167], v[72:75]
	v_mfma_f32_16x16x32_bf16 v[68:71], v[140:143], v[164:167], v[68:71]
	v_mfma_f32_16x16x32_bf16 v[56:59], v[132:135], v[172:175], v[56:59]
	v_mfma_f32_16x16x32_bf16 v[52:55], v[140:143], v[172:175], v[52:55]
	v_mfma_f32_16x16x32_bf16 v[40:43], v[132:135], v[180:183], v[40:43]
	v_mfma_f32_16x16x32_bf16 v[36:39], v[140:143], v[180:183], v[36:39]
	v_mfma_f32_16x16x32_bf16 v[20:23], v[132:135], v[188:191], v[20:23]
	v_mfma_f32_16x16x32_bf16 v[12:15], v[140:143], v[188:191], v[12:15]
	v_mfma_f32_16x16x32_bf16 v[72:75], v[136:139], v[168:171], v[72:75]
	v_mfma_f32_16x16x32_bf16 v[68:71], v[144:147], v[168:171], v[68:71]
	v_mfma_f32_16x16x32_bf16 v[56:59], v[136:139], v[176:179], v[56:59]
	v_mfma_f32_16x16x32_bf16 v[52:55], v[144:147], v[176:179], v[52:55]
	v_mfma_f32_16x16x32_bf16 v[40:43], v[136:139], v[184:187], v[40:43]
	v_mfma_f32_16x16x32_bf16 v[36:39], v[144:147], v[184:187], v[36:39]
	v_mfma_f32_16x16x32_bf16 v[20:23], v[136:139], v[192:195], v[20:23]
	v_mfma_f32_16x16x32_bf16 v[12:15], v[144:147], v[192:195], v[12:15]
	s_setprio 0
	s_mov_b32 m0, s36
	v_lshl_add_u64 v[222:223], s[28:29], 0, v[196:197]
	s_barrier
	ds_read_b128 v[188:191], v230 offset:16384
	ds_read_b128 v[192:195], v230 offset:17408
	ds_read_b128 v[180:183], v230 offset:18432
	ds_read_b128 v[184:187], v230 offset:19456
	ds_read_b128 v[172:175], v230 offset:20480
	ds_read_b128 v[176:179], v230 offset:21504
	ds_read_b128 v[164:167], v230 offset:22528
	ds_read_b128 v[168:171], v230 offset:23552
	global_load_lds_dwordx4 v196, s[28:29]
	v_lshl_add_u64 v[224:225], s[28:29], 0, v[200:201]
	s_mov_b32 m0, s37
	v_cmp_ne_u32_e64 s[10:11], 1, v233
	global_load_lds_dwordx4 v200, s[28:29]
	s_barrier
	s_waitcnt lgkmcnt(0)
	s_andn2_b64 vcc, exec, s[24:25]
	s_cbranch_vccnz .LBB0_4260
	s_setprio 1
	s_waitcnt lgkmcnt(0)
	v_mfma_f32_16x16x32_bf16 v[128:131], v[148:151], v[188:191], v[128:131]
	v_mfma_f32_16x16x32_bf16 v[124:127], v[156:159], v[188:191], v[124:127]
	v_mfma_f32_16x16x32_bf16 v[112:115], v[148:151], v[180:183], v[112:115]
	v_mfma_f32_16x16x32_bf16 v[108:111], v[156:159], v[180:183], v[108:111]
	v_mfma_f32_16x16x32_bf16 v[96:99], v[148:151], v[172:175], v[96:99]
	v_mfma_f32_16x16x32_bf16 v[92:95], v[156:159], v[172:175], v[92:95]
	v_mfma_f32_16x16x32_bf16 v[28:31], v[148:151], v[164:167], v[28:31]
	v_mfma_f32_16x16x32_bf16 v[16:19], v[156:159], v[164:167], v[16:19]
	v_mfma_f32_16x16x32_bf16 v[128:131], v[152:155], v[192:195], v[128:131]
	v_mfma_f32_16x16x32_bf16 v[124:127], v[160:163], v[192:195], v[124:127]
	v_mfma_f32_16x16x32_bf16 v[112:115], v[152:155], v[184:187], v[112:115]
	v_mfma_f32_16x16x32_bf16 v[108:111], v[160:163], v[184:187], v[108:111]
	v_mfma_f32_16x16x32_bf16 v[96:99], v[152:155], v[176:179], v[96:99]
	v_mfma_f32_16x16x32_bf16 v[92:95], v[160:163], v[176:179], v[92:95]
	v_mfma_f32_16x16x32_bf16 v[28:31], v[152:155], v[168:171], v[28:31]
	v_mfma_f32_16x16x32_bf16 v[16:19], v[160:163], v[168:171], v[16:19]
	s_setprio 0
.LBB0_4260:
	s_barrier
	s_add_u32 s54, s26, 0xb0000
	s_addc_u32 s55, s27, 0
	s_mov_b32 m0, s38
	s_nop 0
	global_load_lds_dwordx4 v198, s[54:55]
	s_mov_b32 m0, s39
	s_and_b64 vcc, exec, s[10:11]
	global_load_lds_dwordx4 v202, s[54:55]
	s_waitcnt vmcnt(6)
	s_barrier
	s_cbranch_vccnz .LBB0_4262
	s_setprio 1
	s_waitcnt lgkmcnt(0)
	v_mfma_f32_16x16x32_bf16 v[120:123], v[132:135], v[188:191], v[120:123]
	v_mfma_f32_16x16x32_bf16 v[116:119], v[140:143], v[188:191], v[116:119]
	v_mfma_f32_16x16x32_bf16 v[104:107], v[132:135], v[180:183], v[104:107]
	v_mfma_f32_16x16x32_bf16 v[100:103], v[140:143], v[180:183], v[100:103]
	v_mfma_f32_16x16x32_bf16 v[88:91], v[132:135], v[172:175], v[88:91]
	v_mfma_f32_16x16x32_bf16 v[80:83], v[140:143], v[172:175], v[80:83]
	v_mfma_f32_16x16x32_bf16 v[8:11], v[132:135], v[164:167], v[8:11]
	v_mfma_f32_16x16x32_bf16 v[4:7], v[140:143], v[164:167], v[4:7]
	v_mfma_f32_16x16x32_bf16 v[120:123], v[136:139], v[192:195], v[120:123]
	v_mfma_f32_16x16x32_bf16 v[116:119], v[144:147], v[192:195], v[116:119]
	v_mfma_f32_16x16x32_bf16 v[104:107], v[136:139], v[184:187], v[104:107]
	v_mfma_f32_16x16x32_bf16 v[100:103], v[144:147], v[184:187], v[100:103]
	v_mfma_f32_16x16x32_bf16 v[88:91], v[136:139], v[176:179], v[88:91]
	v_mfma_f32_16x16x32_bf16 v[80:83], v[144:147], v[176:179], v[80:83]
	v_mfma_f32_16x16x32_bf16 v[8:11], v[136:139], v[168:171], v[8:11]
	v_mfma_f32_16x16x32_bf16 v[4:7], v[144:147], v[168:171], v[4:7]
	s_setprio 0
.LBB0_4262:
	s_add_i32 s54, 0, 0x18000
	v_add_u32_e32 v1, s54, v226
	s_barrier
	ds_read_b128 v[148:151], v1
	ds_read_b128 v[152:155], v1 offset:1024
	ds_read_b128 v[156:159], v1 offset:2048
	ds_read_b128 v[160:163], v1 offset:3072
	s_add_u32 s28, s28, 0xb0000
	s_addc_u32 s29, s29, 0
	s_mov_b32 m0, s40
	s_waitcnt lgkmcnt(0)
	ds_read_b128 v[164:167], v230 offset:32768
	ds_read_b128 v[168:171], v230 offset:33792
	ds_read_b128 v[172:175], v230 offset:34816
	ds_read_b128 v[176:179], v230 offset:35840
	ds_read_b128 v[180:183], v230 offset:36864
	ds_read_b128 v[184:187], v230 offset:37888
	ds_read_b128 v[188:191], v230 offset:38912
	ds_read_b128 v[192:195], v230 offset:39936
	global_load_lds_dwordx4 v196, s[28:29]
	s_mov_b32 m0, s41
	s_nop 0
	global_load_lds_dwordx4 v200, s[28:29]
	s_waitcnt lgkmcnt(8)
	s_barrier
	s_waitcnt lgkmcnt(0)
	s_setprio 1
	s_waitcnt lgkmcnt(0)
	v_mfma_f32_16x16x32_bf16 v[84:87], v[148:151], v[164:167], v[84:87]
	v_mfma_f32_16x16x32_bf16 v[76:79], v[156:159], v[164:167], v[76:79]
	v_mfma_f32_16x16x32_bf16 v[64:67], v[148:151], v[172:175], v[64:67]
	v_mfma_f32_16x16x32_bf16 v[60:63], v[156:159], v[172:175], v[60:63]
	v_mfma_f32_16x16x32_bf16 v[48:51], v[148:151], v[180:183], v[48:51]
	v_mfma_f32_16x16x32_bf16 v[44:47], v[156:159], v[180:183], v[44:47]
	v_mfma_f32_16x16x32_bf16 v[32:35], v[148:151], v[188:191], v[32:35]
	v_mfma_f32_16x16x32_bf16 v[24:27], v[156:159], v[188:191], v[24:27]
	v_mfma_f32_16x16x32_bf16 v[84:87], v[152:155], v[168:171], v[84:87]
	v_mfma_f32_16x16x32_bf16 v[76:79], v[160:163], v[168:171], v[76:79]
	v_mfma_f32_16x16x32_bf16 v[64:67], v[152:155], v[176:179], v[64:67]
	v_mfma_f32_16x16x32_bf16 v[60:63], v[160:163], v[176:179], v[60:63]
	v_mfma_f32_16x16x32_bf16 v[48:51], v[152:155], v[184:187], v[48:51]
	v_mfma_f32_16x16x32_bf16 v[44:47], v[160:163], v[184:187], v[44:47]
	v_mfma_f32_16x16x32_bf16 v[32:35], v[152:155], v[192:195], v[32:35]
	v_mfma_f32_16x16x32_bf16 v[24:27], v[160:163], v[192:195], v[24:27]
	s_setprio 0
	s_barrier
	s_add_i32 s28, s54, s34
	v_add_u32_e32 v1, 0x1c000, v231
	v_lshl_add_u64 v[2:3], v[2:3], 0, s[14:15]
	s_mov_b32 m0, s28
	ds_read_b128 v[132:135], v1
	ds_read_b128 v[136:139], v1 offset:1024
	ds_read_b128 v[140:143], v1 offset:2048
	ds_read_b128 v[144:147], v1 offset:3072
	global_load_lds_dwordx4 v[2:3], off
	v_lshl_add_u64 v[2:3], v[220:221], 0, s[14:15]
	s_add_i32 m0, s28, 0x2000
	s_nop 0
	global_load_lds_dwordx4 v[2:3], off
	s_barrier
	s_waitcnt lgkmcnt(0)
	s_setprio 1
	s_waitcnt lgkmcnt(0)
	v_mfma_f32_16x16x32_bf16 v[72:75], v[132:135], v[164:167], v[72:75]
	v_mfma_f32_16x16x32_bf16 v[68:71], v[140:143], v[164:167], v[68:71]
	v_mfma_f32_16x16x32_bf16 v[56:59], v[132:135], v[172:175], v[56:59]
	v_mfma_f32_16x16x32_bf16 v[52:55], v[140:143], v[172:175], v[52:55]
	v_mfma_f32_16x16x32_bf16 v[40:43], v[132:135], v[180:183], v[40:43]
	v_mfma_f32_16x16x32_bf16 v[36:39], v[140:143], v[180:183], v[36:39]
	v_mfma_f32_16x16x32_bf16 v[20:23], v[132:135], v[188:191], v[20:23]
	v_mfma_f32_16x16x32_bf16 v[12:15], v[140:143], v[188:191], v[12:15]
	v_mfma_f32_16x16x32_bf16 v[72:75], v[136:139], v[168:171], v[72:75]
	v_mfma_f32_16x16x32_bf16 v[68:71], v[144:147], v[168:171], v[68:71]
	v_mfma_f32_16x16x32_bf16 v[56:59], v[136:139], v[176:179], v[56:59]
	v_mfma_f32_16x16x32_bf16 v[52:55], v[144:147], v[176:179], v[52:55]
	v_mfma_f32_16x16x32_bf16 v[40:43], v[136:139], v[184:187], v[40:43]
	v_mfma_f32_16x16x32_bf16 v[36:39], v[144:147], v[184:187], v[36:39]
	v_mfma_f32_16x16x32_bf16 v[20:23], v[136:139], v[192:195], v[20:23]
	v_mfma_f32_16x16x32_bf16 v[12:15], v[144:147], v[192:195], v[12:15]
	s_setprio 0
	s_mov_b32 m0, s43
	v_lshl_add_u64 v[2:3], v[222:223], 0, s[14:15]
	s_barrier
	ds_read_b128 v[188:191], v230 offset:49152
	ds_read_b128 v[192:195], v230 offset:50176
	ds_read_b128 v[180:183], v230 offset:51200
	ds_read_b128 v[184:187], v230 offset:52224
	ds_read_b128 v[172:175], v230 offset:53248
	ds_read_b128 v[176:179], v230 offset:54272
	ds_read_b128 v[164:167], v230 offset:55296
	ds_read_b128 v[168:171], v230 offset:56320
	global_load_lds_dwordx4 v[2:3], off
	v_lshl_add_u64 v[2:3], v[224:225], 0, s[14:15]
	s_mov_b32 m0, s44
	s_and_b64 vcc, exec, s[10:11]
	global_load_lds_dwordx4 v[2:3], off
	s_barrier
	s_waitcnt lgkmcnt(0)
	s_cbranch_vccnz .LBB0_4264
	s_setprio 1
	s_waitcnt lgkmcnt(0)
	v_mfma_f32_16x16x32_bf16 v[128:131], v[148:151], v[188:191], v[128:131]
	v_mfma_f32_16x16x32_bf16 v[124:127], v[156:159], v[188:191], v[124:127]
	v_mfma_f32_16x16x32_bf16 v[112:115], v[148:151], v[180:183], v[112:115]
	v_mfma_f32_16x16x32_bf16 v[108:111], v[156:159], v[180:183], v[108:111]
	v_mfma_f32_16x16x32_bf16 v[96:99], v[148:151], v[172:175], v[96:99]
	v_mfma_f32_16x16x32_bf16 v[92:95], v[156:159], v[172:175], v[92:95]
	v_mfma_f32_16x16x32_bf16 v[28:31], v[148:151], v[164:167], v[28:31]
	v_mfma_f32_16x16x32_bf16 v[16:19], v[156:159], v[164:167], v[16:19]
	v_mfma_f32_16x16x32_bf16 v[128:131], v[152:155], v[192:195], v[128:131]
	v_mfma_f32_16x16x32_bf16 v[124:127], v[160:163], v[192:195], v[124:127]
	v_mfma_f32_16x16x32_bf16 v[112:115], v[152:155], v[184:187], v[112:115]
	v_mfma_f32_16x16x32_bf16 v[108:111], v[160:163], v[184:187], v[108:111]
	v_mfma_f32_16x16x32_bf16 v[96:99], v[152:155], v[176:179], v[96:99]
	v_mfma_f32_16x16x32_bf16 v[92:95], v[160:163], v[176:179], v[92:95]
	v_mfma_f32_16x16x32_bf16 v[28:31], v[152:155], v[168:171], v[28:31]
	v_mfma_f32_16x16x32_bf16 v[16:19], v[160:163], v[168:171], v[16:19]
	s_setprio 0
.LBB0_4264:
	s_barrier
	s_add_u32 s26, s26, 0xb0080
	s_addc_u32 s27, s27, 0
	s_mov_b32 m0, s45
	s_nop 0
	global_load_lds_dwordx4 v198, s[26:27]
	s_mov_b32 m0, s46
	s_and_b64 vcc, exec, s[10:11]
	global_load_lds_dwordx4 v202, s[26:27]
	s_waitcnt vmcnt(6)
	s_barrier
	s_cbranch_vccnz .LBB0_4257
	s_setprio 1
	s_waitcnt lgkmcnt(0)
	v_mfma_f32_16x16x32_bf16 v[120:123], v[132:135], v[188:191], v[120:123]
	v_mfma_f32_16x16x32_bf16 v[116:119], v[140:143], v[188:191], v[116:119]
	v_mfma_f32_16x16x32_bf16 v[104:107], v[132:135], v[180:183], v[104:107]
	v_mfma_f32_16x16x32_bf16 v[100:103], v[140:143], v[180:183], v[100:103]
	v_mfma_f32_16x16x32_bf16 v[88:91], v[132:135], v[172:175], v[88:91]
	v_mfma_f32_16x16x32_bf16 v[80:83], v[140:143], v[172:175], v[80:83]
	v_mfma_f32_16x16x32_bf16 v[8:11], v[132:135], v[164:167], v[8:11]
	v_mfma_f32_16x16x32_bf16 v[2:5], v[140:143], v[164:167], v[4:7]
	v_mfma_f32_16x16x32_bf16 v[120:123], v[136:139], v[192:195], v[120:123]
	v_mfma_f32_16x16x32_bf16 v[116:119], v[144:147], v[192:195], v[116:119]
	v_mfma_f32_16x16x32_bf16 v[104:107], v[136:139], v[184:187], v[104:107]
	v_mfma_f32_16x16x32_bf16 v[100:103], v[144:147], v[184:187], v[100:103]
	v_mfma_f32_16x16x32_bf16 v[88:91], v[136:139], v[176:179], v[88:91]
	v_mfma_f32_16x16x32_bf16 v[80:83], v[144:147], v[176:179], v[80:83]
	v_mfma_f32_16x16x32_bf16 v[8:11], v[136:139], v[168:171], v[8:11]
	v_mfma_f32_16x16x32_bf16 v[4:7], v[144:147], v[168:171], v[2:5]
	s_setprio 0
	s_branch .LBB0_4257

.LBB0_4346:
	s_or_b64 exec, exec, s[2:3]
	s_waitcnt lgkmcnt(0)
	v_mov_b32_e32 v0, 0
	s_barrier
	v_readlane_b32 s2, v255, 13
	v_mbcnt_lo_u32_b32 v0, -1, v0
	v_mbcnt_hi_u32_b32 v0, -1, v0
	v_add_u32_e32 v12, s33, v0
	s_mov_b32 s3, 0
	v_readfirstlane_b32 s1, v12
	s_ashr_i32 s1, s1, 6
	s_add_i32 s4, s1, s2
	v_mov_b32_e32 v1, 0
	s_mov_b32 s6, 0
	s_cmpk_gt_i32 s4, 0x407f
	s_cbranch_scc1 .LBB0_4362
	s_ashr_i32 s7, s6, 31
	s_lshl_b64 s[6:7], s[6:7], 3
	v_readlane_b32 s8, v255, 2
	v_readlane_b32 s9, v255, 3
	s_add_u32 s6, s8, s6
	s_addc_u32 s7, s9, s7
	s_load_dwordx2 s[6:7], s[6:7], 0xb8
	v_lshlrev_b32_e32 v4, 2, v12
	v_and_b32_e32 v14, 0xfc, v4
	v_readlane_b32 s8, v255, 39
	v_lshlrev_b32_e32 v0, 2, v14
	v_readlane_b32 s9, v255, 40
	s_movk_i32 s1, 0x80
	v_bfrev_b32_e32 v5, 0.5
	v_lshl_add_u64 v[2:3], s[8:9], 0, v[0:1]
	v_bitop3_b32 v30, v4, s1, v5 bitop3:0x6c
	v_bitop3_b32 v31, v4, 64, v5 bitop3:0x6c
	v_bitop3_b32 v32, v4, 32, v5 bitop3:0x6c
	v_bitop3_b32 v33, v4, 16, v5 bitop3:0x6c
	v_bitop3_b32 v34, v4, 8, v5 bitop3:0x6c
	v_bitop3_b32 v35, v4, 4, v5 bitop3:0x6c
	s_waitcnt lgkmcnt(0)
	v_lshl_add_u64 v[4:5], s[6:7], 0, v[0:1]
	s_lshl_b32 s6, s0, 3
	v_or_b32_e32 v6, 0x400, v0
	v_or_b32_e32 v8, 0x800, v0
	v_or_b32_e32 v0, 0xc00, v0
	s_ashr_i32 s5, s4, 31
	v_mov_b32_e32 v7, v1
	v_mov_b32_e32 v9, v1
	v_lshl_add_u64 v[10:11], s[8:9], 0, v[0:1]
	s_ashr_i32 s7, s6, 31
	s_lshl_b64 s[0:1], s[4:5], 11
	v_and_b32_e32 v0, 63, v12
	v_lshl_add_u64 v[6:7], s[8:9], 0, v[6:7]
	v_lshl_add_u64 v[8:9], s[8:9], 0, v[8:9]
	s_lshl_b64 s[8:9], s[4:5], 7
	s_lshl_b64 s[10:11], s[6:7], 7
	v_lshl_or_b32 v12, v0, 3, s0
	v_mov_b32_e32 v13, s1
	s_lshl_b64 s[12:13], s[6:7], 11
	v_mov_b32_e32 v0, 0x34ff7000
	v_mov_b32_e32 v36, 0x358637bd
	s_mov_b32 s18, 0x800000
	v_lshlrev_b32_e32 v37, 2, v14
	global_load_dwordx4 v[100:103], v[4:5], off
	global_load_dwordx4 v[104:107], v[4:5], off offset:1024
	global_load_dwordx4 v[108:111], v[4:5], off offset:2048
	global_load_dwordx4 v[112:115], v[4:5], off offset:3072
	s_cmpk_lt_i32 s4, 0x4000
	s_cbranch_scc0 .LBB0_4349
.Lmy_fin_loop:
	v_lshl_add_u64 v[22:23], s[82:83], 0, v[12:13]
	v_add_co_u32_e32 v14, vcc, 0xba67000, v22
	s_add_u32 s0, s82, s8
	s_addc_u32 s1, s83, s9
	v_addc_co_u32_e32 v15, vcc, 0, v23, vcc
	global_load_dwordx2 v[120:121], v[14:15], off offset:768
	global_load_dwordx2 v[122:123], v[14:15], off offset:1280
	global_load_dwordx2 v[124:125], v[14:15], off offset:1792
	global_load_dwordx2 v[126:127], v[14:15], off offset:2304
	global_load_dwordx4 v[40:43], v0, s[0:1] offset:768
	s_add_u32 s0, s0, 0x34ff7300
	s_addc_u32 s1, s1, 0
	global_load_dwordx4 v[44:47], v1, s[0:1] offset:16
	global_load_dwordx4 v[48:51], v1, s[0:1] offset:32
	global_load_dwordx4 v[52:55], v1, s[0:1] offset:48
	s_lshl_b64 s[14:15], s[4:5], 12
	s_add_u32 s0, s80, s14
	s_addc_u32 s1, s81, s15
	s_add_u32 s4, s4, s6
	s_addc_u32 s5, s5, s7
	s_add_u32 s8, s8, s10
	s_addc_u32 s9, s9, s11
	v_lshl_add_u64 v[12:13], v[12:13], 0, s[12:13]
	s_waitcnt vmcnt(0)
	v_add_f32_e32 v56, v40, v41
	v_add_f32_e32 v57, v42, v43
	v_add_f32_e32 v58, v44, v45
	v_add_f32_e32 v59, v46, v47
	v_add_f32_e32 v60, v48, v49
	v_add_f32_e32 v61, v50, v51
	v_add_f32_e32 v62, v52, v53
	v_add_f32_e32 v63, v54, v55
	v_add_f32_e32 v56, v56, v57
	v_add_f32_e32 v58, v58, v59
	v_add_f32_e32 v60, v60, v61
	v_add_f32_e32 v62, v62, v63
	v_add_f32_e32 v39, v56, v58
	v_add_f32_e32 v39, v39, v60
	v_add_f32_e32 v39, v39, v62
	v_fmamk_f32 v38, v39, 0x3a800000, v36
	v_mul_f32_e32 v39, 0x4b800000, v38
	v_cmp_gt_f32_e32 vcc, s18, v38
	s_nop 1
	v_cndmask_b32_e32 v38, v38, v39, vcc
	v_rsq_f32_e32 v38, v38
	s_nop 0
	v_mul_f32_e32 v39, 0x45800000, v38
	v_cndmask_b32_e32 v38, v38, v39, vcc
	v_lshlrev_b32_e32 v64, 16, v120
	v_and_b32_e32 v65, 0xffff0000, v120
	v_lshlrev_b32_e32 v66, 16, v121
	v_and_b32_e32 v67, 0xffff0000, v121
	v_mul_f32_e32 v64, v64, v38
	v_mul_f32_e32 v65, v65, v38
	v_mul_f32_e32 v66, v66, v38
	v_mul_f32_e32 v67, v67, v38
	v_mul_f32_e32 v64, v100, v64
	v_mul_f32_e32 v65, v101, v65
	v_mul_f32_e32 v66, v102, v66
	v_mul_f32_e32 v67, v103, v67
	global_store_dwordx4 v37, v[64:67], s[0:1]
	v_lshlrev_b32_e32 v68, 16, v122
	v_and_b32_e32 v69, 0xffff0000, v122
	v_lshlrev_b32_e32 v70, 16, v123
	v_and_b32_e32 v71, 0xffff0000, v123
	v_mul_f32_e32 v68, v68, v38
	v_mul_f32_e32 v69, v69, v38
	v_mul_f32_e32 v70, v70, v38
	v_mul_f32_e32 v71, v71, v38
	v_mul_f32_e32 v68, v104, v68
	v_mul_f32_e32 v69, v105, v69
	v_mul_f32_e32 v70, v106, v70
	v_mul_f32_e32 v71, v107, v71
	global_store_dwordx4 v37, v[68:71], s[0:1] offset:1024
	v_lshlrev_b32_e32 v72, 16, v124
	v_and_b32_e32 v73, 0xffff0000, v124
	v_lshlrev_b32_e32 v74, 16, v125
	v_and_b32_e32 v75, 0xffff0000, v125
	v_mul_f32_e32 v72, v72, v38
	v_mul_f32_e32 v73, v73, v38
	v_mul_f32_e32 v74, v74, v38
	v_mul_f32_e32 v75, v75, v38
	v_mul_f32_e32 v72, v108, v72
	v_mul_f32_e32 v73, v109, v73
	v_mul_f32_e32 v74, v110, v74
	v_mul_f32_e32 v75, v111, v75
	global_store_dwordx4 v37, v[72:75], s[0:1] offset:2048
	v_lshlrev_b32_e32 v76, 16, v126
	v_and_b32_e32 v77, 0xffff0000, v126
	v_lshlrev_b32_e32 v78, 16, v127
	v_and_b32_e32 v79, 0xffff0000, v127
	v_mul_f32_e32 v76, v76, v38
	v_mul_f32_e32 v77, v77, v38
	v_mul_f32_e32 v78, v78, v38
	v_mul_f32_e32 v79, v79, v38
	v_mul_f32_e32 v76, v112, v76
	v_mul_f32_e32 v77, v113, v77
	v_mul_f32_e32 v78, v114, v78
	v_mul_f32_e32 v79, v115, v79
	global_store_dwordx4 v37, v[76:79], s[0:1] offset:3072
	s_cmpk_lt_i32 s4, 0x4000
	s_cbranch_scc1 .Lmy_fin_loop
	s_cmpk_lt_i32 s4, 0x4080
	s_cbranch_scc1 .LBB0_4349
	s_branch .LBB0_4362
